# HGRN: per-step raw q/f/v rows staged by 9 LDS-DMA loads into a 4-slot LDS ring instead of 96 per-lane gathers, role-block LDS reads hoisted; weight-conversion items assigned round-robin across jobs
# speedup vs baseline: 1.0105x; 1.0105x over previous
; #define LAS __attribute__((address_space(3)))
; __device__ __forceinline__ int otid() { int t = threadIdx.x; asm volatile("" : "+v"(t)); return t; }
; __device__ __forceinline__ void convert_weights(LAS unsigned char* lds, int layer, int j0, int j1) {
;     const int tid = otid(); const int lane = tid & 63, wid = tid >> 6;
;     LAS float* scr = (LAS float*)(lds + wid * 8704);
;     const int gw = blockIdx.x * NWAVES + wid, NGW = gridDim.x * NWAVES;
;     for (int j = j0; j < j1; ++j) {
;         const Job J = get_job(layer, j);
;         const int nitems = (J.K / 64) * (J.Nd / 32);
;         for (int it = gw; it < nitems; it += NGW) convert_item(J, scr, it, lane);
.LBB0_7:
	s_cmp_lt_i32 s94, 1
	s_cselect_b64 s[10:11], -1, 0
	s_cmp_gt_i32 s95, 0
	s_cselect_b64 s[4:5], -1, 0
	s_and_b64 s[4:5], s[10:11], s[4:5]
	s_andn2_b64 vcc, exec, s[4:5]
	s_cbranch_vccnz .LBB0_137
	s_mov_b32 s60, 0
	s_mov_b64 s[14:15], s[90:91]
	v_mov_b32_e32 v10, v234
	v_mov_b32_e32 v2, v234
	s_load_dwordx2 s[12:13], s[14:15], 0xd0
	s_movk_i32 s4, 0x2200
	v_ashrrev_i32_e32 v3, 6, v2
	v_mul_lo_u32 v4, v3, s4
	v_lshlrev_b32_e32 v6, 2, v2
	v_and_b32_e32 v8, 7, v2
	v_bfe_u32 v23, v2, 3, 3
	v_add_u32_e32 v4, 0, v4
	v_and_b32_e32 v11, 31, v2
	v_and_b32_e32 v6, 16, v6
	v_lshrrev_b32_e32 v7, 1, v2
	v_lshlrev_b32_e32 v12, 3, v8
	v_mul_u32_u24_e32 v8, 0x420, v8
	v_lshlrev_b32_e32 v16, 2, v23
	v_and_b32_e32 v5, 3, v2
	v_lshl_add_u32 v9, v11, 2, v4
	v_add3_u32 v25, v4, v8, v16
	v_and_or_b32 v4, v7, 12, v6
	s_lshl_b32 s33, s2, 3
	s_lshl_b32 s1, s2, 9
	v_bfe_u32 v17, v2, 5, 1
	v_or3_b32 v16, v5, v4, 64
	s_lshl_b32 s38, s2, 8
	v_and_b32_e32 v4, 0xffffffc0, v2
	v_add_u32_e32 v1, s33, v3
	s_movk_i32 s4, 0x280
	v_mul_u32_u24_e32 v14, 0x84, v17
	v_lshl_add_u32 v27, v3, 5, s38
	v_add_u32_e32 v30, s1, v4
	v_lshlrev_b32_e32 v4, 4, v3
	v_lshlrev_b16_e32 v3, 5, v3
	s_lshl_b32 s3, s20, 3
	s_mov_b32 s39, 0
	v_or3_b32 v13, v5, v6, s4
	v_mov_b32_e32 v15, 0
	v_lshl_add_u32 v31, s2, 7, v4
	v_bitop3_b16 v32, v3, v2, 31 bitop3:0xf8
	s_movk_i32 s40, 0x1ff
	s_movk_i32 s41, 0x60
	s_movk_i32 s42, 0x27f
	s_movk_i32 s43, 0x67f
	s_movk_i32 s44, 0xe7f
	s_movk_i32 s45, 0xea0
	v_add_u32_e32 v33, v9, v14
	v_lshlrev_b32_e32 v18, 2, v12
	s_branch .LBB0_10

; __device__ __forceinline__ void convert_weights(LAS unsigned char* lds, int layer, int j0, int j1) {
;     ...
;     for (int j = j0; j < j1; ++j) {
;         const Job J = get_job(layer, j);
;         const int nitems = (J.K / 64) * (J.Nd / 32);
;         for (int it = gw; it < nitems; it += NGW) convert_item(J, scr, it, lane);
.LBB0_70:
	s_waitcnt lgkmcnt(0)
	s_lshr_b32 s22, s46, 6
	s_mul_i32 s50, s48, s22
	v_subrev_u32_e32 v100, s60, v1
	v_add_u32_e32 v101, s3, v100
	v_cmp_gt_i32_e32 vcc, 0, v100
	s_nop 1
	v_cndmask_b32_e32 v100, v100, v101, vcc
	s_add_i32 s60, s60, s50
	s_cmp_ge_u32 s60, s3
	s_cselect_b32 s61, s3, 0
	s_sub_i32 s60, s60, s61
	s_cmp_ge_u32 s60, s3
	s_cselect_b32 s61, s3, 0
	s_sub_i32 s60, s60, s61
	v_cmp_gt_i32_e32 vcc, s50, v100
	s_and_saveexec_b64 s[22:23], vcc
	s_cbranch_execz .LBB0_9
	v_cvt_f32_u32_e32 v2, s48
	s_lshl_b64 s[26:27], s[18:19], 3
	s_load_dwordx2 s[24:25], s[4:5], 0x0
	v_mov_b32_e32 v19, v15
	v_rcp_iflag_f32_e32 v2, v2
	s_cmp_lg_u64 s[30:31], 0
	v_lshl_add_u64 v[20:21], s[30:31], 0, v[18:19]
	s_cselect_b64 s[30:31], -1, 0
	v_mul_f32_e32 v2, 0x4f7ffffe, v2
	v_cvt_u32_f32_e32 v2, v2
	s_sub_i32 s51, 0, s48
	s_lshl_b32 s4, s48, 6
	s_lshl_b32 s52, s48, 5
	v_mul_lo_u32 v3, s51, v2
	v_mul_hi_u32 v3, v2, v3
	s_sub_i32 s55, 0, s4
	s_lshl_b32 s4, s48, 4
	s_mov_b64 s[28:29], 0
	v_add_u32_e32 v19, v2, v3
	s_sub_i32 s53, 0, s52
	s_lshl_b32 s54, s3, 5
	s_lshl_b32 s56, s3, 6
	s_sub_i32 s57, 0, s4
	s_lshl_b32 s58, s3, 4
	v_sub_u32_e32 v101, v100, v1
	v_lshlrev_b32_e32 v102, 5, v101
	v_add_u16_e32 v34, v32, v102
	v_lshl_add_u32 v22, v101, 4, v31
	v_lshl_add_u32 v24, v101, 6, v30
	v_lshl_add_u32 v35, v101, 5, v27
	v_mov_b32_e32 v26, v100
	s_branch .LBB0_75

; __device__ __forceinline__ u32x4 pack8(f32x4 a, f32x4 b) { u32x4 w; w.x = cvtpk(a[0], a[1]); w.y = cvtpk(a[2], a[3]); w.z = cvtpk(b[0], b[1]); w.w = cvtpk(b[2], b[3]); return w; }
; __global__ void __launch_bounds__(NTHREADS, 2) fwd_megakernel(Params Pkern) {
;     ...
;             for (int rr = 0; rr < 2; ++rr) { float ss = 0.f;
; #pragma unroll
;                 for (int j = 0; j < 2; ++j) { const f32x4 a = va[rr][2 * j], b = va[rr][2 * j + 1];
;                     *(u32x4*)(HB + (size_t)(m + rr) * DM + 512 * j + lane * 8) = pack8(a, b);
;                     ss += (a[0] * a[0] + a[1] * a[1]) + (a[2] * a[2] + a[3] * a[3]) + (b[0] * b[0] + b[1] * b[1]) + (b[2] * b[2] + b[3] * b[3]); }
; #pragma unroll
;                 for (int o = 1; o < 64; o <<= 1) ss += __shfl_xor(ss, o);
;                 if (lane == 0) RS[m + rr] = ss; }
.LBB0_132:
	global_load_dwordx4 v[26:29], v[24:25], off offset:-4096
	global_load_dwordx4 v[36:39], v[24:25], off offset:-4080
	global_load_dwordx4 v[40:43], v[24:25], off offset:-2048
	global_load_dwordx4 v[44:47], v[24:25], off offset:-2032
	global_load_dwordx4 v[10:13], v[24:25], off offset:16
	global_load_dwordx4 v[14:17], v[24:25], off
	global_load_dwordx4 v[2:5], v[24:25], off offset:2064
	s_waitcnt lgkmcnt(0)
	global_load_dwordx4 v[6:9], v[24:25], off offset:2048
	s_waitcnt vmcnt(7)
	v_mul_f32_e32 v19, v27, v27
	v_mul_f32_e32 v35, v29, v29
	s_waitcnt vmcnt(5)
	v_mul_f32_e32 v50, v41, v41
	v_mul_f32_e32 v51, v43, v43
	v_mul_f32_e32 v48, v37, v37
	s_waitcnt vmcnt(4)
	v_mul_f32_e32 v52, v45, v45
	v_fmac_f32_e32 v19, v26, v26
	v_fmac_f32_e32 v35, v28, v28
	v_fmac_f32_e32 v50, v40, v40
	v_fmac_f32_e32 v51, v42, v42
	v_mul_f32_e32 v49, v39, v39
	v_mul_f32_e32 v53, v47, v47
	v_fmac_f32_e32 v48, v36, v36
	v_fmac_f32_e32 v52, v44, v44
	v_add_f32_e32 v19, v19, v35
	v_add_f32_e32 v35, v50, v51
	v_fmac_f32_e32 v49, v38, v38
	v_fmac_f32_e32 v53, v46, v46
	v_add_f32_e32 v19, v19, v48
	v_add_f32_e32 v35, v35, v52
	v_add_f32_e32 v19, v49, v19
	v_add_f32_e32 v35, v53, v35
	v_add_f32_e32 v19, v19, v35
	ds_bpermute_b32 v35, v1, v19
	v_cvt_pk_bf16_f32 v49, v28, v29
	v_lshl_add_u64 v[52:53], s[12:13], 0, v[22:23]
	v_cvt_pk_bf16_f32 v48, v26, v27
	v_add_co_u32_e64 v26, s[4:5], s1, v52
	s_waitcnt lgkmcnt(0)
	v_add_f32_e32 v19, v19, v35
	ds_bpermute_b32 v35, v30, v19
	v_cvt_pk_bf16_f32 v50, v36, v37
	v_cvt_pk_bf16_f32 v51, v38, v39
	v_addc_co_u32_e64 v27, s[4:5], 0, v53, s[4:5]
	s_waitcnt lgkmcnt(0)
	v_add_f32_e32 v19, v19, v35
	ds_bpermute_b32 v35, v31, v19
	v_cvt_pk_bf16_f32 v36, v40, v41
	v_cvt_pk_bf16_f32 v37, v42, v43
	v_cvt_pk_bf16_f32 v38, v44, v45
	v_cvt_pk_bf16_f32 v39, v46, v47
	s_waitcnt lgkmcnt(0)
	v_add_f32_e32 v19, v19, v35
	ds_bpermute_b32 v35, v32, v19
	global_store_dwordx4 v[26:27], v[48:51], off
	global_store_dwordx4 v[26:27], v[36:39], off offset:1024
	s_waitcnt lgkmcnt(0)
	v_add_f32_e32 v19, v19, v35
	ds_bpermute_b32 v28, v33, v19
	s_waitcnt lgkmcnt(0)
	v_add_f32_e32 v19, v19, v28
	ds_bpermute_b32 v35, v34, v19
	v_lshl_add_u64 v[28:29], s[12:13], 0, v[20:21]
	s_and_saveexec_b64 s[4:5], vcc
	s_cbranch_execz .LBB0_134
	s_waitcnt lgkmcnt(0)
	v_add_f32_e32 v19, v19, v35
	global_store_dword v[28:29], v19, off offset:-4
.LBB0_134:
	s_or_b64 exec, exec, s[4:5]
	s_waitcnt vmcnt(4)
	v_mul_f32_e32 v19, v15, v15
	s_waitcnt lgkmcnt(0)
	v_mul_f32_e32 v35, v17, v17
	v_fmac_f32_e32 v19, v14, v14
	v_fmac_f32_e32 v35, v16, v16
	v_add_f32_e32 v19, v19, v35
	v_mul_f32_e32 v35, v11, v11
	v_fmac_f32_e32 v35, v10, v10
	v_add_f32_e32 v19, v19, v35
	v_mul_f32_e32 v35, v13, v13
	v_fmac_f32_e32 v35, v12, v12
	v_add_f32_e32 v19, v35, v19
	s_waitcnt vmcnt(2)
	v_mul_f32_e32 v35, v7, v7
	v_mul_f32_e32 v36, v9, v9
	v_fmac_f32_e32 v35, v6, v6
	v_fmac_f32_e32 v36, v8, v8
	v_add_f32_e32 v35, v35, v36
	v_mul_f32_e32 v36, v3, v3
	v_fmac_f32_e32 v36, v2, v2
	v_add_f32_e32 v35, v35, v36
	v_mul_f32_e32 v36, v5, v5
	v_fmac_f32_e32 v36, v4, v4
	v_add_f32_e32 v35, v36, v35
	v_add_f32_e32 v19, v19, v35
	ds_bpermute_b32 v35, v1, v19
	v_cvt_pk_bf16_f32 v14, v14, v15
	v_cvt_pk_bf16_f32 v15, v16, v17
	v_cvt_pk_bf16_f32 v16, v10, v11
	v_cvt_pk_bf16_f32 v10, v6, v7
	s_waitcnt lgkmcnt(0)
	v_add_f32_e32 v19, v19, v35
	ds_bpermute_b32 v35, v30, v19
	v_cvt_pk_bf16_f32 v17, v12, v13
	v_cvt_pk_bf16_f32 v11, v8, v9
	v_cvt_pk_bf16_f32 v12, v2, v3
	v_cvt_pk_bf16_f32 v13, v4, v5
	s_waitcnt lgkmcnt(0)
	v_add_f32_e32 v19, v19, v35
	ds_bpermute_b32 v35, v31, v19
	global_store_dwordx4 v[26:27], v[14:17], off offset:2048
	global_store_dwordx4 v[26:27], v[10:13], off offset:3072
	s_waitcnt lgkmcnt(0)
	v_add_f32_e32 v19, v19, v35
	ds_bpermute_b32 v35, v32, v19
	s_waitcnt lgkmcnt(0)
	v_add_f32_e32 v19, v19, v35
	ds_bpermute_b32 v35, v33, v19
	s_waitcnt lgkmcnt(0)
	v_add_f32_e32 v6, v19, v35
	ds_bpermute_b32 v7, v34, v6
	s_and_saveexec_b64 s[4:5], vcc
	s_cbranch_execz .LBB0_131
	s_waitcnt lgkmcnt(0)
	v_add_f32_e32 v2, v6, v7
	global_store_dword v[28:29], v2, off
	s_branch .LBB0_131

; __device__ __forceinline__ float rstd_of(float ss, float invn) { return __builtin_amdgcn_rsqf(ss * invn + EPS); }
; __device__ __forceinline__ u32x4 pack8(f32x4 a, f32x4 b) { u32x4 w; w.x = cvtpk(a[0], a[1]); w.y = cvtpk(a[2], a[3]); w.z = cvtpk(b[0], b[1]); w.w = cvtpk(b[2], b[3]); return w; }
;     __device__ __forceinline__ void operator()(const Acc& acc, const Unit& u, int wr, int wc, int fr, int fq) const {
;         const int col0 = u.pn * 128 + wc * 32 + 8 * fq;
;         float tpre[2][4];
; #pragma unroll
;         for (int ai = 0; ai < 2; ++ai)
; #pragma unroll
;             for (int m = 0; m < 4; ++m) tpre[ai][m] = rs[u.pm * BM + ai * HALF + wr * 64 + m * 16 + fr];
;         asm volatile("" ::: "memory");
; #pragma unroll
;         for (int ai = 0; ai < 2; ++ai)
; #pragma unroll
;             for (int m = 0; m < 4; ++m) {
;                 const int r = u.pm * BM + ai * HALF + wr * 64 + m * 16 + fr; const float t = rstd_of(tpre[ai][m], 1.f / 1024.f);
;                 const float tl = -t * 1.4426950408889634f, t2 = t * t;
;                 f32x4 o0, o1;
; #pragma unroll
;                 for (int n = 0; n < 2; ++n)
; #pragma unroll
;                     for (int jj = 0; jj < 2; ++jj) {
;                         const f32x2_t g = {acc[ai][0][m][n][2 * jj], acc[ai][0][m][n][2 * jj + 1]}, uu = {acc[ai][1][m][n][2 * jj], acc[ai][1][m][n][2 * jj + 1]};
;                         const f32x2_t z = g * tl; f32x2_t e; e.x = __builtin_amdgcn_exp2f(z.x); e.y = __builtin_amdgcn_exp2f(z.y);
;                         const f32x2_t d = e + 1.0f; f32x2_t rr; rr.x = __builtin_amdgcn_rcpf(d.x); rr.y = __builtin_amdgcn_rcpf(d.y);
;                         const f32x2_t o = (g * uu) * (rr * t2);
;                         if (n == 0) { o0[2 * jj] = o.x; o0[2 * jj + 1] = o.y; } else { o1[2 * jj] = o.x; o1[2 * jj + 1] = o.y; }
;                     }
;                 *(u32x4*)(H + (size_t)r * FF + col0) = pack8(o0, o1);
;             }
.LBB0_166:
	v_lshl_add_u32 v142, s60, 8, v3
	v_ashrrev_i32_e32 v143, 31, v142
	v_lshl_add_u64 v[160:161], v[142:143], 2, s[10:11]
	global_load_dword v159, v[160:161], off
	global_load_dword v163, v[160:161], off offset:64
	global_load_dword v157, v[160:161], off offset:128
	global_load_dword v155, v[160:161], off offset:192
	global_load_dword v153, v[160:161], off offset:512
	global_load_dword v151, v[160:161], off offset:576
	global_load_dword v149, v[160:161], off offset:640
	global_load_dword v147, v[160:161], off offset:704
	v_pk_mul_f32 v[116:117], v[120:121], v[116:117]
	v_pk_mul_f32 v[124:125], v[128:129], v[124:125]
	v_lshl_or_b32 v160, s59, 7, v145
	v_pk_mul_f32 v[118:119], v[122:123], v[118:119]
	v_ashrrev_i32_e32 v161, 31, v160
	v_pk_mul_f32 v[126:127], v[130:131], v[126:127]
	v_pk_mul_f32 v[108:109], v[112:113], v[108:109]
	v_pk_mul_f32 v[104:105], v[100:101], v[104:105]
	v_pk_mul_f32 v[106:107], v[102:103], v[106:107]
	v_or_b32_e32 v158, 16, v142
	v_pk_mul_f32 v[110:111], v[114:115], v[110:111]
	v_pk_mul_f32 v[88:89], v[84:85], v[88:89]
	v_pk_mul_f32 v[98:99], v[94:95], v[98:99]
	v_pk_mul_f32 v[96:97], v[92:93], v[96:97]
	v_or_b32_e32 v156, 32, v142
	v_pk_mul_f32 v[90:91], v[86:87], v[90:91]
	v_pk_mul_f32 v[72:73], v[68:69], v[72:73]
	v_pk_mul_f32 v[82:83], v[78:79], v[82:83]
	v_pk_mul_f32 v[80:81], v[76:77], v[80:81]
	v_or_b32_e32 v154, 48, v142
	v_pk_mul_f32 v[74:75], v[70:71], v[74:75]
	v_pk_mul_f32 v[56:57], v[52:53], v[56:57]
	v_pk_mul_f32 v[66:67], v[62:63], v[66:67]
	v_pk_mul_f32 v[64:65], v[60:61], v[64:65]
	v_add_u32_e32 v152, 0x80, v142
	v_pk_mul_f32 v[58:59], v[54:55], v[58:59]
	v_pk_mul_f32 v[40:41], v[36:37], v[40:41]
	v_pk_mul_f32 v[50:51], v[46:47], v[50:51]
	v_pk_mul_f32 v[48:49], v[44:45], v[48:49]
	v_add_u32_e32 v150, 0x90, v142
	v_pk_mul_f32 v[42:43], v[38:39], v[42:43]
	v_pk_mul_f32 v[24:25], v[20:21], v[24:25]
	v_pk_mul_f32 v[34:35], v[30:31], v[34:35]
	v_pk_mul_f32 v[32:33], v[28:29], v[32:33]
	v_add_u32_e32 v148, 0xa0, v142
	v_pk_mul_f32 v[26:27], v[22:23], v[26:27]
	v_pk_mul_f32 v[18:19], v[14:15], v[18:19]
	v_pk_mul_f32 v[16:17], v[12:13], v[16:17]
	v_pk_mul_f32 v[10:11], v[6:7], v[10:11]
	v_pk_mul_f32 v[8:9], v[4:5], v[8:9]
	v_add_u32_e32 v143, 0xb0, v142
	v_readlane_b32 s64, v252, 28
	v_readlane_b32 s66, v252, 30
	v_readlane_b32 s68, v252, 32
	s_andn2_b64 vcc, exec, s[38:39]
	v_readlane_b32 s65, v252, 29
	v_readlane_b32 s67, v252, 31
	v_readlane_b32 s69, v252, 33
	s_waitcnt vmcnt(0)
	v_fmamk_f32 v159, v159, 0x3a800000, v236
	v_rsq_f32_e32 v159, v159
	s_nop 0
	v_mul_f32_e32 v162, 0xbfb8aa3b, v159
	v_pk_mul_f32 v[120:121], v[120:121], v[162:163] op_sel_hi:[1,0]
	v_pk_mul_f32 v[128:129], v[128:129], v[162:163] op_sel_hi:[1,0]
	v_exp_f32_e32 v120, v120
	v_exp_f32_e32 v121, v121
	v_exp_f32_e32 v128, v128
	v_exp_f32_e32 v129, v129
	v_mul_f32_e32 v164, v159, v159
	v_pk_add_f32 v[120:121], v[120:121], 1.0 op_sel_hi:[1,0]
	v_pk_add_f32 v[128:129], v[128:129], 1.0 op_sel_hi:[1,0]
	v_rcp_f32_e32 v120, v120
	v_rcp_f32_e32 v121, v121
	v_rcp_f32_e32 v128, v128
	v_rcp_f32_e32 v129, v129
	v_pk_mul_f32 v[120:121], v[164:165], v[120:121] op_sel_hi:[0,1]
	v_pk_mul_f32 v[116:117], v[116:117], v[120:121]
	v_pk_mul_f32 v[128:129], v[164:165], v[128:129] op_sel_hi:[0,1]
	v_pk_mul_f32 v[120:121], v[122:123], v[162:163] op_sel_hi:[1,0]
	v_pk_mul_f32 v[124:125], v[124:125], v[128:129]
	v_pk_mul_f32 v[128:129], v[130:131], v[162:163] op_sel_hi:[1,0]
	v_exp_f32_e32 v120, v120
	v_exp_f32_e32 v121, v121
	v_exp_f32_e32 v128, v128
	v_exp_f32_e32 v129, v129
	v_cvt_pk_bf16_f32 v122, v116, v117
	v_pk_add_f32 v[120:121], v[120:121], 1.0 op_sel_hi:[1,0]
	v_mov_b64_e32 v[116:117], s[8:9]
	v_pk_add_f32 v[128:129], v[128:129], 1.0 op_sel_hi:[1,0]
	v_rcp_f32_e32 v120, v120
	v_rcp_f32_e32 v121, v121
	v_rcp_f32_e32 v128, v128
	v_rcp_f32_e32 v129, v129
	v_pk_mul_f32 v[120:121], v[164:165], v[120:121] op_sel_hi:[0,1]
	v_pk_mul_f32 v[118:119], v[118:119], v[120:121]
	v_pk_mul_f32 v[128:129], v[164:165], v[128:129] op_sel_hi:[0,1]
	v_pk_mul_f32 v[126:127], v[126:127], v[128:129]
	v_cvt_pk_bf16_f32 v120, v124, v125
	v_cvt_pk_bf16_f32 v123, v118, v119
	v_mad_i64_i32 v[124:125], s[22:23], v142, s0, v[116:117]
	v_lshlrev_b64 v[118:119], 1, v[160:161]
	v_cvt_pk_bf16_f32 v121, v126, v127
	v_lshl_add_u64 v[124:125], v[124:125], 0, v[118:119]
	global_store_dwordx4 v[124:125], v[120:123], off
	s_nop 1
	v_fmamk_f32 v120, v163, 0x3a800000, v236
	v_rsq_f32_e32 v120, v120
	s_nop 0
	v_mul_f32_e32 v122, 0xbfb8aa3b, v120
	v_pk_mul_f32 v[112:113], v[112:113], v[122:123] op_sel_hi:[1,0]
	v_mul_f32_e32 v120, v120, v120
	v_exp_f32_e32 v112, v112
	v_exp_f32_e32 v113, v113
	v_pk_mul_f32 v[100:101], v[100:101], v[122:123] op_sel_hi:[1,0]
	v_pk_mul_f32 v[102:103], v[102:103], v[122:123] op_sel_hi:[1,0]
	v_exp_f32_e32 v100, v100
	v_pk_add_f32 v[112:113], v[112:113], 1.0 op_sel_hi:[1,0]
	v_exp_f32_e32 v101, v101
	v_rcp_f32_e32 v112, v112
	v_rcp_f32_e32 v113, v113
	v_exp_f32_e32 v102, v102
	v_exp_f32_e32 v103, v103
	v_pk_add_f32 v[100:101], v[100:101], 1.0 op_sel_hi:[1,0]
	v_pk_mul_f32 v[112:113], v[120:121], v[112:113] op_sel_hi:[0,1]
	v_pk_mul_f32 v[108:109], v[108:109], v[112:113]
	v_pk_mul_f32 v[112:113], v[114:115], v[122:123] op_sel_hi:[1,0]
	v_rcp_f32_e32 v100, v100
	v_exp_f32_e32 v112, v112
	v_exp_f32_e32 v113, v113
	v_rcp_f32_e32 v101, v101
	v_pk_add_f32 v[102:103], v[102:103], 1.0 op_sel_hi:[1,0]
	v_pk_add_f32 v[112:113], v[112:113], 1.0 op_sel_hi:[1,0]
	s_nop 0
	v_rcp_f32_e32 v112, v112
	v_rcp_f32_e32 v113, v113
	v_rcp_f32_e32 v102, v102
	v_rcp_f32_e32 v103, v103
	v_pk_mul_f32 v[100:101], v[120:121], v[100:101] op_sel_hi:[0,1]
; __device__ __forceinline__ float rstd_of(float ss, float invn) { return __builtin_amdgcn_rsqf(ss * invn + EPS); }
; __device__ __forceinline__ u32x4 pack8(f32x4 a, f32x4 b) { u32x4 w; w.x = cvtpk(a[0], a[1]); w.y = cvtpk(a[2], a[3]); w.z = cvtpk(b[0], b[1]); w.w = cvtpk(b[2], b[3]); return w; }
;     __device__ __forceinline__ void operator()(const Acc& acc, const Unit& u, int wr, int wc, int fr, int fq) const {
;     ...
;                 const int r = u.pm * BM + ai * HALF + wr * 64 + m * 16 + fr; const float t = rstd_of(tpre[ai][m], 1.f / 1024.f);
;                 const float tl = -t * 1.4426950408889634f, t2 = t * t;
;                 f32x4 o0, o1;
; #pragma unroll
;                 for (int n = 0; n < 2; ++n)
; #pragma unroll
;                     for (int jj = 0; jj < 2; ++jj) {
;                         const f32x2_t g = {acc[ai][0][m][n][2 * jj], acc[ai][0][m][n][2 * jj + 1]}, uu = {acc[ai][1][m][n][2 * jj], acc[ai][1][m][n][2 * jj + 1]};
;                         const f32x2_t z = g * tl; f32x2_t e; e.x = __builtin_amdgcn_exp2f(z.x); e.y = __builtin_amdgcn_exp2f(z.y);
;                         const f32x2_t d = e + 1.0f; f32x2_t rr; rr.x = __builtin_amdgcn_rcpf(d.x); rr.y = __builtin_amdgcn_rcpf(d.y);
;                         const f32x2_t o = (g * uu) * (rr * t2);
;                         if (n == 0) { o0[2 * jj] = o.x; o0[2 * jj + 1] = o.y; } else { o1[2 * jj] = o.x; o1[2 * jj + 1] = o.y; }
;                     }
;                 *(u32x4*)(H + (size_t)r * FF + col0) = pack8(o0, o1);
	v_pk_mul_f32 v[112:113], v[120:121], v[112:113] op_sel_hi:[0,1]
	v_pk_mul_f32 v[100:101], v[104:105], v[100:101]
	v_pk_mul_f32 v[102:103], v[120:121], v[102:103] op_sel_hi:[0,1]
	v_pk_mul_f32 v[110:111], v[110:111], v[112:113]
	v_pk_mul_f32 v[106:107], v[106:107], v[102:103]
	v_cvt_pk_bf16_f32 v104, v100, v101
	v_mad_i64_i32 v[100:101], s[22:23], v158, s0, v[116:117]
	v_cvt_pk_bf16_f32 v102, v108, v109
	v_cvt_pk_bf16_f32 v103, v110, v111
	v_cvt_pk_bf16_f32 v105, v106, v107
	v_lshl_add_u64 v[100:101], v[100:101], 0, v[118:119]
	global_store_dwordx4 v[100:101], v[102:105], off
	v_fmamk_f32 v100, v157, 0x3a800000, v236
	v_rsq_f32_e32 v101, v100
	s_nop 0
	v_mul_f32_e32 v100, 0xbfb8aa3b, v101
	v_pk_mul_f32 v[84:85], v[84:85], v[100:101] op_sel_hi:[1,0]
	v_mul_f32_e32 v102, v101, v101
	v_exp_f32_e32 v84, v84
	v_exp_f32_e32 v85, v85
	v_pk_mul_f32 v[92:93], v[92:93], v[100:101] op_sel_hi:[1,0]
	v_pk_mul_f32 v[94:95], v[94:95], v[100:101] op_sel_hi:[1,0]
	v_exp_f32_e32 v92, v92
	v_pk_add_f32 v[84:85], v[84:85], 1.0 op_sel_hi:[1,0]
	v_exp_f32_e32 v93, v93
	v_rcp_f32_e32 v84, v84
	v_rcp_f32_e32 v85, v85
	v_exp_f32_e32 v94, v94
	v_exp_f32_e32 v95, v95
	v_pk_add_f32 v[92:93], v[92:93], 1.0 op_sel_hi:[1,0]
	v_pk_mul_f32 v[84:85], v[102:103], v[84:85] op_sel_hi:[0,1]
	v_pk_mul_f32 v[88:89], v[88:89], v[84:85]
	v_pk_mul_f32 v[84:85], v[86:87], v[100:101] op_sel_hi:[1,0]
	v_pk_add_f32 v[94:95], v[94:95], 1.0 op_sel_hi:[1,0]
	v_exp_f32_e32 v84, v84
	v_exp_f32_e32 v85, v85
	v_rcp_f32_e32 v92, v92
	v_rcp_f32_e32 v93, v93
	v_rcp_f32_e32 v94, v94
	v_pk_add_f32 v[84:85], v[84:85], 1.0 op_sel_hi:[1,0]
	v_rcp_f32_e32 v95, v95
	v_rcp_f32_e32 v84, v84
	v_rcp_f32_e32 v85, v85
	v_pk_mul_f32 v[92:93], v[102:103], v[92:93] op_sel_hi:[0,1]
	v_pk_mul_f32 v[94:95], v[102:103], v[94:95] op_sel_hi:[0,1]
	v_pk_mul_f32 v[92:93], v[96:97], v[92:93]
	v_pk_mul_f32 v[84:85], v[102:103], v[84:85] op_sel_hi:[0,1]
	v_pk_mul_f32 v[94:95], v[98:99], v[94:95]
	v_pk_mul_f32 v[90:91], v[90:91], v[84:85]
	v_cvt_pk_bf16_f32 v86, v88, v89
	v_mad_i64_i32 v[88:89], s[22:23], v156, s0, v[116:117]
	v_cvt_pk_bf16_f32 v84, v92, v93
	v_cvt_pk_bf16_f32 v85, v94, v95
	v_cvt_pk_bf16_f32 v87, v90, v91
	v_lshl_add_u64 v[88:89], v[88:89], 0, v[118:119]
	global_store_dwordx4 v[88:89], v[84:87], off
	s_nop 1
	v_fmamk_f32 v84, v155, 0x3a800000, v236
	v_rsq_f32_e32 v85, v84
	s_nop 0
	v_mul_f32_e32 v84, 0xbfb8aa3b, v85
	v_pk_mul_f32 v[68:69], v[68:69], v[84:85] op_sel_hi:[1,0]
	v_mul_f32_e32 v86, v85, v85
	v_exp_f32_e32 v68, v68
	v_exp_f32_e32 v69, v69
	v_pk_mul_f32 v[76:77], v[76:77], v[84:85] op_sel_hi:[1,0]
	v_pk_mul_f32 v[78:79], v[78:79], v[84:85] op_sel_hi:[1,0]
	v_exp_f32_e32 v76, v76
	v_pk_add_f32 v[68:69], v[68:69], 1.0 op_sel_hi:[1,0]
	v_exp_f32_e32 v77, v77
	v_rcp_f32_e32 v68, v68
	v_rcp_f32_e32 v69, v69
	v_exp_f32_e32 v78, v78
	v_exp_f32_e32 v79, v79
	v_pk_add_f32 v[76:77], v[76:77], 1.0 op_sel_hi:[1,0]
	v_pk_mul_f32 v[68:69], v[86:87], v[68:69] op_sel_hi:[0,1]
	v_pk_mul_f32 v[72:73], v[72:73], v[68:69]
	v_pk_mul_f32 v[68:69], v[70:71], v[84:85] op_sel_hi:[1,0]
	v_pk_add_f32 v[78:79], v[78:79], 1.0 op_sel_hi:[1,0]
	v_exp_f32_e32 v68, v68
	v_exp_f32_e32 v69, v69
	v_rcp_f32_e32 v76, v76
	v_rcp_f32_e32 v77, v77
	v_rcp_f32_e32 v78, v78
	v_pk_add_f32 v[68:69], v[68:69], 1.0 op_sel_hi:[1,0]
	v_rcp_f32_e32 v79, v79
	v_rcp_f32_e32 v68, v68
	v_rcp_f32_e32 v69, v69
	v_pk_mul_f32 v[76:77], v[86:87], v[76:77] op_sel_hi:[0,1]
	v_pk_mul_f32 v[78:79], v[86:87], v[78:79] op_sel_hi:[0,1]
	v_pk_mul_f32 v[76:77], v[80:81], v[76:77]
	v_pk_mul_f32 v[68:69], v[86:87], v[68:69] op_sel_hi:[0,1]
	v_pk_mul_f32 v[78:79], v[82:83], v[78:79]
	v_pk_mul_f32 v[74:75], v[74:75], v[68:69]
	v_cvt_pk_bf16_f32 v70, v72, v73
	v_mad_i64_i32 v[72:73], s[22:23], v154, s0, v[116:117]
	v_cvt_pk_bf16_f32 v68, v76, v77
	v_cvt_pk_bf16_f32 v69, v78, v79
	v_cvt_pk_bf16_f32 v71, v74, v75
	v_lshl_add_u64 v[72:73], v[72:73], 0, v[118:119]
	global_store_dwordx4 v[72:73], v[68:71], off
	s_nop 1
	v_fmamk_f32 v68, v153, 0x3a800000, v236
	v_rsq_f32_e32 v69, v68
	s_nop 0
	v_mul_f32_e32 v68, 0xbfb8aa3b, v69
	v_pk_mul_f32 v[52:53], v[52:53], v[68:69] op_sel_hi:[1,0]
	v_mul_f32_e32 v70, v69, v69
	v_exp_f32_e32 v52, v52
	v_exp_f32_e32 v53, v53
	v_pk_mul_f32 v[60:61], v[60:61], v[68:69] op_sel_hi:[1,0]
	v_pk_mul_f32 v[62:63], v[62:63], v[68:69] op_sel_hi:[1,0]
	v_exp_f32_e32 v60, v60
	v_pk_add_f32 v[52:53], v[52:53], 1.0 op_sel_hi:[1,0]
	v_exp_f32_e32 v61, v61
	v_rcp_f32_e32 v52, v52
	v_rcp_f32_e32 v53, v53
	v_exp_f32_e32 v62, v62
	v_exp_f32_e32 v63, v63
	v_pk_add_f32 v[60:61], v[60:61], 1.0 op_sel_hi:[1,0]
	v_pk_mul_f32 v[52:53], v[70:71], v[52:53] op_sel_hi:[0,1]
	v_pk_mul_f32 v[56:57], v[56:57], v[52:53]
	v_pk_mul_f32 v[52:53], v[54:55], v[68:69] op_sel_hi:[1,0]
	v_pk_add_f32 v[62:63], v[62:63], 1.0 op_sel_hi:[1,0]
	v_exp_f32_e32 v52, v52
	v_exp_f32_e32 v53, v53
	v_rcp_f32_e32 v60, v60
	v_rcp_f32_e32 v61, v61
	v_rcp_f32_e32 v62, v62
	v_pk_add_f32 v[52:53], v[52:53], 1.0 op_sel_hi:[1,0]
	v_rcp_f32_e32 v63, v63
	v_rcp_f32_e32 v52, v52
	v_rcp_f32_e32 v53, v53
	v_pk_mul_f32 v[60:61], v[70:71], v[60:61] op_sel_hi:[0,1]
	v_pk_mul_f32 v[62:63], v[70:71], v[62:63] op_sel_hi:[0,1]
	v_pk_mul_f32 v[60:61], v[64:65], v[60:61]
	v_pk_mul_f32 v[52:53], v[70:71], v[52:53] op_sel_hi:[0,1]
	v_pk_mul_f32 v[62:63], v[66:67], v[62:63]
	v_pk_mul_f32 v[58:59], v[58:59], v[52:53]
	v_cvt_pk_bf16_f32 v54, v56, v57
; __device__ __forceinline__ float rstd_of(float ss, float invn) { return __builtin_amdgcn_rsqf(ss * invn + EPS); }
; __device__ __forceinline__ u32x4 pack8(f32x4 a, f32x4 b) { u32x4 w; w.x = cvtpk(a[0], a[1]); w.y = cvtpk(a[2], a[3]); w.z = cvtpk(b[0], b[1]); w.w = cvtpk(b[2], b[3]); return w; }
;     __device__ __forceinline__ void operator()(const Acc& acc, const Unit& u, int wr, int wc, int fr, int fq) const {
;     ...
;                 const int r = u.pm * BM + ai * HALF + wr * 64 + m * 16 + fr; const float t = rstd_of(tpre[ai][m], 1.f / 1024.f);
;                 const float tl = -t * 1.4426950408889634f, t2 = t * t;
;                 f32x4 o0, o1;
; #pragma unroll
;                 for (int n = 0; n < 2; ++n)
; #pragma unroll
;                     for (int jj = 0; jj < 2; ++jj) {
;                         const f32x2_t g = {acc[ai][0][m][n][2 * jj], acc[ai][0][m][n][2 * jj + 1]}, uu = {acc[ai][1][m][n][2 * jj], acc[ai][1][m][n][2 * jj + 1]};
;                         const f32x2_t z = g * tl; f32x2_t e; e.x = __builtin_amdgcn_exp2f(z.x); e.y = __builtin_amdgcn_exp2f(z.y);
;                         const f32x2_t d = e + 1.0f; f32x2_t rr; rr.x = __builtin_amdgcn_rcpf(d.x); rr.y = __builtin_amdgcn_rcpf(d.y);
;                         const f32x2_t o = (g * uu) * (rr * t2);
;                         if (n == 0) { o0[2 * jj] = o.x; o0[2 * jj + 1] = o.y; } else { o1[2 * jj] = o.x; o1[2 * jj + 1] = o.y; }
;                     }
;                 *(u32x4*)(H + (size_t)r * FF + col0) = pack8(o0, o1);
	v_mad_i64_i32 v[56:57], s[22:23], v152, s0, v[116:117]
	v_cvt_pk_bf16_f32 v52, v60, v61
	v_cvt_pk_bf16_f32 v53, v62, v63
	v_cvt_pk_bf16_f32 v55, v58, v59
	v_lshl_add_u64 v[56:57], v[56:57], 0, v[118:119]
	global_store_dwordx4 v[56:57], v[52:55], off
	s_nop 1
	v_fmamk_f32 v52, v151, 0x3a800000, v236
	v_rsq_f32_e32 v53, v52
	s_nop 0
	v_mul_f32_e32 v52, 0xbfb8aa3b, v53
	v_pk_mul_f32 v[36:37], v[36:37], v[52:53] op_sel_hi:[1,0]
	v_mul_f32_e32 v54, v53, v53
	v_exp_f32_e32 v36, v36
	v_exp_f32_e32 v37, v37
	v_pk_mul_f32 v[44:45], v[44:45], v[52:53] op_sel_hi:[1,0]
	v_pk_mul_f32 v[46:47], v[46:47], v[52:53] op_sel_hi:[1,0]
	v_exp_f32_e32 v44, v44
	v_pk_add_f32 v[36:37], v[36:37], 1.0 op_sel_hi:[1,0]
	v_exp_f32_e32 v45, v45
	v_rcp_f32_e32 v36, v36
	v_rcp_f32_e32 v37, v37
	v_exp_f32_e32 v46, v46
	v_exp_f32_e32 v47, v47
	v_pk_add_f32 v[44:45], v[44:45], 1.0 op_sel_hi:[1,0]
	v_pk_mul_f32 v[36:37], v[54:55], v[36:37] op_sel_hi:[0,1]
	v_pk_mul_f32 v[40:41], v[40:41], v[36:37]
	v_pk_mul_f32 v[36:37], v[38:39], v[52:53] op_sel_hi:[1,0]
	v_pk_add_f32 v[46:47], v[46:47], 1.0 op_sel_hi:[1,0]
	v_exp_f32_e32 v36, v36
	v_exp_f32_e32 v37, v37
	v_rcp_f32_e32 v44, v44
	v_rcp_f32_e32 v45, v45
	v_rcp_f32_e32 v46, v46
	v_pk_add_f32 v[36:37], v[36:37], 1.0 op_sel_hi:[1,0]
	v_rcp_f32_e32 v47, v47
	v_rcp_f32_e32 v36, v36
	v_rcp_f32_e32 v37, v37
	v_pk_mul_f32 v[44:45], v[54:55], v[44:45] op_sel_hi:[0,1]
	v_pk_mul_f32 v[46:47], v[54:55], v[46:47] op_sel_hi:[0,1]
	v_pk_mul_f32 v[44:45], v[48:49], v[44:45]
	v_pk_mul_f32 v[36:37], v[54:55], v[36:37] op_sel_hi:[0,1]
	v_pk_mul_f32 v[46:47], v[50:51], v[46:47]
	v_pk_mul_f32 v[42:43], v[42:43], v[36:37]
	v_cvt_pk_bf16_f32 v38, v40, v41
	v_mad_i64_i32 v[40:41], s[22:23], v150, s0, v[116:117]
	v_cvt_pk_bf16_f32 v36, v44, v45
	v_cvt_pk_bf16_f32 v37, v46, v47
	v_cvt_pk_bf16_f32 v39, v42, v43
	v_lshl_add_u64 v[40:41], v[40:41], 0, v[118:119]
	global_store_dwordx4 v[40:41], v[36:39], off
	s_nop 1
	v_fmamk_f32 v36, v149, 0x3a800000, v236
	v_rsq_f32_e32 v37, v36
	s_nop 0
	v_mul_f32_e32 v36, 0xbfb8aa3b, v37
	v_pk_mul_f32 v[20:21], v[20:21], v[36:37] op_sel_hi:[1,0]
	v_mul_f32_e32 v38, v37, v37
	v_exp_f32_e32 v20, v20
	v_exp_f32_e32 v21, v21
	v_pk_mul_f32 v[28:29], v[28:29], v[36:37] op_sel_hi:[1,0]
	v_pk_mul_f32 v[30:31], v[30:31], v[36:37] op_sel_hi:[1,0]
	v_exp_f32_e32 v28, v28
	v_pk_add_f32 v[20:21], v[20:21], 1.0 op_sel_hi:[1,0]
	v_exp_f32_e32 v29, v29
	v_rcp_f32_e32 v20, v20
	v_rcp_f32_e32 v21, v21
	v_exp_f32_e32 v30, v30
	v_exp_f32_e32 v31, v31
	v_pk_add_f32 v[28:29], v[28:29], 1.0 op_sel_hi:[1,0]
	v_pk_mul_f32 v[20:21], v[38:39], v[20:21] op_sel_hi:[0,1]
	v_pk_mul_f32 v[24:25], v[24:25], v[20:21]
	v_pk_mul_f32 v[20:21], v[22:23], v[36:37] op_sel_hi:[1,0]
	v_pk_add_f32 v[30:31], v[30:31], 1.0 op_sel_hi:[1,0]
	v_exp_f32_e32 v20, v20
	v_exp_f32_e32 v21, v21
	v_rcp_f32_e32 v28, v28
	v_rcp_f32_e32 v29, v29
	v_rcp_f32_e32 v30, v30
	v_pk_add_f32 v[20:21], v[20:21], 1.0 op_sel_hi:[1,0]
	v_rcp_f32_e32 v31, v31
	v_rcp_f32_e32 v20, v20
	v_rcp_f32_e32 v21, v21
	v_pk_mul_f32 v[28:29], v[38:39], v[28:29] op_sel_hi:[0,1]
	v_pk_mul_f32 v[30:31], v[38:39], v[30:31] op_sel_hi:[0,1]
	v_pk_mul_f32 v[28:29], v[32:33], v[28:29]
	v_pk_mul_f32 v[20:21], v[38:39], v[20:21] op_sel_hi:[0,1]
	v_pk_mul_f32 v[30:31], v[34:35], v[30:31]
	v_pk_mul_f32 v[26:27], v[26:27], v[20:21]
	v_cvt_pk_bf16_f32 v22, v24, v25
	v_mad_i64_i32 v[24:25], s[22:23], v148, s0, v[116:117]
	v_cvt_pk_bf16_f32 v20, v28, v29
	v_cvt_pk_bf16_f32 v21, v30, v31
	v_cvt_pk_bf16_f32 v23, v26, v27
	v_lshl_add_u64 v[24:25], v[24:25], 0, v[118:119]
	global_store_dwordx4 v[24:25], v[20:23], off
	s_nop 1
	v_fmamk_f32 v20, v147, 0x3a800000, v236
	v_rsq_f32_e32 v21, v20
	s_nop 0
	v_mul_f32_e32 v22, 0xbfb8aa3b, v21
	v_pk_mul_f32 v[14:15], v[14:15], v[22:23] op_sel_hi:[1,0]
	v_pk_mul_f32 v[12:13], v[12:13], v[22:23] op_sel_hi:[1,0]
	v_pk_mul_f32 v[6:7], v[6:7], v[22:23] op_sel_hi:[1,0]
	v_pk_mul_f32 v[4:5], v[4:5], v[22:23] op_sel_hi:[1,0]
	v_exp_f32_e32 v14, v14
	v_exp_f32_e32 v15, v15
	v_exp_f32_e32 v12, v12
	v_exp_f32_e32 v13, v13
	v_exp_f32_e32 v6, v6
	v_exp_f32_e32 v7, v7
	v_exp_f32_e32 v4, v4
	v_exp_f32_e32 v5, v5
	v_pk_add_f32 v[14:15], v[14:15], 1.0 op_sel_hi:[1,0]
	v_pk_add_f32 v[12:13], v[12:13], 1.0 op_sel_hi:[1,0]
	v_pk_add_f32 v[6:7], v[6:7], 1.0 op_sel_hi:[1,0]
	v_pk_add_f32 v[4:5], v[4:5], 1.0 op_sel_hi:[1,0]
	v_rcp_f32_e32 v14, v14
	v_rcp_f32_e32 v15, v15
	v_rcp_f32_e32 v12, v12
	v_rcp_f32_e32 v13, v13
	v_rcp_f32_e32 v6, v6
	v_rcp_f32_e32 v7, v7
	v_rcp_f32_e32 v4, v4
	v_rcp_f32_e32 v5, v5
	v_mul_f32_e32 v20, v21, v21
	v_pk_mul_f32 v[14:15], v[20:21], v[14:15] op_sel_hi:[0,1]
	v_pk_mul_f32 v[12:13], v[20:21], v[12:13] op_sel_hi:[0,1]
	v_pk_mul_f32 v[6:7], v[20:21], v[6:7] op_sel_hi:[0,1]
	v_pk_mul_f32 v[4:5], v[20:21], v[4:5] op_sel_hi:[0,1]
	v_pk_mul_f32 v[14:15], v[18:19], v[14:15]
	v_pk_mul_f32 v[12:13], v[16:17], v[12:13]
	v_pk_mul_f32 v[6:7], v[10:11], v[6:7]
	v_pk_mul_f32 v[4:5], v[8:9], v[4:5]
	v_mad_i64_i32 v[8:9], s[22:23], v143, s0, v[116:117]
	v_cvt_pk_bf16_f32 v4, v4, v5
	v_cvt_pk_bf16_f32 v5, v6, v7
	v_cvt_pk_bf16_f32 v6, v12, v13
	v_cvt_pk_bf16_f32 v7, v14, v15
	v_lshl_add_u64 v[8:9], v[8:9], 0, v[118:119]
	s_mov_b64 s[22:23], -1
	global_store_dwordx4 v[8:9], v[4:7], off
	s_cbranch_vccnz .LBB0_159
	s_andn2_b64 vcc, exec, s[6:7]
	s_cbranch_vccnz .LBB0_158
	s_barrier
	s_branch .LBB0_158

;     __device__ __forceinline__ void operator()(const Acc& acc, const Unit& u, int wr, int wc, int fr, int fq) const {
;         constexpr int MB = PLE ? 2 : 4;
; #pragma unroll
;         for (int ai = 0; ai < 2; ++ai)
; #pragma unroll
;         for (int mb = 0; mb < 4; mb += MB) {
;             f32x4 pa[MB][2], pb[MB][2]; u32x4 pt[MB][2]; float tt[MB];
; #pragma unroll
;             for (int mm = 0; mm < MB; ++mm) {
;                 const int m = mb + mm; const int r = u.pm * BM + ai * HALF + wr * 64 + m * 16 + fr;
;                 tt[mm] = PLE ? rs_in[r] : 0.f;
; #pragma unroll
;                 for (int bj = 0; bj < 2; ++bj) {
;                     const int c0 = u.pn * BM + wc * 64 + bj * 32 + 8 * fq; const float* hs = hsrc + (size_t)r * DM + c0;
;                     pa[mm][bj] = *(const f32x4*)hs; pb[mm][bj] = *(const f32x4*)(hs + 4);
;                     if (PLE) pt[mm][bj] = *(const u32x4*)(tmp + (size_t)r * DM + c0);
;                 }
;             }
; #pragma unroll
;             for (int mm = 0; mm < MB; ++mm) {
;                 const int m = mb + mm; const int r = u.pm * BM + ai * HALF + wr * 64 + m * 16 + fr; float ss = 0.f;
;                 const float t = PLE ? rstd_of(tt[mm], 1.f / 1024.f) : 1.f; const float tl = -t * 1.4426950408889634f; (void)tl;
; #pragma unroll
;                 for (int bj = 0; bj < 2; ++bj) {
;                     const int c0 = u.pn * BM + wc * 64 + bj * 32 + 8 * fq; float* hp = h + (size_t)r * DM + c0;
;                     f32x4 a = pa[mm][bj], b = pb[mm][bj];
;                     if (PLE) { f32x4 ta, tb; unpack8(pt[mm][bj], ta, tb);
; #pragma unroll
;                         for (int j = 0; j < 4; ++j) { a[j] += ta[j] * __builtin_amdgcn_rcpf(1.f + __builtin_amdgcn_exp2f(acc[ai][bj][m][0][j] * tl)); b[j] += tb[j] * __builtin_amdgcn_rcpf(1.f + __builtin_amdgcn_exp2f(acc[ai][bj][m][1][j] * tl)); } }
;                     else { a += acc[ai][bj][m][0] * alpha; b += acc[ai][bj][m][1] * alpha; }
;                     if (!dry || a[0] == 1234.56789f) { *(f32x4*)hp = a; *(f32x4*)(hp + 4) = b;
;                     *(u32x4*)(hb + (size_t)r * DM + c0) = pack8(a, b); }
;                     ss += (a[0] * a[0] + a[1] * a[1]) + (a[2] * a[2] + a[3] * a[3]) + (b[0] * b[0] + b[1] * b[1]) + (b[2] * b[2] + b[3] * b[3]);
;                 }
;                 ss += __shfl_xor(ss, 16); ss += __shfl_xor(ss, 32);
.LBB0_243:
	v_xor_b32_e32 v132, 16, v238
	v_add_u32_e32 v133, 64, v239
	v_cmp_lt_i32_e32 vcc, v132, v133
	v_lshl_add_u32 v216, s66, 8, v3
	v_lshl_or_b32 v212, s65, 8, v231
	v_cndmask_b32_e32 v132, v238, v132, vcc
	v_lshlrev_b32_e32 v242, 2, v132
	v_xor_b32_e32 v132, 32, v238
	v_cmp_lt_i32_e32 vcc, v132, v133
	v_ashrrev_i32_e32 v217, 31, v216
	v_ashrrev_i32_e32 v213, 31, v212
	v_cndmask_b32_e32 v132, v238, v132, vcc
	v_lshlrev_b64 v[196:197], 12, v[216:217]
	v_lshlrev_b32_e32 v233, 2, v132
	v_lshl_add_u64 v[132:133], s[10:11], 0, v[196:197]
	v_lshlrev_b64 v[214:215], 2, v[212:213]
	v_lshl_add_u64 v[132:133], v[132:133], 0, v[214:215]
	global_load_dwordx4 v[244:247], v[132:133], off offset:16
	global_load_dwordx4 v[248:251], v[132:133], off
	global_load_dwordx4 v[180:183], v[132:133], off offset:144
	global_load_dwordx4 v[184:187], v[132:133], off offset:128
	v_or_b32_e32 v224, 16, v216
	v_ashrrev_i32_e32 v225, 31, v224
	v_lshlrev_b64 v[228:229], 12, v[224:225]
	v_or_b32_e32 v220, 32, v216
	v_lshl_add_u64 v[132:133], s[10:11], 0, v[228:229]
	v_ashrrev_i32_e32 v221, 31, v220
	v_lshl_add_u64 v[132:133], v[132:133], 0, v[214:215]
	v_lshlrev_b64 v[226:227], 12, v[220:221]
	v_or_b32_e32 v218, 48, v216
	global_load_dwordx4 v[172:175], v[132:133], off offset:16
	global_load_dwordx4 v[176:179], v[132:133], off
	global_load_dwordx4 v[164:167], v[132:133], off offset:144
	global_load_dwordx4 v[168:171], v[132:133], off offset:128
	v_lshl_add_u64 v[132:133], s[10:11], 0, v[226:227]
	v_ashrrev_i32_e32 v219, 31, v218
	v_lshl_add_u64 v[132:133], v[132:133], 0, v[214:215]
	v_lshlrev_b64 v[222:223], 12, v[218:219]
	global_load_dwordx4 v[156:159], v[132:133], off offset:16
	global_load_dwordx4 v[160:163], v[132:133], off
	global_load_dwordx4 v[140:143], v[132:133], off offset:144
	global_load_dwordx4 v[144:147], v[132:133], off offset:128
	v_lshl_add_u64 v[132:133], s[10:11], 0, v[222:223]
	v_lshl_add_u64 v[136:137], v[132:133], 0, v[214:215]
	global_load_dwordx4 v[148:151], v[136:137], off offset:16
	global_load_dwordx4 v[152:155], v[136:137], off
	global_load_dwordx4 v[132:135], v[136:137], off offset:144
	s_nop 0
	global_load_dwordx4 v[136:139], v[136:137], off offset:128
	v_lshl_add_u64 v[196:197], s[8:9], 0, v[196:197]
	v_lshl_add_u64 v[196:197], v[196:197], 0, v[214:215]
	v_lshlrev_b64 v[198:199], 11, v[216:217]
	v_lshl_add_u64 v[198:199], s[14:15], 0, v[198:199]
	v_lshl_add_u64 v[198:199], v[212:213], 1, v[198:199]
	s_waitcnt vmcnt(0)
	v_pk_fma_f32 v[126:127], v[126:127], 0.5, v[246:247] op_sel_hi:[1,0,1]
	v_pk_fma_f32 v[130:131], v[130:131], 0.5, v[250:251] op_sel_hi:[1,0,1]
	v_pk_fma_f32 v[128:129], v[128:129], 0.5, v[248:249] op_sel_hi:[1,0,1]
	v_pk_fma_f32 v[124:125], v[124:125], 0.5, v[244:245] op_sel_hi:[1,0,1]
	global_store_dwordx4 v[196:197], v[128:131], off
	global_store_dwordx4 v[196:197], v[124:127], off offset:16
	v_cvt_pk_bf16_f32 v244, v128, v129
	v_mul_f32_e32 v129, v129, v129
	v_fmac_f32_e32 v129, v128, v128
	v_mul_f32_e32 v128, v131, v131
	v_cvt_pk_bf16_f32 v246, v124, v125
	v_fmac_f32_e32 v128, v130, v130
	v_mul_f32_e32 v125, v125, v125
	v_add_f32_e32 v128, v129, v128
	v_fmac_f32_e32 v125, v124, v124
	v_add_f32_e32 v124, v125, v128
	v_mul_f32_e32 v125, v127, v127
	v_cvt_pk_bf16_f32 v245, v130, v131
	v_cvt_pk_bf16_f32 v247, v126, v127
	v_fmac_f32_e32 v125, v126, v126
	v_pk_fma_f32 v[122:123], v[122:123], 0.5, v[186:187] op_sel_hi:[1,0,1]
	v_pk_fma_f32 v[120:121], v[120:121], 0.5, v[184:185] op_sel_hi:[1,0,1]
	global_store_dwordx4 v[198:199], v[244:247], off
	v_add_f32_e32 v128, v125, v124
	v_pk_fma_f32 v[118:119], v[118:119], 0.5, v[182:183] op_sel_hi:[1,0,1]
	v_pk_fma_f32 v[116:117], v[116:117], 0.5, v[180:181] op_sel_hi:[1,0,1]
	global_store_dwordx4 v[196:197], v[120:123], off offset:128
	global_store_dwordx4 v[196:197], v[116:119], off offset:144
	v_cvt_pk_bf16_f32 v124, v120, v121
	v_mul_f32_e32 v121, v121, v121
	v_fmac_f32_e32 v121, v120, v120
	v_mul_f32_e32 v120, v123, v123
	v_cvt_pk_bf16_f32 v126, v116, v117
	v_fmac_f32_e32 v120, v122, v122
	v_mul_f32_e32 v117, v117, v117
	v_add_f32_e32 v120, v121, v120
	v_fmac_f32_e32 v117, v116, v116
	v_add_f32_e32 v116, v117, v120
	v_mul_f32_e32 v117, v119, v119
	v_fmac_f32_e32 v117, v118, v118
	v_add_f32_e32 v116, v117, v116
	v_add_f32_e32 v116, v128, v116
	ds_bpermute_b32 v117, v242, v116
	v_cvt_pk_bf16_f32 v125, v122, v123
	v_cvt_pk_bf16_f32 v127, v118, v119
	global_store_dwordx4 v[198:199], v[124:127], off offset:64
	s_waitcnt lgkmcnt(0)
	v_add_f32_e32 v116, v116, v117
	ds_bpermute_b32 v117, v233, v116
	s_and_saveexec_b64 s[22:23], s[42:43]
	v_readlane_b32 s68, v252, 32
	v_readlane_b32 s69, v252, 33
	s_cbranch_execz .LBB0_245
	s_waitcnt lgkmcnt(0)
	v_add_f32_e32 v118, v116, v117
	v_lshl_add_u64 v[116:117], v[216:217], 2, s[34:35]
	global_atomic_add_f32 v[116:117], v118, off
; __device__ __forceinline__ float rstd_of(float ss, float invn) { return __builtin_amdgcn_rsqf(ss * invn + EPS); }
; __device__ __forceinline__ u32x4 pack8(f32x4 a, f32x4 b) { u32x4 w; w.x = cvtpk(a[0], a[1]); w.y = cvtpk(a[2], a[3]); w.z = cvtpk(b[0], b[1]); w.w = cvtpk(b[2], b[3]); return w; }
; __device__ __forceinline__ void unpack8(u32x4 w, f32x4& a, f32x4& b) { a = (f32x4){bflo(w.x), bfhi(w.x), bflo(w.y), bfhi(w.y)}; b = (f32x4){bflo(w.z), bfhi(w.z), bflo(w.w), bfhi(w.w)}; }
;     __device__ __forceinline__ void operator()(const Acc& acc, const Unit& u, int wr, int wc, int fr, int fq) const {
;     ...
;             for (int mm = 0; mm < MB; ++mm) {
;                 const int m = mb + mm; const int r = u.pm * BM + ai * HALF + wr * 64 + m * 16 + fr; float ss = 0.f;
;                 const float t = PLE ? rstd_of(tt[mm], 1.f / 1024.f) : 1.f; const float tl = -t * 1.4426950408889634f; (void)tl;
; #pragma unroll
;                 for (int bj = 0; bj < 2; ++bj) {
;                     const int c0 = u.pn * BM + wc * 64 + bj * 32 + 8 * fq; float* hp = h + (size_t)r * DM + c0;
;                     f32x4 a = pa[mm][bj], b = pb[mm][bj];
;                     if (PLE) { f32x4 ta, tb; unpack8(pt[mm][bj], ta, tb);
; #pragma unroll
;                         for (int j = 0; j < 4; ++j) { a[j] += ta[j] * __builtin_amdgcn_rcpf(1.f + __builtin_amdgcn_exp2f(acc[ai][bj][m][0][j] * tl)); b[j] += tb[j] * __builtin_amdgcn_rcpf(1.f + __builtin_amdgcn_exp2f(acc[ai][bj][m][1][j] * tl)); } }
;                     else { a += acc[ai][bj][m][0] * alpha; b += acc[ai][bj][m][1] * alpha; }
;                     if (!dry || a[0] == 1234.56789f) { *(f32x4*)hp = a; *(f32x4*)(hp + 4) = b;
;                     *(u32x4*)(hb + (size_t)r * DM + c0) = pack8(a, b); }
;                     ss += (a[0] * a[0] + a[1] * a[1]) + (a[2] * a[2] + a[3] * a[3]) + (b[0] * b[0] + b[1] * b[1]) + (b[2] * b[2] + b[3] * b[3]);
;                 }
;                 ss += __shfl_xor(ss, 16); ss += __shfl_xor(ss, 32);
;                 if (fq == 0 && (!dry || ss == 1234.56789f)) unsafeAtomicAdd(rs_out + r, ss);
.LBB0_245:
	s_or_b64 exec, exec, s[22:23]
	s_waitcnt lgkmcnt(0)
	v_lshl_add_u64 v[116:117], s[8:9], 0, v[228:229]
	v_pk_fma_f32 v[114:115], v[114:115], 0.5, v[178:179] op_sel_hi:[1,0,1]
	v_pk_fma_f32 v[112:113], v[112:113], 0.5, v[176:177] op_sel_hi:[1,0,1]
	v_lshl_add_u64 v[120:121], v[212:213], 2, v[116:117]
	v_pk_fma_f32 v[110:111], v[110:111], 0.5, v[174:175] op_sel_hi:[1,0,1]
	v_pk_fma_f32 v[108:109], v[108:109], 0.5, v[172:173] op_sel_hi:[1,0,1]
	global_store_dwordx4 v[120:121], v[112:115], off
	global_store_dwordx4 v[120:121], v[108:111], off offset:16
	v_cvt_pk_bf16_f32 v116, v112, v113
	v_mul_f32_e32 v113, v113, v113
	v_fmac_f32_e32 v113, v112, v112
	v_mul_f32_e32 v112, v115, v115
	v_cvt_pk_bf16_f32 v118, v108, v109
	v_fmac_f32_e32 v112, v114, v114
	v_mul_f32_e32 v109, v109, v109
	v_add_f32_e32 v112, v113, v112
	v_fmac_f32_e32 v109, v108, v108
	v_add_f32_e32 v108, v109, v112
	v_mul_f32_e32 v109, v111, v111
	v_fmac_f32_e32 v109, v110, v110
	v_pk_fma_f32 v[106:107], v[106:107], 0.5, v[170:171] op_sel_hi:[1,0,1]
	v_pk_fma_f32 v[104:105], v[104:105], 0.5, v[168:169] op_sel_hi:[1,0,1]
	v_add_f32_e32 v112, v109, v108
	v_pk_fma_f32 v[108:109], v[100:101], 0.5, v[164:165] op_sel_hi:[1,0,1]
	v_mul_f32_e32 v100, v105, v105
	v_mul_f32_e32 v101, v107, v107
	v_fmac_f32_e32 v100, v104, v104
	v_fmac_f32_e32 v101, v106, v106
	v_add_f32_e32 v100, v100, v101
	v_mul_f32_e32 v101, v109, v109
	v_cvt_pk_bf16_f32 v119, v110, v111
	v_pk_fma_f32 v[110:111], v[102:103], 0.5, v[166:167] op_sel_hi:[1,0,1]
	v_fmac_f32_e32 v101, v108, v108
	v_add_f32_e32 v100, v101, v100
	v_mul_f32_e32 v101, v111, v111
	v_fmac_f32_e32 v101, v110, v110
	v_add_f32_e32 v100, v101, v100
	v_add_f32_e32 v100, v112, v100
	ds_bpermute_b32 v101, v242, v100
	v_lshlrev_b64 v[122:123], 11, v[224:225]
	v_lshl_add_u64 v[122:123], s[14:15], 0, v[122:123]
	v_cvt_pk_bf16_f32 v117, v114, v115
	v_lshl_add_u64 v[122:123], v[212:213], 1, v[122:123]
	s_waitcnt lgkmcnt(0)
	v_add_f32_e32 v100, v100, v101
	ds_bpermute_b32 v101, v233, v100
	global_store_dwordx4 v[122:123], v[116:119], off
	global_store_dwordx4 v[120:121], v[104:107], off offset:128
	global_store_dwordx4 v[120:121], v[108:111], off offset:144
	v_cvt_pk_bf16_f32 v102, v104, v105
	v_cvt_pk_bf16_f32 v103, v106, v107
	v_cvt_pk_bf16_f32 v104, v108, v109
	v_cvt_pk_bf16_f32 v105, v110, v111
	global_store_dwordx4 v[122:123], v[102:105], off offset:64
	s_and_saveexec_b64 s[22:23], s[42:43]
	s_cbranch_execz .LBB0_247
	s_waitcnt lgkmcnt(0)
	v_add_f32_e32 v102, v100, v101
	v_lshl_add_u64 v[100:101], v[224:225], 2, s[34:35]
	global_atomic_add_f32 v[100:101], v102, off
.LBB0_247:
	s_or_b64 exec, exec, s[22:23]
	s_waitcnt lgkmcnt(0)
	v_lshl_add_u64 v[100:101], s[8:9], 0, v[226:227]
	v_pk_fma_f32 v[98:99], v[98:99], 0.5, v[162:163] op_sel_hi:[1,0,1]
	v_pk_fma_f32 v[96:97], v[96:97], 0.5, v[160:161] op_sel_hi:[1,0,1]
	v_lshl_add_u64 v[104:105], v[212:213], 2, v[100:101]
	v_pk_fma_f32 v[94:95], v[94:95], 0.5, v[158:159] op_sel_hi:[1,0,1]
	v_pk_fma_f32 v[92:93], v[92:93], 0.5, v[156:157] op_sel_hi:[1,0,1]
	global_store_dwordx4 v[104:105], v[96:99], off
	global_store_dwordx4 v[104:105], v[92:95], off offset:16
	v_cvt_pk_bf16_f32 v100, v96, v97
	v_mul_f32_e32 v97, v97, v97
	v_fmac_f32_e32 v97, v96, v96
	v_mul_f32_e32 v96, v99, v99
	v_cvt_pk_bf16_f32 v102, v92, v93
	v_fmac_f32_e32 v96, v98, v98
	v_mul_f32_e32 v93, v93, v93
	v_add_f32_e32 v96, v97, v96
	v_fmac_f32_e32 v93, v92, v92
	v_add_f32_e32 v92, v93, v96
	v_mul_f32_e32 v93, v95, v95
	v_fmac_f32_e32 v93, v94, v94
	v_pk_fma_f32 v[90:91], v[90:91], 0.5, v[146:147] op_sel_hi:[1,0,1]
	v_pk_fma_f32 v[88:89], v[88:89], 0.5, v[144:145] op_sel_hi:[1,0,1]
	v_add_f32_e32 v96, v93, v92
	v_pk_fma_f32 v[92:93], v[84:85], 0.5, v[140:141] op_sel_hi:[1,0,1]
	v_mul_f32_e32 v84, v89, v89
	v_mul_f32_e32 v85, v91, v91
	v_fmac_f32_e32 v84, v88, v88
	v_fmac_f32_e32 v85, v90, v90
	v_add_f32_e32 v84, v84, v85
	v_mul_f32_e32 v85, v93, v93
	v_cvt_pk_bf16_f32 v103, v94, v95
	v_pk_fma_f32 v[94:95], v[86:87], 0.5, v[142:143] op_sel_hi:[1,0,1]
	v_fmac_f32_e32 v85, v92, v92
	v_add_f32_e32 v84, v85, v84
	v_mul_f32_e32 v85, v95, v95
	v_fmac_f32_e32 v85, v94, v94
	v_add_f32_e32 v84, v85, v84
	v_add_f32_e32 v84, v96, v84
	ds_bpermute_b32 v85, v242, v84
	v_lshlrev_b64 v[106:107], 11, v[220:221]
	v_lshl_add_u64 v[106:107], s[14:15], 0, v[106:107]
	v_cvt_pk_bf16_f32 v101, v98, v99
	v_lshl_add_u64 v[106:107], v[212:213], 1, v[106:107]
	s_waitcnt lgkmcnt(0)
	v_add_f32_e32 v84, v84, v85
	ds_bpermute_b32 v85, v233, v84
	global_store_dwordx4 v[106:107], v[100:103], off
	global_store_dwordx4 v[104:105], v[88:91], off offset:128
	global_store_dwordx4 v[104:105], v[92:95], off offset:144
	v_cvt_pk_bf16_f32 v86, v88, v89
	v_cvt_pk_bf16_f32 v87, v90, v91
	v_cvt_pk_bf16_f32 v88, v92, v93
	v_cvt_pk_bf16_f32 v89, v94, v95
	global_store_dwordx4 v[106:107], v[86:89], off offset:64
	s_and_saveexec_b64 s[22:23], s[42:43]
	s_cbranch_execz .LBB0_249
	s_waitcnt lgkmcnt(0)
	v_add_f32_e32 v86, v84, v85
	v_lshl_add_u64 v[84:85], v[220:221], 2, s[34:35]
	global_atomic_add_f32 v[84:85], v86, off
;     __device__ __forceinline__ void operator()(const Acc& acc, const Unit& u, int wr, int wc, int fr, int fq) const {
;     ...
;         for (int mb = 0; mb < 4; mb += MB) {
;             f32x4 pa[MB][2], pb[MB][2]; u32x4 pt[MB][2]; float tt[MB];
; #pragma unroll
;             for (int mm = 0; mm < MB; ++mm) {
;                 const int m = mb + mm; const int r = u.pm * BM + ai * HALF + wr * 64 + m * 16 + fr;
;                 tt[mm] = PLE ? rs_in[r] : 0.f;
; #pragma unroll
;                 for (int bj = 0; bj < 2; ++bj) {
;                     const int c0 = u.pn * BM + wc * 64 + bj * 32 + 8 * fq; const float* hs = hsrc + (size_t)r * DM + c0;
;                     pa[mm][bj] = *(const f32x4*)hs; pb[mm][bj] = *(const f32x4*)(hs + 4);
;                     if (PLE) pt[mm][bj] = *(const u32x4*)(tmp + (size_t)r * DM + c0);
;                 }
;             }
; #pragma unroll
;             for (int mm = 0; mm < MB; ++mm) {
;                 const int m = mb + mm; const int r = u.pm * BM + ai * HALF + wr * 64 + m * 16 + fr; float ss = 0.f;
;                 const float t = PLE ? rstd_of(tt[mm], 1.f / 1024.f) : 1.f; const float tl = -t * 1.4426950408889634f; (void)tl;
; #pragma unroll
;                 for (int bj = 0; bj < 2; ++bj) {
;                     const int c0 = u.pn * BM + wc * 64 + bj * 32 + 8 * fq; float* hp = h + (size_t)r * DM + c0;
;                     f32x4 a = pa[mm][bj], b = pb[mm][bj];
;                     if (PLE) { f32x4 ta, tb; unpack8(pt[mm][bj], ta, tb);
; #pragma unroll
;                         for (int j = 0; j < 4; ++j) { a[j] += ta[j] * __builtin_amdgcn_rcpf(1.f + __builtin_amdgcn_exp2f(acc[ai][bj][m][0][j] * tl)); b[j] += tb[j] * __builtin_amdgcn_rcpf(1.f + __builtin_amdgcn_exp2f(acc[ai][bj][m][1][j] * tl)); } }
;                     else { a += acc[ai][bj][m][0] * alpha; b += acc[ai][bj][m][1] * alpha; }
;                     if (!dry || a[0] == 1234.56789f) { *(f32x4*)hp = a; *(f32x4*)(hp + 4) = b;
;                     *(u32x4*)(hb + (size_t)r * DM + c0) = pack8(a, b); }
;                     ss += (a[0] * a[0] + a[1] * a[1]) + (a[2] * a[2] + a[3] * a[3]) + (b[0] * b[0] + b[1] * b[1]) + (b[2] * b[2] + b[3] * b[3]);
;                 }
;                 ss += __shfl_xor(ss, 16); ss += __shfl_xor(ss, 32);
;                 if (fq == 0 && (!dry || ss == 1234.56789f)) unsafeAtomicAdd(rs_out + r, ss);
.LBB0_249:
	s_or_b64 exec, exec, s[22:23]
	s_waitcnt lgkmcnt(0)
	v_lshl_add_u64 v[84:85], s[8:9], 0, v[222:223]
	v_pk_fma_f32 v[82:83], v[82:83], 0.5, v[154:155] op_sel_hi:[1,0,1]
	v_pk_fma_f32 v[80:81], v[80:81], 0.5, v[152:153] op_sel_hi:[1,0,1]
	v_lshl_add_u64 v[88:89], v[212:213], 2, v[84:85]
	v_pk_fma_f32 v[78:79], v[78:79], 0.5, v[150:151] op_sel_hi:[1,0,1]
	v_pk_fma_f32 v[76:77], v[76:77], 0.5, v[148:149] op_sel_hi:[1,0,1]
	global_store_dwordx4 v[88:89], v[80:83], off
	global_store_dwordx4 v[88:89], v[76:79], off offset:16
	v_cvt_pk_bf16_f32 v84, v80, v81
	v_mul_f32_e32 v81, v81, v81
	v_fmac_f32_e32 v81, v80, v80
	v_mul_f32_e32 v80, v83, v83
	v_cvt_pk_bf16_f32 v86, v76, v77
	v_fmac_f32_e32 v80, v82, v82
	v_mul_f32_e32 v77, v77, v77
	v_add_f32_e32 v80, v81, v80
	v_fmac_f32_e32 v77, v76, v76
	v_add_f32_e32 v76, v77, v80
	v_mul_f32_e32 v77, v79, v79
	v_fmac_f32_e32 v77, v78, v78
	v_pk_fma_f32 v[74:75], v[74:75], 0.5, v[138:139] op_sel_hi:[1,0,1]
	v_pk_fma_f32 v[72:73], v[72:73], 0.5, v[136:137] op_sel_hi:[1,0,1]
	v_add_f32_e32 v80, v77, v76
	v_pk_fma_f32 v[76:77], v[68:69], 0.5, v[132:133] op_sel_hi:[1,0,1]
	v_mul_f32_e32 v68, v73, v73
	v_mul_f32_e32 v69, v75, v75
	v_fmac_f32_e32 v68, v72, v72
	v_fmac_f32_e32 v69, v74, v74
	v_add_f32_e32 v68, v68, v69
	v_mul_f32_e32 v69, v77, v77
	v_cvt_pk_bf16_f32 v87, v78, v79
	v_pk_fma_f32 v[78:79], v[70:71], 0.5, v[134:135] op_sel_hi:[1,0,1]
	v_fmac_f32_e32 v69, v76, v76
	v_add_f32_e32 v68, v69, v68
	v_mul_f32_e32 v69, v79, v79
	v_fmac_f32_e32 v69, v78, v78
	v_add_f32_e32 v68, v69, v68
	v_add_f32_e32 v68, v80, v68
	ds_bpermute_b32 v69, v242, v68
	v_lshlrev_b64 v[90:91], 11, v[218:219]
	v_lshl_add_u64 v[90:91], s[14:15], 0, v[90:91]
	v_cvt_pk_bf16_f32 v85, v82, v83
	v_lshl_add_u64 v[90:91], v[212:213], 1, v[90:91]
	s_waitcnt lgkmcnt(0)
	v_add_f32_e32 v68, v68, v69
	ds_bpermute_b32 v69, v233, v68
	global_store_dwordx4 v[90:91], v[84:87], off
	global_store_dwordx4 v[88:89], v[72:75], off offset:128
	global_store_dwordx4 v[88:89], v[76:79], off offset:144
	v_cvt_pk_bf16_f32 v70, v72, v73
	v_cvt_pk_bf16_f32 v71, v74, v75
	v_cvt_pk_bf16_f32 v72, v76, v77
	v_cvt_pk_bf16_f32 v73, v78, v79
	global_store_dwordx4 v[90:91], v[70:73], off offset:64
	s_and_saveexec_b64 s[22:23], s[42:43]
	s_cbranch_execz .LBB0_251
	s_waitcnt lgkmcnt(0)
	v_add_f32_e32 v70, v68, v69
	v_lshl_add_u64 v[68:69], v[218:219], 2, s[34:35]
	global_atomic_add_f32 v[68:69], v70, off
.LBB0_251:
	s_or_b64 exec, exec, s[22:23]
	v_add_u32_e32 v134, 0x80, v216
	v_ashrrev_i32_e32 v135, 31, v134
	v_lshlrev_b64 v[146:147], 12, v[134:135]
	s_waitcnt lgkmcnt(0)
	v_lshl_add_u64 v[68:69], s[10:11], 0, v[146:147]
	v_lshl_add_u64 v[68:69], v[68:69], 0, v[214:215]
	global_load_dwordx4 v[138:141], v[68:69], off offset:16
	global_load_dwordx4 v[142:145], v[68:69], off
	global_load_dwordx4 v[116:119], v[68:69], off offset:144
	global_load_dwordx4 v[120:123], v[68:69], off offset:128
	v_add_u32_e32 v130, 0x90, v216
	v_ashrrev_i32_e32 v131, 31, v130
	v_lshlrev_b64 v[136:137], 12, v[130:131]
	v_add_u32_e32 v126, 0xa0, v216
	v_lshl_add_u64 v[68:69], s[10:11], 0, v[136:137]
	v_ashrrev_i32_e32 v127, 31, v126
	v_lshl_add_u64 v[68:69], v[68:69], 0, v[214:215]
	v_lshlrev_b64 v[132:133], 12, v[126:127]
	v_add_u32_e32 v124, 0xb0, v216
	global_load_dwordx4 v[108:111], v[68:69], off offset:16
	global_load_dwordx4 v[112:115], v[68:69], off
	global_load_dwordx4 v[100:103], v[68:69], off offset:144
	global_load_dwordx4 v[104:107], v[68:69], off offset:128
	v_lshl_add_u64 v[68:69], s[10:11], 0, v[132:133]
	v_ashrrev_i32_e32 v125, 31, v124
	v_lshl_add_u64 v[68:69], v[68:69], 0, v[214:215]
	v_lshlrev_b64 v[128:129], 12, v[124:125]
	global_load_dwordx4 v[92:95], v[68:69], off offset:16
	global_load_dwordx4 v[96:99], v[68:69], off
	global_load_dwordx4 v[76:79], v[68:69], off offset:144
	global_load_dwordx4 v[80:83], v[68:69], off offset:128
	v_lshl_add_u64 v[68:69], s[10:11], 0, v[128:129]
	v_lshl_add_u64 v[72:73], v[68:69], 0, v[214:215]
	global_load_dwordx4 v[84:87], v[72:73], off offset:16
	global_load_dwordx4 v[88:91], v[72:73], off
	global_load_dwordx4 v[68:71], v[72:73], off offset:144
	s_nop 0
	global_load_dwordx4 v[72:75], v[72:73], off offset:128
	s_waitcnt vmcnt(15)
	v_pk_fma_f32 v[60:61], v[60:61], 0.5, v[138:139] op_sel_hi:[1,0,1]
	v_lshl_add_u64 v[138:139], s[8:9], 0, v[146:147]
	s_waitcnt vmcnt(14)
	v_pk_fma_f32 v[66:67], v[66:67], 0.5, v[144:145] op_sel_hi:[1,0,1]
	v_pk_fma_f32 v[64:65], v[64:65], 0.5, v[142:143] op_sel_hi:[1,0,1]
	v_lshl_add_u64 v[142:143], v[138:139], 0, v[214:215]
	v_pk_fma_f32 v[62:63], v[62:63], 0.5, v[140:141] op_sel_hi:[1,0,1]
	global_store_dwordx4 v[142:143], v[64:67], off
	global_store_dwordx4 v[142:143], v[60:63], off offset:16
	v_cvt_pk_bf16_f32 v138, v64, v65
	v_mul_f32_e32 v65, v65, v65
	v_fmac_f32_e32 v65, v64, v64
	v_mul_f32_e32 v64, v67, v67
	v_cvt_pk_bf16_f32 v140, v60, v61
	v_fmac_f32_e32 v64, v66, v66
	v_mul_f32_e32 v61, v61, v61
	v_lshlrev_b64 v[144:145], 11, v[134:135]
	v_add_f32_e32 v64, v65, v64
	v_fmac_f32_e32 v61, v60, v60
	v_lshl_add_u64 v[144:145], s[14:15], 0, v[144:145]
	v_add_f32_e32 v60, v61, v64
	v_mul_f32_e32 v61, v63, v63
	v_cvt_pk_bf16_f32 v139, v66, v67
	v_cvt_pk_bf16_f32 v141, v62, v63
	v_lshl_add_u64 v[144:145], v[212:213], 1, v[144:145]
	v_fmac_f32_e32 v61, v62, v62
	s_waitcnt vmcnt(14)
	v_pk_fma_f32 v[58:59], v[58:59], 0.5, v[122:123] op_sel_hi:[1,0,1]
	v_pk_fma_f32 v[56:57], v[56:57], 0.5, v[120:121] op_sel_hi:[1,0,1]
	global_store_dwordx4 v[144:145], v[138:141], off
	v_add_f32_e32 v64, v61, v60
	v_pk_fma_f32 v[54:55], v[54:55], 0.5, v[118:119] op_sel_hi:[1,0,1]
	v_pk_fma_f32 v[52:53], v[52:53], 0.5, v[116:117] op_sel_hi:[1,0,1]
	global_store_dwordx4 v[142:143], v[56:59], off offset:128
	global_store_dwordx4 v[142:143], v[52:55], off offset:144
	v_cvt_pk_bf16_f32 v60, v56, v57
	v_mul_f32_e32 v57, v57, v57
	v_fmac_f32_e32 v57, v56, v56
	v_mul_f32_e32 v56, v59, v59
	v_cvt_pk_bf16_f32 v62, v52, v53
	v_fmac_f32_e32 v56, v58, v58
	v_mul_f32_e32 v53, v53, v53
	v_add_f32_e32 v56, v57, v56
	v_fmac_f32_e32 v53, v52, v52
	v_add_f32_e32 v52, v53, v56
	v_mul_f32_e32 v53, v55, v55
	v_fmac_f32_e32 v53, v54, v54
	v_add_f32_e32 v52, v53, v52
	v_add_f32_e32 v52, v64, v52
	ds_bpermute_b32 v53, v242, v52
	v_cvt_pk_bf16_f32 v61, v58, v59
	v_cvt_pk_bf16_f32 v63, v54, v55
	global_store_dwordx4 v[144:145], v[60:63], off offset:64
	s_waitcnt lgkmcnt(0)
	v_add_f32_e32 v52, v52, v53
	ds_bpermute_b32 v53, v233, v52
	s_and_saveexec_b64 s[22:23], s[42:43]
	s_cbranch_execz .LBB0_253
	s_waitcnt lgkmcnt(0)
	v_add_f32_e32 v54, v52, v53
	v_lshl_add_u64 v[52:53], v[134:135], 2, s[34:35]
	global_atomic_add_f32 v[52:53], v54, off
; __device__ __forceinline__ float rstd_of(float ss, float invn) { return __builtin_amdgcn_rsqf(ss * invn + EPS); }
; __device__ __forceinline__ u32x4 pack8(f32x4 a, f32x4 b) { u32x4 w; w.x = cvtpk(a[0], a[1]); w.y = cvtpk(a[2], a[3]); w.z = cvtpk(b[0], b[1]); w.w = cvtpk(b[2], b[3]); return w; }
; __device__ __forceinline__ void unpack8(u32x4 w, f32x4& a, f32x4& b) { a = (f32x4){bflo(w.x), bfhi(w.x), bflo(w.y), bfhi(w.y)}; b = (f32x4){bflo(w.z), bfhi(w.z), bflo(w.w), bfhi(w.w)}; }
;     __device__ __forceinline__ void operator()(const Acc& acc, const Unit& u, int wr, int wc, int fr, int fq) const {
;     ...
;             for (int mm = 0; mm < MB; ++mm) {
;                 const int m = mb + mm; const int r = u.pm * BM + ai * HALF + wr * 64 + m * 16 + fr; float ss = 0.f;
;                 const float t = PLE ? rstd_of(tt[mm], 1.f / 1024.f) : 1.f; const float tl = -t * 1.4426950408889634f; (void)tl;
; #pragma unroll
;                 for (int bj = 0; bj < 2; ++bj) {
;                     const int c0 = u.pn * BM + wc * 64 + bj * 32 + 8 * fq; float* hp = h + (size_t)r * DM + c0;
;                     f32x4 a = pa[mm][bj], b = pb[mm][bj];
;                     if (PLE) { f32x4 ta, tb; unpack8(pt[mm][bj], ta, tb);
; #pragma unroll
;                         for (int j = 0; j < 4; ++j) { a[j] += ta[j] * __builtin_amdgcn_rcpf(1.f + __builtin_amdgcn_exp2f(acc[ai][bj][m][0][j] * tl)); b[j] += tb[j] * __builtin_amdgcn_rcpf(1.f + __builtin_amdgcn_exp2f(acc[ai][bj][m][1][j] * tl)); } }
;                     else { a += acc[ai][bj][m][0] * alpha; b += acc[ai][bj][m][1] * alpha; }
;                     if (!dry || a[0] == 1234.56789f) { *(f32x4*)hp = a; *(f32x4*)(hp + 4) = b;
;                     *(u32x4*)(hb + (size_t)r * DM + c0) = pack8(a, b); }
;                     ss += (a[0] * a[0] + a[1] * a[1]) + (a[2] * a[2] + a[3] * a[3]) + (b[0] * b[0] + b[1] * b[1]) + (b[2] * b[2] + b[3] * b[3]);
;                 }
;                 ss += __shfl_xor(ss, 16); ss += __shfl_xor(ss, 32);
;                 if (fq == 0 && (!dry || ss == 1234.56789f)) unsafeAtomicAdd(rs_out + r, ss);
.LBB0_253:
	s_or_b64 exec, exec, s[22:23]
	s_waitcnt lgkmcnt(0)
	v_lshl_add_u64 v[52:53], s[8:9], 0, v[136:137]
	s_waitcnt vmcnt(16)
	v_pk_fma_f32 v[50:51], v[50:51], 0.5, v[114:115] op_sel_hi:[1,0,1]
	v_pk_fma_f32 v[48:49], v[48:49], 0.5, v[112:113] op_sel_hi:[1,0,1]
	v_lshl_add_u64 v[56:57], v[212:213], 2, v[52:53]
	v_pk_fma_f32 v[46:47], v[46:47], 0.5, v[110:111] op_sel_hi:[1,0,1]
	v_pk_fma_f32 v[44:45], v[44:45], 0.5, v[108:109] op_sel_hi:[1,0,1]
	global_store_dwordx4 v[56:57], v[48:51], off
	global_store_dwordx4 v[56:57], v[44:47], off offset:16
	v_cvt_pk_bf16_f32 v52, v48, v49
	v_mul_f32_e32 v49, v49, v49
	v_fmac_f32_e32 v49, v48, v48
	v_mul_f32_e32 v48, v51, v51
	v_cvt_pk_bf16_f32 v54, v44, v45
	v_fmac_f32_e32 v48, v50, v50
	v_mul_f32_e32 v45, v45, v45
	v_add_f32_e32 v48, v49, v48
	v_fmac_f32_e32 v45, v44, v44
	v_add_f32_e32 v44, v45, v48
	v_mul_f32_e32 v45, v47, v47
	v_fmac_f32_e32 v45, v46, v46
	s_waitcnt vmcnt(16)
	v_pk_fma_f32 v[42:43], v[42:43], 0.5, v[106:107] op_sel_hi:[1,0,1]
	v_pk_fma_f32 v[40:41], v[40:41], 0.5, v[104:105] op_sel_hi:[1,0,1]
	v_add_f32_e32 v48, v45, v44
	v_pk_fma_f32 v[44:45], v[36:37], 0.5, v[100:101] op_sel_hi:[1,0,1]
	v_mul_f32_e32 v36, v41, v41
	v_mul_f32_e32 v37, v43, v43
	v_fmac_f32_e32 v36, v40, v40
	v_fmac_f32_e32 v37, v42, v42
	v_add_f32_e32 v36, v36, v37
	v_mul_f32_e32 v37, v45, v45
	v_cvt_pk_bf16_f32 v55, v46, v47
	v_pk_fma_f32 v[46:47], v[38:39], 0.5, v[102:103] op_sel_hi:[1,0,1]
	v_fmac_f32_e32 v37, v44, v44
	v_add_f32_e32 v36, v37, v36
	v_mul_f32_e32 v37, v47, v47
	v_fmac_f32_e32 v37, v46, v46
	v_add_f32_e32 v36, v37, v36
	v_add_f32_e32 v36, v48, v36
	ds_bpermute_b32 v37, v242, v36
	v_lshlrev_b64 v[58:59], 11, v[130:131]
	v_lshl_add_u64 v[58:59], s[14:15], 0, v[58:59]
	v_cvt_pk_bf16_f32 v53, v50, v51
	v_lshl_add_u64 v[58:59], v[212:213], 1, v[58:59]
	s_waitcnt lgkmcnt(0)
	v_add_f32_e32 v36, v36, v37
	ds_bpermute_b32 v37, v233, v36
	global_store_dwordx4 v[58:59], v[52:55], off
	global_store_dwordx4 v[56:57], v[40:43], off offset:128
	global_store_dwordx4 v[56:57], v[44:47], off offset:144
	v_cvt_pk_bf16_f32 v38, v40, v41
	v_cvt_pk_bf16_f32 v39, v42, v43
	v_cvt_pk_bf16_f32 v40, v44, v45
	v_cvt_pk_bf16_f32 v41, v46, v47
	global_store_dwordx4 v[58:59], v[38:41], off offset:64
	s_and_saveexec_b64 s[22:23], s[42:43]
	s_cbranch_execz .LBB0_255
	s_waitcnt lgkmcnt(0)
	v_add_f32_e32 v38, v36, v37
	v_lshl_add_u64 v[36:37], v[130:131], 2, s[34:35]
	global_atomic_add_f32 v[36:37], v38, off
; __device__ __forceinline__ float rstd_of(float ss, float invn) { return __builtin_amdgcn_rsqf(ss * invn + EPS); }
; __device__ __forceinline__ u32x4 pack8(f32x4 a, f32x4 b) { u32x4 w; w.x = cvtpk(a[0], a[1]); w.y = cvtpk(a[2], a[3]); w.z = cvtpk(b[0], b[1]); w.w = cvtpk(b[2], b[3]); return w; }
; __device__ __forceinline__ void unpack8(u32x4 w, f32x4& a, f32x4& b) { a = (f32x4){bflo(w.x), bfhi(w.x), bflo(w.y), bfhi(w.y)}; b = (f32x4){bflo(w.z), bfhi(w.z), bflo(w.w), bfhi(w.w)}; }
;     __device__ __forceinline__ void operator()(const Acc& acc, const Unit& u, int wr, int wc, int fr, int fq) const {
;     ...
;             for (int mm = 0; mm < MB; ++mm) {
;                 const int m = mb + mm; const int r = u.pm * BM + ai * HALF + wr * 64 + m * 16 + fr; float ss = 0.f;
;                 const float t = PLE ? rstd_of(tt[mm], 1.f / 1024.f) : 1.f; const float tl = -t * 1.4426950408889634f; (void)tl;
; #pragma unroll
;                 for (int bj = 0; bj < 2; ++bj) {
;                     const int c0 = u.pn * BM + wc * 64 + bj * 32 + 8 * fq; float* hp = h + (size_t)r * DM + c0;
;                     f32x4 a = pa[mm][bj], b = pb[mm][bj];
;                     if (PLE) { f32x4 ta, tb; unpack8(pt[mm][bj], ta, tb);
; #pragma unroll
;                         for (int j = 0; j < 4; ++j) { a[j] += ta[j] * __builtin_amdgcn_rcpf(1.f + __builtin_amdgcn_exp2f(acc[ai][bj][m][0][j] * tl)); b[j] += tb[j] * __builtin_amdgcn_rcpf(1.f + __builtin_amdgcn_exp2f(acc[ai][bj][m][1][j] * tl)); } }
;                     else { a += acc[ai][bj][m][0] * alpha; b += acc[ai][bj][m][1] * alpha; }
;                     if (!dry || a[0] == 1234.56789f) { *(f32x4*)hp = a; *(f32x4*)(hp + 4) = b;
;                     *(u32x4*)(hb + (size_t)r * DM + c0) = pack8(a, b); }
;                     ss += (a[0] * a[0] + a[1] * a[1]) + (a[2] * a[2] + a[3] * a[3]) + (b[0] * b[0] + b[1] * b[1]) + (b[2] * b[2] + b[3] * b[3]);
;                 }
;                 ss += __shfl_xor(ss, 16); ss += __shfl_xor(ss, 32);
;                 if (fq == 0 && (!dry || ss == 1234.56789f)) unsafeAtomicAdd(rs_out + r, ss);
.LBB0_255:
	s_or_b64 exec, exec, s[22:23]
	s_waitcnt lgkmcnt(0)
	v_lshl_add_u64 v[36:37], s[8:9], 0, v[132:133]
	s_waitcnt vmcnt(18)
	v_pk_fma_f32 v[34:35], v[34:35], 0.5, v[98:99] op_sel_hi:[1,0,1]
	v_pk_fma_f32 v[32:33], v[32:33], 0.5, v[96:97] op_sel_hi:[1,0,1]
	v_lshl_add_u64 v[40:41], v[212:213], 2, v[36:37]
	v_pk_fma_f32 v[30:31], v[30:31], 0.5, v[94:95] op_sel_hi:[1,0,1]
	v_pk_fma_f32 v[28:29], v[28:29], 0.5, v[92:93] op_sel_hi:[1,0,1]
	global_store_dwordx4 v[40:41], v[32:35], off
	global_store_dwordx4 v[40:41], v[28:31], off offset:16
	v_cvt_pk_bf16_f32 v36, v32, v33
	v_mul_f32_e32 v33, v33, v33
	v_fmac_f32_e32 v33, v32, v32
	v_mul_f32_e32 v32, v35, v35
	v_cvt_pk_bf16_f32 v38, v28, v29
	v_fmac_f32_e32 v32, v34, v34
	v_mul_f32_e32 v29, v29, v29
	v_add_f32_e32 v32, v33, v32
	v_fmac_f32_e32 v29, v28, v28
	v_add_f32_e32 v28, v29, v32
	v_mul_f32_e32 v29, v31, v31
	v_fmac_f32_e32 v29, v30, v30
	s_waitcnt vmcnt(18)
	v_pk_fma_f32 v[26:27], v[26:27], 0.5, v[82:83] op_sel_hi:[1,0,1]
	v_pk_fma_f32 v[24:25], v[24:25], 0.5, v[80:81] op_sel_hi:[1,0,1]
	v_add_f32_e32 v32, v29, v28
	v_pk_fma_f32 v[28:29], v[20:21], 0.5, v[76:77] op_sel_hi:[1,0,1]
	v_mul_f32_e32 v20, v25, v25
	v_mul_f32_e32 v21, v27, v27
	v_fmac_f32_e32 v20, v24, v24
	v_fmac_f32_e32 v21, v26, v26
	v_add_f32_e32 v20, v20, v21
	v_mul_f32_e32 v21, v29, v29
	v_cvt_pk_bf16_f32 v39, v30, v31
	v_pk_fma_f32 v[30:31], v[22:23], 0.5, v[78:79] op_sel_hi:[1,0,1]
	v_fmac_f32_e32 v21, v28, v28
	v_add_f32_e32 v20, v21, v20
	v_mul_f32_e32 v21, v31, v31
	v_fmac_f32_e32 v21, v30, v30
	v_add_f32_e32 v20, v21, v20
	v_add_f32_e32 v20, v32, v20
	ds_bpermute_b32 v21, v242, v20
	v_lshlrev_b64 v[42:43], 11, v[126:127]
	v_lshl_add_u64 v[42:43], s[14:15], 0, v[42:43]
	v_cvt_pk_bf16_f32 v37, v34, v35
	v_lshl_add_u64 v[42:43], v[212:213], 1, v[42:43]
	s_waitcnt lgkmcnt(0)
	v_add_f32_e32 v20, v20, v21
	ds_bpermute_b32 v21, v233, v20
	global_store_dwordx4 v[42:43], v[36:39], off
	global_store_dwordx4 v[40:41], v[24:27], off offset:128
	global_store_dwordx4 v[40:41], v[28:31], off offset:144
	v_cvt_pk_bf16_f32 v22, v24, v25
	v_cvt_pk_bf16_f32 v23, v26, v27
	v_cvt_pk_bf16_f32 v24, v28, v29
	v_cvt_pk_bf16_f32 v25, v30, v31
	global_store_dwordx4 v[42:43], v[22:25], off offset:64
	s_and_saveexec_b64 s[22:23], s[42:43]
	s_cbranch_execz .LBB0_257
	s_waitcnt lgkmcnt(0)
	v_add_f32_e32 v22, v20, v21
	v_lshl_add_u64 v[20:21], v[126:127], 2, s[34:35]
	global_atomic_add_f32 v[20:21], v22, off
.LBB0_257:
	s_or_b64 exec, exec, s[22:23]
	s_waitcnt lgkmcnt(0)
	v_lshl_add_u64 v[20:21], s[8:9], 0, v[128:129]
	s_waitcnt vmcnt(20)
	v_pk_fma_f32 v[18:19], v[18:19], 0.5, v[90:91] op_sel_hi:[1,0,1]
	v_pk_fma_f32 v[16:17], v[16:17], 0.5, v[88:89] op_sel_hi:[1,0,1]
	v_lshl_add_u64 v[24:25], v[212:213], 2, v[20:21]
	v_pk_fma_f32 v[14:15], v[14:15], 0.5, v[86:87] op_sel_hi:[1,0,1]
	v_pk_fma_f32 v[12:13], v[12:13], 0.5, v[84:85] op_sel_hi:[1,0,1]
	global_store_dwordx4 v[24:25], v[16:19], off
	global_store_dwordx4 v[24:25], v[12:15], off offset:16
	v_cvt_pk_bf16_f32 v20, v16, v17
	v_mul_f32_e32 v17, v17, v17
	v_fmac_f32_e32 v17, v16, v16
	v_mul_f32_e32 v16, v19, v19
	v_cvt_pk_bf16_f32 v22, v12, v13
	v_fmac_f32_e32 v16, v18, v18
	v_mul_f32_e32 v13, v13, v13
	v_add_f32_e32 v16, v17, v16
	v_fmac_f32_e32 v13, v12, v12
	v_add_f32_e32 v12, v13, v16
	v_mul_f32_e32 v13, v15, v15
	v_fmac_f32_e32 v13, v14, v14
	s_waitcnt vmcnt(20)
	v_pk_fma_f32 v[10:11], v[10:11], 0.5, v[74:75] op_sel_hi:[1,0,1]
	v_pk_fma_f32 v[8:9], v[8:9], 0.5, v[72:73] op_sel_hi:[1,0,1]
	v_add_f32_e32 v16, v13, v12
	v_pk_fma_f32 v[12:13], v[4:5], 0.5, v[68:69] op_sel_hi:[1,0,1]
	v_mul_f32_e32 v4, v9, v9
	v_mul_f32_e32 v5, v11, v11
	v_fmac_f32_e32 v4, v8, v8
	v_fmac_f32_e32 v5, v10, v10
	v_add_f32_e32 v4, v4, v5
	v_mul_f32_e32 v5, v13, v13
	v_cvt_pk_bf16_f32 v23, v14, v15
	v_pk_fma_f32 v[14:15], v[6:7], 0.5, v[70:71] op_sel_hi:[1,0,1]
	v_fmac_f32_e32 v5, v12, v12
	v_add_f32_e32 v4, v5, v4
	v_mul_f32_e32 v5, v15, v15
	v_fmac_f32_e32 v5, v14, v14
	v_add_f32_e32 v4, v5, v4
	v_add_f32_e32 v4, v16, v4
	ds_bpermute_b32 v5, v242, v4
	v_lshlrev_b64 v[26:27], 11, v[124:125]
	v_lshl_add_u64 v[26:27], s[14:15], 0, v[26:27]
	v_cvt_pk_bf16_f32 v21, v18, v19
	v_lshl_add_u64 v[26:27], v[212:213], 1, v[26:27]
	s_waitcnt lgkmcnt(0)
	v_add_f32_e32 v4, v4, v5
	ds_bpermute_b32 v5, v233, v4
	global_store_dwordx4 v[26:27], v[20:23], off
	global_store_dwordx4 v[24:25], v[8:11], off offset:128
	global_store_dwordx4 v[24:25], v[12:15], off offset:144
	v_cvt_pk_bf16_f32 v6, v8, v9
	v_cvt_pk_bf16_f32 v7, v10, v11
	v_cvt_pk_bf16_f32 v8, v12, v13
	v_cvt_pk_bf16_f32 v9, v14, v15
	global_store_dwordx4 v[26:27], v[6:9], off offset:64
	s_and_saveexec_b64 s[22:23], s[42:43]
	s_cbranch_execz .LBB0_259
	s_waitcnt lgkmcnt(0)
	v_add_f32_e32 v6, v4, v5
	v_lshl_add_u64 v[4:5], v[124:125], 2, s[34:35]
	global_atomic_add_f32 v[4:5], v6, off

; __device__ __forceinline__ float rstd_of(float ss, float invn) { return __builtin_amdgcn_rsqf(ss * invn + EPS); }
;     __device__ __forceinline__ void operator()(const Acc& acc, const Unit& u, int wr, int wc, int fr, int fq) const {
;         float tpre[2][4];
; #pragma unroll
;         for (int ai = 0; ai < 2; ++ai)
; #pragma unroll
;             for (int m = 0; m < 4; ++m) tpre[ai][m] = rs[u.pm * BM + ai * HALF + wr * 64 + m * 16 + fr];
;         asm volatile("" ::: "memory");
; #pragma unroll
;         for (int ai = 0; ai < 2; ++ai)
; #pragma unroll
;             for (int m = 0; m < 4; ++m) {
;                 const int r = u.pm * BM + ai * HALF + wr * 64 + m * 16 + fr; const float t = rstd_of(tpre[ai][m], 1.f / 1024.f);
; #pragma unroll
;                 for (int bj = 0; bj < 2; ++bj) {
;                     const int G32 = 8 * u.pn + 2 * wc + bj; const int c0 = 32 * G32 + 8 * fq;
;                     f32x4 v0 = acc[ai][bj][m][0] * t, v1 = acc[ai][bj][m][1] * t;
;                     if (G32 < 20) {
;                         float ss = (v0[0] * v0[0] + v0[1] * v0[1]) + (v0[2] * v0[2] + v0[3] * v0[3]) + (v1[0] * v1[0] + v1[1] * v1[1]) + (v1[2] * v1[2] + v1[3] * v1[3]);
;                         ss += __shfl_xor(ss, 16); ss += __shfl_xor(ss, 32);
;                         if (fq == 0 && (!dry || ss == 1234.56789f)) unsafeAtomicAdd((G32 < 12 ? rs_q : rs_kv) + r, ss);
.LBB0_326:
	v_lshl_add_u32 v156, s40, 8, v3
	v_ashrrev_i32_e32 v157, 31, v156
	v_or_b32_e32 v170, 16, v156
	v_lshl_add_u64 v[132:133], v[156:157], 2, s[12:13]
	v_ashrrev_i32_e32 v171, 31, v170
	v_or_b32_e32 v168, 32, v156
	global_load_dword v134, v[132:133], off
	v_lshl_add_u64 v[132:133], v[170:171], 2, s[12:13]
	v_ashrrev_i32_e32 v169, 31, v168
	v_or_b32_e32 v166, 48, v156
	global_load_dword v181, v[132:133], off
	v_lshl_add_u64 v[132:133], v[168:169], 2, s[12:13]
	v_ashrrev_i32_e32 v167, 31, v166
	v_add_u32_e32 v164, 0x80, v156
	global_load_dword v180, v[132:133], off
	v_lshl_add_u64 v[132:133], v[166:167], 2, s[12:13]
	v_ashrrev_i32_e32 v165, 31, v164
	v_add_u32_e32 v162, 0x90, v156
	global_load_dword v179, v[132:133], off
	v_lshl_add_u64 v[132:133], v[164:165], 2, s[12:13]
	v_ashrrev_i32_e32 v163, 31, v162
	v_add_u32_e32 v160, 0xa0, v156
	global_load_dword v178, v[132:133], off
	v_lshl_add_u64 v[132:133], v[162:163], 2, s[12:13]
	v_ashrrev_i32_e32 v161, 31, v160
	v_add_u32_e32 v158, 0xb0, v156
	global_load_dword v177, v[132:133], off
	v_lshl_add_u64 v[132:133], v[160:161], 2, s[12:13]
	v_ashrrev_i32_e32 v159, 31, v158
	global_load_dword v176, v[132:133], off
	v_lshl_add_u64 v[132:133], v[158:159], 2, s[12:13]
	global_load_dword v175, v[132:133], off
	s_lshl_b32 s22, s28, 3
	s_or_b32 s59, s22, s87
	s_cmp_lt_i32 s59, 20
	s_cselect_b64 s[34:35], -1, 0
	s_cmp_gt_i32 s59, 19
	s_waitcnt vmcnt(0)
	v_fmamk_f32 v132, v134, 0x3a800000, v236
	v_rsq_f32_e32 v172, v132
	s_nop 0
	v_pk_mul_f32 v[130:131], v[130:131], v[172:173] op_sel_hi:[1,0]
	v_pk_mul_f32 v[128:129], v[128:129], v[172:173] op_sel_hi:[1,0]
	v_pk_mul_f32 v[126:127], v[126:127], v[172:173] op_sel_hi:[1,0]
	v_pk_mul_f32 v[124:125], v[124:125], v[172:173] op_sel_hi:[1,0]
	s_cbranch_scc1 .LBB0_330
	v_mul_f32_e32 v132, v129, v129
	v_mul_f32_e32 v133, v131, v131
	v_fmac_f32_e32 v132, v128, v128
	v_fmac_f32_e32 v133, v130, v130
	v_add_f32_e32 v132, v132, v133
	v_mul_f32_e32 v133, v125, v125
	v_fmac_f32_e32 v133, v124, v124
	v_add_f32_e32 v132, v133, v132
	v_mul_f32_e32 v133, v127, v127
	v_fmac_f32_e32 v133, v126, v126
	v_add_f32_e32 v132, v133, v132
	v_xor_b32_e32 v133, 16, v238
	v_add_u32_e32 v134, 64, v239
	v_cmp_lt_i32_e32 vcc, v133, v134
	s_nop 1
	v_cndmask_b32_e32 v133, v238, v133, vcc
	v_lshlrev_b32_e32 v133, 2, v133
	ds_bpermute_b32 v133, v133, v132
	s_waitcnt lgkmcnt(0)
	v_add_f32_e32 v132, v132, v133
	v_xor_b32_e32 v133, 32, v238
	v_cmp_lt_i32_e32 vcc, v133, v134
	s_nop 1
	v_cndmask_b32_e32 v133, v238, v133, vcc
	v_lshlrev_b32_e32 v133, 2, v133
	ds_bpermute_b32 v133, v133, v132
	s_and_saveexec_b64 s[22:23], s[42:43]
	s_cbranch_execz .LBB0_329
	s_cmp_lt_i32 s59, 12
	s_cselect_b32 s28, s80, s82
	s_cselect_b32 s38, s79, s81
	s_waitcnt lgkmcnt(0)
	v_add_f32_e32 v134, v132, v133
	v_mov_b32_e32 v132, s38
	v_mov_b32_e32 v133, s28
	v_lshl_add_u64 v[132:133], v[156:157], 2, v[132:133]
	global_atomic_add_f32 v[132:133], v134, off

;     __device__ __forceinline__ void operator()(const Acc& acc, const Unit& u, int wr, int wc, int fr, int fq) const {
;     ...
;                 for (int bj = 0; bj < 2; ++bj) {
;                     const int G32 = 8 * u.pn + 2 * wc + bj; const int c0 = 32 * G32 + 8 * fq;
;                     f32x4 v0 = acc[ai][bj][m][0] * t, v1 = acc[ai][bj][m][1] * t;
;                     if (G32 < 20) {
;                         float ss = (v0[0] * v0[0] + v0[1] * v0[1]) + (v0[2] * v0[2] + v0[3] * v0[3]) + (v1[0] * v1[0] + v1[1] * v1[1]) + (v1[2] * v1[2] + v1[3] * v1[3]);
;                         ss += __shfl_xor(ss, 16); ss += __shfl_xor(ss, 32);
;                         if (fq == 0 && (!dry || ss == 1234.56789f)) unsafeAtomicAdd((G32 < 12 ? rs_q : rs_kv) + r, ss);
.LBB0_340:
	s_or_b32 s61, s59, 1
	v_mov_b32_e32 v173, v172
	v_mov_b32_e32 v126, v172
	v_mov_b32_e32 v127, v172
	s_cmp_lt_i32 s61, 20
	s_waitcnt lgkmcnt(0)
	v_pk_mul_f32 v[132:133], v[122:123], v[126:127]
	v_pk_mul_f32 v[134:135], v[120:121], v[172:173]
	v_pk_mul_f32 v[126:127], v[118:119], v[126:127]
	s_cselect_b64 s[54:55], -1, 0
	s_cmp_gt_i32 s61, 19
	v_pk_mul_f32 v[130:131], v[116:117], v[172:173]
	s_cbranch_scc1 .LBB0_344
	v_mul_f32_e32 v116, v135, v135
	v_mul_f32_e32 v117, v133, v133
	v_fmac_f32_e32 v116, v134, v134
	v_fmac_f32_e32 v117, v132, v132
	v_add_f32_e32 v116, v116, v117
	v_mul_f32_e32 v117, v131, v131
	v_fmac_f32_e32 v117, v130, v130
	v_add_f32_e32 v116, v117, v116
	v_mul_f32_e32 v117, v127, v127
	v_fmac_f32_e32 v117, v126, v126
	v_add_f32_e32 v116, v117, v116
	v_xor_b32_e32 v117, 16, v238
	v_add_u32_e32 v118, 64, v239
	v_cmp_lt_i32_e32 vcc, v117, v118
	s_nop 1
	v_cndmask_b32_e32 v117, v238, v117, vcc
	v_lshlrev_b32_e32 v117, 2, v117
	ds_bpermute_b32 v117, v117, v116
	s_waitcnt lgkmcnt(0)
	v_add_f32_e32 v116, v116, v117
	v_xor_b32_e32 v117, 32, v238
	v_cmp_lt_i32_e32 vcc, v117, v118
	s_nop 1
	v_cndmask_b32_e32 v117, v238, v117, vcc
	v_lshlrev_b32_e32 v117, 2, v117
	ds_bpermute_b32 v117, v117, v116
	s_and_saveexec_b64 s[22:23], s[42:43]
	s_cbranch_execz .LBB0_343
	s_cmp_lt_i32 s61, 12
	s_cselect_b32 s46, s80, s82
	s_cselect_b32 s47, s79, s81
	s_waitcnt lgkmcnt(0)
	v_add_f32_e32 v118, v116, v117
	v_mov_b32_e32 v116, s47
	v_mov_b32_e32 v117, s46
	v_lshl_add_u64 v[116:117], v[156:157], 2, v[116:117]
	global_atomic_add_f32 v[116:117], v118, off

; __device__ __forceinline__ float rstd_of(float ss, float invn) { return __builtin_amdgcn_rsqf(ss * invn + EPS); }
;     __device__ __forceinline__ void operator()(const Acc& acc, const Unit& u, int wr, int wc, int fr, int fq) const {
;     ...
;                 const int r = u.pm * BM + ai * HALF + wr * 64 + m * 16 + fr; const float t = rstd_of(tpre[ai][m], 1.f / 1024.f);
; #pragma unroll
;                 for (int bj = 0; bj < 2; ++bj) {
;                     const int G32 = 8 * u.pn + 2 * wc + bj; const int c0 = 32 * G32 + 8 * fq;
;                     f32x4 v0 = acc[ai][bj][m][0] * t, v1 = acc[ai][bj][m][1] * t;
;                     if (G32 < 20) {
;                         float ss = (v0[0] * v0[0] + v0[1] * v0[1]) + (v0[2] * v0[2] + v0[3] * v0[3]) + (v1[0] * v1[0] + v1[1] * v1[1]) + (v1[2] * v1[2] + v1[3] * v1[3]);
;                         ss += __shfl_xor(ss, 16); ss += __shfl_xor(ss, 32);
;                         if (fq == 0 && (!dry || ss == 1234.56789f)) unsafeAtomicAdd((G32 < 12 ? rs_q : rs_kv) + r, ss);
.LBB0_352:
	v_fmamk_f32 v116, v181, 0x3a800000, v236
	v_rsq_f32_e32 v128, v116
	v_cndmask_b32_e64 v116, 0, 1, s[34:35]
	v_cmp_ne_u32_e64 s[46:47], 1, v116
	s_andn2_b64 vcc, exec, s[34:35]
	v_pk_mul_f32 v[114:115], v[114:115], v[128:129] op_sel_hi:[1,0]
	v_pk_mul_f32 v[112:113], v[112:113], v[128:129] op_sel_hi:[1,0]
	v_pk_mul_f32 v[110:111], v[110:111], v[128:129] op_sel_hi:[1,0]
	v_pk_mul_f32 v[108:109], v[108:109], v[128:129] op_sel_hi:[1,0]
	s_cbranch_vccnz .LBB0_356
	v_mul_f32_e32 v116, v113, v113
	s_waitcnt lgkmcnt(0)
	v_mul_f32_e32 v117, v115, v115
	v_fmac_f32_e32 v116, v112, v112
	v_fmac_f32_e32 v117, v114, v114
	v_add_f32_e32 v116, v116, v117
	v_mul_f32_e32 v117, v109, v109
	v_fmac_f32_e32 v117, v108, v108
	v_add_f32_e32 v116, v117, v116
	v_mul_f32_e32 v117, v111, v111
	v_fmac_f32_e32 v117, v110, v110
	v_add_f32_e32 v116, v117, v116
	v_xor_b32_e32 v117, 16, v238
	v_add_u32_e32 v118, 64, v239
	v_cmp_lt_i32_e32 vcc, v117, v118
	s_nop 1
	v_cndmask_b32_e32 v117, v238, v117, vcc
	v_lshlrev_b32_e32 v117, 2, v117
	ds_bpermute_b32 v117, v117, v116
	s_waitcnt lgkmcnt(0)
	v_add_f32_e32 v116, v116, v117
	v_xor_b32_e32 v117, 32, v238
	v_cmp_lt_i32_e32 vcc, v117, v118
	s_nop 1
	v_cndmask_b32_e32 v117, v238, v117, vcc
	v_lshlrev_b32_e32 v117, 2, v117
	ds_bpermute_b32 v117, v117, v116
	s_and_saveexec_b64 s[22:23], s[42:43]
	s_cbranch_execz .LBB0_355
	s_cmp_lt_i32 s59, 12
	s_cselect_b32 s34, s80, s82
	s_cselect_b32 s35, s79, s81
	s_waitcnt lgkmcnt(0)
	v_add_f32_e32 v118, v116, v117
	v_mov_b32_e32 v116, s35
	v_mov_b32_e32 v117, s34
	v_lshl_add_u64 v[116:117], v[156:157], 2, v[116:117]
	global_atomic_add_f32 v[116:117], v118, off offset:64

;     __device__ __forceinline__ void operator()(const Acc& acc, const Unit& u, int wr, int wc, int fr, int fq) const {
;     ...
;                 for (int bj = 0; bj < 2; ++bj) {
;                     const int G32 = 8 * u.pn + 2 * wc + bj; const int c0 = 32 * G32 + 8 * fq;
;                     f32x4 v0 = acc[ai][bj][m][0] * t, v1 = acc[ai][bj][m][1] * t;
;                     if (G32 < 20) {
;                         float ss = (v0[0] * v0[0] + v0[1] * v0[1]) + (v0[2] * v0[2] + v0[3] * v0[3]) + (v1[0] * v1[0] + v1[1] * v1[1]) + (v1[2] * v1[2] + v1[3] * v1[3]);
;                         ss += __shfl_xor(ss, 16); ss += __shfl_xor(ss, 32);
;                         if (fq == 0 && (!dry || ss == 1234.56789f)) unsafeAtomicAdd((G32 < 12 ? rs_q : rs_kv) + r, ss);
.LBB0_366:
	s_nop 1
	v_mov_b32_e32 v110, v128
	v_mov_b32_e32 v111, v128
	v_mov_b32_e32 v129, v128
	v_pk_mul_f32 v[114:115], v[106:107], v[110:111]
	v_pk_mul_f32 v[110:111], v[102:103], v[110:111]
	v_cndmask_b32_e64 v102, 0, 1, s[54:55]
	s_waitcnt lgkmcnt(0)
	v_pk_mul_f32 v[116:117], v[104:105], v[128:129]
	v_cmp_ne_u32_e64 s[52:53], 1, v102
	s_andn2_b64 vcc, exec, s[54:55]
	v_pk_mul_f32 v[112:113], v[100:101], v[128:129]
	s_cbranch_vccnz .LBB0_370
	v_mul_f32_e32 v100, v117, v117
	v_mul_f32_e32 v101, v115, v115
	v_fmac_f32_e32 v100, v116, v116
	v_fmac_f32_e32 v101, v114, v114
	v_add_f32_e32 v100, v100, v101
	v_mul_f32_e32 v101, v113, v113
	v_fmac_f32_e32 v101, v112, v112
	v_add_f32_e32 v100, v101, v100
	v_mul_f32_e32 v101, v111, v111
	v_fmac_f32_e32 v101, v110, v110
	v_add_f32_e32 v100, v101, v100
	v_xor_b32_e32 v101, 16, v238
	v_add_u32_e32 v102, 64, v239
	v_cmp_lt_i32_e32 vcc, v101, v102
	s_nop 1
	v_cndmask_b32_e32 v101, v238, v101, vcc
	v_lshlrev_b32_e32 v101, 2, v101
	ds_bpermute_b32 v101, v101, v100
	s_waitcnt lgkmcnt(0)
	v_add_f32_e32 v100, v100, v101
	v_xor_b32_e32 v101, 32, v238
	v_cmp_lt_i32_e32 vcc, v101, v102
	s_nop 1
	v_cndmask_b32_e32 v101, v238, v101, vcc
	v_lshlrev_b32_e32 v101, 2, v101
	ds_bpermute_b32 v101, v101, v100
	s_and_saveexec_b64 s[22:23], s[42:43]
	s_cbranch_execz .LBB0_369
	s_cmp_lt_i32 s61, 12
	s_cselect_b32 s34, s80, s82
	s_cselect_b32 s35, s79, s81
	s_waitcnt lgkmcnt(0)
	v_add_f32_e32 v102, v100, v101
	v_mov_b32_e32 v100, s35
	v_mov_b32_e32 v101, s34
	v_lshl_add_u64 v[100:101], v[156:157], 2, v[100:101]
	global_atomic_add_f32 v[100:101], v102, off offset:64

; __device__ __forceinline__ float rstd_of(float ss, float invn) { return __builtin_amdgcn_rsqf(ss * invn + EPS); }
;     __device__ __forceinline__ void operator()(const Acc& acc, const Unit& u, int wr, int wc, int fr, int fq) const {
;     ...
;                 const int r = u.pm * BM + ai * HALF + wr * 64 + m * 16 + fr; const float t = rstd_of(tpre[ai][m], 1.f / 1024.f);
; #pragma unroll
;                 for (int bj = 0; bj < 2; ++bj) {
;                     const int G32 = 8 * u.pn + 2 * wc + bj; const int c0 = 32 * G32 + 8 * fq;
;                     f32x4 v0 = acc[ai][bj][m][0] * t, v1 = acc[ai][bj][m][1] * t;
;                     if (G32 < 20) {
;                         float ss = (v0[0] * v0[0] + v0[1] * v0[1]) + (v0[2] * v0[2] + v0[3] * v0[3]) + (v1[0] * v1[0] + v1[1] * v1[1]) + (v1[2] * v1[2] + v1[3] * v1[3]);
;                         ss += __shfl_xor(ss, 16); ss += __shfl_xor(ss, 32);
;                         if (fq == 0 && (!dry || ss == 1234.56789f)) unsafeAtomicAdd((G32 < 12 ? rs_q : rs_kv) + r, ss);
.LBB0_376:
	v_fmamk_f32 v100, v180, 0x3a800000, v236
	v_rsq_f32_e32 v108, v100
	v_readlane_b32 s68, v252, 32
	s_and_b64 vcc, exec, s[46:47]
	v_readlane_b32 s69, v252, 33
	v_pk_mul_f32 v[98:99], v[98:99], v[108:109] op_sel_hi:[1,0]
	v_pk_mul_f32 v[96:97], v[96:97], v[108:109] op_sel_hi:[1,0]
	v_pk_mul_f32 v[94:95], v[94:95], v[108:109] op_sel_hi:[1,0]
	v_pk_mul_f32 v[92:93], v[92:93], v[108:109] op_sel_hi:[1,0]
	s_cbranch_vccnz .LBB0_380
	v_mul_f32_e32 v100, v97, v97
	s_waitcnt lgkmcnt(0)
	v_mul_f32_e32 v101, v99, v99
	v_fmac_f32_e32 v100, v96, v96
	v_fmac_f32_e32 v101, v98, v98
	v_add_f32_e32 v100, v100, v101
	v_mul_f32_e32 v101, v93, v93
	v_fmac_f32_e32 v101, v92, v92
	v_add_f32_e32 v100, v101, v100
	v_mul_f32_e32 v101, v95, v95
	v_fmac_f32_e32 v101, v94, v94
	v_add_f32_e32 v100, v101, v100
	v_xor_b32_e32 v101, 16, v238
	v_add_u32_e32 v102, 64, v239
	v_cmp_lt_i32_e32 vcc, v101, v102
	s_nop 1
	v_cndmask_b32_e32 v101, v238, v101, vcc
	v_lshlrev_b32_e32 v101, 2, v101
	ds_bpermute_b32 v101, v101, v100
	s_waitcnt lgkmcnt(0)
	v_add_f32_e32 v100, v100, v101
	v_xor_b32_e32 v101, 32, v238
	v_cmp_lt_i32_e32 vcc, v101, v102
	s_nop 1
	v_cndmask_b32_e32 v101, v238, v101, vcc
	v_lshlrev_b32_e32 v101, 2, v101
	ds_bpermute_b32 v101, v101, v100
	s_and_saveexec_b64 s[22:23], s[42:43]
	s_cbranch_execz .LBB0_379
	s_cmp_lt_i32 s59, 12
	s_cselect_b32 s34, s80, s82
	s_cselect_b32 s35, s79, s81
	s_waitcnt lgkmcnt(0)
	v_add_f32_e32 v102, v100, v101
	v_mov_b32_e32 v100, s35
	v_mov_b32_e32 v101, s34
	v_lshl_add_u64 v[100:101], v[156:157], 2, v[100:101]
	global_atomic_add_f32 v[100:101], v102, off offset:128

;     __device__ __forceinline__ void operator()(const Acc& acc, const Unit& u, int wr, int wc, int fr, int fq) const {
;     ...
;                 for (int bj = 0; bj < 2; ++bj) {
;                     const int G32 = 8 * u.pn + 2 * wc + bj; const int c0 = 32 * G32 + 8 * fq;
;                     f32x4 v0 = acc[ai][bj][m][0] * t, v1 = acc[ai][bj][m][1] * t;
;                     if (G32 < 20) {
;                         float ss = (v0[0] * v0[0] + v0[1] * v0[1]) + (v0[2] * v0[2] + v0[3] * v0[3]) + (v1[0] * v1[0] + v1[1] * v1[1]) + (v1[2] * v1[2] + v1[3] * v1[3]);
;                         ss += __shfl_xor(ss, 16); ss += __shfl_xor(ss, 32);
;                         if (fq == 0 && (!dry || ss == 1234.56789f)) unsafeAtomicAdd((G32 < 12 ? rs_q : rs_kv) + r, ss);
.LBB0_392:
	v_mov_b32_e32 v109, v108
	s_nop 0
	v_mov_b32_e32 v94, v108
	v_mov_b32_e32 v95, v108
	v_pk_mul_f32 v[98:99], v[90:91], v[94:95]
	s_waitcnt lgkmcnt(0)
	v_pk_mul_f32 v[100:101], v[88:89], v[108:109]
	v_pk_mul_f32 v[94:95], v[86:87], v[94:95]
	s_and_b64 vcc, exec, s[52:53]
	v_pk_mul_f32 v[96:97], v[84:85], v[108:109]
	s_cbranch_vccnz .LBB0_396
	v_mul_f32_e32 v84, v101, v101
	v_mul_f32_e32 v85, v99, v99
	v_fmac_f32_e32 v84, v100, v100
	v_fmac_f32_e32 v85, v98, v98
	v_add_f32_e32 v84, v84, v85
	v_mul_f32_e32 v85, v97, v97
	v_fmac_f32_e32 v85, v96, v96
	v_add_f32_e32 v84, v85, v84
	v_mul_f32_e32 v85, v95, v95
	v_fmac_f32_e32 v85, v94, v94
	v_add_f32_e32 v84, v85, v84
	v_xor_b32_e32 v85, 16, v238
	v_add_u32_e32 v86, 64, v239
	v_cmp_lt_i32_e32 vcc, v85, v86
	s_nop 1
	v_cndmask_b32_e32 v85, v238, v85, vcc
	v_lshlrev_b32_e32 v85, 2, v85
	ds_bpermute_b32 v85, v85, v84
	s_waitcnt lgkmcnt(0)
	v_add_f32_e32 v84, v84, v85
	v_xor_b32_e32 v85, 32, v238
	v_cmp_lt_i32_e32 vcc, v85, v86
	s_nop 1
	v_cndmask_b32_e32 v85, v238, v85, vcc
	v_lshlrev_b32_e32 v85, 2, v85
	ds_bpermute_b32 v85, v85, v84
	s_and_saveexec_b64 s[22:23], s[42:43]
	s_cbranch_execz .LBB0_395
	s_cmp_lt_i32 s61, 12
	s_cselect_b32 s34, s80, s82
	s_cselect_b32 s35, s79, s81
	s_waitcnt lgkmcnt(0)
	v_add_f32_e32 v86, v84, v85
	v_mov_b32_e32 v84, s35
	v_mov_b32_e32 v85, s34
	v_lshl_add_u64 v[84:85], v[156:157], 2, v[84:85]
	global_atomic_add_f32 v[84:85], v86, off offset:128

; __device__ __forceinline__ float rstd_of(float ss, float invn) { return __builtin_amdgcn_rsqf(ss * invn + EPS); }
;     __device__ __forceinline__ void operator()(const Acc& acc, const Unit& u, int wr, int wc, int fr, int fq) const {
;     ...
;                 const int r = u.pm * BM + ai * HALF + wr * 64 + m * 16 + fr; const float t = rstd_of(tpre[ai][m], 1.f / 1024.f);
; #pragma unroll
;                 for (int bj = 0; bj < 2; ++bj) {
;                     const int G32 = 8 * u.pn + 2 * wc + bj; const int c0 = 32 * G32 + 8 * fq;
;                     f32x4 v0 = acc[ai][bj][m][0] * t, v1 = acc[ai][bj][m][1] * t;
;                     if (G32 < 20) {
;                         float ss = (v0[0] * v0[0] + v0[1] * v0[1]) + (v0[2] * v0[2] + v0[3] * v0[3]) + (v1[0] * v1[0] + v1[1] * v1[1]) + (v1[2] * v1[2] + v1[3] * v1[3]);
;                         ss += __shfl_xor(ss, 16); ss += __shfl_xor(ss, 32);
;                         if (fq == 0 && (!dry || ss == 1234.56789f)) unsafeAtomicAdd((G32 < 12 ? rs_q : rs_kv) + r, ss);
.LBB0_402:
	v_fmamk_f32 v84, v179, 0x3a800000, v236
	v_rsq_f32_e32 v92, v84
	s_and_b64 vcc, exec, s[46:47]
	v_pk_mul_f32 v[82:83], v[82:83], v[92:93] op_sel_hi:[1,0]
	v_pk_mul_f32 v[80:81], v[80:81], v[92:93] op_sel_hi:[1,0]
	v_pk_mul_f32 v[78:79], v[78:79], v[92:93] op_sel_hi:[1,0]
	v_pk_mul_f32 v[76:77], v[76:77], v[92:93] op_sel_hi:[1,0]
	s_cbranch_vccnz .LBB0_406
	v_mul_f32_e32 v84, v81, v81
	s_waitcnt lgkmcnt(0)
	v_mul_f32_e32 v85, v83, v83
	v_fmac_f32_e32 v84, v80, v80
	v_fmac_f32_e32 v85, v82, v82
	v_add_f32_e32 v84, v84, v85
	v_mul_f32_e32 v85, v77, v77
	v_fmac_f32_e32 v85, v76, v76
	v_add_f32_e32 v84, v85, v84
	v_mul_f32_e32 v85, v79, v79
	v_fmac_f32_e32 v85, v78, v78
	v_add_f32_e32 v84, v85, v84
	v_xor_b32_e32 v85, 16, v238
	v_add_u32_e32 v86, 64, v239
	v_cmp_lt_i32_e32 vcc, v85, v86
	s_nop 1
	v_cndmask_b32_e32 v85, v238, v85, vcc
	v_lshlrev_b32_e32 v85, 2, v85
	ds_bpermute_b32 v85, v85, v84
	s_waitcnt lgkmcnt(0)
	v_add_f32_e32 v84, v84, v85
	v_xor_b32_e32 v85, 32, v238
	v_cmp_lt_i32_e32 vcc, v85, v86
	s_nop 1
	v_cndmask_b32_e32 v85, v238, v85, vcc
	v_lshlrev_b32_e32 v85, 2, v85
	ds_bpermute_b32 v85, v85, v84
	s_and_saveexec_b64 s[22:23], s[42:43]
	s_cbranch_execz .LBB0_405
	s_cmp_lt_i32 s59, 12
	s_cselect_b32 s34, s80, s82
	s_cselect_b32 s35, s79, s81
	s_waitcnt lgkmcnt(0)
	v_add_f32_e32 v86, v84, v85
	v_mov_b32_e32 v84, s35
	v_mov_b32_e32 v85, s34
	v_lshl_add_u64 v[84:85], v[156:157], 2, v[84:85]
	global_atomic_add_f32 v[84:85], v86, off offset:192

;     __device__ __forceinline__ void operator()(const Acc& acc, const Unit& u, int wr, int wc, int fr, int fq) const {
;     ...
;                 for (int bj = 0; bj < 2; ++bj) {
;                     const int G32 = 8 * u.pn + 2 * wc + bj; const int c0 = 32 * G32 + 8 * fq;
;                     f32x4 v0 = acc[ai][bj][m][0] * t, v1 = acc[ai][bj][m][1] * t;
;                     if (G32 < 20) {
;                         float ss = (v0[0] * v0[0] + v0[1] * v0[1]) + (v0[2] * v0[2] + v0[3] * v0[3]) + (v1[0] * v1[0] + v1[1] * v1[1]) + (v1[2] * v1[2] + v1[3] * v1[3]);
;                         ss += __shfl_xor(ss, 16); ss += __shfl_xor(ss, 32);
;                         if (fq == 0 && (!dry || ss == 1234.56789f)) unsafeAtomicAdd((G32 < 12 ? rs_q : rs_kv) + r, ss);
.LBB0_418:
	v_mov_b32_e32 v93, v92
	s_nop 0
	v_mov_b32_e32 v78, v92
	v_mov_b32_e32 v79, v92
	v_pk_mul_f32 v[82:83], v[74:75], v[78:79]
	s_waitcnt lgkmcnt(0)
	v_pk_mul_f32 v[84:85], v[72:73], v[92:93]
	v_pk_mul_f32 v[78:79], v[70:71], v[78:79]
	s_and_b64 vcc, exec, s[52:53]
	v_pk_mul_f32 v[80:81], v[68:69], v[92:93]
	s_cbranch_vccnz .LBB0_422
	v_mul_f32_e32 v68, v85, v85
	v_mul_f32_e32 v69, v83, v83
	v_fmac_f32_e32 v68, v84, v84
	v_fmac_f32_e32 v69, v82, v82
	v_add_f32_e32 v68, v68, v69
	v_mul_f32_e32 v69, v81, v81
	v_fmac_f32_e32 v69, v80, v80
	v_add_f32_e32 v68, v69, v68
	v_mul_f32_e32 v69, v79, v79
	v_fmac_f32_e32 v69, v78, v78
	v_add_f32_e32 v68, v69, v68
	v_xor_b32_e32 v69, 16, v238
	v_add_u32_e32 v70, 64, v239
	v_cmp_lt_i32_e32 vcc, v69, v70
	s_nop 1
	v_cndmask_b32_e32 v69, v238, v69, vcc
	v_lshlrev_b32_e32 v69, 2, v69
	ds_bpermute_b32 v69, v69, v68
	s_waitcnt lgkmcnt(0)
	v_add_f32_e32 v68, v68, v69
	v_xor_b32_e32 v69, 32, v238
	v_cmp_lt_i32_e32 vcc, v69, v70
	s_nop 1
	v_cndmask_b32_e32 v69, v238, v69, vcc
	v_lshlrev_b32_e32 v69, 2, v69
	ds_bpermute_b32 v69, v69, v68
	s_and_saveexec_b64 s[22:23], s[42:43]
	s_cbranch_execz .LBB0_421
	s_cmp_lt_i32 s61, 12
	s_cselect_b32 s34, s80, s82
	s_cselect_b32 s35, s79, s81
	s_waitcnt lgkmcnt(0)
	v_add_f32_e32 v70, v68, v69
	v_mov_b32_e32 v68, s35
	v_mov_b32_e32 v69, s34
	v_lshl_add_u64 v[68:69], v[156:157], 2, v[68:69]
	global_atomic_add_f32 v[68:69], v70, off offset:192

; __device__ __forceinline__ float rstd_of(float ss, float invn) { return __builtin_amdgcn_rsqf(ss * invn + EPS); }
;     __device__ __forceinline__ void operator()(const Acc& acc, const Unit& u, int wr, int wc, int fr, int fq) const {
;     ...
;                 const int r = u.pm * BM + ai * HALF + wr * 64 + m * 16 + fr; const float t = rstd_of(tpre[ai][m], 1.f / 1024.f);
; #pragma unroll
;                 for (int bj = 0; bj < 2; ++bj) {
;                     const int G32 = 8 * u.pn + 2 * wc + bj; const int c0 = 32 * G32 + 8 * fq;
;                     f32x4 v0 = acc[ai][bj][m][0] * t, v1 = acc[ai][bj][m][1] * t;
;                     if (G32 < 20) {
;                         float ss = (v0[0] * v0[0] + v0[1] * v0[1]) + (v0[2] * v0[2] + v0[3] * v0[3]) + (v1[0] * v1[0] + v1[1] * v1[1]) + (v1[2] * v1[2] + v1[3] * v1[3]);
;                         ss += __shfl_xor(ss, 16); ss += __shfl_xor(ss, 32);
;                         if (fq == 0 && (!dry || ss == 1234.56789f)) unsafeAtomicAdd((G32 < 12 ? rs_q : rs_kv) + r, ss);
.LBB0_428:
	v_fmamk_f32 v68, v178, 0x3a800000, v236
	v_rsq_f32_e32 v76, v68
	s_and_b64 vcc, exec, s[46:47]
	v_pk_mul_f32 v[66:67], v[66:67], v[76:77] op_sel_hi:[1,0]
	v_pk_mul_f32 v[64:65], v[64:65], v[76:77] op_sel_hi:[1,0]
	v_pk_mul_f32 v[62:63], v[62:63], v[76:77] op_sel_hi:[1,0]
	v_pk_mul_f32 v[60:61], v[60:61], v[76:77] op_sel_hi:[1,0]
	s_cbranch_vccnz .LBB0_432
	v_mul_f32_e32 v68, v65, v65
	s_waitcnt lgkmcnt(0)
	v_mul_f32_e32 v69, v67, v67
	v_fmac_f32_e32 v68, v64, v64
	v_fmac_f32_e32 v69, v66, v66
	v_add_f32_e32 v68, v68, v69
	v_mul_f32_e32 v69, v61, v61
	v_fmac_f32_e32 v69, v60, v60
	v_add_f32_e32 v68, v69, v68
	v_mul_f32_e32 v69, v63, v63
	v_fmac_f32_e32 v69, v62, v62
	v_add_f32_e32 v68, v69, v68
	v_xor_b32_e32 v69, 16, v238
	v_add_u32_e32 v70, 64, v239
	v_cmp_lt_i32_e32 vcc, v69, v70
	s_nop 1
	v_cndmask_b32_e32 v69, v238, v69, vcc
	v_lshlrev_b32_e32 v69, 2, v69
	ds_bpermute_b32 v69, v69, v68
	s_waitcnt lgkmcnt(0)
	v_add_f32_e32 v68, v68, v69
	v_xor_b32_e32 v69, 32, v238
	v_cmp_lt_i32_e32 vcc, v69, v70
	s_nop 1
	v_cndmask_b32_e32 v69, v238, v69, vcc
	v_lshlrev_b32_e32 v69, 2, v69
	ds_bpermute_b32 v69, v69, v68
	s_and_saveexec_b64 s[22:23], s[42:43]
	s_cbranch_execz .LBB0_431
	s_cmp_lt_i32 s59, 12
	s_cselect_b32 s34, s80, s82
	s_cselect_b32 s35, s79, s81
	s_waitcnt lgkmcnt(0)
	v_add_f32_e32 v70, v68, v69
	v_mov_b32_e32 v68, s35
	v_mov_b32_e32 v69, s34
	v_lshl_add_u64 v[68:69], v[156:157], 2, v[68:69]
	global_atomic_add_f32 v[68:69], v70, off offset:512

;     __device__ __forceinline__ void operator()(const Acc& acc, const Unit& u, int wr, int wc, int fr, int fq) const {
;     ...
;                 for (int bj = 0; bj < 2; ++bj) {
;                     const int G32 = 8 * u.pn + 2 * wc + bj; const int c0 = 32 * G32 + 8 * fq;
;                     f32x4 v0 = acc[ai][bj][m][0] * t, v1 = acc[ai][bj][m][1] * t;
;                     if (G32 < 20) {
;                         float ss = (v0[0] * v0[0] + v0[1] * v0[1]) + (v0[2] * v0[2] + v0[3] * v0[3]) + (v1[0] * v1[0] + v1[1] * v1[1]) + (v1[2] * v1[2] + v1[3] * v1[3]);
;                         ss += __shfl_xor(ss, 16); ss += __shfl_xor(ss, 32);
;                         if (fq == 0 && (!dry || ss == 1234.56789f)) unsafeAtomicAdd((G32 < 12 ? rs_q : rs_kv) + r, ss);
.LBB0_444:
	v_mov_b32_e32 v77, v76
	s_nop 0
	v_mov_b32_e32 v62, v76
	v_mov_b32_e32 v63, v76
	v_pk_mul_f32 v[66:67], v[58:59], v[62:63]
	s_waitcnt lgkmcnt(0)
	v_pk_mul_f32 v[68:69], v[56:57], v[76:77]
	v_pk_mul_f32 v[62:63], v[54:55], v[62:63]
	s_and_b64 vcc, exec, s[52:53]
	v_pk_mul_f32 v[64:65], v[52:53], v[76:77]
	s_cbranch_vccnz .LBB0_448
	v_mul_f32_e32 v52, v69, v69
	v_mul_f32_e32 v53, v67, v67
	v_fmac_f32_e32 v52, v68, v68
	v_fmac_f32_e32 v53, v66, v66
	v_add_f32_e32 v52, v52, v53
	v_mul_f32_e32 v53, v65, v65
	v_fmac_f32_e32 v53, v64, v64
	v_add_f32_e32 v52, v53, v52
	v_mul_f32_e32 v53, v63, v63
	v_fmac_f32_e32 v53, v62, v62
	v_add_f32_e32 v52, v53, v52
	v_xor_b32_e32 v53, 16, v238
	v_add_u32_e32 v54, 64, v239
	v_cmp_lt_i32_e32 vcc, v53, v54
	s_nop 1
	v_cndmask_b32_e32 v53, v238, v53, vcc
	v_lshlrev_b32_e32 v53, 2, v53
	ds_bpermute_b32 v53, v53, v52
	s_waitcnt lgkmcnt(0)
	v_add_f32_e32 v52, v52, v53
	v_xor_b32_e32 v53, 32, v238
	v_cmp_lt_i32_e32 vcc, v53, v54
	s_nop 1
	v_cndmask_b32_e32 v53, v238, v53, vcc
	v_lshlrev_b32_e32 v53, 2, v53
	ds_bpermute_b32 v53, v53, v52
	s_and_saveexec_b64 s[22:23], s[42:43]
	s_cbranch_execz .LBB0_447
	s_cmp_lt_i32 s61, 12
	s_cselect_b32 s34, s80, s82
	s_cselect_b32 s35, s79, s81
	s_waitcnt lgkmcnt(0)
	v_add_f32_e32 v54, v52, v53
	v_mov_b32_e32 v52, s35
	v_mov_b32_e32 v53, s34
	v_lshl_add_u64 v[52:53], v[156:157], 2, v[52:53]
	global_atomic_add_f32 v[52:53], v54, off offset:512

; __device__ __forceinline__ float rstd_of(float ss, float invn) { return __builtin_amdgcn_rsqf(ss * invn + EPS); }
;     __device__ __forceinline__ void operator()(const Acc& acc, const Unit& u, int wr, int wc, int fr, int fq) const {
;     ...
;                 const int r = u.pm * BM + ai * HALF + wr * 64 + m * 16 + fr; const float t = rstd_of(tpre[ai][m], 1.f / 1024.f);
; #pragma unroll
;                 for (int bj = 0; bj < 2; ++bj) {
;                     const int G32 = 8 * u.pn + 2 * wc + bj; const int c0 = 32 * G32 + 8 * fq;
;                     f32x4 v0 = acc[ai][bj][m][0] * t, v1 = acc[ai][bj][m][1] * t;
;                     if (G32 < 20) {
;                         float ss = (v0[0] * v0[0] + v0[1] * v0[1]) + (v0[2] * v0[2] + v0[3] * v0[3]) + (v1[0] * v1[0] + v1[1] * v1[1]) + (v1[2] * v1[2] + v1[3] * v1[3]);
;                         ss += __shfl_xor(ss, 16); ss += __shfl_xor(ss, 32);
;                         if (fq == 0 && (!dry || ss == 1234.56789f)) unsafeAtomicAdd((G32 < 12 ? rs_q : rs_kv) + r, ss);
.LBB0_454:
	v_fmamk_f32 v52, v177, 0x3a800000, v236
	v_rsq_f32_e32 v60, v52
	s_and_b64 vcc, exec, s[46:47]
	v_pk_mul_f32 v[50:51], v[50:51], v[60:61] op_sel_hi:[1,0]
	v_pk_mul_f32 v[48:49], v[48:49], v[60:61] op_sel_hi:[1,0]
	v_pk_mul_f32 v[46:47], v[46:47], v[60:61] op_sel_hi:[1,0]
	v_pk_mul_f32 v[44:45], v[44:45], v[60:61] op_sel_hi:[1,0]
	s_cbranch_vccnz .LBB0_458
	v_mul_f32_e32 v52, v49, v49
	s_waitcnt lgkmcnt(0)
	v_mul_f32_e32 v53, v51, v51
	v_fmac_f32_e32 v52, v48, v48
	v_fmac_f32_e32 v53, v50, v50
	v_add_f32_e32 v52, v52, v53
	v_mul_f32_e32 v53, v45, v45
	v_fmac_f32_e32 v53, v44, v44
	v_add_f32_e32 v52, v53, v52
	v_mul_f32_e32 v53, v47, v47
	v_fmac_f32_e32 v53, v46, v46
	v_add_f32_e32 v52, v53, v52
	v_xor_b32_e32 v53, 16, v238
	v_add_u32_e32 v54, 64, v239
	v_cmp_lt_i32_e32 vcc, v53, v54
	s_nop 1
	v_cndmask_b32_e32 v53, v238, v53, vcc
	v_lshlrev_b32_e32 v53, 2, v53
	ds_bpermute_b32 v53, v53, v52
	s_waitcnt lgkmcnt(0)
	v_add_f32_e32 v52, v52, v53
	v_xor_b32_e32 v53, 32, v238
	v_cmp_lt_i32_e32 vcc, v53, v54
	s_nop 1
	v_cndmask_b32_e32 v53, v238, v53, vcc
	v_lshlrev_b32_e32 v53, 2, v53
	ds_bpermute_b32 v53, v53, v52
	s_and_saveexec_b64 s[22:23], s[42:43]
	s_cbranch_execz .LBB0_457
	s_cmp_lt_i32 s59, 12
	s_cselect_b32 s34, s80, s82
	s_cselect_b32 s35, s79, s81
	s_waitcnt lgkmcnt(0)
	v_add_f32_e32 v54, v52, v53
	v_mov_b32_e32 v52, s35
	v_mov_b32_e32 v53, s34
	v_lshl_add_u64 v[52:53], v[156:157], 2, v[52:53]
	global_atomic_add_f32 v[52:53], v54, off offset:576

;     __device__ __forceinline__ void operator()(const Acc& acc, const Unit& u, int wr, int wc, int fr, int fq) const {
;     ...
;                 for (int bj = 0; bj < 2; ++bj) {
;                     const int G32 = 8 * u.pn + 2 * wc + bj; const int c0 = 32 * G32 + 8 * fq;
;                     f32x4 v0 = acc[ai][bj][m][0] * t, v1 = acc[ai][bj][m][1] * t;
;                     if (G32 < 20) {
;                         float ss = (v0[0] * v0[0] + v0[1] * v0[1]) + (v0[2] * v0[2] + v0[3] * v0[3]) + (v1[0] * v1[0] + v1[1] * v1[1]) + (v1[2] * v1[2] + v1[3] * v1[3]);
;                         ss += __shfl_xor(ss, 16); ss += __shfl_xor(ss, 32);
;                         if (fq == 0 && (!dry || ss == 1234.56789f)) unsafeAtomicAdd((G32 < 12 ? rs_q : rs_kv) + r, ss);
.LBB0_470:
	v_mov_b32_e32 v61, v60
	s_nop 0
	v_mov_b32_e32 v46, v60
	v_mov_b32_e32 v47, v60
	v_pk_mul_f32 v[50:51], v[42:43], v[46:47]
	s_waitcnt lgkmcnt(0)
	v_pk_mul_f32 v[52:53], v[40:41], v[60:61]
	v_pk_mul_f32 v[46:47], v[38:39], v[46:47]
	s_and_b64 vcc, exec, s[52:53]
	v_pk_mul_f32 v[48:49], v[36:37], v[60:61]
	s_cbranch_vccnz .LBB0_474
	v_mul_f32_e32 v36, v53, v53
	v_mul_f32_e32 v37, v51, v51
	v_fmac_f32_e32 v36, v52, v52
	v_fmac_f32_e32 v37, v50, v50
	v_add_f32_e32 v36, v36, v37
	v_mul_f32_e32 v37, v49, v49
	v_fmac_f32_e32 v37, v48, v48
	v_add_f32_e32 v36, v37, v36
	v_mul_f32_e32 v37, v47, v47
	v_fmac_f32_e32 v37, v46, v46
	v_add_f32_e32 v36, v37, v36
	v_xor_b32_e32 v37, 16, v238
	v_add_u32_e32 v38, 64, v239
	v_cmp_lt_i32_e32 vcc, v37, v38
	s_nop 1
	v_cndmask_b32_e32 v37, v238, v37, vcc
	v_lshlrev_b32_e32 v37, 2, v37
	ds_bpermute_b32 v37, v37, v36
	s_waitcnt lgkmcnt(0)
	v_add_f32_e32 v36, v36, v37
	v_xor_b32_e32 v37, 32, v238
	v_cmp_lt_i32_e32 vcc, v37, v38
	s_nop 1
	v_cndmask_b32_e32 v37, v238, v37, vcc
	v_lshlrev_b32_e32 v37, 2, v37
	ds_bpermute_b32 v37, v37, v36
	s_and_saveexec_b64 s[22:23], s[42:43]
	s_cbranch_execz .LBB0_473
	s_cmp_lt_i32 s61, 12
	s_cselect_b32 s34, s80, s82
	s_cselect_b32 s35, s79, s81
	s_waitcnt lgkmcnt(0)
	v_add_f32_e32 v38, v36, v37
	v_mov_b32_e32 v36, s35
	v_mov_b32_e32 v37, s34
	v_lshl_add_u64 v[36:37], v[156:157], 2, v[36:37]
	global_atomic_add_f32 v[36:37], v38, off offset:576

; __device__ __forceinline__ float rstd_of(float ss, float invn) { return __builtin_amdgcn_rsqf(ss * invn + EPS); }
;     __device__ __forceinline__ void operator()(const Acc& acc, const Unit& u, int wr, int wc, int fr, int fq) const {
;     ...
;                 const int r = u.pm * BM + ai * HALF + wr * 64 + m * 16 + fr; const float t = rstd_of(tpre[ai][m], 1.f / 1024.f);
; #pragma unroll
;                 for (int bj = 0; bj < 2; ++bj) {
;                     const int G32 = 8 * u.pn + 2 * wc + bj; const int c0 = 32 * G32 + 8 * fq;
;                     f32x4 v0 = acc[ai][bj][m][0] * t, v1 = acc[ai][bj][m][1] * t;
;                     if (G32 < 20) {
;                         float ss = (v0[0] * v0[0] + v0[1] * v0[1]) + (v0[2] * v0[2] + v0[3] * v0[3]) + (v1[0] * v1[0] + v1[1] * v1[1]) + (v1[2] * v1[2] + v1[3] * v1[3]);
;                         ss += __shfl_xor(ss, 16); ss += __shfl_xor(ss, 32);
;                         if (fq == 0 && (!dry || ss == 1234.56789f)) unsafeAtomicAdd((G32 < 12 ? rs_q : rs_kv) + r, ss);
.LBB0_480:
	v_fmamk_f32 v36, v176, 0x3a800000, v236
	v_rsq_f32_e32 v44, v36
	s_and_b64 vcc, exec, s[46:47]
	v_pk_mul_f32 v[34:35], v[34:35], v[44:45] op_sel_hi:[1,0]
	v_pk_mul_f32 v[32:33], v[32:33], v[44:45] op_sel_hi:[1,0]
	v_pk_mul_f32 v[30:31], v[30:31], v[44:45] op_sel_hi:[1,0]
	v_pk_mul_f32 v[28:29], v[28:29], v[44:45] op_sel_hi:[1,0]
	s_cbranch_vccnz .LBB0_484
	v_mul_f32_e32 v36, v33, v33
	s_waitcnt lgkmcnt(0)
	v_mul_f32_e32 v37, v35, v35
	v_fmac_f32_e32 v36, v32, v32
	v_fmac_f32_e32 v37, v34, v34
	v_add_f32_e32 v36, v36, v37
	v_mul_f32_e32 v37, v29, v29
	v_fmac_f32_e32 v37, v28, v28
	v_add_f32_e32 v36, v37, v36
	v_mul_f32_e32 v37, v31, v31
	v_fmac_f32_e32 v37, v30, v30
	v_add_f32_e32 v36, v37, v36
	v_xor_b32_e32 v37, 16, v238
	v_add_u32_e32 v38, 64, v239
	v_cmp_lt_i32_e32 vcc, v37, v38
	s_nop 1
	v_cndmask_b32_e32 v37, v238, v37, vcc
	v_lshlrev_b32_e32 v37, 2, v37
	ds_bpermute_b32 v37, v37, v36
	s_waitcnt lgkmcnt(0)
	v_add_f32_e32 v36, v36, v37
	v_xor_b32_e32 v37, 32, v238
	v_cmp_lt_i32_e32 vcc, v37, v38
	s_nop 1
	v_cndmask_b32_e32 v37, v238, v37, vcc
	v_lshlrev_b32_e32 v37, 2, v37
	ds_bpermute_b32 v37, v37, v36
	s_and_saveexec_b64 s[22:23], s[42:43]
	s_cbranch_execz .LBB0_483
	s_cmp_lt_i32 s59, 12
	s_cselect_b32 s34, s80, s82
	s_cselect_b32 s35, s79, s81
	s_waitcnt lgkmcnt(0)
	v_add_f32_e32 v38, v36, v37
	v_mov_b32_e32 v36, s35
	v_mov_b32_e32 v37, s34
	v_lshl_add_u64 v[36:37], v[156:157], 2, v[36:37]
	global_atomic_add_f32 v[36:37], v38, off offset:640

;     __device__ __forceinline__ void operator()(const Acc& acc, const Unit& u, int wr, int wc, int fr, int fq) const {
;     ...
;                 for (int bj = 0; bj < 2; ++bj) {
;                     const int G32 = 8 * u.pn + 2 * wc + bj; const int c0 = 32 * G32 + 8 * fq;
;                     f32x4 v0 = acc[ai][bj][m][0] * t, v1 = acc[ai][bj][m][1] * t;
;                     if (G32 < 20) {
;                         float ss = (v0[0] * v0[0] + v0[1] * v0[1]) + (v0[2] * v0[2] + v0[3] * v0[3]) + (v1[0] * v1[0] + v1[1] * v1[1]) + (v1[2] * v1[2] + v1[3] * v1[3]);
;                         ss += __shfl_xor(ss, 16); ss += __shfl_xor(ss, 32);
;                         if (fq == 0 && (!dry || ss == 1234.56789f)) unsafeAtomicAdd((G32 < 12 ? rs_q : rs_kv) + r, ss);
.LBB0_496:
	v_mov_b32_e32 v45, v44
	s_nop 0
	v_mov_b32_e32 v30, v44
	v_mov_b32_e32 v31, v44
	v_pk_mul_f32 v[34:35], v[26:27], v[30:31]
	s_waitcnt lgkmcnt(0)
	v_pk_mul_f32 v[36:37], v[24:25], v[44:45]
	v_pk_mul_f32 v[30:31], v[22:23], v[30:31]
	s_and_b64 vcc, exec, s[52:53]
	v_pk_mul_f32 v[32:33], v[20:21], v[44:45]
	s_cbranch_vccnz .LBB0_500
	v_mul_f32_e32 v20, v37, v37
	v_mul_f32_e32 v21, v35, v35
	v_fmac_f32_e32 v20, v36, v36
	v_fmac_f32_e32 v21, v34, v34
	v_add_f32_e32 v20, v20, v21
	v_mul_f32_e32 v21, v33, v33
	v_fmac_f32_e32 v21, v32, v32
	v_add_f32_e32 v20, v21, v20
	v_mul_f32_e32 v21, v31, v31
	v_fmac_f32_e32 v21, v30, v30
	v_add_f32_e32 v20, v21, v20
	v_xor_b32_e32 v21, 16, v238
	v_add_u32_e32 v22, 64, v239
	v_cmp_lt_i32_e32 vcc, v21, v22
	s_nop 1
	v_cndmask_b32_e32 v21, v238, v21, vcc
	v_lshlrev_b32_e32 v21, 2, v21
	ds_bpermute_b32 v21, v21, v20
	s_waitcnt lgkmcnt(0)
	v_add_f32_e32 v20, v20, v21
	v_xor_b32_e32 v21, 32, v238
	v_cmp_lt_i32_e32 vcc, v21, v22
	s_nop 1
	v_cndmask_b32_e32 v21, v238, v21, vcc
	v_lshlrev_b32_e32 v21, 2, v21
	ds_bpermute_b32 v21, v21, v20
	s_and_saveexec_b64 s[22:23], s[42:43]
	s_cbranch_execz .LBB0_499
	s_cmp_lt_i32 s61, 12
	s_cselect_b32 s34, s80, s82
	s_cselect_b32 s35, s79, s81
	s_waitcnt lgkmcnt(0)
	v_add_f32_e32 v22, v20, v21
	v_mov_b32_e32 v20, s35
	v_mov_b32_e32 v21, s34
	v_lshl_add_u64 v[20:21], v[156:157], 2, v[20:21]
	global_atomic_add_f32 v[20:21], v22, off offset:640

; __device__ __forceinline__ float rstd_of(float ss, float invn) { return __builtin_amdgcn_rsqf(ss * invn + EPS); }
;     __device__ __forceinline__ void operator()(const Acc& acc, const Unit& u, int wr, int wc, int fr, int fq) const {
;     ...
;                 const int r = u.pm * BM + ai * HALF + wr * 64 + m * 16 + fr; const float t = rstd_of(tpre[ai][m], 1.f / 1024.f);
; #pragma unroll
;                 for (int bj = 0; bj < 2; ++bj) {
;                     const int G32 = 8 * u.pn + 2 * wc + bj; const int c0 = 32 * G32 + 8 * fq;
;                     f32x4 v0 = acc[ai][bj][m][0] * t, v1 = acc[ai][bj][m][1] * t;
;                     if (G32 < 20) {
;                         float ss = (v0[0] * v0[0] + v0[1] * v0[1]) + (v0[2] * v0[2] + v0[3] * v0[3]) + (v1[0] * v1[0] + v1[1] * v1[1]) + (v1[2] * v1[2] + v1[3] * v1[3]);
;                         ss += __shfl_xor(ss, 16); ss += __shfl_xor(ss, 32);
;                         if (fq == 0 && (!dry || ss == 1234.56789f)) unsafeAtomicAdd((G32 < 12 ? rs_q : rs_kv) + r, ss);
.LBB0_506:
	v_fmamk_f32 v20, v175, 0x3a800000, v236
	v_rsq_f32_e32 v28, v20
	s_and_b64 vcc, exec, s[46:47]
	v_pk_mul_f32 v[18:19], v[18:19], v[28:29] op_sel_hi:[1,0]
	v_pk_mul_f32 v[16:17], v[16:17], v[28:29] op_sel_hi:[1,0]
	v_pk_mul_f32 v[14:15], v[14:15], v[28:29] op_sel_hi:[1,0]
	v_pk_mul_f32 v[12:13], v[12:13], v[28:29] op_sel_hi:[1,0]
	s_cbranch_vccnz .LBB0_510
	v_mul_f32_e32 v20, v17, v17
	s_waitcnt lgkmcnt(0)
	v_mul_f32_e32 v21, v19, v19
	v_fmac_f32_e32 v20, v16, v16
	v_fmac_f32_e32 v21, v18, v18
	v_add_f32_e32 v20, v20, v21
	v_mul_f32_e32 v21, v13, v13
	v_fmac_f32_e32 v21, v12, v12
	v_add_f32_e32 v20, v21, v20
	v_mul_f32_e32 v21, v15, v15
	v_fmac_f32_e32 v21, v14, v14
	v_add_f32_e32 v20, v21, v20
	v_xor_b32_e32 v21, 16, v238
	v_add_u32_e32 v22, 64, v239
	v_cmp_lt_i32_e32 vcc, v21, v22
	s_nop 1
	v_cndmask_b32_e32 v21, v238, v21, vcc
	v_lshlrev_b32_e32 v21, 2, v21
	ds_bpermute_b32 v21, v21, v20
	s_waitcnt lgkmcnt(0)
	v_add_f32_e32 v20, v20, v21
	v_xor_b32_e32 v21, 32, v238
	v_cmp_lt_i32_e32 vcc, v21, v22
	s_nop 1
	v_cndmask_b32_e32 v21, v238, v21, vcc
	v_lshlrev_b32_e32 v21, 2, v21
	ds_bpermute_b32 v21, v21, v20
	s_and_saveexec_b64 s[22:23], s[42:43]
	s_cbranch_execz .LBB0_509
	s_cmp_lt_i32 s59, 12
	s_cselect_b32 s34, s80, s82
	s_cselect_b32 s35, s79, s81
	s_waitcnt lgkmcnt(0)
	v_add_f32_e32 v22, v20, v21
	v_mov_b32_e32 v20, s35
	v_mov_b32_e32 v21, s34
	v_lshl_add_u64 v[20:21], v[156:157], 2, v[20:21]
	global_atomic_add_f32 v[20:21], v22, off offset:704

;     __device__ __forceinline__ void operator()(const Acc& acc, const Unit& u, int wr, int wc, int fr, int fq) const {
;     ...
;                 for (int bj = 0; bj < 2; ++bj) {
;                     const int G32 = 8 * u.pn + 2 * wc + bj; const int c0 = 32 * G32 + 8 * fq;
;                     f32x4 v0 = acc[ai][bj][m][0] * t, v1 = acc[ai][bj][m][1] * t;
;                     if (G32 < 20) {
;                         float ss = (v0[0] * v0[0] + v0[1] * v0[1]) + (v0[2] * v0[2] + v0[3] * v0[3]) + (v1[0] * v1[0] + v1[1] * v1[1]) + (v1[2] * v1[2] + v1[3] * v1[3]);
;                         ss += __shfl_xor(ss, 16); ss += __shfl_xor(ss, 32);
;                         if (fq == 0 && (!dry || ss == 1234.56789f)) unsafeAtomicAdd((G32 < 12 ? rs_q : rs_kv) + r, ss);
.LBB0_522:
	v_mov_b32_e32 v29, v28
	s_nop 0
	v_mov_b32_e32 v14, v28
	v_mov_b32_e32 v15, v28
	v_pk_mul_f32 v[18:19], v[10:11], v[14:15]
	s_waitcnt lgkmcnt(0)
	v_pk_mul_f32 v[20:21], v[8:9], v[28:29]
	v_pk_mul_f32 v[14:15], v[6:7], v[14:15]
	s_and_b64 vcc, exec, s[52:53]
	v_pk_mul_f32 v[16:17], v[4:5], v[28:29]
	s_cbranch_vccnz .LBB0_526
	v_mul_f32_e32 v4, v21, v21
	v_mul_f32_e32 v5, v19, v19
	v_fmac_f32_e32 v4, v20, v20
	v_fmac_f32_e32 v5, v18, v18
	v_add_f32_e32 v4, v4, v5
	v_mul_f32_e32 v5, v17, v17
	v_fmac_f32_e32 v5, v16, v16
	v_add_f32_e32 v4, v5, v4
	v_mul_f32_e32 v5, v15, v15
	v_fmac_f32_e32 v5, v14, v14
	v_add_f32_e32 v4, v5, v4
	v_xor_b32_e32 v5, 16, v238
	v_add_u32_e32 v6, 64, v239
	v_cmp_lt_i32_e32 vcc, v5, v6
	s_nop 1
	v_cndmask_b32_e32 v5, v238, v5, vcc
	v_lshlrev_b32_e32 v5, 2, v5
	ds_bpermute_b32 v5, v5, v4
	s_waitcnt lgkmcnt(0)
	v_add_f32_e32 v4, v4, v5
	v_xor_b32_e32 v5, 32, v238
	v_cmp_lt_i32_e32 vcc, v5, v6
	s_nop 1
	v_cndmask_b32_e32 v5, v238, v5, vcc
	v_lshlrev_b32_e32 v5, 2, v5
	ds_bpermute_b32 v5, v5, v4
	s_and_saveexec_b64 s[22:23], s[42:43]
	s_cbranch_execz .LBB0_525
	s_cmp_lt_i32 s61, 12
	s_cselect_b32 s28, s80, s82
	s_cselect_b32 s34, s79, s81
	s_waitcnt lgkmcnt(0)
	v_add_f32_e32 v6, v4, v5
	v_mov_b32_e32 v4, s34
	v_mov_b32_e32 v5, s28
	v_lshl_add_u64 v[4:5], v[156:157], 2, v[4:5]
	global_atomic_add_f32 v[4:5], v6, off offset:704

; __device__ __forceinline__ float rstd_of(float ss, float invn) { return __builtin_amdgcn_rsqf(ss * invn + EPS); }
; __device__ __forceinline__ u32x4 pack8(f32x4 a, f32x4 b) { u32x4 w; w.x = cvtpk(a[0], a[1]); w.y = cvtpk(a[2], a[3]); w.z = cvtpk(b[0], b[1]); w.w = cvtpk(b[2], b[3]); return w; }
;     __device__ __forceinline__ void operator()(const Acc& acc, const Unit& u, int wr, int wc, int fr, int fq) const {
; #pragma unroll
;         for (int bj = 0; bj < 2; ++bj) {
;             const int c0 = u.pn * BM + wc * 64 + bj * 32 + 8 * fq;
;             f32x4 t0 = *(const f32x4*)(rs + c0), t1 = *(const f32x4*)(rs + c0 + 4);
; #pragma unroll
;             for (int j = 0; j < 4; ++j) { t0[j] = rstd_of(t0[j], invn); t1[j] = rstd_of(t1[j], invn); }
; #pragma unroll
;             for (int ai = 0; ai < 2; ++ai)
; #pragma unroll
;                 for (int m = 0; m < 4; ++m) {
;                     const int r = u.pm * BM + ai * HALF + wr * 64 + m * 16 + fr;
;                     *(u32x4*)(O + (size_t)r * ldc + c0) = pack8(acc[ai][bj][m][0] * t0, acc[ai][bj][m][1] * t1);
;                 }
.LBB0_554:
	v_lshl_or_b32 v142, s59, 8, v153
	v_ashrrev_i32_e32 v143, 31, v142
	v_lshl_add_u64 v[144:145], v[142:143], 2, s[6:7]
	global_load_dwordx4 v[156:159], v[144:145], off offset:16
	global_load_dwordx4 v[146:149], v[144:145], off
	v_lshl_add_u32 v155, s60, 8, v3
	v_readlane_b32 s66, v252, 30
	v_readlane_b32 s68, v252, 32
	s_andn2_b64 vcc, exec, s[42:43]
	v_readlane_b32 s67, v252, 31
	v_readlane_b32 s69, v252, 33
	s_waitcnt vmcnt(0)
	v_fmamk_f32 v148, v148, 0x3a800000, v236
	v_fmamk_f32 v149, v149, 0x3a800000, v236
	v_fmamk_f32 v144, v146, 0x3a800000, v236
	v_fmamk_f32 v145, v147, 0x3a800000, v236
	v_rsq_f32_e32 v150, v148
	v_fmamk_f32 v148, v158, 0x3a800000, v236
	v_rsq_f32_e32 v151, v149
	v_fmamk_f32 v149, v159, 0x3a800000, v236
	v_rsq_f32_e32 v146, v144
	v_fmamk_f32 v144, v156, 0x3a800000, v236
	v_rsq_f32_e32 v147, v145
	v_fmamk_f32 v145, v157, 0x3a800000, v236
	v_rsq_f32_e32 v148, v148
	v_rsq_f32_e32 v149, v149
	v_rsq_f32_e32 v144, v144
	v_rsq_f32_e32 v145, v145
	v_pk_mul_f32 v[128:129], v[128:129], v[146:147]
	v_pk_mul_f32 v[126:127], v[126:127], v[148:149]
	v_pk_mul_f32 v[130:131], v[130:131], v[150:151]
	v_cvt_pk_bf16_f32 v156, v128, v129
	v_cvt_pk_bf16_f32 v159, v126, v127
	v_mov_b64_e32 v[126:127], s[10:11]
	v_lshlrev_b64 v[128:129], 1, v[142:143]
	v_or_b32_e32 v143, 16, v155
	v_pk_mul_f32 v[120:121], v[120:121], v[146:147]
	v_pk_mul_f32 v[116:117], v[116:117], v[144:145]
	v_cvt_pk_bf16_f32 v157, v130, v131
	v_pk_mul_f32 v[122:123], v[122:123], v[150:151]
	v_pk_mul_f32 v[130:131], v[118:119], v[148:149]
	v_cvt_pk_bf16_f32 v118, v120, v121
	v_cvt_pk_bf16_f32 v120, v116, v117
	v_mad_i64_i32 v[116:117], s[22:23], v143, s37, v[126:127]
	v_cvt_pk_bf16_f32 v119, v122, v123
	v_cvt_pk_bf16_f32 v121, v130, v131
	v_lshl_add_u64 v[116:117], v[116:117], 0, v[128:129]
	global_store_dwordx4 v[116:117], v[118:121], off
	v_pk_mul_f32 v[112:113], v[112:113], v[146:147]
	v_pk_mul_f32 v[108:109], v[108:109], v[144:145]
	v_or_b32_e32 v120, 32, v155
	v_pk_mul_f32 v[114:115], v[114:115], v[150:151]
	v_pk_mul_f32 v[118:119], v[110:111], v[148:149]
	v_cvt_pk_bf16_f32 v110, v112, v113
	v_cvt_pk_bf16_f32 v112, v108, v109
	v_mad_i64_i32 v[108:109], s[22:23], v120, s37, v[126:127]
	v_cvt_pk_bf16_f32 v111, v114, v115
	v_cvt_pk_bf16_f32 v113, v118, v119
	v_lshl_add_u64 v[108:109], v[108:109], 0, v[128:129]
	global_store_dwordx4 v[108:109], v[110:113], off
	v_pk_mul_f32 v[104:105], v[104:105], v[146:147]
	v_pk_mul_f32 v[100:101], v[100:101], v[144:145]
	v_or_b32_e32 v112, 48, v155
	v_pk_mul_f32 v[106:107], v[106:107], v[150:151]
	v_pk_mul_f32 v[110:111], v[102:103], v[148:149]
	v_cvt_pk_bf16_f32 v102, v104, v105
	v_cvt_pk_bf16_f32 v104, v100, v101
	v_mad_i64_i32 v[100:101], s[22:23], v112, s37, v[126:127]
	v_cvt_pk_bf16_f32 v103, v106, v107
	v_cvt_pk_bf16_f32 v105, v110, v111
	v_lshl_add_u64 v[100:101], v[100:101], 0, v[128:129]
	global_store_dwordx4 v[100:101], v[102:105], off
	v_pk_mul_f32 v[96:97], v[96:97], v[146:147]
	v_pk_mul_f32 v[92:93], v[92:93], v[144:145]
	v_add_u32_e32 v104, 0x80, v155
	v_pk_mul_f32 v[98:99], v[98:99], v[150:151]
	v_pk_mul_f32 v[102:103], v[94:95], v[148:149]
	v_cvt_pk_bf16_f32 v94, v96, v97
	v_cvt_pk_bf16_f32 v96, v92, v93
	v_mad_i64_i32 v[92:93], s[22:23], v104, s37, v[126:127]
	v_cvt_pk_bf16_f32 v95, v98, v99
	v_cvt_pk_bf16_f32 v97, v102, v103
	v_lshl_add_u64 v[92:93], v[92:93], 0, v[128:129]
	global_store_dwordx4 v[92:93], v[94:97], off
	v_pk_mul_f32 v[88:89], v[88:89], v[146:147]
	v_pk_mul_f32 v[84:85], v[84:85], v[144:145]
	v_add_u32_e32 v96, 0x90, v155
	v_pk_mul_f32 v[90:91], v[90:91], v[150:151]
	v_pk_mul_f32 v[94:95], v[86:87], v[148:149]
	v_cvt_pk_bf16_f32 v86, v88, v89
	v_cvt_pk_bf16_f32 v88, v84, v85
	v_mad_i64_i32 v[84:85], s[22:23], v96, s37, v[126:127]
	v_cvt_pk_bf16_f32 v87, v90, v91
	v_cvt_pk_bf16_f32 v89, v94, v95
	v_lshl_add_u64 v[84:85], v[84:85], 0, v[128:129]
	global_store_dwordx4 v[84:85], v[86:89], off
	v_pk_mul_f32 v[80:81], v[80:81], v[146:147]
	v_pk_mul_f32 v[76:77], v[76:77], v[144:145]
	v_add_u32_e32 v88, 0xa0, v155
	v_pk_mul_f32 v[82:83], v[82:83], v[150:151]
	v_pk_mul_f32 v[86:87], v[78:79], v[148:149]
	v_cvt_pk_bf16_f32 v78, v80, v81
	v_cvt_pk_bf16_f32 v80, v76, v77
	v_mad_i64_i32 v[76:77], s[22:23], v88, s37, v[126:127]
	v_cvt_pk_bf16_f32 v79, v82, v83
	v_cvt_pk_bf16_f32 v81, v86, v87
	v_lshl_add_u64 v[76:77], v[76:77], 0, v[128:129]
	global_store_dwordx4 v[76:77], v[78:81], off
	v_pk_mul_f32 v[72:73], v[72:73], v[146:147]
	v_pk_mul_f32 v[68:69], v[68:69], v[144:145]
	v_add_u32_e32 v80, 0xb0, v155
	v_pk_mul_f32 v[74:75], v[74:75], v[150:151]
	v_pk_mul_f32 v[78:79], v[70:71], v[148:149]
	v_cvt_pk_bf16_f32 v70, v72, v73
	v_cvt_pk_bf16_f32 v72, v68, v69
	v_mad_i64_i32 v[68:69], s[22:23], v80, s37, v[126:127]
	v_pk_mul_f32 v[124:125], v[124:125], v[144:145]
	v_cvt_pk_bf16_f32 v71, v74, v75
	v_cvt_pk_bf16_f32 v73, v78, v79
	v_lshl_add_u64 v[68:69], v[68:69], 0, v[128:129]
	v_cvt_pk_bf16_f32 v158, v124, v125
	v_mad_i64_i32 v[124:125], s[22:23], v155, s37, v[126:127]
	global_store_dwordx4 v[68:69], v[70:73], off
	v_lshl_add_u64 v[124:125], v[124:125], 0, v[128:129]
	global_store_dwordx4 v[124:125], v[156:159], off
	v_or_b32_e32 v70, 32, v142
	v_ashrrev_i32_e32 v71, 31, v70
	v_lshl_add_u64 v[70:71], v[70:71], 2, s[6:7]
	global_load_dwordx4 v[78:81], v[70:71], off offset:16
	global_load_dwordx4 v[72:75], v[70:71], off
	s_mov_b64 s[22:23], -1
	s_waitcnt vmcnt(1)
; __device__ __forceinline__ float rstd_of(float ss, float invn) { return __builtin_amdgcn_rsqf(ss * invn + EPS); }
; __device__ __forceinline__ u32x4 pack8(f32x4 a, f32x4 b) { u32x4 w; w.x = cvtpk(a[0], a[1]); w.y = cvtpk(a[2], a[3]); w.z = cvtpk(b[0], b[1]); w.w = cvtpk(b[2], b[3]); return w; }
;     __device__ __forceinline__ void operator()(const Acc& acc, const Unit& u, int wr, int wc, int fr, int fq) const {
;     ...
;         for (int bj = 0; bj < 2; ++bj) {
;             const int c0 = u.pn * BM + wc * 64 + bj * 32 + 8 * fq;
;             f32x4 t0 = *(const f32x4*)(rs + c0), t1 = *(const f32x4*)(rs + c0 + 4);
; #pragma unroll
;             for (int j = 0; j < 4; ++j) { t0[j] = rstd_of(t0[j], invn); t1[j] = rstd_of(t1[j], invn); }
; #pragma unroll
;             for (int ai = 0; ai < 2; ++ai)
; #pragma unroll
;                 for (int m = 0; m < 4; ++m) {
;                     const int r = u.pm * BM + ai * HALF + wr * 64 + m * 16 + fr;
;                     *(u32x4*)(O + (size_t)r * ldc + c0) = pack8(acc[ai][bj][m][0] * t0, acc[ai][bj][m][1] * t1);
;                 }
	v_fmamk_f32 v71, v78, 0x3a800000, v236
	s_waitcnt vmcnt(0)
	v_fmamk_f32 v70, v72, 0x3a800000, v236
	v_rsq_f32_e32 v72, v71
	v_fmamk_f32 v71, v73, 0x3a800000, v236
	v_fmamk_f32 v73, v79, 0x3a800000, v236
	v_fmamk_f32 v74, v74, 0x3a800000, v236
	v_fmamk_f32 v78, v80, 0x3a800000, v236
	v_fmamk_f32 v75, v75, 0x3a800000, v236
	v_fmamk_f32 v79, v81, 0x3a800000, v236
	v_rsq_f32_e32 v70, v70
	v_rsq_f32_e32 v71, v71
	v_rsq_f32_e32 v73, v73
	v_rsq_f32_e32 v74, v74
	v_rsq_f32_e32 v78, v78
	v_rsq_f32_e32 v75, v75
	v_rsq_f32_e32 v79, v79
	v_pk_mul_f32 v[64:65], v[64:65], v[70:71]
	v_pk_mul_f32 v[56:57], v[56:57], v[70:71]
	v_pk_mul_f32 v[66:67], v[66:67], v[74:75]
	v_pk_mul_f32 v[80:81], v[62:63], v[78:79]
	v_pk_mul_f32 v[62:63], v[60:61], v[72:73]
	v_cvt_pk_bf16_f32 v60, v64, v65
	v_cvt_pk_bf16_f32 v61, v66, v67
	v_cvt_pk_bf16_f32 v62, v62, v63
	v_cvt_pk_bf16_f32 v63, v80, v81
	global_store_dwordx4 v[124:125], v[60:63], off offset:64
	v_pk_mul_f32 v[58:59], v[58:59], v[74:75]
	v_pk_mul_f32 v[50:51], v[50:51], v[74:75]
	v_pk_mul_f32 v[60:61], v[54:55], v[78:79]
	v_pk_mul_f32 v[54:55], v[52:53], v[72:73]
	v_cvt_pk_bf16_f32 v52, v56, v57
	v_cvt_pk_bf16_f32 v53, v58, v59
	v_cvt_pk_bf16_f32 v54, v54, v55
	v_cvt_pk_bf16_f32 v55, v60, v61
	global_store_dwordx4 v[116:117], v[52:55], off offset:64
	v_pk_mul_f32 v[48:49], v[48:49], v[70:71]
	v_pk_mul_f32 v[42:43], v[42:43], v[74:75]
	v_pk_mul_f32 v[52:53], v[46:47], v[78:79]
	v_pk_mul_f32 v[46:47], v[44:45], v[72:73]
	v_cvt_pk_bf16_f32 v44, v48, v49
	v_cvt_pk_bf16_f32 v45, v50, v51
	v_cvt_pk_bf16_f32 v46, v46, v47
	v_cvt_pk_bf16_f32 v47, v52, v53
	global_store_dwordx4 v[108:109], v[44:47], off offset:64
	v_pk_mul_f32 v[40:41], v[40:41], v[70:71]
	v_pk_mul_f32 v[34:35], v[34:35], v[74:75]
	v_pk_mul_f32 v[44:45], v[38:39], v[78:79]
	v_pk_mul_f32 v[38:39], v[36:37], v[72:73]
	v_cvt_pk_bf16_f32 v36, v40, v41
	v_cvt_pk_bf16_f32 v37, v42, v43
	v_cvt_pk_bf16_f32 v38, v38, v39
	v_cvt_pk_bf16_f32 v39, v44, v45
	global_store_dwordx4 v[100:101], v[36:39], off offset:64
	v_pk_mul_f32 v[32:33], v[32:33], v[70:71]
	v_pk_mul_f32 v[26:27], v[26:27], v[74:75]
	v_pk_mul_f32 v[36:37], v[30:31], v[78:79]
	v_pk_mul_f32 v[30:31], v[28:29], v[72:73]
	v_cvt_pk_bf16_f32 v28, v32, v33
	v_cvt_pk_bf16_f32 v29, v34, v35
	v_cvt_pk_bf16_f32 v30, v30, v31
	v_cvt_pk_bf16_f32 v31, v36, v37
	global_store_dwordx4 v[92:93], v[28:31], off offset:64
	v_pk_mul_f32 v[24:25], v[24:25], v[70:71]
	v_pk_mul_f32 v[18:19], v[18:19], v[74:75]
	v_pk_mul_f32 v[28:29], v[22:23], v[78:79]
	v_pk_mul_f32 v[22:23], v[20:21], v[72:73]
	v_cvt_pk_bf16_f32 v20, v24, v25
	v_cvt_pk_bf16_f32 v21, v26, v27
	v_cvt_pk_bf16_f32 v22, v22, v23
	v_cvt_pk_bf16_f32 v23, v28, v29
	global_store_dwordx4 v[84:85], v[20:23], off offset:64
	v_pk_mul_f32 v[16:17], v[16:17], v[70:71]
	v_pk_mul_f32 v[10:11], v[10:11], v[74:75]
	v_pk_mul_f32 v[20:21], v[14:15], v[78:79]
	v_pk_mul_f32 v[14:15], v[12:13], v[72:73]
	v_cvt_pk_bf16_f32 v12, v16, v17
	v_cvt_pk_bf16_f32 v13, v18, v19
	v_cvt_pk_bf16_f32 v14, v14, v15
	v_cvt_pk_bf16_f32 v15, v20, v21
	global_store_dwordx4 v[76:77], v[12:15], off offset:64
	v_pk_mul_f32 v[8:9], v[8:9], v[70:71]
	s_nop 0
	v_pk_mul_f32 v[12:13], v[6:7], v[78:79]
	v_pk_mul_f32 v[6:7], v[4:5], v[72:73]
	v_cvt_pk_bf16_f32 v4, v8, v9
	v_cvt_pk_bf16_f32 v5, v10, v11
	v_cvt_pk_bf16_f32 v6, v6, v7
	v_cvt_pk_bf16_f32 v7, v12, v13
	global_store_dwordx4 v[68:69], v[4:7], off offset:64
	s_cbranch_vccnz .LBB0_543
	s_andn2_b64 vcc, exec, s[8:9]
	s_cbranch_vccnz .LBB0_542
	s_barrier
	s_branch .LBB0_542

; __global__ void __launch_bounds__(NTHREADS, 2) fwd_megakernel(Params Pkern) {
;     ...
;             if (PM(12)) { SETUP const float* lbraw = Pp->lbraw; if (DUPMASK & 1) for (int u = blockIdx.x; u < 256; u += gridDim.x) hgrn_unit<true>(lds, u >> 4, (u >> 2) & 3, u & 3, layer, PB, lbraw);
;               for (int u = blockIdx.x; u < 256; u += gridDim.x) hgrn_unit<false>(lds, u >> 4, (u >> 2) & 3, u & 3, layer, PB, lbraw); }
.LBB0_611:
	s_add_i32 s22, s22, s20
	s_cmpk_gt_i32 s22, 0xff
	s_waitcnt vmcnt(0)
	s_barrier
	s_cbranch_scc1 .LBB0_647

; #define LAS __attribute__((address_space(3)))
; __device__ __forceinline__ int otid() { int t = threadIdx.x; asm volatile("" : "+v"(t)); return t; }
; template <bool DRY> __device__ __forceinline__ void hgrn_unit(LAS unsigned char* lds, int b, int h, int vs, int layer, bf16_t* Pm, const float* lbraw) {
;     ...
;     const int tid = otid(), lane = tid & 63; const int wid = __builtin_amdgcn_readfirstlane(tid >> 6);
;     const size_t tok0 = (size_t)b * SEQ;
;     const int kl = lane & 15, tq = lane >> 4, kch = 16 * wid + kl;
;     (void)layer; (void)lbraw;
;     const bf16_t* qsrc = Pm + (tok0 + 4 * tq) * PW + PC_HQ + h * 128 + (kch & ~1);
;     const bf16_t* fsrc = Pm + (tok0 + 4 * tq) * PW + PC_HF + h * 128 + (kch & ~1);
;     const bool isv = tid < 128; const int vv = tid & 31, vtq = (tid >> 5) & 3;
;     const bf16_t* vsrc = Pm + (tok0 + 4 * vtq) * PW + PC_HI + h * 128 + vs * 32 + (vv & ~1);
;     constexpr int NSTEP = SEQ / 16;
;     for (int i = tid; i < SB / 4; i += NTHREADS) ((LAS unsigned*)(lds + OFF_S + SB))[i] = 0u;
;     Raw ra, rb;
;     load_raw(ra, qsrc, fsrc, vsrc, 0, isv);
;     prep(ra, lds, lane, kch, tq, isv, vv, vtq);
.LBB0_615:
	s_or_b64 exec, exec, s[6:7]
	s_ashr_i32 s6, s22, 4
	s_ashr_i32 s7, s6, 31
	v_bfe_u32 v9, v3, 4, 2
	s_lshl_b64 s[14:15], s[6:7], 11
	v_lshlrev_b32_e32 v8, 2, v9
	v_or_b32_e32 v0, s14, v8
	v_mov_b64_e32 v[4:5], s[4:5]
	v_bfe_u32 v12, v3, 5, 2
	s_ashr_i32 s28, s10, 6
	s_mov_b32 s65, s28
	v_mad_u64_u32 v[0:1], s[6:7], v0, s24, v[4:5]
	s_lshl_b32 s10, s22, 5
	v_lshl_or_b32 v6, v12, 2, s14
	s_and_b32 s6, s10, 0x180
	v_mad_u64_u32 v[4:5], s[8:9], v6, s24, v[4:5]
	v_and_b32_e32 v7, 15, v3
	s_lshl_b32 s34, s28, 4
	v_mad_i32_i24 v1, s15, v240, v1
	s_lshl_b32 s6, s6, 1
	s_mov_b32 s7, s29
	v_mad_i32_i24 v5, s15, v240, v5
	v_lshl_add_u64 v[0:1], v[0:1], 0, s[6:7]
	v_bitop3_b32 v10, s34, -2, v7 bitop3:0xc8
	v_lshl_add_u64 v[4:5], v[4:5], 0, s[6:7]
	s_and_b32 s7, s10, 0x60
	v_ashrrev_i32_e32 v11, 31, v10
	s_lshl_b32 s8, s7, 1
	s_mul_i32 s41, s14, 0x1d40
	s_add_u32 s38, s4, s41
	s_addc_u32 s39, s5, 0
	s_add_u32 s38, s38, s6
	s_addc_u32 s39, s39, 0
	s_add_u32 s38, s38, 0xd00
	s_addc_u32 s39, s39, 0
	s_mov_b32 s9, s29
	v_and_b32_e32 v6, 30, v3
	v_lshl_add_u64 v[0:1], v[10:11], 1, v[0:1]
	v_lshl_add_u64 v[4:5], v[4:5], 0, s[8:9]
	v_lshlrev_b32_e32 v10, 1, v6
	v_mov_b32_e32 v11, v2
	s_movk_i32 s7, 0x1000
	v_lshl_add_u64 v[4:5], v[4:5], 0, v[10:11]
	v_add_co_u32_e32 v10, vcc, s7, v0
	v_cmp_eq_u32_e64 s[50:51], 3, v9
	s_nop 0
	v_addc_co_u32_e32 v11, vcc, 0, v1, vcc
	v_add_co_u32_e32 v14, vcc, s7, v4
	s_movk_i32 s7, 0x2000
	s_nop 0
	v_addc_co_u32_e32 v15, vcc, 0, v5, vcc
	v_add_co_u32_e32 v16, vcc, s7, v0
	s_movk_i32 s7, 0x3000
	s_nop 0
	v_addc_co_u32_e32 v17, vcc, 0, v1, vcc
	v_add_co_u32_e32 v18, vcc, s7, v4
	s_movk_i32 s7, 0x4000
	s_nop 0
	v_addc_co_u32_e32 v19, vcc, 0, v5, vcc
	v_add_co_u32_e32 v20, vcc, s7, v0
	s_nop 1
	v_addc_co_u32_e32 v21, vcc, 0, v1, vcc
	s_nop 0
	s_nop 0
	s_nop 0
	s_nop 0
	v_add_co_u32_e32 v10, vcc, s7, v4
	s_movk_i32 s7, 0x6000
	s_nop 0
	v_addc_co_u32_e32 v11, vcc, 0, v5, vcc
	v_add_co_u32_e32 v10, vcc, s7, v0
	s_nop 1
	v_addc_co_u32_e32 v11, vcc, 0, v1, vcc
	v_add_co_u32_e32 v18, vcc, s7, v4
	s_movk_i32 s7, 0x440
	s_nop 0
	v_addc_co_u32_e32 v19, vcc, 0, v5, vcc
	s_nop 0
	v_and_b32_e32 v19, 1, v3
	v_cmp_eq_u32_e64 s[44:45], 0, v19
	v_and_b32_e32 v11, 63, v3
	v_cmp_gt_u32_e64 s[46:47], 16, v11
	v_cmp_lt_u32_e64 s[48:49], 31, v11
	v_or_b32_e32 v10, s34, v7
	v_lshl_add_u32 v36, v10, 1, 0
	v_mad_u32_u24 v42, v9, s7, v36
	v_bfe_u32 v140, v234, 4, 2
	v_mul_u32_u24_e32 v136, 0x440, v140
	v_lshrrev_b32_e32 v140, 6, v234
	v_and_b32_e32 v141, 15, v234
	v_lshl_or_b32 v140, v140, 4, v141
	v_lshrrev_b32_e32 v140, 1, v140
	v_lshl_add_u32 v136, v140, 2, v136
	v_add_u32_e32 v136, 0xd400, v136
	v_bfe_u32 v140, v234, 5, 2
	v_and_b32_e32 v141, 31, v234
	v_lshrrev_b32_e32 v141, 1, v141
	v_lshlrev_b32_e32 v141, 2, v141
	v_lshl_add_u32 v137, v140, 8, v141
	v_add_u32_e32 v137, 0xf600, v137
	v_and_b32_e32 v140, 63, v234
	v_lshrrev_b32_e32 v141, 4, v140
	v_lshrrev_b32_e32 v142, 6, v234
	v_and_b32_e32 v143, 3, v142
	v_lshl_add_u32 v141, v143, 2, v141
	v_mul_u32_u24_e32 v138, 0x1d40, v141
	v_and_b32_e32 v141, 15, v140
	v_lshl_add_u32 v138, v141, 4, v138
	v_lshrrev_b32_e32 v142, 2, v142
	v_lshl_add_u32 v138, v142, 10, v138
	v_lshrrev_b32_e32 v141, 2, v140
	v_mul_u32_u24_e32 v139, 0x1d40, v141
	v_and_b32_e32 v141, 3, v140
	v_lshl_add_u32 v139, v141, 4, v139
	v_add_u32_e32 v139, 0x800, v139
	v_add_u32_e32 v139, s8, v139
	s_mul_i32 s64, s65, 0x440
	s_add_i32 s64, s64, 0xd400
	s_mov_b64 s[42:43], s[38:39]
	s_cmp_lg_u32 s65, 7
	s_cbranch_scc1 .Lhg_pro_nov
	s_add_i32 m0, s64, 0
	s_nop 0
	global_load_lds_dwordx4 v138, s[42:43]
	s_mov_b32 m0, 0xf600
	s_nop 0
	global_load_lds_dwordx4 v139, s[42:43]
	s_add_u32 s42, s42, 0x1d400
	s_addc_u32 s43, s43, 0
	s_add_i32 m0, s64, 9792
	s_nop 0
	global_load_lds_dwordx4 v138, s[42:43]
	s_mov_b32 m0, 0x11c40
	s_nop 0
	global_load_lds_dwordx4 v139, s[42:43]
	s_add_u32 s42, s42, 0x1d400
	s_addc_u32 s43, s43, 0
	s_add_i32 m0, s64, 19584
	s_nop 0
	global_load_lds_dwordx4 v138, s[42:43]
	s_mov_b32 m0, 0x14280
	s_nop 0
	global_load_lds_dwordx4 v139, s[42:43]
	s_add_u32 s42, s42, 0x1d400
	s_addc_u32 s43, s43, 0
	s_add_i32 m0, s64, 29376
	s_nop 0
	global_load_lds_dwordx4 v138, s[42:43]
	s_mov_b32 m0, 0x168c0
	s_nop 0
	global_load_lds_dwordx4 v139, s[42:43]
	s_waitcnt vmcnt(4)
	s_branch .Lhg_pro_done
; __device__ __forceinline__ void prep(const Raw& Rin, LAS unsigned char* buf, int lane, int kch, int tq, bool isv, int vv, int vtq) {
;     Raw R = Rin; const bool kodd = kch & 1, vodd = vv & 1;
; #pragma unroll
;     for (int i = 0; i < 4; ++i) { asm volatile("" : "+v"(R.q[i])); asm volatile("" : "+v"(R.f[i])); asm volatile("" : "+v"(R.v[i])); }
;     float qv[4], kk[4], c[4]; float run = 0.f;
; #pragma unroll
;     for (int i = 0; i < 4; ++i) {
;         qv[i] = __uint_as_float(kodd ? (R.q[i] & 0xffff0000u) : (R.q[i] << 16));
;         const float l2 = __uint_as_float(kodd ? (R.f[i] & 0xffff0000u) : (R.f[i] << 16));
;         kk[i] = 1.f - __builtin_amdgcn_exp2f(l2);
;         run += l2; c[i] = run;
;     }
;     const float p1 = __shfl(run, (lane - 16) & 63), p2 = __shfl(run, (lane - 32) & 63), p3 = __shfl(run, (lane - 48) & 63);
;     const float off = (tq >= 1 ? p1 : 0.f) + (tq >= 2 ? p2 : 0.f) + (tq >= 3 ? p3 : 0.f);
;     const float btot = __shfl(off + run, 48 + (lane & 15));
;     unsigned short kf[4];
; #pragma unroll
;     for (int i = 0; i < 4; ++i) {
;         const float bt = off + c[i];
;         const float qf = qv[i] * __builtin_amdgcn_exp2f(bt), kfv = kk[i] * __builtin_amdgcn_exp2f(-bt);
;         const unsigned pk = cvtpk(qf, kfv);
;         *(LAS unsigned short*)(buf + OFF_QF + (4 * tq + i) * STR + kch * 2) = (unsigned short)(pk & 0xffffu);
;         kf[i] = (unsigned short)(pk >> 16);
;         *(LAS unsigned short*)(buf + OFF_KF + (4 * tq + i) * STR + kch * 2) = kf[i];
;     }
;     *(LAS u32x2*)(buf + OFF_KFT + kch * 32 + tq * 8) = (u32x2){(unsigned)kf[0] | ((unsigned)kf[1] << 16), (unsigned)kf[2] | ((unsigned)kf[3] << 16)};
;     if (tq == 0) *(LAS float*)(buf + OFF_D + kch * 4) = __builtin_amdgcn_exp2f(btot);
;     if (isv) { unsigned v0 = vodd ? R.v[0] >> 16 : R.v[0] & 0xffffu, v1 = vodd ? R.v[1] >> 16 : R.v[1] & 0xffffu, v2 = vodd ? R.v[2] >> 16 : R.v[2] & 0xffffu, v3 = vodd ? R.v[3] >> 16 : R.v[3] & 0xffffu;
;         *(LAS u32x2*)(buf + OFF_VT + vv * 32 + vtq * 8) = (u32x2){v0 | (v1 << 16), v2 | (v3 << 16)}; }
; }
; template <bool DRY> __device__ __forceinline__ void hgrn_unit(LAS unsigned char* lds, int b, int h, int vs, int layer, bf16_t* Pm, const float* lbraw) {
;     ...
;     prep(ra, lds, lane, kch, tq, isv, vv, vtq);
;     load_raw(ra, qsrc, fsrc, vsrc, 1, isv); load_raw(rb, qsrc, fsrc, vsrc, 2, isv);
;     f32x16 sacc = {};
.Lhg_pro_nov:
	s_add_i32 m0, s64, 0
	s_nop 0
	global_load_lds_dwordx4 v138, s[42:43]
	s_add_u32 s42, s42, 0x1d400
	s_addc_u32 s43, s43, 0
	s_add_i32 m0, s64, 9792
	s_nop 0
	global_load_lds_dwordx4 v138, s[42:43]
	s_add_u32 s42, s42, 0x1d400
	s_addc_u32 s43, s43, 0
	s_add_i32 m0, s64, 19584
	s_nop 0
	global_load_lds_dwordx4 v138, s[42:43]
	s_add_u32 s42, s42, 0x1d400
	s_addc_u32 s43, s43, 0
	s_add_i32 m0, s64, 29376
	s_nop 0
	global_load_lds_dwordx4 v138, s[42:43]
	s_waitcnt vmcnt(2)
.Lhg_pro_done:
	s_barrier
	ds_read_b32 v6, v136
	ds_read_b32 v15, v136 offset:256
	ds_read_b32 v25, v136 offset:512
	ds_read_b32 v26, v136 offset:768
	ds_read_b32 v22, v136 offset:4352
	ds_read_b32 v16, v136 offset:4608
	ds_read_b32 v21, v136 offset:4864
	ds_read_b32 v29, v136 offset:5120
	ds_read_b32 v13, v137
	ds_read_b32 v14, v137 offset:64
	ds_read_b32 v17, v137 offset:128
	ds_read_b32 v18, v137 offset:192
	s_waitcnt lgkmcnt(0)
	s_nop 0
	v_and_b32_e32 v20, 0xffff0000, v6
	v_lshlrev_b32_e32 v6, 16, v6
	v_cndmask_b32_e64 v20, v20, v6, s[44:45]
	v_and_b32_e32 v6, 0xffff0000, v22
	v_lshlrev_b32_e32 v19, 16, v22
	v_cndmask_b32_e64 v6, v6, v19, s[44:45]
	v_exp_f32_e32 v19, v6
	v_add_f32_e32 v6, 0, v6
	v_sub_f32_e32 v23, 1.0, v19
	v_and_b32_e32 v19, 0xffff0000, v16
	v_lshlrev_b32_e32 v16, 16, v16
	v_cndmask_b32_e64 v16, v19, v16, s[44:45]
	v_exp_f32_e32 v19, v16
	v_and_b32_e32 v22, 0xffff0000, v15
	v_lshlrev_b32_e32 v15, 16, v15
	v_cndmask_b32_e64 v24, v22, v15, s[44:45]
	v_sub_f32_e32 v27, 1.0, v19
	v_add_f32_e32 v15, v6, v16
	v_and_b32_e32 v16, 0xffff0000, v21
	v_lshlrev_b32_e32 v19, 16, v21
	v_cndmask_b32_e64 v16, v16, v19, s[44:45]
	v_exp_f32_e32 v19, v16
	v_and_b32_e32 v21, 0xffff0000, v25
	v_lshlrev_b32_e32 v22, 16, v25
	v_cndmask_b32_e64 v28, v21, v22, s[44:45]
	v_sub_f32_e32 v31, 1.0, v19
	v_add_f32_e32 v19, v15, v16
	v_and_b32_e32 v16, 0xffff0000, v29
	v_lshlrev_b32_e32 v21, 16, v29
	v_cndmask_b32_e64 v16, v16, v21, s[44:45]
	v_exp_f32_e32 v21, v16
	v_and_b32_e32 v22, 0xffff0000, v26
	v_lshlrev_b32_e32 v25, 16, v26
	v_cndmask_b32_e64 v38, v22, v25, s[44:45]
	v_sub_f32_e32 v41, 1.0, v21
	v_add_u32_e32 v21, 48, v3
	v_or_b32_e32 v22, v239, v11
	v_and_or_b32 v21, v21, 63, v239
	v_lshlrev_b32_e32 v25, 2, v22
	v_add_u32_e32 v26, 16, v3
	v_add_f32_e32 v16, v19, v16
	v_lshlrev_b32_e32 v32, 2, v21
	v_xor_b32_e32 v33, 0x80, v25
	v_and_or_b32 v26, v26, 63, v239
	ds_bpermute_b32 v21, v32, v16
	ds_bpermute_b32 v22, v33, v16
	v_lshlrev_b32_e32 v34, 2, v26
	ds_bpermute_b32 v26, v34, v16
	v_or_b32_e32 v35, 0xc0, v25
	s_waitcnt lgkmcnt(2)
	v_cndmask_b32_e64 v21, v21, 0, s[46:47]
	s_waitcnt lgkmcnt(1)
	v_cndmask_b32_e64 v22, 0, v22, s[48:49]
	v_add_f32_e32 v21, v21, v22
	s_waitcnt lgkmcnt(0)
	v_cndmask_b32_e64 v22, 0, v26, s[50:51]
	v_add_f32_e32 v29, v21, v22
	v_add_f32_e32 v6, v6, v29
	v_exp_f32_e32 v22, v6
	v_exp_f32_e64 v21, -v6
	v_add_f32_e32 v15, v15, v29
	v_exp_f32_e32 v26, v15
	v_exp_f32_e64 v25, -v15
	v_add_f32_e32 v37, v16, v29
	v_add_f32_e32 v19, v19, v29
	v_pk_mul_f32 v[20:21], v[22:23], v[20:21]
	v_exp_f32_e32 v30, v19
	v_exp_f32_e64 v29, -v19
	v_exp_f32_e32 v40, v37
	v_exp_f32_e64 v39, -v37
	v_cvt_pk_bf16_f32 v6, v20, v21
	v_lshrrev_b32_e32 v15, 16, v6
	v_pk_mul_f32 v[20:21], v[26:27], v[24:25]
	ds_write_b16 v42, v15 offset:4352
	v_cvt_pk_bf16_f32 v15, v20, v21
	v_lshrrev_b32_e32 v19, 16, v15
	v_pk_mul_f32 v[20:21], v[30:31], v[28:29]
	v_pk_mul_f32 v[22:23], v[40:41], v[38:39]
	ds_bpermute_b32 v16, v35, v37
	ds_write_b16 v42, v6
	ds_write_b16 v42, v19 offset:4624
	v_cvt_pk_bf16_f32 v19, v20, v21
	v_perm_b32 v20, v15, v6, s17
	v_cvt_pk_bf16_f32 v6, v22, v23
	ds_write_b16 v42, v15 offset:272
	v_lshrrev_b32_e32 v15, 16, v6
	v_lshrrev_b32_e32 v21, 16, v19
	ds_write_b16 v42, v15 offset:5168
	v_mul_lo_u32 v15, v10, 30
	ds_write_b16 v42, v21 offset:4896
	ds_write_b16 v42, v6 offset:816
	v_perm_b32 v21, v6, v19, s17
	v_add_u32_e32 v6, v36, v15
	v_lshlrev_b32_e32 v37, 3, v9
	v_add_u32_e32 v38, v6, v37
	ds_write_b16 v42, v19 offset:544
	ds_write_b64 v38, v[20:21] offset:8704
	s_and_saveexec_b64 s[10:11], s[46:47]
	s_cbranch_execz .LBB0_617
	s_waitcnt lgkmcnt(8)
	v_exp_f32_e32 v16, v16
	s_movk_i32 s7, 0xffe4
	v_mad_u64_u32 v[20:21], s[12:13], v10, s7, v[6:7]
	ds_write_b32 v20, v16 offset:13824

; #define LAS __attribute__((address_space(3)))
; #define LDS_BARRIER() do { asm volatile("s_waitcnt lgkmcnt(0)" ::: "memory"); __builtin_amdgcn_s_barrier(); asm volatile("" ::: "memory"); } while (0)
; template <bool DRY> __device__ __forceinline__ void hgrn_unit(LAS unsigned char* lds, int b, int h, int vs, int layer, bf16_t* Pm, const float* lbraw) {
;     ...
;     f32x16 sacc = {};
;     const int c16 = lane & 15, kq = lane >> 4, r32 = lane & 31, hh = lane >> 5;
;     __syncthreads();
;     ...
;         {
;             const int row = tid >> 2, chk = tid & 3;
;             const u32x4 ov = *(const LAS u32x4*)(lds + OFF_O + row * 64 + chk * 16);
;             if (!DRY || ov.x == 0x12345678u) *(u32x4*)(Pm + (tok0 + (size_t)g8 * 16 + row) * PW + PC_HI + h * 128 + vs * 32 + chk * 8) = ov;
;             __builtin_amdgcn_s_waitcnt(0x0F70);
;             LDS_BARRIER();
;         }
.LBB0_621:
	s_or_b64 exec, exec, s[10:11]
	s_mov_b64 s[10:11], 0xd00
	v_lshl_add_u64 v[20:21], v[0:1], 0, s[10:11]
	s_mov_b64 s[10:11], 0x1100
	v_lshl_add_u64 v[22:23], v[0:1], 0, s[10:11]
	v_add_co_u32_e32 v0, vcc, 0x1d000, v20
	s_mov_b64 s[10:11], 0x1500
	s_nop 0
	v_addc_co_u32_e32 v1, vcc, 0, v21, vcc
	v_lshl_add_u64 v[24:25], v[4:5], 0, s[10:11]
	v_add_co_u32_e32 v4, vcc, 0x1d000, v22
	s_mov_b32 s7, 0x20000
	s_nop 0
	v_addc_co_u32_e32 v5, vcc, 0, v23, vcc
	v_add_co_u32_e32 v12, vcc, 0x1d000, v24
	s_cmp_gt_i32 s28, 3
	s_nop 0
	v_addc_co_u32_e32 v13, vcc, 0, v25, vcc
	v_add_co_u32_e32 v26, vcc, 0x1f000, v20
	s_movk_i32 s9, 0x110
	s_nop 0
	v_addc_co_u32_e32 v27, vcc, 0, v21, vcc
	v_add_co_u32_e32 v28, vcc, 0x1f000, v22
	v_and_b32_e32 v48, 48, v3
	s_nop 0
	v_addc_co_u32_e32 v29, vcc, 0, v23, vcc
	v_add_co_u32_e32 v30, vcc, 0x1f000, v24
	s_mov_b32 s23, 0
	s_nop 0
	v_addc_co_u32_e32 v31, vcc, 0, v25, vcc
	v_add_co_u32_e32 v42, vcc, s7, v20
	v_cmp_gt_u32_e64 s[54:55], v8, v7
	s_nop 0
	v_addc_co_u32_e32 v43, vcc, 0, v21, vcc
	v_add_co_u32_e32 v44, vcc, s7, v22
	v_cmp_lt_u32_e64 s[56:57], v8, v7
	s_nop 0
	v_addc_co_u32_e32 v45, vcc, 0, v23, vcc
	v_add_co_u32_e32 v0, vcc, s7, v24
	s_mov_b32 s7, 0x22000
	s_nop 0
	v_addc_co_u32_e32 v1, vcc, 0, v25, vcc
	v_add_co_u32_e32 v4, vcc, s7, v20
	s_nop 1
	v_addc_co_u32_e32 v5, vcc, 0, v21, vcc
	v_add_co_u32_e32 v12, vcc, s7, v22
	s_nop 1
	v_addc_co_u32_e32 v13, vcc, 0, v23, vcc
	v_add_co_u32_e32 v26, vcc, s7, v24
	s_mov_b32 s7, 0x3a000
	s_nop 0
	v_addc_co_u32_e32 v27, vcc, 0, v25, vcc
	v_add_co_u32_e32 v28, vcc, s7, v20
	s_nop 1
	v_addc_co_u32_e32 v29, vcc, 0, v21, vcc
	v_add_co_u32_e32 v30, vcc, s7, v22
	s_nop 1
	v_addc_co_u32_e32 v31, vcc, 0, v23, vcc
	v_add_co_u32_e32 v42, vcc, s7, v24
	s_mov_b32 s7, 0x3c000
	s_nop 0
	v_addc_co_u32_e32 v43, vcc, 0, v25, vcc
	v_add_co_u32_e32 v44, vcc, s7, v20
	s_nop 1
	v_addc_co_u32_e32 v45, vcc, 0, v21, vcc
	s_nop 0
	s_nop 0
	v_add_co_u32_e32 v0, vcc, s7, v22
	v_mul_u32_u24_e32 v43, 0x440, v9
	s_nop 0
	v_addc_co_u32_e32 v1, vcc, 0, v23, vcc
	v_add_co_u32_e32 v4, vcc, s7, v24
	s_mov_b32 s7, 0x3e000
	s_nop 0
	v_addc_co_u32_e32 v5, vcc, 0, v25, vcc
	v_add_co_u32_e32 v12, vcc, s7, v20
	s_nop 1
	v_addc_co_u32_e32 v13, vcc, 0, v21, vcc
	v_add_co_u32_e32 v26, vcc, s7, v22
	s_nop 1
	v_addc_co_u32_e32 v27, vcc, 0, v23, vcc
	v_add_co_u32_e32 v28, vcc, s7, v24
	s_mov_b32 s7, 0x3f000
	s_nop 0
	v_addc_co_u32_e32 v29, vcc, 0, v25, vcc
	v_add_co_u32_e32 v30, vcc, s7, v20
	s_nop 1
	v_addc_co_u32_e32 v31, vcc, 0, v21, vcc
	v_add_co_u32_e32 v44, vcc, s7, v22
	s_nop 1
	v_addc_co_u32_e32 v45, vcc, 0, v23, vcc
	v_add_co_u32_e32 v46, vcc, s7, v24
	s_movk_i32 s7, 0xffe2
	s_nop 0
	v_addc_co_u32_e32 v47, vcc, 0, v25, vcc
	v_mad_u64_u32 v[26:27], s[10:11], v10, s7, v[6:7]
	s_movk_i32 s7, 0xffe4
	s_cselect_b64 s[10:11], -1, 0
	s_cmp_lt_u32 s28, 6
	v_mul_lo_u32 v45, v10, s7
	s_cselect_b64 s[12:13], -1, 0
	s_sub_i32 s7, s34, 64
	v_or_b32_e32 v1, s7, v7
	v_lshrrev_b32_e32 v0, 5, v11
	v_lshlrev_b32_e32 v49, 5, v1
	v_mul_lo_u32 v1, v1, s9
	s_lshl_b32 s7, s28, 5
	v_add_u32_e32 v50, 0, v1
	v_or_b32_e32 v1, s7, v16
	v_lshlrev_b32_e32 v51, 4, v0
	v_lshl_or_b32 v4, v0, 2, s7
	v_ashrrev_i32_e32 v0, 2, v3
	v_lshl_add_u32 v5, v1, 5, 0
	v_ashrrev_i32_e32 v1, 31, v0
	v_and_b32_e32 v3, 3, v3
	v_lshl_add_u64 v[28:29], s[14:15], 0, v[0:1]
	v_or_b32_e32 v1, 2, v8
	v_lshl_add_u32 v10, v0, 6, 0
	v_lshlrev_b32_e32 v11, 4, v3
	v_lshlrev_b32_e32 v0, 3, v3
	v_cmp_gt_u32_e64 s[58:59], v1, v7
	v_or_b32_e32 v1, 3, v8
	v_lshl_add_u32 v3, v7, 6, s7
	v_mad_u32_u24 v6, v16, s9, 0
	v_lshlrev_b32_e32 v9, 1, v4
	v_cmp_gt_u32_e64 s[60:61], v1, v7
	v_lshlrev_b32_e32 v1, 2, v4
	v_or_b32_e32 v3, v3, v37
	v_readlane_b32 s7, v252, 6
	v_mov_b32_e32 v4, 0
	v_add_u32_e32 v44, 0, v37
	v_add_u32_e32 v27, v26, v15
	v_add_u32_e32 v46, 0, v19
	v_mad_u32_u24 v47, v7, s9, 0
	v_add_u32_e32 v57, s7, v3
	v_add_u32_e32 v58, v10, v11
	v_lshlrev_b32_e32 v30, 1, v0
	v_add_u32_e32 v59, v5, v51
	v_add_u32_e32 v60, 0, v1
	v_add_u32_e32 v61, v6, v9
	v_mov_b32_e32 v5, v4
	v_mov_b32_e32 v6, v4
	v_mov_b32_e32 v7, v4
	v_mov_b32_e32 v8, v4
	v_mov_b32_e32 v9, v4
	v_mov_b32_e32 v10, v4
	v_mov_b32_e32 v11, v4
	v_mov_b32_e32 v12, v4
	v_mov_b32_e32 v13, v4
	v_mov_b32_e32 v14, v4
	v_mov_b32_e32 v15, v4
	v_mov_b32_e32 v16, v4
	v_mov_b32_e32 v17, v4
	v_mov_b32_e32 v18, v4
	v_mov_b32_e32 v19, v4
	s_waitcnt lgkmcnt(0)
	s_barrier
	s_branch .LBB0_623
.LBB0_622:
	s_lshl_b32 s28, s23, 4
	v_lshl_add_u64 v[0:1], v[28:29], 0, s[28:29]
	v_mov_b64_e32 v[82:83], s[4:5]
	v_mad_u64_u32 v[82:83], s[14:15], v0, s24, v[82:83]
	v_mad_i32_i24 v83, v1, s24, v83
	s_mov_b32 s7, s29
	ds_read_b128 v[78:81], v58 offset:46080
	v_lshl_add_u64 v[0:1], v[82:83], 0, s[6:7]
	s_mov_b32 s9, s29
	v_lshl_add_u64 v[0:1], v[0:1], 0, s[8:9]
	v_mov_b32_e32 v31, v2
	v_lshl_add_u64 v[0:1], v[0:1], 0, v[30:31]
	v_add_co_u32_e32 v0, vcc, 0x1000, v0
	s_cmpk_gt_u32 s23, 0x77
	s_nop 0
	v_addc_co_u32_e32 v1, vcc, 0, v1, vcc
	s_waitcnt lgkmcnt(0)
	global_store_dwordx4 v[0:1], v[78:81], off offset:1280
	s_waitcnt lgkmcnt(0)
	s_barrier
	s_mov_b32 s23, s34
	s_cbranch_scc1 .LBB0_611

; #define LAS __attribute__((address_space(3)))
; __device__ __forceinline__ unsigned cvtpk(float lo, float hi) { f32x2_t v = {lo, hi}; bf16x2_t b = __builtin_convertvector(v, bf16x2_t); return __builtin_bit_cast(unsigned, b); }
; __device__ __forceinline__ void prep(const Raw& Rin, LAS unsigned char* buf, int lane, int kch, int tq, bool isv, int vv, int vtq) {
;     Raw R = Rin; const bool kodd = kch & 1, vodd = vv & 1;
; #pragma unroll
;     for (int i = 0; i < 4; ++i) { asm volatile("" : "+v"(R.q[i])); asm volatile("" : "+v"(R.f[i])); asm volatile("" : "+v"(R.v[i])); }
;     float qv[4], kk[4], c[4]; float run = 0.f;
; #pragma unroll
;     for (int i = 0; i < 4; ++i) {
;         qv[i] = __uint_as_float(kodd ? (R.q[i] & 0xffff0000u) : (R.q[i] << 16));
;         const float l2 = __uint_as_float(kodd ? (R.f[i] & 0xffff0000u) : (R.f[i] << 16));
;         kk[i] = 1.f - __builtin_amdgcn_exp2f(l2);
;         run += l2; c[i] = run;
;     }
;     const float p1 = __shfl(run, (lane - 16) & 63), p2 = __shfl(run, (lane - 32) & 63), p3 = __shfl(run, (lane - 48) & 63);
;     const float off = (tq >= 1 ? p1 : 0.f) + (tq >= 2 ? p2 : 0.f) + (tq >= 3 ? p3 : 0.f);
;     const float btot = __shfl(off + run, 48 + (lane & 15));
;     unsigned short kf[4];
; #pragma unroll
;     for (int i = 0; i < 4; ++i) {
;         const float bt = off + c[i];
;         const float qf = qv[i] * __builtin_amdgcn_exp2f(bt), kfv = kk[i] * __builtin_amdgcn_exp2f(-bt);
;         const unsigned pk = cvtpk(qf, kfv);
;         *(LAS unsigned short*)(buf + OFF_QF + (4 * tq + i) * STR + kch * 2) = (unsigned short)(pk & 0xffffu);
;         kf[i] = (unsigned short)(pk >> 16);
;         *(LAS unsigned short*)(buf + OFF_KF + (4 * tq + i) * STR + kch * 2) = kf[i];
;     }
;     *(LAS u32x2*)(buf + OFF_KFT + kch * 32 + tq * 8) = (u32x2){(unsigned)kf[0] | ((unsigned)kf[1] << 16), (unsigned)kf[2] | ((unsigned)kf[3] << 16)};
;     if (tq == 0) *(LAS float*)(buf + OFF_D + kch * 4) = __builtin_amdgcn_exp2f(btot);
.LBB0_624:
	s_waitcnt lgkmcnt(0)
	s_cmp_eq_u32 s65, 7
	s_cbranch_scc1 .Lhg_w7_b
	s_waitcnt vmcnt(2)
	s_branch .Lhg_wd_b
.Lhg_w7_b:
	s_waitcnt vmcnt(4)
.Lhg_wd_b:
	s_barrier
	s_add_i32 s7, s7, 2
	s_cmp_ge_u32 s7, s34
	v_add_u32_e32 v31, 0x800, v31
	s_cbranch_scc1 .LBB0_622
.LBB0_625:
	s_add_i32 s41, s7, 4
	s_min_u32 s41, s41, 0x7f
	s_mul_i32 s41, s41, 0x1d400
	s_add_u32 s42, s38, s41
	s_addc_u32 s43, s39, 0
	s_add_i32 s41, s7, 0
	s_and_b32 s41, s41, 3
	s_mul_i32 s41, s41, 9792
	s_add_i32 m0, s41, s64
	s_nop 0
	global_load_lds_dwordx4 v138, s[42:43]
	s_cmp_lg_u32 s65, 7
	s_cbranch_scc1 .Lhg_nov_a
	s_add_i32 m0, s41, 0xf600
	s_nop 0
	global_load_lds_dwordx4 v139, s[42:43]
.Lhg_nov_a:
	s_add_i32 s41, s7, 1
	s_and_b32 s41, s41, 3
	s_mul_i32 s41, s41, 9792
	v_add_u32_e32 v140, s41, v136
	v_add_u32_e32 v141, s41, v137
	ds_read_b32 v52, v140
	ds_read_b32 v56, v140 offset:256
	ds_read_b32 v63, v140 offset:512
	ds_read_b32 v71, v140 offset:768
	ds_read_b32 v54, v140 offset:4352
	ds_read_b32 v62, v140 offset:4608
	ds_read_b32 v69, v140 offset:4864
	ds_read_b32 v73, v140 offset:5120
	ds_read_b32 v40, v141
	ds_read_b32 v41, v141 offset:64
	ds_read_b32 v53, v141 offset:128
	ds_read_b32 v64, v141 offset:192
	s_waitcnt lgkmcnt(0)
	v_and_b32_e32 v3, 0xffff0000, v52
	v_and_b32_e32 v0, 0xffff0000, v54
	v_lshlrev_b32_e32 v1, 16, v54
	v_cndmask_b32_e64 v0, v0, v1, s[44:45]
	v_exp_f32_e32 v1, v0
	v_lshlrev_b32_e32 v52, 16, v52
	v_cndmask_b32_e64 v78, v3, v52, s[44:45]
	v_lshlrev_b32_e32 v3, 16, v62
	v_sub_f32_e32 v81, 1.0, v1
	v_and_b32_e32 v1, 0xffff0000, v62
	v_cndmask_b32_e64 v1, v1, v3, s[44:45]
	v_exp_f32_e32 v3, v1
	v_and_b32_e32 v52, 0xffff0000, v56
	v_lshlrev_b32_e32 v54, 16, v56
	v_cndmask_b32_e64 v62, v52, v54, s[44:45]
	v_sub_f32_e32 v83, 1.0, v3
	v_and_b32_e32 v3, 0xffff0000, v69
	v_lshlrev_b32_e32 v52, 16, v69
	v_cndmask_b32_e64 v3, v3, v52, s[44:45]
	v_add_f32_e32 v0, 0, v0
	v_exp_f32_e32 v52, v3
	v_and_b32_e32 v54, 0xffff0000, v63
	v_lshlrev_b32_e32 v56, 16, v63
	v_add_f32_e32 v1, v0, v1
	v_cndmask_b32_e64 v84, v54, v56, s[44:45]
	v_and_b32_e32 v56, 0xffff0000, v73
	v_lshlrev_b32_e32 v63, 16, v73
	v_add_f32_e32 v3, v1, v3
	v_cndmask_b32_e64 v56, v56, v63, s[44:45]
	v_add_f32_e32 v63, v3, v56
	v_sub_f32_e32 v87, 1.0, v52
	v_and_b32_e32 v52, 0xffff0000, v71
	v_lshlrev_b32_e32 v54, 16, v71
	ds_bpermute_b32 v69, v32, v63
	ds_bpermute_b32 v71, v33, v63
	v_cndmask_b32_e64 v88, v52, v54, s[44:45]
	ds_bpermute_b32 v52, v34, v63
	v_exp_f32_e32 v54, v56
	s_waitcnt lgkmcnt(2)
	v_cndmask_b32_e64 v56, v69, 0, s[46:47]
	s_waitcnt lgkmcnt(1)
	v_cndmask_b32_e64 v69, 0, v71, s[48:49]
	v_add_f32_e32 v56, v56, v69
	s_waitcnt lgkmcnt(0)
	v_cndmask_b32_e64 v52, 0, v52, s[50:51]
	v_add_f32_e32 v52, v56, v52
	v_add_f32_e32 v0, v0, v52
	v_exp_f32_e32 v80, v0
	v_exp_f32_e64 v79, -v0
	v_add_f32_e32 v1, v1, v52
	v_sub_f32_e32 v91, 1.0, v54
	v_add_f32_e32 v54, v63, v52
	v_exp_f32_e32 v82, v1
	v_exp_f32_e64 v63, -v1
	v_add_f32_e32 v3, v3, v52
	v_pk_mul_f32 v[78:79], v[80:81], v[78:79]
	v_exp_f32_e32 v86, v3
	v_exp_f32_e64 v85, -v3
	v_cvt_pk_bf16_f32 v56, v78, v79
	v_exp_f32_e32 v90, v54
	v_exp_f32_e64 v89, -v54
	v_add_u32_e32 v69, v26, v43
	v_lshrrev_b32_e32 v1, 16, v56
	v_pk_mul_f32 v[62:63], v[82:83], v[62:63]
	ds_bpermute_b32 v0, v35, v54
	ds_write_b16 v69, v1 offset:18688
	v_cvt_pk_bf16_f32 v1, v62, v63
	v_lshrrev_b32_e32 v3, 16, v1
	v_pk_mul_f32 v[62:63], v[86:87], v[84:85]
	ds_write_b16 v69, v3 offset:18960
	v_cvt_pk_bf16_f32 v3, v62, v63
	v_pk_mul_f32 v[78:79], v[90:91], v[88:89]
	ds_write_b16 v69, v1 offset:14608
	v_lshrrev_b32_e32 v52, 16, v3
	v_perm_b32 v62, v1, v56, s17
	v_cvt_pk_bf16_f32 v1, v78, v79
	ds_write_b16 v69, v52 offset:19232
	ds_write_b16 v69, v1 offset:15152
	v_lshrrev_b32_e32 v52, 16, v1
	v_perm_b32 v63, v1, v3, s17
	v_add_u32_e32 v1, v27, v37
	ds_write_b16 v69, v56 offset:14336
	ds_write_b16 v69, v3 offset:14880
	ds_write_b16 v69, v52 offset:19504
	ds_write_b64 v1, v[62:63] offset:23040
	s_and_saveexec_b64 s[14:15], s[46:47]
	s_cbranch_execz .LBB0_627
	s_waitcnt lgkmcnt(9)
	v_exp_f32_e32 v0, v0
	v_add_u32_e32 v1, v27, v45
	ds_write_b32 v1, v0 offset:28160

.LBB0_629:
	s_or_b64 exec, exec, s[14:15]
	s_waitcnt lgkmcnt(9)
	s_mov_b64 s[14:15], -1
	v_cndmask_b32_e64 v0, 0, 1, s[12:13]
	s_and_b64 vcc, exec, s[10:11]
	v_cmp_ne_u32_e64 s[62:63], 1, v0
	s_cbranch_vccz .LBB0_633
	s_and_b64 vcc, exec, s[62:63]
	s_cbranch_vccnz .LBB0_632
	s_waitcnt lgkmcnt(2)
	v_add_u32_e32 v0, v47, v48
	v_add_u32_e32 v104, v44, v49
	v_add_u32_e32 v105, v50, v48
	ds_read_b128 v[78:81], v0
	ds_read_b128 v[82:85], v0 offset:4352
	ds_read_b128 v[86:89], v0 offset:64
	ds_read_b128 v[90:93], v0 offset:4416
	ds_read_b128 v[106:109], v0 offset:128
	ds_read_b128 v[94:97], v0 offset:4480
	ds_read_b128 v[110:113], v0 offset:192
	ds_read_b128 v[98:101], v0 offset:4544
	ds_read_b64 v[132:133], v104 offset:12800
	ds_read_b128 v[116:119], v105 offset:37376
	ds_read_b128 v[120:123], v105 offset:37440
	ds_read_b128 v[124:127], v105 offset:37504
	ds_read_b128 v[128:131], v105 offset:37568
	v_mov_b32_e32 v134, v2
	v_mov_b32_e32 v135, v2
	s_waitcnt lgkmcnt(11)
	v_mfma_f32_16x16x32_bf16 v[82:85], v[82:85], v[78:81], 0
	s_waitcnt lgkmcnt(9)
	v_mfma_f32_16x16x32_bf16 v[82:85], v[90:93], v[86:89], v[82:85]
	s_waitcnt lgkmcnt(7)
	v_mfma_f32_16x16x32_bf16 v[82:85], v[94:97], v[106:109], v[82:85]
	s_waitcnt lgkmcnt(5)
	v_mfma_f32_16x16x32_bf16 v[82:85], v[98:101], v[110:113], v[82:85]
	s_nop 7
	v_cndmask_b32_e64 v0, v82, 0, s[54:55]
	v_cndmask_b32_e64 v1, 0, v83, s[56:57]
	v_cndmask_b32_e64 v3, v84, 0, s[58:59]
	v_cndmask_b32_e64 v82, v85, 0, s[60:61]
	v_cvt_pk_bf16_f32 v0, v0, v1
	v_cvt_pk_bf16_f32 v1, v3, v82
	v_mov_b32_e32 v3, v2
	s_waitcnt lgkmcnt(4)
	s_nop 1
	v_mfma_f32_16x16x32_bf16 v[82:85], v[132:135], v[0:3], 0
	s_waitcnt lgkmcnt(3)
	v_mfma_f32_16x16x32_bf16 v[78:81], v[116:119], v[78:81], v[82:85]
	s_waitcnt lgkmcnt(2)
	v_mfma_f32_16x16x32_bf16 v[78:81], v[120:123], v[86:89], v[78:81]
	s_waitcnt lgkmcnt(1)
	v_mfma_f32_16x16x32_bf16 v[78:81], v[124:127], v[106:109], v[78:81]
	s_waitcnt lgkmcnt(0)
	v_mfma_f32_16x16x32_bf16 v[78:81], v[128:131], v[110:113], v[78:81]
	s_nop 7
	v_cvt_pk_bf16_f32 v0, v78, v79
	v_cvt_pk_bf16_f32 v1, v80, v81
	ds_write_b64 v31, v[0:1]

.LBB0_633:
	s_andn2_b64 vcc, exec, s[14:15]
	v_add_u32_e32 v78, v46, v51
	s_cbranch_vccnz .LBB0_635
	s_waitcnt lgkmcnt(2)
	ds_read_b128 v[80:83], v59 offset:8704
	ds_read_b128 v[84:87], v78 offset:12800
	ds_read_b128 v[104:107], v60 offset:13824
	ds_read_b128 v[108:111], v60 offset:13856
	ds_read_b128 v[112:115], v60 offset:13888
	ds_read_b128 v[116:119], v60 offset:13920
	s_waitcnt lgkmcnt(4)
	v_mfma_f32_32x32x16_bf16 v[4:19], v[80:83], v[84:87], v[4:19]
	s_waitcnt lgkmcnt(0)
	s_nop 10
	v_pk_mul_f32 v[4:5], v[4:5], v[104:105]
	v_pk_mul_f32 v[6:7], v[6:7], v[106:107]
	v_pk_mul_f32 v[8:9], v[8:9], v[108:109]
	v_pk_mul_f32 v[10:11], v[10:11], v[110:111]
	v_pk_mul_f32 v[12:13], v[12:13], v[112:113]
	v_pk_mul_f32 v[14:15], v[14:15], v[114:115]
	v_pk_mul_f32 v[16:17], v[16:17], v[116:117]
	v_pk_mul_f32 v[18:19], v[18:19], v[118:119]
	v_cvt_pk_bf16_f32 v0, v4, v5
	v_cvt_pk_bf16_f32 v1, v6, v7
	v_cvt_pk_bf16_f32 v80, v8, v9
	v_cvt_pk_bf16_f32 v81, v10, v11
	v_cvt_pk_bf16_f32 v82, v12, v13
	v_cvt_pk_bf16_f32 v83, v14, v15
	v_cvt_pk_bf16_f32 v84, v16, v17
	v_cvt_pk_bf16_f32 v85, v18, v19
	ds_write_b64 v61, v[0:1] offset:28672
	ds_write_b64 v61, v[80:81] offset:28688
	ds_write_b64 v61, v[82:83] offset:28704
	ds_write_b64 v61, v[84:85] offset:28720

; #define LAS __attribute__((address_space(3)))
; __device__ __forceinline__ unsigned cvtpk(float lo, float hi) { f32x2_t v = {lo, hi}; bf16x2_t b = __builtin_convertvector(v, bf16x2_t); return __builtin_bit_cast(unsigned, b); }
; __device__ __forceinline__ void prep(const Raw& Rin, LAS unsigned char* buf, int lane, int kch, int tq, bool isv, int vv, int vtq) {
;     Raw R = Rin; const bool kodd = kch & 1, vodd = vv & 1;
; #pragma unroll
;     for (int i = 0; i < 4; ++i) { asm volatile("" : "+v"(R.q[i])); asm volatile("" : "+v"(R.f[i])); asm volatile("" : "+v"(R.v[i])); }
;     float qv[4], kk[4], c[4]; float run = 0.f;
; #pragma unroll
;     for (int i = 0; i < 4; ++i) {
;         qv[i] = __uint_as_float(kodd ? (R.q[i] & 0xffff0000u) : (R.q[i] << 16));
;         const float l2 = __uint_as_float(kodd ? (R.f[i] & 0xffff0000u) : (R.f[i] << 16));
;         kk[i] = 1.f - __builtin_amdgcn_exp2f(l2);
;         run += l2; c[i] = run;
;     }
;     const float p1 = __shfl(run, (lane - 16) & 63), p2 = __shfl(run, (lane - 32) & 63), p3 = __shfl(run, (lane - 48) & 63);
;     const float off = (tq >= 1 ? p1 : 0.f) + (tq >= 2 ? p2 : 0.f) + (tq >= 3 ? p3 : 0.f);
;     const float btot = __shfl(off + run, 48 + (lane & 15));
;     unsigned short kf[4];
; #pragma unroll
;     for (int i = 0; i < 4; ++i) {
;         const float bt = off + c[i];
;         const float qf = qv[i] * __builtin_amdgcn_exp2f(bt), kfv = kk[i] * __builtin_amdgcn_exp2f(-bt);
;         const unsigned pk = cvtpk(qf, kfv);
;         *(LAS unsigned short*)(buf + OFF_QF + (4 * tq + i) * STR + kch * 2) = (unsigned short)(pk & 0xffffu);
;         kf[i] = (unsigned short)(pk >> 16);
;         *(LAS unsigned short*)(buf + OFF_KF + (4 * tq + i) * STR + kch * 2) = kf[i];
;     }
;     *(LAS u32x2*)(buf + OFF_KFT + kch * 32 + tq * 8) = (u32x2){(unsigned)kf[0] | ((unsigned)kf[1] << 16), (unsigned)kf[2] | ((unsigned)kf[3] << 16)};
;     if (tq == 0) *(LAS float*)(buf + OFF_D + kch * 4) = __builtin_amdgcn_exp2f(btot);
.Lhg_wd_a:
	s_barrier
	s_cmpk_gt_u32 s7, 0x7d
	s_cbranch_scc1 .LBB0_642
	s_add_i32 s41, s7, 5
	s_min_u32 s41, s41, 0x7f
	s_mul_i32 s41, s41, 0x1d400
	s_add_u32 s42, s38, s41
	s_addc_u32 s43, s39, 0
	s_add_i32 s41, s7, 1
	s_and_b32 s41, s41, 3
	s_mul_i32 s41, s41, 9792
	s_add_i32 m0, s41, s64
	s_nop 0
	global_load_lds_dwordx4 v138, s[42:43]
	s_cmp_lg_u32 s65, 7
	s_cbranch_scc1 .Lhg_nov_b
	s_add_i32 m0, s41, 0xf600
	s_nop 0
	global_load_lds_dwordx4 v139, s[42:43]
.Lhg_nov_b:
	s_add_i32 s41, s7, 2
	s_and_b32 s41, s41, 3
	s_mul_i32 s41, s41, 9792
	v_add_u32_e32 v140, s41, v136
	v_add_u32_e32 v141, s41, v137
	ds_read_b32 v66, v140
	ds_read_b32 v68, v140 offset:256
	ds_read_b32 v74, v140 offset:512
	ds_read_b32 v76, v140 offset:768
	ds_read_b32 v67, v140 offset:4352
	ds_read_b32 v72, v140 offset:4608
	ds_read_b32 v75, v140 offset:4864
	ds_read_b32 v77, v140 offset:5120
	ds_read_b32 v42, v141
	ds_read_b32 v55, v141 offset:64
	ds_read_b32 v65, v141 offset:128
	ds_read_b32 v70, v141 offset:192
	s_waitcnt lgkmcnt(0)
	v_and_b32_e32 v3, 0xffff0000, v66
	v_and_b32_e32 v0, 0xffff0000, v67
	v_lshlrev_b32_e32 v1, 16, v67
	v_cndmask_b32_e64 v0, v0, v1, s[44:45]
	v_exp_f32_e32 v1, v0
	v_lshlrev_b32_e32 v66, 16, v66
	v_cndmask_b32_e64 v66, v3, v66, s[44:45]
	v_lshlrev_b32_e32 v3, 16, v72
	v_sub_f32_e32 v81, 1.0, v1
	v_and_b32_e32 v1, 0xffff0000, v72
	v_cndmask_b32_e64 v1, v1, v3, s[44:45]
	v_exp_f32_e32 v3, v1
	v_and_b32_e32 v67, 0xffff0000, v68
	v_lshlrev_b32_e32 v68, 16, v68
	v_cndmask_b32_e64 v82, v67, v68, s[44:45]
	v_sub_f32_e32 v85, 1.0, v3
	v_and_b32_e32 v3, 0xffff0000, v75
	v_lshlrev_b32_e32 v67, 16, v75
	v_cndmask_b32_e64 v3, v3, v67, s[44:45]
	v_add_f32_e32 v0, 0, v0
	v_exp_f32_e32 v67, v3
	v_and_b32_e32 v68, 0xffff0000, v74
	v_lshlrev_b32_e32 v72, 16, v74
	v_add_f32_e32 v1, v0, v1
	v_cndmask_b32_e64 v74, v68, v72, s[44:45]
	v_and_b32_e32 v72, 0xffff0000, v77
	v_lshlrev_b32_e32 v75, 16, v77
	v_add_f32_e32 v3, v1, v3
	v_cndmask_b32_e64 v72, v72, v75, s[44:45]
	v_add_f32_e32 v75, v3, v72
	v_sub_f32_e32 v87, 1.0, v67
	v_and_b32_e32 v67, 0xffff0000, v76
	v_lshlrev_b32_e32 v68, 16, v76
	ds_bpermute_b32 v77, v32, v75
	ds_bpermute_b32 v79, v33, v75
	v_cndmask_b32_e64 v76, v67, v68, s[44:45]
	ds_bpermute_b32 v67, v34, v75
	v_exp_f32_e32 v68, v72
	s_waitcnt lgkmcnt(2)
	v_cndmask_b32_e64 v72, v77, 0, s[46:47]
	s_waitcnt lgkmcnt(1)
	v_cndmask_b32_e64 v77, 0, v79, s[48:49]
	v_add_f32_e32 v72, v72, v77
	s_waitcnt lgkmcnt(0)
	v_cndmask_b32_e64 v67, 0, v67, s[50:51]
	v_add_f32_e32 v72, v72, v67
	v_add_f32_e32 v0, v0, v72
	v_exp_f32_e32 v80, v0
	v_exp_f32_e64 v67, -v0
	v_add_f32_e32 v1, v1, v72
	v_exp_f32_e32 v84, v1
	v_exp_f32_e64 v83, -v1
	v_sub_f32_e32 v89, 1.0, v68
	v_add_f32_e32 v68, v75, v72
	v_add_f32_e32 v3, v3, v72
	v_pk_mul_f32 v[66:67], v[80:81], v[66:67]
	v_exp_f32_e32 v86, v3
	v_exp_f32_e64 v75, -v3
	v_exp_f32_e32 v88, v68
	v_exp_f32_e64 v77, -v68
	v_cvt_pk_bf16_f32 v79, v66, v67
	ds_bpermute_b32 v0, v35, v68
	v_add_u32_e32 v80, v36, v43
	v_lshrrev_b32_e32 v1, 16, v79
	v_pk_mul_f32 v[66:67], v[84:85], v[82:83]
	ds_write_b16 v80, v1 offset:4352
	v_cvt_pk_bf16_f32 v1, v66, v67
	v_lshrrev_b32_e32 v3, 16, v1
	v_pk_mul_f32 v[66:67], v[86:87], v[74:75]
	v_pk_mul_f32 v[74:75], v[88:89], v[76:77]
	ds_write_b16 v80, v1 offset:272
	ds_write_b16 v80, v3 offset:4624
	v_cvt_pk_bf16_f32 v3, v66, v67
	v_perm_b32 v66, v1, v79, s17
	v_cvt_pk_bf16_f32 v1, v74, v75
	v_lshrrev_b32_e32 v67, 16, v3
	v_lshrrev_b32_e32 v68, 16, v1
	ds_write_b16 v80, v79
	ds_write_b16 v80, v3 offset:544
	ds_write_b16 v80, v67 offset:4896
	ds_write_b16 v80, v1 offset:816
	v_perm_b32 v67, v1, v3, s17
	ds_write_b16 v80, v68 offset:5168
	ds_write_b64 v38, v[66:67] offset:8704
	s_and_saveexec_b64 s[14:15], s[46:47]
	s_cbranch_execz .LBB0_638
	s_waitcnt lgkmcnt(9)
	v_exp_f32_e32 v0, v0
	v_add_u32_e32 v1, v27, v45
	ds_write_b32 v1, v0 offset:13824

.LBB0_640:
	s_or_b64 exec, exec, s[14:15]
	s_waitcnt lgkmcnt(9)
	s_mov_b64 s[14:15], -1
	s_and_b64 vcc, exec, s[10:11]
	s_cbranch_vccnz .LBB0_643

.LBB0_643:
	s_and_b64 vcc, exec, s[62:63]
	s_cbranch_vccnz .LBB0_645
	s_waitcnt lgkmcnt(2)
	v_add_u32_e32 v0, v47, v48
	v_add_u32_e32 v104, v44, v49
	v_add_u32_e32 v105, v50, v48
	ds_read_b128 v[78:81], v0 offset:14336
	ds_read_b128 v[82:85], v0 offset:18688
	ds_read_b128 v[86:89], v0 offset:14400
	ds_read_b128 v[90:93], v0 offset:18752
	ds_read_b128 v[106:109], v0 offset:14464
	ds_read_b128 v[94:97], v0 offset:18816
	ds_read_b128 v[110:113], v0 offset:14528
	ds_read_b128 v[98:101], v0 offset:18880
	ds_read_b64 v[132:133], v104 offset:27136
	ds_read_b128 v[116:119], v105 offset:28672
	ds_read_b128 v[120:123], v105 offset:28736
	ds_read_b128 v[124:127], v105 offset:28800
	ds_read_b128 v[128:131], v105 offset:28864
	v_mov_b32_e32 v134, v2
	v_mov_b32_e32 v135, v2
	s_waitcnt lgkmcnt(11)
	v_mfma_f32_16x16x32_bf16 v[82:85], v[82:85], v[78:81], 0
	s_waitcnt lgkmcnt(9)
	v_mfma_f32_16x16x32_bf16 v[82:85], v[90:93], v[86:89], v[82:85]
	s_waitcnt lgkmcnt(7)
	v_mfma_f32_16x16x32_bf16 v[82:85], v[94:97], v[106:109], v[82:85]
	s_waitcnt lgkmcnt(5)
	v_mfma_f32_16x16x32_bf16 v[82:85], v[98:101], v[110:113], v[82:85]
	s_nop 7
	v_cndmask_b32_e64 v0, v82, 0, s[54:55]
	v_cndmask_b32_e64 v1, 0, v83, s[56:57]
	v_cndmask_b32_e64 v3, v84, 0, s[58:59]
	v_cndmask_b32_e64 v82, v85, 0, s[60:61]
	v_cvt_pk_bf16_f32 v0, v0, v1
	v_cvt_pk_bf16_f32 v1, v3, v82
	v_mov_b32_e32 v3, v2
	s_waitcnt lgkmcnt(4)
	s_nop 1
	v_mfma_f32_16x16x32_bf16 v[82:85], v[132:135], v[0:3], 0
	s_waitcnt lgkmcnt(3)
	v_mfma_f32_16x16x32_bf16 v[78:81], v[116:119], v[78:81], v[82:85]
	s_waitcnt lgkmcnt(2)
	v_mfma_f32_16x16x32_bf16 v[78:81], v[120:123], v[86:89], v[78:81]
	s_waitcnt lgkmcnt(1)
	v_mfma_f32_16x16x32_bf16 v[78:81], v[124:127], v[106:109], v[78:81]
	s_waitcnt lgkmcnt(0)
	v_mfma_f32_16x16x32_bf16 v[78:81], v[128:131], v[110:113], v[78:81]
	s_nop 7
	v_cvt_pk_bf16_f32 v0, v78, v79
	v_cvt_pk_bf16_f32 v1, v80, v81
	ds_write_b64 v31, v[0:1] offset:1024

.LBB0_646:
	s_waitcnt lgkmcnt(2)
	ds_read_b128 v[80:83], v59 offset:23040
	ds_read_b128 v[84:87], v78 offset:27136
	ds_read_b128 v[104:107], v60 offset:28160
	ds_read_b128 v[108:111], v60 offset:28192
	ds_read_b128 v[112:115], v60 offset:28224
	ds_read_b128 v[116:119], v60 offset:28256
	s_waitcnt lgkmcnt(4)
	v_mfma_f32_32x32x16_bf16 v[4:19], v[80:83], v[84:87], v[4:19]
	s_waitcnt lgkmcnt(0)
	s_nop 10
	v_pk_mul_f32 v[4:5], v[4:5], v[104:105]
	v_pk_mul_f32 v[6:7], v[6:7], v[106:107]
	v_pk_mul_f32 v[8:9], v[8:9], v[108:109]
	v_pk_mul_f32 v[10:11], v[10:11], v[110:111]
	v_pk_mul_f32 v[12:13], v[12:13], v[112:113]
	v_pk_mul_f32 v[14:15], v[14:15], v[114:115]
	v_pk_mul_f32 v[16:17], v[16:17], v[116:117]
	v_pk_mul_f32 v[18:19], v[18:19], v[118:119]
	v_cvt_pk_bf16_f32 v0, v4, v5
	v_cvt_pk_bf16_f32 v1, v6, v7
	v_cvt_pk_bf16_f32 v80, v8, v9
	v_cvt_pk_bf16_f32 v81, v10, v11
	v_cvt_pk_bf16_f32 v82, v12, v13
	v_cvt_pk_bf16_f32 v83, v14, v15
	v_cvt_pk_bf16_f32 v84, v16, v17
	v_cvt_pk_bf16_f32 v85, v18, v19
	ds_write_b64 v61, v[0:1] offset:37376
	ds_write_b64 v61, v[80:81] offset:37392
	ds_write_b64 v61, v[82:83] offset:37408
	ds_write_b64 v61, v[84:85] offset:37424
	s_branch .LBB0_624

; __device__ __forceinline__ float rstd_of(float ss, float invn) { return __builtin_amdgcn_rsqf(ss * invn + EPS); }
; __device__ __forceinline__ u32x4 pack8(f32x4 a, f32x4 b) { u32x4 w; w.x = cvtpk(a[0], a[1]); w.y = cvtpk(a[2], a[3]); w.z = cvtpk(b[0], b[1]); w.w = cvtpk(b[2], b[3]); return w; }
;     __device__ __forceinline__ void operator()(const Acc& acc, const Unit& u, int wr, int wc, int fr, int fq) const {
;         float tpre[2][4];
; #pragma unroll
;         for (int ai = 0; ai < 2; ++ai)
; #pragma unroll
;             for (int m = 0; m < 4; ++m) tpre[ai][m] = rs_q[u.pm * BM + ai * HALF + wr * 64 + m * 16 + fr];
;         asm volatile("" ::: "memory");
; #pragma unroll
;         for (int ai = 0; ai < 2; ++ai)
; #pragma unroll
;             for (int m = 0; m < 4; ++m) {
;                 const int r = u.pm * BM + ai * HALF + wr * 64 + m * 16 + fr; const float t = rstd_of(tpre[ai][m], 1.f / 384.f);
; #pragma unroll
;                 for (int bj = 0; bj < 2; ++bj) {
;                     const int c0 = u.pn * BM + wc * 64 + bj * 32 + 8 * fq;
;                     f32x4 v0 = acc[ai][bj][m][0] * t, v1 = acc[ai][bj][m][1] * t;
;                     if (u.pn == 2) rope8(v0, v1, rope + (size_t)r * 16, rope + (size_t)T * 16 + (size_t)r * 16, fq);
;                     *(u32x4*)(Q + (size_t)r * 768 + c0) = pack8(v0, v1);
;                 }
;             }
.LBB0_663:
	v_lshl_add_u32 v160, s47, 8, v3
	v_ashrrev_i32_e32 v161, 31, v160
	v_or_b32_e32 v158, 16, v160
	v_lshl_add_u64 v[146:147], v[160:161], 2, s[10:11]
	v_ashrrev_i32_e32 v159, 31, v158
	v_or_b32_e32 v156, 32, v160
	global_load_dword v164, v[146:147], off
	v_lshl_add_u64 v[146:147], v[158:159], 2, s[10:11]
	v_ashrrev_i32_e32 v157, 31, v156
	v_or_b32_e32 v154, 48, v160
	global_load_dword v179, v[146:147], off
	v_lshl_add_u64 v[146:147], v[156:157], 2, s[10:11]
	v_ashrrev_i32_e32 v155, 31, v154
	v_add_u32_e32 v152, 0x80, v160
	global_load_dword v178, v[146:147], off
	v_lshl_add_u64 v[146:147], v[154:155], 2, s[10:11]
	v_ashrrev_i32_e32 v153, 31, v152
	v_add_u32_e32 v150, 0x90, v160
	global_load_dword v177, v[146:147], off
	v_lshl_add_u64 v[146:147], v[152:153], 2, s[10:11]
	v_ashrrev_i32_e32 v151, 31, v150
	v_add_u32_e32 v148, 0xa0, v160
	global_load_dword v176, v[146:147], off
	v_lshl_add_u64 v[146:147], v[150:151], 2, s[10:11]
	v_ashrrev_i32_e32 v149, 31, v148
	global_load_dword v175, v[146:147], off
	v_lshl_add_u64 v[146:147], v[148:149], 2, s[10:11]
	global_load_dword v174, v[146:147], off
	v_add_u32_e32 v146, 0xb0, v160
	v_ashrrev_i32_e32 v147, 31, v146
	v_lshl_add_u64 v[162:163], v[146:147], 2, s[10:11]
	global_load_dword v173, v[162:163], off
	v_lshlrev_b64 v[166:167], 4, v[160:161]
	s_cmp_eq_u32 s46, 2
	s_cselect_b64 s[22:23], -1, 0
	s_cmp_lg_u32 s46, 2
	s_waitcnt vmcnt(0)
	v_fmamk_f32 v162, v164, 0x3b2aaaab, v236
	v_rsq_f32_e32 v162, v162
	s_nop 0
	v_pk_mul_f32 v[164:165], v[124:125], v[162:163] op_sel_hi:[1,0]
	v_lshlrev_b64 v[124:125], 2, v[166:167]
	v_pk_mul_f32 v[130:131], v[130:131], v[162:163] op_sel_hi:[1,0]
	v_pk_mul_f32 v[128:129], v[128:129], v[162:163] op_sel_hi:[1,0]
	v_pk_mul_f32 v[126:127], v[126:127], v[162:163] op_sel_hi:[1,0]
	v_lshl_add_u64 v[166:167], v[138:139], 0, v[124:125]
	v_lshl_add_u64 v[168:169], v[140:141], 0, v[124:125]
	s_cbranch_scc1 .LBB0_665
	global_load_dwordx4 v[180:183], v[168:169], off
	global_load_dwordx4 v[184:187], v[166:167], off
	s_waitcnt vmcnt(1)
	v_pk_mul_f32 v[124:125], v[126:127], v[182:183]
	v_pk_mul_f32 v[188:189], v[164:165], v[180:181]
	v_pk_mul_f32 v[182:183], v[130:131], v[182:183]
	v_pk_mul_f32 v[180:181], v[128:129], v[180:181]
	s_waitcnt vmcnt(0)
	v_pk_fma_f32 v[130:131], v[130:131], v[186:187], v[124:125] neg_lo:[0,0,1] neg_hi:[0,0,1]
	v_pk_fma_f32 v[128:129], v[128:129], v[184:185], v[188:189] neg_lo:[0,0,1] neg_hi:[0,0,1]
	v_pk_fma_f32 v[126:127], v[126:127], v[186:187], v[182:183]
	v_pk_fma_f32 v[164:165], v[164:165], v[184:185], v[180:181]

; __device__ __forceinline__ float rstd_of(float ss, float invn) { return __builtin_amdgcn_rsqf(ss * invn + EPS); }
; __device__ __forceinline__ u32x4 pack8(f32x4 a, f32x4 b) { u32x4 w; w.x = cvtpk(a[0], a[1]); w.y = cvtpk(a[2], a[3]); w.z = cvtpk(b[0], b[1]); w.w = cvtpk(b[2], b[3]); return w; }
;     __device__ __forceinline__ void operator()(const Acc& acc, const Unit& u, int wr, int wc, int fr, int fq) const {
;         float tpre[2][4];
; #pragma unroll
;         for (int ai = 0; ai < 2; ++ai)
; #pragma unroll
;             for (int m = 0; m < 4; ++m) tpre[ai][m] = rs_q[u.pm * BM + ai * HALF + wr * 64 + m * 16 + fr];
;         asm volatile("" ::: "memory");
; #pragma unroll
;         for (int ai = 0; ai < 2; ++ai)
; #pragma unroll
;             for (int m = 0; m < 4; ++m) {
;                 const int r = u.pm * BM + ai * HALF + wr * 64 + m * 16 + fr; const float t = rstd_of(tpre[ai][m], 1.f / 384.f);
; #pragma unroll
;                 for (int bj = 0; bj < 2; ++bj) {
;                     const int c0 = u.pn * BM + wc * 64 + bj * 32 + 8 * fq;
;                     f32x4 v0 = acc[ai][bj][m][0] * t, v1 = acc[ai][bj][m][1] * t;
;                     if (u.pn == 2) rope8(v0, v1, rope + (size_t)r * 16, rope + (size_t)T * 16 + (size_t)r * 16, fq);
;                     *(u32x4*)(Q + (size_t)r * 768 + c0) = pack8(v0, v1);
;                 }
;             }
.LBB0_667:
	v_cvt_pk_bf16_f32 v120, v120, v121
	v_cvt_pk_bf16_f32 v121, v122, v123
	v_cvt_pk_bf16_f32 v122, v116, v117
	v_fmamk_f32 v116, v179, 0x3b2aaaab, v236
	v_rsq_f32_e32 v116, v116
	v_cvt_pk_bf16_f32 v123, v118, v119
	global_store_dwordx4 v[126:127], v[120:123], off offset:64
	s_and_b64 vcc, exec, s[46:47]
	v_pk_mul_f32 v[118:119], v[110:111], v[116:117] op_sel_hi:[1,0]
	v_lshlrev_b64 v[122:123], 4, v[158:159]
	v_lshlrev_b64 v[110:111], 2, v[122:123]
	v_pk_mul_f32 v[114:115], v[114:115], v[116:117] op_sel_hi:[1,0]
	v_pk_mul_f32 v[112:113], v[112:113], v[116:117] op_sel_hi:[1,0]
	v_pk_mul_f32 v[120:121], v[108:109], v[116:117] op_sel_hi:[1,0]
	v_lshl_add_u64 v[108:109], v[138:139], 0, v[110:111]
	v_lshl_add_u64 v[110:111], v[140:141], 0, v[110:111]
	s_cbranch_vccnz .LBB0_669
	global_load_dwordx4 v[126:129], v[110:111], off
	global_load_dwordx4 v[160:163], v[108:109], off
	s_waitcnt vmcnt(1)
	v_pk_mul_f32 v[122:123], v[118:119], v[128:129]
	v_pk_mul_f32 v[130:131], v[120:121], v[126:127]
	v_pk_mul_f32 v[128:129], v[114:115], v[128:129]
	v_pk_mul_f32 v[126:127], v[112:113], v[126:127]
	s_waitcnt vmcnt(0)
	v_pk_fma_f32 v[114:115], v[114:115], v[162:163], v[122:123] neg_lo:[0,0,1] neg_hi:[0,0,1]
	v_pk_fma_f32 v[112:113], v[112:113], v[160:161], v[130:131] neg_lo:[0,0,1] neg_hi:[0,0,1]
	v_pk_fma_f32 v[118:119], v[118:119], v[162:163], v[128:129]
	v_pk_fma_f32 v[120:121], v[120:121], v[160:161], v[126:127]

; __device__ __forceinline__ float rstd_of(float ss, float invn) { return __builtin_amdgcn_rsqf(ss * invn + EPS); }
; __device__ __forceinline__ u32x4 pack8(f32x4 a, f32x4 b) { u32x4 w; w.x = cvtpk(a[0], a[1]); w.y = cvtpk(a[2], a[3]); w.z = cvtpk(b[0], b[1]); w.w = cvtpk(b[2], b[3]); return w; }
;     __device__ __forceinline__ void operator()(const Acc& acc, const Unit& u, int wr, int wc, int fr, int fq) const {
;         float tpre[2][4];
; #pragma unroll
;         for (int ai = 0; ai < 2; ++ai)
; #pragma unroll
;             for (int m = 0; m < 4; ++m) tpre[ai][m] = rs_q[u.pm * BM + ai * HALF + wr * 64 + m * 16 + fr];
;         asm volatile("" ::: "memory");
; #pragma unroll
;         for (int ai = 0; ai < 2; ++ai)
; #pragma unroll
;             for (int m = 0; m < 4; ++m) {
;                 const int r = u.pm * BM + ai * HALF + wr * 64 + m * 16 + fr; const float t = rstd_of(tpre[ai][m], 1.f / 384.f);
; #pragma unroll
;                 for (int bj = 0; bj < 2; ++bj) {
;                     const int c0 = u.pn * BM + wc * 64 + bj * 32 + 8 * fq;
;                     f32x4 v0 = acc[ai][bj][m][0] * t, v1 = acc[ai][bj][m][1] * t;
;                     if (u.pn == 2) rope8(v0, v1, rope + (size_t)r * 16, rope + (size_t)T * 16 + (size_t)r * 16, fq);
;                     *(u32x4*)(Q + (size_t)r * 768 + c0) = pack8(v0, v1);
;                 }
;             }
.LBB0_671:
	v_cvt_pk_bf16_f32 v104, v104, v105
	v_cvt_pk_bf16_f32 v105, v106, v107
	v_cvt_pk_bf16_f32 v106, v100, v101
	v_fmamk_f32 v100, v178, 0x3b2aaaab, v236
	v_rsq_f32_e32 v100, v100
	v_cvt_pk_bf16_f32 v107, v102, v103
	global_store_dwordx4 v[112:113], v[104:107], off offset:64
	s_and_b64 vcc, exec, s[46:47]
	v_pk_mul_f32 v[102:103], v[94:95], v[100:101] op_sel_hi:[1,0]
	v_lshlrev_b64 v[106:107], 4, v[156:157]
	v_lshlrev_b64 v[94:95], 2, v[106:107]
	v_pk_mul_f32 v[98:99], v[98:99], v[100:101] op_sel_hi:[1,0]
	v_pk_mul_f32 v[96:97], v[96:97], v[100:101] op_sel_hi:[1,0]
	v_pk_mul_f32 v[104:105], v[92:93], v[100:101] op_sel_hi:[1,0]
	v_lshl_add_u64 v[92:93], v[138:139], 0, v[94:95]
	v_lshl_add_u64 v[94:95], v[140:141], 0, v[94:95]
	s_cbranch_vccnz .LBB0_673
	global_load_dwordx4 v[106:109], v[94:95], off
	global_load_dwordx4 v[110:113], v[92:93], off
	s_waitcnt vmcnt(1)
	v_pk_mul_f32 v[114:115], v[102:103], v[108:109]
	v_pk_mul_f32 v[116:117], v[104:105], v[106:107]
	v_pk_mul_f32 v[108:109], v[98:99], v[108:109]
	v_pk_mul_f32 v[106:107], v[96:97], v[106:107]
	s_waitcnt vmcnt(0)
	v_pk_fma_f32 v[98:99], v[98:99], v[112:113], v[114:115] neg_lo:[0,0,1] neg_hi:[0,0,1]
	v_pk_fma_f32 v[96:97], v[96:97], v[110:111], v[116:117] neg_lo:[0,0,1] neg_hi:[0,0,1]
	v_pk_fma_f32 v[102:103], v[102:103], v[112:113], v[108:109]
	v_pk_fma_f32 v[104:105], v[104:105], v[110:111], v[106:107]

; __device__ __forceinline__ float rstd_of(float ss, float invn) { return __builtin_amdgcn_rsqf(ss * invn + EPS); }
; __device__ __forceinline__ u32x4 pack8(f32x4 a, f32x4 b) { u32x4 w; w.x = cvtpk(a[0], a[1]); w.y = cvtpk(a[2], a[3]); w.z = cvtpk(b[0], b[1]); w.w = cvtpk(b[2], b[3]); return w; }
;     __device__ __forceinline__ void operator()(const Acc& acc, const Unit& u, int wr, int wc, int fr, int fq) const {
;         float tpre[2][4];
; #pragma unroll
;         for (int ai = 0; ai < 2; ++ai)
; #pragma unroll
;             for (int m = 0; m < 4; ++m) tpre[ai][m] = rs_q[u.pm * BM + ai * HALF + wr * 64 + m * 16 + fr];
;         asm volatile("" ::: "memory");
; #pragma unroll
;         for (int ai = 0; ai < 2; ++ai)
; #pragma unroll
;             for (int m = 0; m < 4; ++m) {
;                 const int r = u.pm * BM + ai * HALF + wr * 64 + m * 16 + fr; const float t = rstd_of(tpre[ai][m], 1.f / 384.f);
; #pragma unroll
;                 for (int bj = 0; bj < 2; ++bj) {
;                     const int c0 = u.pn * BM + wc * 64 + bj * 32 + 8 * fq;
;                     f32x4 v0 = acc[ai][bj][m][0] * t, v1 = acc[ai][bj][m][1] * t;
;                     if (u.pn == 2) rope8(v0, v1, rope + (size_t)r * 16, rope + (size_t)T * 16 + (size_t)r * 16, fq);
;                     *(u32x4*)(Q + (size_t)r * 768 + c0) = pack8(v0, v1);
;                 }
;             }
.LBB0_675:
	v_cvt_pk_bf16_f32 v88, v88, v89
	v_cvt_pk_bf16_f32 v89, v90, v91
	v_cvt_pk_bf16_f32 v90, v84, v85
	v_fmamk_f32 v84, v177, 0x3b2aaaab, v236
	v_rsq_f32_e32 v84, v84
	v_cvt_pk_bf16_f32 v91, v86, v87
	global_store_dwordx4 v[96:97], v[88:91], off offset:64
	s_and_b64 vcc, exec, s[46:47]
	v_pk_mul_f32 v[86:87], v[78:79], v[84:85] op_sel_hi:[1,0]
	v_lshlrev_b64 v[90:91], 4, v[154:155]
	v_lshlrev_b64 v[78:79], 2, v[90:91]
	v_pk_mul_f32 v[82:83], v[82:83], v[84:85] op_sel_hi:[1,0]
	v_pk_mul_f32 v[80:81], v[80:81], v[84:85] op_sel_hi:[1,0]
	v_pk_mul_f32 v[88:89], v[76:77], v[84:85] op_sel_hi:[1,0]
	v_lshl_add_u64 v[76:77], v[138:139], 0, v[78:79]
	v_lshl_add_u64 v[78:79], v[140:141], 0, v[78:79]
	s_cbranch_vccnz .LBB0_677
	global_load_dwordx4 v[90:93], v[78:79], off
	global_load_dwordx4 v[94:97], v[76:77], off
	s_waitcnt vmcnt(1)
	v_pk_mul_f32 v[98:99], v[86:87], v[92:93]
	v_pk_mul_f32 v[100:101], v[88:89], v[90:91]
	v_pk_mul_f32 v[92:93], v[82:83], v[92:93]
	v_pk_mul_f32 v[90:91], v[80:81], v[90:91]
	s_waitcnt vmcnt(0)
	v_pk_fma_f32 v[82:83], v[82:83], v[96:97], v[98:99] neg_lo:[0,0,1] neg_hi:[0,0,1]
	v_pk_fma_f32 v[80:81], v[80:81], v[94:95], v[100:101] neg_lo:[0,0,1] neg_hi:[0,0,1]
	v_pk_fma_f32 v[86:87], v[86:87], v[96:97], v[92:93]
	v_pk_fma_f32 v[88:89], v[88:89], v[94:95], v[90:91]

; __device__ __forceinline__ float rstd_of(float ss, float invn) { return __builtin_amdgcn_rsqf(ss * invn + EPS); }
; __device__ __forceinline__ u32x4 pack8(f32x4 a, f32x4 b) { u32x4 w; w.x = cvtpk(a[0], a[1]); w.y = cvtpk(a[2], a[3]); w.z = cvtpk(b[0], b[1]); w.w = cvtpk(b[2], b[3]); return w; }
;     __device__ __forceinline__ void operator()(const Acc& acc, const Unit& u, int wr, int wc, int fr, int fq) const {
;         float tpre[2][4];
; #pragma unroll
;         for (int ai = 0; ai < 2; ++ai)
; #pragma unroll
;             for (int m = 0; m < 4; ++m) tpre[ai][m] = rs_q[u.pm * BM + ai * HALF + wr * 64 + m * 16 + fr];
;         asm volatile("" ::: "memory");
; #pragma unroll
;         for (int ai = 0; ai < 2; ++ai)
; #pragma unroll
;             for (int m = 0; m < 4; ++m) {
;                 const int r = u.pm * BM + ai * HALF + wr * 64 + m * 16 + fr; const float t = rstd_of(tpre[ai][m], 1.f / 384.f);
; #pragma unroll
;                 for (int bj = 0; bj < 2; ++bj) {
;                     const int c0 = u.pn * BM + wc * 64 + bj * 32 + 8 * fq;
;                     f32x4 v0 = acc[ai][bj][m][0] * t, v1 = acc[ai][bj][m][1] * t;
;                     if (u.pn == 2) rope8(v0, v1, rope + (size_t)r * 16, rope + (size_t)T * 16 + (size_t)r * 16, fq);
;                     *(u32x4*)(Q + (size_t)r * 768 + c0) = pack8(v0, v1);
;                 }
;             }
.LBB0_679:
	v_cvt_pk_bf16_f32 v72, v72, v73
	v_cvt_pk_bf16_f32 v73, v74, v75
	v_cvt_pk_bf16_f32 v74, v68, v69
	v_fmamk_f32 v68, v176, 0x3b2aaaab, v236
	v_rsq_f32_e32 v68, v68
	v_cvt_pk_bf16_f32 v75, v70, v71
	global_store_dwordx4 v[80:81], v[72:75], off offset:64
	s_and_b64 vcc, exec, s[46:47]
	v_pk_mul_f32 v[70:71], v[62:63], v[68:69] op_sel_hi:[1,0]
	v_lshlrev_b64 v[74:75], 4, v[152:153]
	v_lshlrev_b64 v[62:63], 2, v[74:75]
	v_pk_mul_f32 v[66:67], v[66:67], v[68:69] op_sel_hi:[1,0]
	v_pk_mul_f32 v[64:65], v[64:65], v[68:69] op_sel_hi:[1,0]
	v_pk_mul_f32 v[72:73], v[60:61], v[68:69] op_sel_hi:[1,0]
	v_lshl_add_u64 v[60:61], v[138:139], 0, v[62:63]
	v_lshl_add_u64 v[62:63], v[140:141], 0, v[62:63]
	s_cbranch_vccnz .LBB0_681
	global_load_dwordx4 v[74:77], v[62:63], off
	global_load_dwordx4 v[78:81], v[60:61], off
	s_waitcnt vmcnt(1)
	v_pk_mul_f32 v[82:83], v[70:71], v[76:77]
	v_pk_mul_f32 v[84:85], v[72:73], v[74:75]
	v_pk_mul_f32 v[76:77], v[66:67], v[76:77]
	v_pk_mul_f32 v[74:75], v[64:65], v[74:75]
	s_waitcnt vmcnt(0)
	v_pk_fma_f32 v[66:67], v[66:67], v[80:81], v[82:83] neg_lo:[0,0,1] neg_hi:[0,0,1]
	v_pk_fma_f32 v[64:65], v[64:65], v[78:79], v[84:85] neg_lo:[0,0,1] neg_hi:[0,0,1]
	v_pk_fma_f32 v[70:71], v[70:71], v[80:81], v[76:77]
	v_pk_fma_f32 v[72:73], v[72:73], v[78:79], v[74:75]

; __device__ __forceinline__ float rstd_of(float ss, float invn) { return __builtin_amdgcn_rsqf(ss * invn + EPS); }
; __device__ __forceinline__ u32x4 pack8(f32x4 a, f32x4 b) { u32x4 w; w.x = cvtpk(a[0], a[1]); w.y = cvtpk(a[2], a[3]); w.z = cvtpk(b[0], b[1]); w.w = cvtpk(b[2], b[3]); return w; }
;     __device__ __forceinline__ void operator()(const Acc& acc, const Unit& u, int wr, int wc, int fr, int fq) const {
;         float tpre[2][4];
; #pragma unroll
;         for (int ai = 0; ai < 2; ++ai)
; #pragma unroll
;             for (int m = 0; m < 4; ++m) tpre[ai][m] = rs_q[u.pm * BM + ai * HALF + wr * 64 + m * 16 + fr];
;         asm volatile("" ::: "memory");
; #pragma unroll
;         for (int ai = 0; ai < 2; ++ai)
; #pragma unroll
;             for (int m = 0; m < 4; ++m) {
;                 const int r = u.pm * BM + ai * HALF + wr * 64 + m * 16 + fr; const float t = rstd_of(tpre[ai][m], 1.f / 384.f);
; #pragma unroll
;                 for (int bj = 0; bj < 2; ++bj) {
;                     const int c0 = u.pn * BM + wc * 64 + bj * 32 + 8 * fq;
;                     f32x4 v0 = acc[ai][bj][m][0] * t, v1 = acc[ai][bj][m][1] * t;
;                     if (u.pn == 2) rope8(v0, v1, rope + (size_t)r * 16, rope + (size_t)T * 16 + (size_t)r * 16, fq);
;                     *(u32x4*)(Q + (size_t)r * 768 + c0) = pack8(v0, v1);
;                 }
;             }
.LBB0_683:
	v_cvt_pk_bf16_f32 v56, v56, v57
	v_cvt_pk_bf16_f32 v57, v58, v59
	v_cvt_pk_bf16_f32 v58, v52, v53
	v_fmamk_f32 v52, v175, 0x3b2aaaab, v236
	v_rsq_f32_e32 v52, v52
	v_cvt_pk_bf16_f32 v59, v54, v55
	global_store_dwordx4 v[64:65], v[56:59], off offset:64
	s_and_b64 vcc, exec, s[46:47]
	v_pk_mul_f32 v[54:55], v[46:47], v[52:53] op_sel_hi:[1,0]
	v_lshlrev_b64 v[58:59], 4, v[150:151]
	v_lshlrev_b64 v[46:47], 2, v[58:59]
	v_pk_mul_f32 v[50:51], v[50:51], v[52:53] op_sel_hi:[1,0]
	v_pk_mul_f32 v[48:49], v[48:49], v[52:53] op_sel_hi:[1,0]
	v_pk_mul_f32 v[56:57], v[44:45], v[52:53] op_sel_hi:[1,0]
	v_lshl_add_u64 v[44:45], v[138:139], 0, v[46:47]
	v_lshl_add_u64 v[46:47], v[140:141], 0, v[46:47]
	s_cbranch_vccnz .LBB0_685
	global_load_dwordx4 v[58:61], v[46:47], off
	global_load_dwordx4 v[62:65], v[44:45], off
	s_waitcnt vmcnt(1)
	v_pk_mul_f32 v[66:67], v[54:55], v[60:61]
	v_pk_mul_f32 v[68:69], v[56:57], v[58:59]
	v_pk_mul_f32 v[60:61], v[50:51], v[60:61]
	v_pk_mul_f32 v[58:59], v[48:49], v[58:59]
	s_waitcnt vmcnt(0)
	v_pk_fma_f32 v[50:51], v[50:51], v[64:65], v[66:67] neg_lo:[0,0,1] neg_hi:[0,0,1]
	v_pk_fma_f32 v[48:49], v[48:49], v[62:63], v[68:69] neg_lo:[0,0,1] neg_hi:[0,0,1]
	v_pk_fma_f32 v[54:55], v[54:55], v[64:65], v[60:61]
	v_pk_fma_f32 v[56:57], v[56:57], v[62:63], v[58:59]

; __device__ __forceinline__ float rstd_of(float ss, float invn) { return __builtin_amdgcn_rsqf(ss * invn + EPS); }
; __device__ __forceinline__ u32x4 pack8(f32x4 a, f32x4 b) { u32x4 w; w.x = cvtpk(a[0], a[1]); w.y = cvtpk(a[2], a[3]); w.z = cvtpk(b[0], b[1]); w.w = cvtpk(b[2], b[3]); return w; }
;     __device__ __forceinline__ void operator()(const Acc& acc, const Unit& u, int wr, int wc, int fr, int fq) const {
;         float tpre[2][4];
; #pragma unroll
;         for (int ai = 0; ai < 2; ++ai)
; #pragma unroll
;             for (int m = 0; m < 4; ++m) tpre[ai][m] = rs_q[u.pm * BM + ai * HALF + wr * 64 + m * 16 + fr];
;         asm volatile("" ::: "memory");
; #pragma unroll
;         for (int ai = 0; ai < 2; ++ai)
; #pragma unroll
;             for (int m = 0; m < 4; ++m) {
;                 const int r = u.pm * BM + ai * HALF + wr * 64 + m * 16 + fr; const float t = rstd_of(tpre[ai][m], 1.f / 384.f);
; #pragma unroll
;                 for (int bj = 0; bj < 2; ++bj) {
;                     const int c0 = u.pn * BM + wc * 64 + bj * 32 + 8 * fq;
;                     f32x4 v0 = acc[ai][bj][m][0] * t, v1 = acc[ai][bj][m][1] * t;
;                     if (u.pn == 2) rope8(v0, v1, rope + (size_t)r * 16, rope + (size_t)T * 16 + (size_t)r * 16, fq);
;                     *(u32x4*)(Q + (size_t)r * 768 + c0) = pack8(v0, v1);
;                 }
;             }
.LBB0_687:
	v_cvt_pk_bf16_f32 v40, v40, v41
	v_cvt_pk_bf16_f32 v41, v42, v43
	v_cvt_pk_bf16_f32 v42, v36, v37
	v_fmamk_f32 v36, v174, 0x3b2aaaab, v236
	v_rsq_f32_e32 v36, v36
	v_cvt_pk_bf16_f32 v43, v38, v39
	global_store_dwordx4 v[48:49], v[40:43], off offset:64
	s_and_b64 vcc, exec, s[46:47]
	v_pk_mul_f32 v[38:39], v[30:31], v[36:37] op_sel_hi:[1,0]
	v_lshlrev_b64 v[42:43], 4, v[148:149]
	v_lshlrev_b64 v[30:31], 2, v[42:43]
	v_pk_mul_f32 v[34:35], v[34:35], v[36:37] op_sel_hi:[1,0]
	v_pk_mul_f32 v[32:33], v[32:33], v[36:37] op_sel_hi:[1,0]
	v_pk_mul_f32 v[40:41], v[28:29], v[36:37] op_sel_hi:[1,0]
	v_lshl_add_u64 v[28:29], v[138:139], 0, v[30:31]
	v_lshl_add_u64 v[30:31], v[140:141], 0, v[30:31]
	s_cbranch_vccnz .LBB0_689
	global_load_dwordx4 v[42:45], v[30:31], off
	global_load_dwordx4 v[46:49], v[28:29], off
	s_waitcnt vmcnt(1)
	v_pk_mul_f32 v[50:51], v[38:39], v[44:45]
	v_pk_mul_f32 v[52:53], v[40:41], v[42:43]
	v_pk_mul_f32 v[44:45], v[34:35], v[44:45]
	v_pk_mul_f32 v[42:43], v[32:33], v[42:43]
	s_waitcnt vmcnt(0)
	v_pk_fma_f32 v[34:35], v[34:35], v[48:49], v[50:51] neg_lo:[0,0,1] neg_hi:[0,0,1]
	v_pk_fma_f32 v[32:33], v[32:33], v[46:47], v[52:53] neg_lo:[0,0,1] neg_hi:[0,0,1]
	v_pk_fma_f32 v[38:39], v[38:39], v[48:49], v[44:45]
	v_pk_fma_f32 v[40:41], v[40:41], v[46:47], v[42:43]

; __device__ __forceinline__ float rstd_of(float ss, float invn) { return __builtin_amdgcn_rsqf(ss * invn + EPS); }
; __device__ __forceinline__ u32x4 pack8(f32x4 a, f32x4 b) { u32x4 w; w.x = cvtpk(a[0], a[1]); w.y = cvtpk(a[2], a[3]); w.z = cvtpk(b[0], b[1]); w.w = cvtpk(b[2], b[3]); return w; }
;     __device__ __forceinline__ void operator()(const Acc& acc, const Unit& u, int wr, int wc, int fr, int fq) const {
;         float tpre[2][4];
; #pragma unroll
;         for (int ai = 0; ai < 2; ++ai)
; #pragma unroll
;             for (int m = 0; m < 4; ++m) tpre[ai][m] = rs_q[u.pm * BM + ai * HALF + wr * 64 + m * 16 + fr];
;         asm volatile("" ::: "memory");
; #pragma unroll
;         for (int ai = 0; ai < 2; ++ai)
; #pragma unroll
;             for (int m = 0; m < 4; ++m) {
;                 const int r = u.pm * BM + ai * HALF + wr * 64 + m * 16 + fr; const float t = rstd_of(tpre[ai][m], 1.f / 384.f);
; #pragma unroll
;                 for (int bj = 0; bj < 2; ++bj) {
;                     const int c0 = u.pn * BM + wc * 64 + bj * 32 + 8 * fq;
;                     f32x4 v0 = acc[ai][bj][m][0] * t, v1 = acc[ai][bj][m][1] * t;
;                     if (u.pn == 2) rope8(v0, v1, rope + (size_t)r * 16, rope + (size_t)T * 16 + (size_t)r * 16, fq);
;                     *(u32x4*)(Q + (size_t)r * 768 + c0) = pack8(v0, v1);
;                 }
;             }
.LBB0_691:
	v_cvt_pk_bf16_f32 v24, v24, v25
	v_cvt_pk_bf16_f32 v25, v26, v27
	v_cvt_pk_bf16_f32 v26, v20, v21
	v_fmamk_f32 v20, v173, 0x3b2aaaab, v236
	v_rsq_f32_e32 v20, v20
	v_cvt_pk_bf16_f32 v27, v22, v23
	global_store_dwordx4 v[32:33], v[24:27], off offset:64
	s_and_b64 vcc, exec, s[46:47]
	v_pk_mul_f32 v[22:23], v[14:15], v[20:21] op_sel_hi:[1,0]
	v_lshlrev_b64 v[26:27], 4, v[146:147]
	v_lshlrev_b64 v[14:15], 2, v[26:27]
	v_pk_mul_f32 v[18:19], v[18:19], v[20:21] op_sel_hi:[1,0]
	v_pk_mul_f32 v[16:17], v[16:17], v[20:21] op_sel_hi:[1,0]
	v_pk_mul_f32 v[24:25], v[12:13], v[20:21] op_sel_hi:[1,0]
	v_lshl_add_u64 v[12:13], v[138:139], 0, v[14:15]
	v_lshl_add_u64 v[14:15], v[140:141], 0, v[14:15]
	s_cbranch_vccnz .LBB0_693
	global_load_dwordx4 v[26:29], v[14:15], off
	global_load_dwordx4 v[30:33], v[12:13], off
	s_waitcnt vmcnt(1)
	v_pk_mul_f32 v[34:35], v[22:23], v[28:29]
	v_pk_mul_f32 v[36:37], v[24:25], v[26:27]
	v_pk_mul_f32 v[28:29], v[18:19], v[28:29]
	v_pk_mul_f32 v[26:27], v[16:17], v[26:27]
	s_waitcnt vmcnt(0)
	v_pk_fma_f32 v[18:19], v[18:19], v[32:33], v[34:35] neg_lo:[0,0,1] neg_hi:[0,0,1]
	v_pk_fma_f32 v[16:17], v[16:17], v[30:31], v[36:37] neg_lo:[0,0,1] neg_hi:[0,0,1]
	v_pk_fma_f32 v[22:23], v[22:23], v[32:33], v[28:29]
	v_pk_fma_f32 v[24:25], v[24:25], v[30:31], v[26:27]

; __device__ __forceinline__ float rstd_of(float ss, float invn) { return __builtin_amdgcn_rsqf(ss * invn + EPS); }
; __device__ __forceinline__ u32x4 pack8(f32x4 a, f32x4 b) { u32x4 w; w.x = cvtpk(a[0], a[1]); w.y = cvtpk(a[2], a[3]); w.z = cvtpk(b[0], b[1]); w.w = cvtpk(b[2], b[3]); return w; }
;     __device__ __forceinline__ void operator()(const Acc& acc, const Unit& u, int wr, int wc, int fr, int fq) const {
;         float tpre[2][4];
; #pragma unroll
;         for (int ai = 0; ai < 2; ++ai)
; #pragma unroll
;             for (int m = 0; m < 4; ++m) tpre[ai][m] = rs ? rs[u.pm * BM + ai * HALF + wr * 64 + m * 16 + fr] : 0.f;
;         asm volatile("" ::: "memory");
; #pragma unroll
;         for (int ai = 0; ai < 2; ++ai)
; #pragma unroll
;             for (int m = 0; m < 4; ++m) {
;                 const int r = u.pm * BM + ai * HALF + wr * 64 + m * 16 + fr; const float t = rs ? rstd_of(tpre[ai][m], invn) : 1.f;
; #pragma unroll
;                 for (int bj = 0; bj < 2; ++bj) {
;                     const int c0 = u.pn * BM + wc * 64 + bj * 32 + 8 * fq;
;                     f32x4 v0 = acc[ai][bj][m][0] * t, v1 = acc[ai][bj][m][1] * t;
;                     if (sig) { const float tl = -t * 1.4426950408889634f; const f32x4 z0 = acc[ai][bj][m][0] * tl, z1 = acc[ai][bj][m][1] * tl;
; #pragma unroll
;                         for (int j = 0; j < 4; ++j) { v0[j] = __builtin_amdgcn_rcpf(1.f + __builtin_amdgcn_exp2f(z0[j])); v1[j] = __builtin_amdgcn_rcpf(1.f + __builtin_amdgcn_exp2f(z1[j])); } }
;                     *(u32x4*)(O + (size_t)r * ldc + c0) = pack8(v0, v1);
;                 }
;             }
;     }
.LBB0_713:
	v_lshl_add_u32 v146, s70, 8, v3
	v_ashrrev_i32_e32 v147, 31, v146
	v_lshl_add_u64 v[156:157], v[146:147], 2, s[10:11]
	global_load_dword v158, v[156:157], off
	global_load_dword v159, v[156:157], off offset:64
	global_load_dword v162, v[156:157], off offset:128
	global_load_dword v155, v[156:157], off offset:192
	global_load_dword v154, v[156:157], off offset:512
	global_load_dword v153, v[156:157], off offset:576
	global_load_dword v152, v[156:157], off offset:640
	global_load_dword v151, v[156:157], off offset:704
	v_lshl_or_b32 v156, s69, 8, v149
	v_add_u32_e32 v144, 0x80, v146
	v_ashrrev_i32_e32 v145, 31, v144
	v_add_u32_e32 v142, 0x90, v146
	v_ashrrev_i32_e32 v143, 31, v142
	v_add_u32_e32 v140, 0xa0, v146
	v_ashrrev_i32_e32 v141, 31, v140
	v_add_u32_e32 v138, 0xb0, v146
	v_ashrrev_i32_e32 v139, 31, v138
	s_mov_b64 s[4:5], -1
	s_and_b64 vcc, exec, s[44:45]
	s_waitcnt vmcnt(0)
	v_fmamk_f32 v157, v158, 0x3b800000, v236
	v_rsq_f32_e32 v158, v157
	v_ashrrev_i32_e32 v157, 31, v156
	v_pk_mul_f32 v[128:129], v[128:129], v[158:159] op_sel_hi:[1,0]
	v_pk_mul_f32 v[124:125], v[124:125], v[158:159] op_sel_hi:[1,0]
	v_pk_mul_f32 v[130:131], v[130:131], v[158:159] op_sel_hi:[1,0]
	v_pk_mul_f32 v[160:161], v[126:127], v[158:159] op_sel_hi:[1,0]
	v_cvt_pk_bf16_f32 v126, v128, v129
	v_cvt_pk_bf16_f32 v128, v124, v125
	v_lshlrev_b64 v[124:125], 10, v[146:147]
	v_cvt_pk_bf16_f32 v127, v130, v131
	v_lshl_add_u64 v[130:131], s[8:9], 0, v[124:125]
	v_lshlrev_b64 v[124:125], 1, v[156:157]
	v_cvt_pk_bf16_f32 v129, v160, v161
	v_lshl_add_u64 v[130:131], v[130:131], 0, v[124:125]
	global_store_dwordx4 v[130:131], v[126:129], off
	v_pk_mul_f32 v[122:123], v[122:123], v[158:159] op_sel_hi:[1,0]
	v_pk_mul_f32 v[120:121], v[120:121], v[158:159] op_sel_hi:[1,0]
	v_pk_mul_f32 v[126:127], v[118:119], v[158:159] op_sel_hi:[1,0]
	v_pk_mul_f32 v[118:119], v[116:117], v[158:159] op_sel_hi:[1,0]
	v_cvt_pk_bf16_f32 v116, v120, v121
	v_cvt_pk_bf16_f32 v117, v122, v123
	v_cvt_pk_bf16_f32 v118, v118, v119
	v_cvt_pk_bf16_f32 v119, v126, v127
	global_store_dwordx4 v[130:131], v[116:119], off offset:64
	s_nop 1
	v_fmamk_f32 v117, v159, 0x3b800000, v236
	v_rsq_f32_e32 v118, v117
	v_or_b32_e32 v116, 16, v146
	v_ashrrev_i32_e32 v117, 31, v116
	v_pk_mul_f32 v[112:113], v[112:113], v[118:119] op_sel_hi:[1,0]
	v_pk_mul_f32 v[120:121], v[110:111], v[118:119] op_sel_hi:[1,0]
	v_pk_mul_f32 v[110:111], v[108:109], v[118:119] op_sel_hi:[1,0]
	v_cvt_pk_bf16_f32 v108, v112, v113
	v_lshlrev_b64 v[112:113], 10, v[116:117]
	v_pk_mul_f32 v[114:115], v[114:115], v[118:119] op_sel_hi:[1,0]
	v_lshl_add_u64 v[112:113], s[8:9], 0, v[112:113]
	v_cvt_pk_bf16_f32 v109, v114, v115
	v_cvt_pk_bf16_f32 v110, v110, v111
	v_cvt_pk_bf16_f32 v111, v120, v121
	v_lshl_add_u64 v[112:113], v[112:113], 0, v[124:125]
	global_store_dwordx4 v[112:113], v[108:111], off
	v_pk_mul_f32 v[106:107], v[106:107], v[118:119] op_sel_hi:[1,0]
	v_pk_mul_f32 v[104:105], v[104:105], v[118:119] op_sel_hi:[1,0]
	v_pk_mul_f32 v[108:109], v[102:103], v[118:119] op_sel_hi:[1,0]
	v_pk_mul_f32 v[102:103], v[100:101], v[118:119] op_sel_hi:[1,0]
	v_cvt_pk_bf16_f32 v100, v104, v105
	v_cvt_pk_bf16_f32 v101, v106, v107
	v_cvt_pk_bf16_f32 v102, v102, v103
	v_cvt_pk_bf16_f32 v103, v108, v109
	global_store_dwordx4 v[112:113], v[100:103], off offset:64
	s_nop 1
	v_fmamk_f32 v101, v162, 0x3b800000, v236
	v_rsq_f32_e32 v102, v101
	v_or_b32_e32 v100, 32, v146
	v_ashrrev_i32_e32 v101, 31, v100
	v_pk_mul_f32 v[96:97], v[96:97], v[102:103] op_sel_hi:[1,0]
	v_pk_mul_f32 v[104:105], v[94:95], v[102:103] op_sel_hi:[1,0]
	v_pk_mul_f32 v[94:95], v[92:93], v[102:103] op_sel_hi:[1,0]
	v_cvt_pk_bf16_f32 v92, v96, v97
	v_lshlrev_b64 v[96:97], 10, v[100:101]
	v_pk_mul_f32 v[98:99], v[98:99], v[102:103] op_sel_hi:[1,0]
	v_lshl_add_u64 v[96:97], s[8:9], 0, v[96:97]
	v_cvt_pk_bf16_f32 v93, v98, v99
	v_cvt_pk_bf16_f32 v94, v94, v95
	v_cvt_pk_bf16_f32 v95, v104, v105
	v_lshl_add_u64 v[96:97], v[96:97], 0, v[124:125]
	global_store_dwordx4 v[96:97], v[92:95], off
	v_pk_mul_f32 v[90:91], v[90:91], v[102:103] op_sel_hi:[1,0]
	v_pk_mul_f32 v[88:89], v[88:89], v[102:103] op_sel_hi:[1,0]
	v_pk_mul_f32 v[92:93], v[86:87], v[102:103] op_sel_hi:[1,0]
	v_pk_mul_f32 v[86:87], v[84:85], v[102:103] op_sel_hi:[1,0]
	v_cvt_pk_bf16_f32 v84, v88, v89
	v_cvt_pk_bf16_f32 v85, v90, v91
	v_cvt_pk_bf16_f32 v86, v86, v87
	v_cvt_pk_bf16_f32 v87, v92, v93
	global_store_dwordx4 v[96:97], v[84:87], off offset:64
	s_nop 1
	v_fmamk_f32 v85, v155, 0x3b800000, v236
	v_rsq_f32_e32 v86, v85
	v_or_b32_e32 v84, 48, v146
	v_ashrrev_i32_e32 v85, 31, v84
	v_pk_mul_f32 v[80:81], v[80:81], v[86:87] op_sel_hi:[1,0]
	v_pk_mul_f32 v[88:89], v[78:79], v[86:87] op_sel_hi:[1,0]
	v_pk_mul_f32 v[78:79], v[76:77], v[86:87] op_sel_hi:[1,0]
	v_cvt_pk_bf16_f32 v76, v80, v81
	v_lshlrev_b64 v[80:81], 10, v[84:85]
	v_pk_mul_f32 v[82:83], v[82:83], v[86:87] op_sel_hi:[1,0]
	v_lshl_add_u64 v[80:81], s[8:9], 0, v[80:81]
; __device__ __forceinline__ float rstd_of(float ss, float invn) { return __builtin_amdgcn_rsqf(ss * invn + EPS); }
; __device__ __forceinline__ u32x4 pack8(f32x4 a, f32x4 b) { u32x4 w; w.x = cvtpk(a[0], a[1]); w.y = cvtpk(a[2], a[3]); w.z = cvtpk(b[0], b[1]); w.w = cvtpk(b[2], b[3]); return w; }
;     __device__ __forceinline__ void operator()(const Acc& acc, const Unit& u, int wr, int wc, int fr, int fq) const {
;         float tpre[2][4];
; #pragma unroll
;         for (int ai = 0; ai < 2; ++ai)
; #pragma unroll
;             for (int m = 0; m < 4; ++m) tpre[ai][m] = rs ? rs[u.pm * BM + ai * HALF + wr * 64 + m * 16 + fr] : 0.f;
;         asm volatile("" ::: "memory");
; #pragma unroll
;         for (int ai = 0; ai < 2; ++ai)
; #pragma unroll
;             for (int m = 0; m < 4; ++m) {
;                 const int r = u.pm * BM + ai * HALF + wr * 64 + m * 16 + fr; const float t = rs ? rstd_of(tpre[ai][m], invn) : 1.f;
; #pragma unroll
;                 for (int bj = 0; bj < 2; ++bj) {
;                     const int c0 = u.pn * BM + wc * 64 + bj * 32 + 8 * fq;
;                     f32x4 v0 = acc[ai][bj][m][0] * t, v1 = acc[ai][bj][m][1] * t;
;                     if (sig) { const float tl = -t * 1.4426950408889634f; const f32x4 z0 = acc[ai][bj][m][0] * tl, z1 = acc[ai][bj][m][1] * tl;
; #pragma unroll
;                         for (int j = 0; j < 4; ++j) { v0[j] = __builtin_amdgcn_rcpf(1.f + __builtin_amdgcn_exp2f(z0[j])); v1[j] = __builtin_amdgcn_rcpf(1.f + __builtin_amdgcn_exp2f(z1[j])); } }
;                     *(u32x4*)(O + (size_t)r * ldc + c0) = pack8(v0, v1);
;                 }
;             }
;     }
	v_cvt_pk_bf16_f32 v77, v82, v83
	v_cvt_pk_bf16_f32 v78, v78, v79
	v_cvt_pk_bf16_f32 v79, v88, v89
	v_lshl_add_u64 v[80:81], v[80:81], 0, v[124:125]
	global_store_dwordx4 v[80:81], v[76:79], off
	v_pk_mul_f32 v[74:75], v[74:75], v[86:87] op_sel_hi:[1,0]
	v_pk_mul_f32 v[72:73], v[72:73], v[86:87] op_sel_hi:[1,0]
	v_pk_mul_f32 v[76:77], v[70:71], v[86:87] op_sel_hi:[1,0]
	v_pk_mul_f32 v[70:71], v[68:69], v[86:87] op_sel_hi:[1,0]
	v_cvt_pk_bf16_f32 v68, v72, v73
	v_cvt_pk_bf16_f32 v69, v74, v75
	v_cvt_pk_bf16_f32 v70, v70, v71
	v_cvt_pk_bf16_f32 v71, v76, v77
	global_store_dwordx4 v[80:81], v[68:71], off offset:64
	s_nop 1
	v_fmamk_f32 v68, v154, 0x3b800000, v236
	v_rsq_f32_e32 v68, v68
	s_nop 0
	v_pk_mul_f32 v[64:65], v[64:65], v[68:69] op_sel_hi:[1,0]
	v_pk_mul_f32 v[70:71], v[62:63], v[68:69] op_sel_hi:[1,0]
	v_pk_mul_f32 v[62:63], v[60:61], v[68:69] op_sel_hi:[1,0]
	v_cvt_pk_bf16_f32 v60, v64, v65
	v_lshlrev_b64 v[64:65], 10, v[144:145]
	v_pk_mul_f32 v[66:67], v[66:67], v[68:69] op_sel_hi:[1,0]
	v_lshl_add_u64 v[64:65], s[8:9], 0, v[64:65]
	v_cvt_pk_bf16_f32 v61, v66, v67
	v_cvt_pk_bf16_f32 v62, v62, v63
	v_cvt_pk_bf16_f32 v63, v70, v71
	v_lshl_add_u64 v[64:65], v[64:65], 0, v[124:125]
	global_store_dwordx4 v[64:65], v[60:63], off
	v_pk_mul_f32 v[58:59], v[58:59], v[68:69] op_sel_hi:[1,0]
	v_pk_mul_f32 v[56:57], v[56:57], v[68:69] op_sel_hi:[1,0]
	v_pk_mul_f32 v[60:61], v[54:55], v[68:69] op_sel_hi:[1,0]
	v_pk_mul_f32 v[54:55], v[52:53], v[68:69] op_sel_hi:[1,0]
	v_cvt_pk_bf16_f32 v52, v56, v57
	v_cvt_pk_bf16_f32 v53, v58, v59
	v_cvt_pk_bf16_f32 v54, v54, v55
	v_cvt_pk_bf16_f32 v55, v60, v61
	global_store_dwordx4 v[64:65], v[52:55], off offset:64
	s_nop 1
	v_fmamk_f32 v52, v153, 0x3b800000, v236
	v_rsq_f32_e32 v52, v52
	s_nop 0
	v_pk_mul_f32 v[48:49], v[48:49], v[52:53] op_sel_hi:[1,0]
	v_pk_mul_f32 v[54:55], v[46:47], v[52:53] op_sel_hi:[1,0]
	v_pk_mul_f32 v[46:47], v[44:45], v[52:53] op_sel_hi:[1,0]
	v_cvt_pk_bf16_f32 v44, v48, v49
	v_lshlrev_b64 v[48:49], 10, v[142:143]
	v_pk_mul_f32 v[50:51], v[50:51], v[52:53] op_sel_hi:[1,0]
	v_lshl_add_u64 v[48:49], s[8:9], 0, v[48:49]
	v_cvt_pk_bf16_f32 v45, v50, v51
	v_cvt_pk_bf16_f32 v46, v46, v47
	v_cvt_pk_bf16_f32 v47, v54, v55
	v_lshl_add_u64 v[48:49], v[48:49], 0, v[124:125]
	global_store_dwordx4 v[48:49], v[44:47], off
	v_pk_mul_f32 v[42:43], v[42:43], v[52:53] op_sel_hi:[1,0]
	v_pk_mul_f32 v[40:41], v[40:41], v[52:53] op_sel_hi:[1,0]
	v_pk_mul_f32 v[44:45], v[38:39], v[52:53] op_sel_hi:[1,0]
	v_pk_mul_f32 v[38:39], v[36:37], v[52:53] op_sel_hi:[1,0]
	v_cvt_pk_bf16_f32 v36, v40, v41
	v_cvt_pk_bf16_f32 v37, v42, v43
	v_cvt_pk_bf16_f32 v38, v38, v39
	v_cvt_pk_bf16_f32 v39, v44, v45
	global_store_dwordx4 v[48:49], v[36:39], off offset:64
	s_nop 1
	v_fmamk_f32 v36, v152, 0x3b800000, v236
	v_rsq_f32_e32 v36, v36
	s_nop 0
	v_pk_mul_f32 v[32:33], v[32:33], v[36:37] op_sel_hi:[1,0]
	v_pk_mul_f32 v[38:39], v[30:31], v[36:37] op_sel_hi:[1,0]
	v_pk_mul_f32 v[30:31], v[28:29], v[36:37] op_sel_hi:[1,0]
	v_cvt_pk_bf16_f32 v28, v32, v33
	v_lshlrev_b64 v[32:33], 10, v[140:141]
	v_pk_mul_f32 v[34:35], v[34:35], v[36:37] op_sel_hi:[1,0]
	v_lshl_add_u64 v[32:33], s[8:9], 0, v[32:33]
	v_cvt_pk_bf16_f32 v29, v34, v35
	v_cvt_pk_bf16_f32 v30, v30, v31
	v_cvt_pk_bf16_f32 v31, v38, v39
	v_lshl_add_u64 v[32:33], v[32:33], 0, v[124:125]
	global_store_dwordx4 v[32:33], v[28:31], off
	v_pk_mul_f32 v[26:27], v[26:27], v[36:37] op_sel_hi:[1,0]
	v_pk_mul_f32 v[24:25], v[24:25], v[36:37] op_sel_hi:[1,0]
	v_pk_mul_f32 v[28:29], v[22:23], v[36:37] op_sel_hi:[1,0]
	v_pk_mul_f32 v[22:23], v[20:21], v[36:37] op_sel_hi:[1,0]
	v_cvt_pk_bf16_f32 v20, v24, v25
	v_cvt_pk_bf16_f32 v21, v26, v27
	v_cvt_pk_bf16_f32 v22, v22, v23
	v_cvt_pk_bf16_f32 v23, v28, v29
	global_store_dwordx4 v[32:33], v[20:23], off offset:64
	s_nop 1
	v_fmamk_f32 v20, v151, 0x3b800000, v236
	v_rsq_f32_e32 v20, v20
	s_nop 0
	v_pk_mul_f32 v[16:17], v[16:17], v[20:21] op_sel_hi:[1,0]
	v_pk_mul_f32 v[22:23], v[14:15], v[20:21] op_sel_hi:[1,0]
	v_pk_mul_f32 v[14:15], v[12:13], v[20:21] op_sel_hi:[1,0]
	v_cvt_pk_bf16_f32 v12, v16, v17
	v_lshlrev_b64 v[16:17], 10, v[138:139]
	v_pk_mul_f32 v[18:19], v[18:19], v[20:21] op_sel_hi:[1,0]
	v_lshl_add_u64 v[16:17], s[8:9], 0, v[16:17]
	v_cvt_pk_bf16_f32 v13, v18, v19
	v_cvt_pk_bf16_f32 v14, v14, v15
	v_cvt_pk_bf16_f32 v15, v22, v23
	v_lshl_add_u64 v[16:17], v[16:17], 0, v[124:125]
	global_store_dwordx4 v[16:17], v[12:15], off
	v_pk_mul_f32 v[10:11], v[10:11], v[20:21] op_sel_hi:[1,0]
	v_pk_mul_f32 v[8:9], v[8:9], v[20:21] op_sel_hi:[1,0]
	v_pk_mul_f32 v[12:13], v[6:7], v[20:21] op_sel_hi:[1,0]
	v_pk_mul_f32 v[6:7], v[4:5], v[20:21] op_sel_hi:[1,0]
	v_cvt_pk_bf16_f32 v4, v8, v9
	v_cvt_pk_bf16_f32 v5, v10, v11
	v_cvt_pk_bf16_f32 v6, v6, v7
	v_cvt_pk_bf16_f32 v7, v12, v13
	global_store_dwordx4 v[16:17], v[4:7], off offset:64
	s_cbranch_vccnz .LBB0_704
	s_andn2_b64 vcc, exec, s[6:7]
	s_cbranch_vccnz .LBB0_703
	s_barrier
	s_branch .LBB0_703

; __device__ __forceinline__ float rstd_of(float ss, float invn) { return __builtin_amdgcn_rsqf(ss * invn + EPS); }
; __device__ __forceinline__ u32x4 pack8(f32x4 a, f32x4 b) { u32x4 w; w.x = cvtpk(a[0], a[1]); w.y = cvtpk(a[2], a[3]); w.z = cvtpk(b[0], b[1]); w.w = cvtpk(b[2], b[3]); return w; }
;     __device__ __forceinline__ void operator()(const Acc& acc, const Unit& u, int wr, int wc, int fr, int fq) const {
; #pragma unroll
;         for (int bj = 0; bj < 2; ++bj) {
;             const int c0 = u.pn * BM + wc * 64 + bj * 32 + 8 * fq;
;             f32x4 t0 = *(const f32x4*)(rs + c0), t1 = *(const f32x4*)(rs + c0 + 4);
; #pragma unroll
;             for (int j = 0; j < 4; ++j) { t0[j] = rstd_of(t0[j], invn); t1[j] = rstd_of(t1[j], invn); }
; #pragma unroll
;             for (int ai = 0; ai < 2; ++ai)
; #pragma unroll
;                 for (int m = 0; m < 4; ++m) {
;                     const int r = u.pm * BM + ai * HALF + wr * 64 + m * 16 + fr;
;                     *(u32x4*)(O + (size_t)r * ldc + c0) = pack8(acc[ai][bj][m][0] * t0, acc[ai][bj][m][1] * t1);
;                 }
;         }
;     }
.LBB0_735:
	v_lshl_or_b32 v156, s68, 8, v149
	v_ashrrev_i32_e32 v157, 31, v156
	v_lshl_add_u64 v[138:139], v[156:157], 2, s[10:11]
	global_load_dwordx4 v[152:155], v[138:139], off offset:16
	global_load_dwordx4 v[142:145], v[138:139], off
	v_lshl_add_u32 v151, s69, 8, v3
	s_and_b64 vcc, exec, s[44:45]
	s_waitcnt vmcnt(0)
	v_fmamk_f32 v144, v144, 0x3b800000, v236
	v_fmamk_f32 v145, v145, 0x3b800000, v236
	v_fmamk_f32 v140, v142, 0x3b800000, v236
	v_fmamk_f32 v141, v143, 0x3b800000, v236
	v_rsq_f32_e32 v146, v144
	v_fmamk_f32 v144, v154, 0x3b800000, v236
	v_rsq_f32_e32 v147, v145
	v_fmamk_f32 v145, v155, 0x3b800000, v236
	v_rsq_f32_e32 v142, v140
	v_fmamk_f32 v140, v152, 0x3b800000, v236
	v_rsq_f32_e32 v143, v141
	v_fmamk_f32 v141, v153, 0x3b800000, v236
	v_rsq_f32_e32 v144, v144
	v_rsq_f32_e32 v145, v145
	v_rsq_f32_e32 v140, v140
	v_rsq_f32_e32 v141, v141
	v_pk_mul_f32 v[128:129], v[128:129], v[142:143]
	v_pk_mul_f32 v[126:127], v[126:127], v[144:145]
	v_pk_mul_f32 v[130:131], v[130:131], v[146:147]
	v_pk_mul_f32 v[124:125], v[124:125], v[140:141]
	v_cvt_pk_bf16_f32 v155, v126, v127
	v_mov_b64_e32 v[126:127], s[8:9]
	v_cvt_pk_bf16_f32 v152, v128, v129
	v_cvt_pk_bf16_f32 v154, v124, v125
	v_mad_i64_i32 v[124:125], s[4:5], v151, s37, v[126:127]
	v_lshlrev_b64 v[128:129], 1, v[156:157]
	v_cvt_pk_bf16_f32 v153, v130, v131
	v_lshl_add_u64 v[124:125], v[124:125], 0, v[128:129]
	global_store_dwordx4 v[124:125], v[152:155], off
	v_pk_mul_f32 v[120:121], v[120:121], v[142:143]
	v_pk_mul_f32 v[116:117], v[116:117], v[140:141]
	v_or_b32_e32 v152, 16, v151
	v_pk_mul_f32 v[122:123], v[122:123], v[146:147]
	v_pk_mul_f32 v[130:131], v[118:119], v[144:145]
	v_cvt_pk_bf16_f32 v118, v120, v121
	v_cvt_pk_bf16_f32 v120, v116, v117
	v_mad_i64_i32 v[116:117], s[4:5], v152, s37, v[126:127]
	v_cvt_pk_bf16_f32 v119, v122, v123
	v_cvt_pk_bf16_f32 v121, v130, v131
	v_lshl_add_u64 v[116:117], v[116:117], 0, v[128:129]
	global_store_dwordx4 v[116:117], v[118:121], off
	v_pk_mul_f32 v[112:113], v[112:113], v[142:143]
	v_pk_mul_f32 v[108:109], v[108:109], v[140:141]
	v_or_b32_e32 v120, 32, v151
	v_pk_mul_f32 v[114:115], v[114:115], v[146:147]
	v_pk_mul_f32 v[118:119], v[110:111], v[144:145]
	v_cvt_pk_bf16_f32 v110, v112, v113
	v_cvt_pk_bf16_f32 v112, v108, v109
	v_mad_i64_i32 v[108:109], s[4:5], v120, s37, v[126:127]
	v_cvt_pk_bf16_f32 v111, v114, v115
	v_cvt_pk_bf16_f32 v113, v118, v119
	v_lshl_add_u64 v[108:109], v[108:109], 0, v[128:129]
	global_store_dwordx4 v[108:109], v[110:113], off
	v_pk_mul_f32 v[104:105], v[104:105], v[142:143]
	v_pk_mul_f32 v[100:101], v[100:101], v[140:141]
	v_or_b32_e32 v112, 48, v151
	v_pk_mul_f32 v[106:107], v[106:107], v[146:147]
	v_pk_mul_f32 v[110:111], v[102:103], v[144:145]
	v_cvt_pk_bf16_f32 v102, v104, v105
	v_cvt_pk_bf16_f32 v104, v100, v101
	v_mad_i64_i32 v[100:101], s[4:5], v112, s37, v[126:127]
	v_cvt_pk_bf16_f32 v103, v106, v107
	v_cvt_pk_bf16_f32 v105, v110, v111
	v_lshl_add_u64 v[100:101], v[100:101], 0, v[128:129]
	global_store_dwordx4 v[100:101], v[102:105], off
	v_pk_mul_f32 v[96:97], v[96:97], v[142:143]
	v_pk_mul_f32 v[92:93], v[92:93], v[140:141]
	v_add_u32_e32 v104, 0x80, v151
	v_pk_mul_f32 v[98:99], v[98:99], v[146:147]
	v_pk_mul_f32 v[102:103], v[94:95], v[144:145]
	v_cvt_pk_bf16_f32 v94, v96, v97
	v_cvt_pk_bf16_f32 v96, v92, v93
	v_mad_i64_i32 v[92:93], s[4:5], v104, s37, v[126:127]
	v_cvt_pk_bf16_f32 v95, v98, v99
	v_cvt_pk_bf16_f32 v97, v102, v103
	v_lshl_add_u64 v[92:93], v[92:93], 0, v[128:129]
	global_store_dwordx4 v[92:93], v[94:97], off
	v_pk_mul_f32 v[88:89], v[88:89], v[142:143]
	v_pk_mul_f32 v[84:85], v[84:85], v[140:141]
	v_add_u32_e32 v96, 0x90, v151
	v_pk_mul_f32 v[90:91], v[90:91], v[146:147]
	v_pk_mul_f32 v[94:95], v[86:87], v[144:145]
	v_cvt_pk_bf16_f32 v86, v88, v89
	v_cvt_pk_bf16_f32 v88, v84, v85
	v_mad_i64_i32 v[84:85], s[4:5], v96, s37, v[126:127]
	v_cvt_pk_bf16_f32 v87, v90, v91
	v_cvt_pk_bf16_f32 v89, v94, v95
	v_lshl_add_u64 v[84:85], v[84:85], 0, v[128:129]
	global_store_dwordx4 v[84:85], v[86:89], off
	v_pk_mul_f32 v[80:81], v[80:81], v[142:143]
	v_pk_mul_f32 v[76:77], v[76:77], v[140:141]
	v_add_u32_e32 v88, 0xa0, v151
	v_pk_mul_f32 v[82:83], v[82:83], v[146:147]
	v_pk_mul_f32 v[86:87], v[78:79], v[144:145]
	v_cvt_pk_bf16_f32 v78, v80, v81
	v_cvt_pk_bf16_f32 v80, v76, v77
	v_mad_i64_i32 v[76:77], s[4:5], v88, s37, v[126:127]
	v_cvt_pk_bf16_f32 v79, v82, v83
	v_cvt_pk_bf16_f32 v81, v86, v87
	v_lshl_add_u64 v[76:77], v[76:77], 0, v[128:129]
	global_store_dwordx4 v[76:77], v[78:81], off
	v_pk_mul_f32 v[72:73], v[72:73], v[142:143]
	v_pk_mul_f32 v[68:69], v[68:69], v[140:141]
	v_add_u32_e32 v80, 0xb0, v151
	v_pk_mul_f32 v[74:75], v[74:75], v[146:147]
	v_pk_mul_f32 v[78:79], v[70:71], v[144:145]
	v_cvt_pk_bf16_f32 v70, v72, v73
	v_cvt_pk_bf16_f32 v72, v68, v69
	v_mad_i64_i32 v[68:69], s[4:5], v80, s37, v[126:127]
	v_cvt_pk_bf16_f32 v71, v74, v75
	v_cvt_pk_bf16_f32 v73, v78, v79
	v_lshl_add_u64 v[68:69], v[68:69], 0, v[128:129]
	global_store_dwordx4 v[68:69], v[70:73], off
	global_load_dwordx4 v[78:81], v[138:139], off offset:144
	s_nop 0
	global_load_dwordx4 v[72:75], v[138:139], off offset:128
	s_mov_b64 s[4:5], -1
	s_waitcnt vmcnt(1)
; __device__ __forceinline__ float rstd_of(float ss, float invn) { return __builtin_amdgcn_rsqf(ss * invn + EPS); }
; __device__ __forceinline__ u32x4 pack8(f32x4 a, f32x4 b) { u32x4 w; w.x = cvtpk(a[0], a[1]); w.y = cvtpk(a[2], a[3]); w.z = cvtpk(b[0], b[1]); w.w = cvtpk(b[2], b[3]); return w; }
;     __device__ __forceinline__ void operator()(const Acc& acc, const Unit& u, int wr, int wc, int fr, int fq) const {
; #pragma unroll
;         for (int bj = 0; bj < 2; ++bj) {
;             const int c0 = u.pn * BM + wc * 64 + bj * 32 + 8 * fq;
;             f32x4 t0 = *(const f32x4*)(rs + c0), t1 = *(const f32x4*)(rs + c0 + 4);
; #pragma unroll
;             for (int j = 0; j < 4; ++j) { t0[j] = rstd_of(t0[j], invn); t1[j] = rstd_of(t1[j], invn); }
; #pragma unroll
;             for (int ai = 0; ai < 2; ++ai)
; #pragma unroll
;                 for (int m = 0; m < 4; ++m) {
;                     const int r = u.pm * BM + ai * HALF + wr * 64 + m * 16 + fr;
;                     *(u32x4*)(O + (size_t)r * ldc + c0) = pack8(acc[ai][bj][m][0] * t0, acc[ai][bj][m][1] * t1);
;                 }
;         }
;     }
	v_fmamk_f32 v71, v78, 0x3b800000, v236
	s_waitcnt vmcnt(0)
	v_fmamk_f32 v70, v72, 0x3b800000, v236
	v_rsq_f32_e32 v72, v71
	v_fmamk_f32 v71, v73, 0x3b800000, v236
	v_fmamk_f32 v73, v79, 0x3b800000, v236
	v_fmamk_f32 v74, v74, 0x3b800000, v236
	v_fmamk_f32 v78, v80, 0x3b800000, v236
	v_fmamk_f32 v75, v75, 0x3b800000, v236
	v_fmamk_f32 v79, v81, 0x3b800000, v236
	v_rsq_f32_e32 v70, v70
	v_rsq_f32_e32 v71, v71
	v_rsq_f32_e32 v73, v73
	v_rsq_f32_e32 v74, v74
	v_rsq_f32_e32 v78, v78
	v_rsq_f32_e32 v75, v75
	v_rsq_f32_e32 v79, v79
	v_pk_mul_f32 v[64:65], v[64:65], v[70:71]
	v_pk_mul_f32 v[56:57], v[56:57], v[70:71]
	v_pk_mul_f32 v[66:67], v[66:67], v[74:75]
	v_pk_mul_f32 v[80:81], v[62:63], v[78:79]
	v_pk_mul_f32 v[62:63], v[60:61], v[72:73]
	v_cvt_pk_bf16_f32 v60, v64, v65
	v_cvt_pk_bf16_f32 v61, v66, v67
	v_cvt_pk_bf16_f32 v62, v62, v63
	v_cvt_pk_bf16_f32 v63, v80, v81
	global_store_dwordx4 v[124:125], v[60:63], off offset:64
	v_pk_mul_f32 v[58:59], v[58:59], v[74:75]
	v_pk_mul_f32 v[50:51], v[50:51], v[74:75]
	v_pk_mul_f32 v[60:61], v[54:55], v[78:79]
	v_pk_mul_f32 v[54:55], v[52:53], v[72:73]
	v_cvt_pk_bf16_f32 v52, v56, v57
	v_cvt_pk_bf16_f32 v53, v58, v59
	v_cvt_pk_bf16_f32 v54, v54, v55
	v_cvt_pk_bf16_f32 v55, v60, v61
	global_store_dwordx4 v[116:117], v[52:55], off offset:64
	v_pk_mul_f32 v[48:49], v[48:49], v[70:71]
	v_pk_mul_f32 v[42:43], v[42:43], v[74:75]
	v_pk_mul_f32 v[52:53], v[46:47], v[78:79]
	v_pk_mul_f32 v[46:47], v[44:45], v[72:73]
	v_cvt_pk_bf16_f32 v44, v48, v49
	v_cvt_pk_bf16_f32 v45, v50, v51
	v_cvt_pk_bf16_f32 v46, v46, v47
	v_cvt_pk_bf16_f32 v47, v52, v53
	global_store_dwordx4 v[108:109], v[44:47], off offset:64
	v_pk_mul_f32 v[40:41], v[40:41], v[70:71]
	v_pk_mul_f32 v[34:35], v[34:35], v[74:75]
	v_pk_mul_f32 v[44:45], v[38:39], v[78:79]
	v_pk_mul_f32 v[38:39], v[36:37], v[72:73]
	v_cvt_pk_bf16_f32 v36, v40, v41
	v_cvt_pk_bf16_f32 v37, v42, v43
	v_cvt_pk_bf16_f32 v38, v38, v39
	v_cvt_pk_bf16_f32 v39, v44, v45
	global_store_dwordx4 v[100:101], v[36:39], off offset:64
	v_pk_mul_f32 v[32:33], v[32:33], v[70:71]
	v_pk_mul_f32 v[26:27], v[26:27], v[74:75]
	v_pk_mul_f32 v[36:37], v[30:31], v[78:79]
	v_pk_mul_f32 v[30:31], v[28:29], v[72:73]
	v_cvt_pk_bf16_f32 v28, v32, v33
	v_cvt_pk_bf16_f32 v29, v34, v35
	v_cvt_pk_bf16_f32 v30, v30, v31
	v_cvt_pk_bf16_f32 v31, v36, v37
	global_store_dwordx4 v[92:93], v[28:31], off offset:64
	v_pk_mul_f32 v[24:25], v[24:25], v[70:71]
	v_pk_mul_f32 v[18:19], v[18:19], v[74:75]
	v_pk_mul_f32 v[28:29], v[22:23], v[78:79]
	v_pk_mul_f32 v[22:23], v[20:21], v[72:73]
	v_cvt_pk_bf16_f32 v20, v24, v25
	v_cvt_pk_bf16_f32 v21, v26, v27
	v_cvt_pk_bf16_f32 v22, v22, v23
	v_cvt_pk_bf16_f32 v23, v28, v29
	global_store_dwordx4 v[84:85], v[20:23], off offset:64
	v_pk_mul_f32 v[16:17], v[16:17], v[70:71]
	v_pk_mul_f32 v[10:11], v[10:11], v[74:75]
	v_pk_mul_f32 v[20:21], v[14:15], v[78:79]
	v_pk_mul_f32 v[14:15], v[12:13], v[72:73]
	v_cvt_pk_bf16_f32 v12, v16, v17
	v_cvt_pk_bf16_f32 v13, v18, v19
	v_cvt_pk_bf16_f32 v14, v14, v15
	v_cvt_pk_bf16_f32 v15, v20, v21
	global_store_dwordx4 v[76:77], v[12:15], off offset:64
	v_pk_mul_f32 v[8:9], v[8:9], v[70:71]
	s_nop 0
	v_pk_mul_f32 v[12:13], v[6:7], v[78:79]
	v_pk_mul_f32 v[6:7], v[4:5], v[72:73]
	v_cvt_pk_bf16_f32 v4, v8, v9
	v_cvt_pk_bf16_f32 v5, v10, v11
	v_cvt_pk_bf16_f32 v6, v6, v7
	v_cvt_pk_bf16_f32 v7, v12, v13
	global_store_dwordx4 v[68:69], v[4:7], off offset:64
	s_cbranch_vccnz .LBB0_722
	s_andn2_b64 vcc, exec, s[6:7]
	s_cbranch_vccnz .LBB0_721
	s_barrier
	s_branch .LBB0_721

; __device__ __forceinline__ float rstd_of(float ss, float invn) { return __builtin_amdgcn_rsqf(ss * invn + EPS); }
; __device__ __forceinline__ u32x4 pack8(f32x4 a, f32x4 b) { u32x4 w; w.x = cvtpk(a[0], a[1]); w.y = cvtpk(a[2], a[3]); w.z = cvtpk(b[0], b[1]); w.w = cvtpk(b[2], b[3]); return w; }
;     __device__ __forceinline__ void operator()(const Acc& acc, const Unit& u, int wr, int wc, int fr, int fq) const {
;         float tpre[2][4];
; #pragma unroll
;         for (int ai = 0; ai < 2; ++ai)
; #pragma unroll
;             for (int m = 0; m < 4; ++m) tpre[ai][m] = rs ? rs[u.pm * BM + ai * HALF + wr * 64 + m * 16 + fr] : 0.f;
;         asm volatile("" ::: "memory");
; #pragma unroll
;         for (int ai = 0; ai < 2; ++ai)
; #pragma unroll
;             for (int m = 0; m < 4; ++m) {
;                 const int r = u.pm * BM + ai * HALF + wr * 64 + m * 16 + fr; const float t = rs ? rstd_of(tpre[ai][m], invn) : 1.f;
; #pragma unroll
;                 for (int bj = 0; bj < 2; ++bj) {
;                     const int c0 = u.pn * BM + wc * 64 + bj * 32 + 8 * fq;
;                     f32x4 v0 = acc[ai][bj][m][0] * t, v1 = acc[ai][bj][m][1] * t;
;                     if (sig) { const float tl = -t * 1.4426950408889634f; const f32x4 z0 = acc[ai][bj][m][0] * tl, z1 = acc[ai][bj][m][1] * tl;
; #pragma unroll
;                         for (int j = 0; j < 4; ++j) { v0[j] = __builtin_amdgcn_rcpf(1.f + __builtin_amdgcn_exp2f(z0[j])); v1[j] = __builtin_amdgcn_rcpf(1.f + __builtin_amdgcn_exp2f(z1[j])); } }
;                     *(u32x4*)(O + (size_t)r * ldc + c0) = pack8(v0, v1);
;                 }
;             }
;     }
.LBB0_883:
	v_lshl_add_u32 v150, s66, 8, v3
	v_ashrrev_i32_e32 v151, 31, v150
	v_lshl_add_u64 v[142:143], v[150:151], 2, s[12:13]
	global_load_dword v157, v[142:143], off
	global_load_dword v156, v[142:143], off offset:64
	global_load_dword v155, v[142:143], off offset:128
	global_load_dword v151, v[142:143], off offset:192
	v_add_u32_e32 v148, 0x80, v150
	v_ashrrev_i32_e32 v149, 31, v148
	v_add_u32_e32 v146, 0x90, v150
	v_lshl_add_u64 v[142:143], v[148:149], 2, s[12:13]
	v_ashrrev_i32_e32 v147, 31, v146
	v_add_u32_e32 v144, 0xa0, v150
	global_load_dword v149, v[142:143], off
	v_lshl_add_u64 v[142:143], v[146:147], 2, s[12:13]
	v_ashrrev_i32_e32 v145, 31, v144
	global_load_dword v147, v[142:143], off
	v_lshl_add_u64 v[142:143], v[144:145], 2, s[12:13]
	global_load_dword v145, v[142:143], off
	v_add_u32_e32 v142, 0xb0, v150
	v_ashrrev_i32_e32 v143, 31, v142
	v_lshl_add_u64 v[158:159], v[142:143], 2, s[12:13]
	global_load_dword v143, v[158:159], off
	v_lshl_or_b32 v158, s65, 8, v153
	v_ashrrev_i32_e32 v159, 31, v158
	s_andn2_b64 vcc, exec, s[44:45]
	s_waitcnt vmcnt(0)
	v_fmamk_f32 v157, v157, 0x3a800000, v236
	v_rsq_f32_e32 v157, v157
	s_nop 0
	v_mul_f32_e32 v160, 0xbfb8aa3b, v157
	v_pk_mul_f32 v[130:131], v[130:131], v[160:161] op_sel_hi:[1,0]
	v_pk_mul_f32 v[128:129], v[128:129], v[160:161] op_sel_hi:[1,0]
	v_pk_mul_f32 v[124:125], v[124:125], v[160:161] op_sel_hi:[1,0]
	v_pk_mul_f32 v[126:127], v[126:127], v[160:161] op_sel_hi:[1,0]
	v_exp_f32_e32 v128, v128
	v_exp_f32_e32 v124, v124
	v_exp_f32_e32 v129, v129
	v_exp_f32_e32 v125, v125
	v_exp_f32_e32 v130, v130
	v_exp_f32_e32 v131, v131
	v_exp_f32_e32 v126, v126
	v_exp_f32_e32 v127, v127
	v_add_f32_e32 v128, 1.0, v128
	v_add_f32_e32 v124, 1.0, v124
	v_add_f32_e32 v129, 1.0, v129
	v_add_f32_e32 v125, 1.0, v125
	v_add_f32_e32 v130, 1.0, v130
	v_add_f32_e32 v131, 1.0, v131
	v_rcp_f32_e32 v128, v128
	v_rcp_f32_e32 v124, v124
	v_rcp_f32_e32 v129, v129
	v_rcp_f32_e32 v125, v125
	v_rcp_f32_e32 v130, v130
	v_add_f32_e32 v126, 1.0, v126
	v_rcp_f32_e32 v131, v131
	v_add_f32_e32 v127, 1.0, v127
	v_rcp_f32_e32 v126, v126
	v_rcp_f32_e32 v127, v127
	v_pk_mul_f32 v[118:119], v[118:119], v[160:161] op_sel_hi:[1,0]
	v_pk_mul_f32 v[116:117], v[116:117], v[160:161] op_sel_hi:[1,0]
	v_exp_f32_e32 v118, v118
	v_exp_f32_e32 v116, v116
	v_exp_f32_e32 v117, v117
	v_cvt_pk_bf16_f32 v128, v128, v129
	v_cvt_pk_bf16_f32 v129, v130, v131
	v_cvt_pk_bf16_f32 v130, v124, v125
	v_mov_b64_e32 v[124:125], s[10:11]
	v_cvt_pk_bf16_f32 v131, v126, v127
	v_mad_i64_i32 v[162:163], s[22:23], v150, s24, v[124:125]
	v_lshlrev_b64 v[126:127], 1, v[158:159]
	v_lshl_add_u64 v[158:159], v[162:163], 0, v[126:127]
	v_pk_mul_f32 v[122:123], v[122:123], v[160:161] op_sel_hi:[1,0]
	v_pk_mul_f32 v[120:121], v[120:121], v[160:161] op_sel_hi:[1,0]
	v_add_f32_e32 v116, 1.0, v116
	v_add_f32_e32 v117, 1.0, v117
	v_add_f32_e32 v118, 1.0, v118
	global_store_dwordx4 v[158:159], v[128:131], off
	v_exp_f32_e32 v120, v120
	v_exp_f32_e32 v119, v119
	v_rcp_f32_e32 v128, v116
	v_exp_f32_e32 v116, v121
	v_rcp_f32_e32 v121, v117
	v_exp_f32_e32 v117, v122
	v_rcp_f32_e32 v122, v118
	v_exp_f32_e32 v118, v123
	v_add_f32_e32 v120, 1.0, v120
	v_add_f32_e32 v116, 1.0, v116
	v_add_f32_e32 v117, 1.0, v117
	v_add_f32_e32 v118, 1.0, v118
	v_add_f32_e32 v119, 1.0, v119
	v_rcp_f32_e32 v120, v120
	v_rcp_f32_e32 v116, v116
	v_rcp_f32_e32 v117, v117
	v_rcp_f32_e32 v118, v118
	v_rcp_f32_e32 v119, v119
	v_cvt_pk_bf16_f32 v116, v120, v116
	v_cvt_pk_bf16_f32 v117, v117, v118
	v_cvt_pk_bf16_f32 v118, v128, v121
	v_cvt_pk_bf16_f32 v119, v122, v119
	global_store_dwordx4 v[158:159], v[116:119], off offset:64
	s_nop 1
	v_fmamk_f32 v117, v156, 0x3a800000, v236
	v_rsq_f32_e32 v117, v117
	v_or_b32_e32 v116, 16, v150
	v_mul_f32_e32 v118, 0xbfb8aa3b, v117
	v_pk_mul_f32 v[110:111], v[110:111], v[118:119] op_sel_hi:[1,0]
	v_pk_mul_f32 v[108:109], v[108:109], v[118:119] op_sel_hi:[1,0]
	v_exp_f32_e32 v110, v110
	v_exp_f32_e32 v108, v108
	v_exp_f32_e32 v109, v109
	v_pk_mul_f32 v[114:115], v[114:115], v[118:119] op_sel_hi:[1,0]
	v_pk_mul_f32 v[112:113], v[112:113], v[118:119] op_sel_hi:[1,0]
	v_add_f32_e32 v108, 1.0, v108
	v_add_f32_e32 v109, 1.0, v109
	v_add_f32_e32 v110, 1.0, v110
	v_exp_f32_e32 v112, v112
	v_rcp_f32_e32 v117, v108
	v_exp_f32_e32 v108, v113
	v_rcp_f32_e32 v113, v109
	v_exp_f32_e32 v109, v114
	v_rcp_f32_e32 v114, v110
	v_exp_f32_e32 v110, v115
	v_exp_f32_e32 v111, v111
	v_add_f32_e32 v112, 1.0, v112
	v_add_f32_e32 v108, 1.0, v108
	v_add_f32_e32 v109, 1.0, v109
	v_add_f32_e32 v110, 1.0, v110
	v_rcp_f32_e32 v112, v112
	v_rcp_f32_e32 v108, v108
	v_rcp_f32_e32 v109, v109
	v_rcp_f32_e32 v110, v110
	v_add_f32_e32 v111, 1.0, v111
	v_pk_mul_f32 v[102:103], v[102:103], v[118:119] op_sel_hi:[1,0]
	v_pk_mul_f32 v[100:101], v[100:101], v[118:119] op_sel_hi:[1,0]
	v_rcp_f32_e32 v111, v111
	v_exp_f32_e32 v100, v100
	v_exp_f32_e32 v101, v101
	v_exp_f32_e32 v102, v102
	v_cvt_pk_bf16_f32 v108, v112, v108
	v_cvt_pk_bf16_f32 v109, v109, v110
	v_cvt_pk_bf16_f32 v110, v117, v113
	v_mad_i64_i32 v[112:113], s[22:23], v116, s24, v[124:125]
	v_cvt_pk_bf16_f32 v111, v114, v111
	v_lshl_add_u64 v[112:113], v[112:113], 0, v[126:127]
	v_pk_mul_f32 v[106:107], v[106:107], v[118:119] op_sel_hi:[1,0]
	v_pk_mul_f32 v[104:105], v[104:105], v[118:119] op_sel_hi:[1,0]
	v_add_f32_e32 v100, 1.0, v100
	v_add_f32_e32 v101, 1.0, v101
	v_add_f32_e32 v102, 1.0, v102
	global_store_dwordx4 v[112:113], v[108:111], off
	v_exp_f32_e32 v104, v104
	v_exp_f32_e32 v103, v103
	v_rcp_f32_e32 v108, v100
	v_exp_f32_e32 v100, v105
	v_rcp_f32_e32 v105, v101
	v_exp_f32_e32 v101, v106
	v_rcp_f32_e32 v106, v102
	v_exp_f32_e32 v102, v107
; __device__ __forceinline__ float rstd_of(float ss, float invn) { return __builtin_amdgcn_rsqf(ss * invn + EPS); }
; __device__ __forceinline__ u32x4 pack8(f32x4 a, f32x4 b) { u32x4 w; w.x = cvtpk(a[0], a[1]); w.y = cvtpk(a[2], a[3]); w.z = cvtpk(b[0], b[1]); w.w = cvtpk(b[2], b[3]); return w; }
;     __device__ __forceinline__ void operator()(const Acc& acc, const Unit& u, int wr, int wc, int fr, int fq) const {
;         float tpre[2][4];
; #pragma unroll
;         for (int ai = 0; ai < 2; ++ai)
; #pragma unroll
;             for (int m = 0; m < 4; ++m) tpre[ai][m] = rs ? rs[u.pm * BM + ai * HALF + wr * 64 + m * 16 + fr] : 0.f;
;         asm volatile("" ::: "memory");
; #pragma unroll
;         for (int ai = 0; ai < 2; ++ai)
; #pragma unroll
;             for (int m = 0; m < 4; ++m) {
;                 const int r = u.pm * BM + ai * HALF + wr * 64 + m * 16 + fr; const float t = rs ? rstd_of(tpre[ai][m], invn) : 1.f;
; #pragma unroll
;                 for (int bj = 0; bj < 2; ++bj) {
;                     const int c0 = u.pn * BM + wc * 64 + bj * 32 + 8 * fq;
;                     f32x4 v0 = acc[ai][bj][m][0] * t, v1 = acc[ai][bj][m][1] * t;
;                     if (sig) { const float tl = -t * 1.4426950408889634f; const f32x4 z0 = acc[ai][bj][m][0] * tl, z1 = acc[ai][bj][m][1] * tl;
; #pragma unroll
;                         for (int j = 0; j < 4; ++j) { v0[j] = __builtin_amdgcn_rcpf(1.f + __builtin_amdgcn_exp2f(z0[j])); v1[j] = __builtin_amdgcn_rcpf(1.f + __builtin_amdgcn_exp2f(z1[j])); } }
;                     *(u32x4*)(O + (size_t)r * ldc + c0) = pack8(v0, v1);
;                 }
;             }
;     }
	v_add_f32_e32 v104, 1.0, v104
	v_add_f32_e32 v100, 1.0, v100
	v_add_f32_e32 v101, 1.0, v101
	v_add_f32_e32 v102, 1.0, v102
	v_add_f32_e32 v103, 1.0, v103
	v_rcp_f32_e32 v104, v104
	v_rcp_f32_e32 v100, v100
	v_rcp_f32_e32 v101, v101
	v_rcp_f32_e32 v102, v102
	v_rcp_f32_e32 v103, v103
	v_cvt_pk_bf16_f32 v100, v104, v100
	v_cvt_pk_bf16_f32 v101, v101, v102
	v_cvt_pk_bf16_f32 v102, v108, v105
	v_cvt_pk_bf16_f32 v103, v106, v103
	global_store_dwordx4 v[112:113], v[100:103], off offset:64
	s_nop 1
	v_fmamk_f32 v100, v155, 0x3a800000, v236
	v_rsq_f32_e32 v100, v100
	v_or_b32_e32 v101, 32, v150
	v_mul_f32_e32 v100, 0xbfb8aa3b, v100
	v_pk_mul_f32 v[94:95], v[94:95], v[100:101] op_sel_hi:[1,0]
	v_pk_mul_f32 v[92:93], v[92:93], v[100:101] op_sel_hi:[1,0]
	v_exp_f32_e32 v94, v94
	v_exp_f32_e32 v92, v92
	v_exp_f32_e32 v93, v93
	v_pk_mul_f32 v[98:99], v[98:99], v[100:101] op_sel_hi:[1,0]
	v_pk_mul_f32 v[96:97], v[96:97], v[100:101] op_sel_hi:[1,0]
	v_add_f32_e32 v92, 1.0, v92
	v_add_f32_e32 v93, 1.0, v93
	v_add_f32_e32 v94, 1.0, v94
	v_exp_f32_e32 v96, v96
	v_rcp_f32_e32 v102, v92
	v_exp_f32_e32 v92, v97
	v_rcp_f32_e32 v97, v93
	v_exp_f32_e32 v93, v98
	v_rcp_f32_e32 v98, v94
	v_exp_f32_e32 v94, v99
	v_exp_f32_e32 v95, v95
	v_add_f32_e32 v96, 1.0, v96
	v_add_f32_e32 v92, 1.0, v92
	v_add_f32_e32 v93, 1.0, v93
	v_add_f32_e32 v94, 1.0, v94
	v_rcp_f32_e32 v96, v96
	v_rcp_f32_e32 v92, v92
	v_rcp_f32_e32 v93, v93
	v_rcp_f32_e32 v94, v94
	v_add_f32_e32 v95, 1.0, v95
	v_pk_mul_f32 v[86:87], v[86:87], v[100:101] op_sel_hi:[1,0]
	v_pk_mul_f32 v[84:85], v[84:85], v[100:101] op_sel_hi:[1,0]
	v_rcp_f32_e32 v95, v95
	v_exp_f32_e32 v84, v84
	v_exp_f32_e32 v85, v85
	v_exp_f32_e32 v86, v86
	v_cvt_pk_bf16_f32 v92, v96, v92
	v_cvt_pk_bf16_f32 v93, v93, v94
	v_cvt_pk_bf16_f32 v94, v102, v97
	v_mad_i64_i32 v[96:97], s[22:23], v101, s24, v[124:125]
	v_cvt_pk_bf16_f32 v95, v98, v95
	v_lshl_add_u64 v[96:97], v[96:97], 0, v[126:127]
	v_pk_mul_f32 v[90:91], v[90:91], v[100:101] op_sel_hi:[1,0]
	v_pk_mul_f32 v[88:89], v[88:89], v[100:101] op_sel_hi:[1,0]
	v_add_f32_e32 v84, 1.0, v84
	v_add_f32_e32 v85, 1.0, v85
	v_add_f32_e32 v86, 1.0, v86
	global_store_dwordx4 v[96:97], v[92:95], off
	v_exp_f32_e32 v88, v88
	v_exp_f32_e32 v87, v87
	v_rcp_f32_e32 v92, v84
	v_exp_f32_e32 v84, v89
	v_rcp_f32_e32 v89, v85
	v_exp_f32_e32 v85, v90
	v_rcp_f32_e32 v90, v86
	v_exp_f32_e32 v86, v91
	v_add_f32_e32 v88, 1.0, v88
	v_add_f32_e32 v84, 1.0, v84
	v_add_f32_e32 v85, 1.0, v85
	v_add_f32_e32 v86, 1.0, v86
	v_add_f32_e32 v87, 1.0, v87
	v_rcp_f32_e32 v88, v88
	v_rcp_f32_e32 v84, v84
	v_rcp_f32_e32 v85, v85
	v_rcp_f32_e32 v86, v86
	v_rcp_f32_e32 v87, v87
	v_cvt_pk_bf16_f32 v84, v88, v84
	v_cvt_pk_bf16_f32 v85, v85, v86
	v_cvt_pk_bf16_f32 v86, v92, v89
	v_cvt_pk_bf16_f32 v87, v90, v87
	global_store_dwordx4 v[96:97], v[84:87], off offset:64
	s_nop 1
	v_fmamk_f32 v84, v151, 0x3a800000, v236
	v_rsq_f32_e32 v84, v84
	v_or_b32_e32 v85, 48, v150
	v_mul_f32_e32 v84, 0xbfb8aa3b, v84
	v_pk_mul_f32 v[78:79], v[78:79], v[84:85] op_sel_hi:[1,0]
	v_pk_mul_f32 v[76:77], v[76:77], v[84:85] op_sel_hi:[1,0]
	v_exp_f32_e32 v78, v78
	v_exp_f32_e32 v76, v76
	v_exp_f32_e32 v77, v77
	v_pk_mul_f32 v[82:83], v[82:83], v[84:85] op_sel_hi:[1,0]
	v_pk_mul_f32 v[80:81], v[80:81], v[84:85] op_sel_hi:[1,0]
	v_add_f32_e32 v76, 1.0, v76
	v_add_f32_e32 v77, 1.0, v77
	v_add_f32_e32 v78, 1.0, v78
	v_exp_f32_e32 v80, v80
	v_rcp_f32_e32 v86, v76
	v_exp_f32_e32 v76, v81
	v_rcp_f32_e32 v81, v77
	v_exp_f32_e32 v77, v82
	v_rcp_f32_e32 v82, v78
	v_exp_f32_e32 v78, v83
	v_exp_f32_e32 v79, v79
	v_add_f32_e32 v80, 1.0, v80
	v_add_f32_e32 v76, 1.0, v76
	v_add_f32_e32 v77, 1.0, v77
	v_add_f32_e32 v78, 1.0, v78
	v_rcp_f32_e32 v80, v80
	v_rcp_f32_e32 v76, v76
	v_rcp_f32_e32 v77, v77
	v_rcp_f32_e32 v78, v78
	v_add_f32_e32 v79, 1.0, v79
	v_pk_mul_f32 v[70:71], v[70:71], v[84:85] op_sel_hi:[1,0]
	v_pk_mul_f32 v[68:69], v[68:69], v[84:85] op_sel_hi:[1,0]
	v_rcp_f32_e32 v79, v79
	v_exp_f32_e32 v68, v68
	v_exp_f32_e32 v69, v69
	v_exp_f32_e32 v70, v70
	v_cvt_pk_bf16_f32 v76, v80, v76
	v_cvt_pk_bf16_f32 v77, v77, v78
	v_cvt_pk_bf16_f32 v78, v86, v81
	v_mad_i64_i32 v[80:81], s[22:23], v85, s24, v[124:125]
	v_cvt_pk_bf16_f32 v79, v82, v79
	v_lshl_add_u64 v[80:81], v[80:81], 0, v[126:127]
	v_pk_mul_f32 v[74:75], v[74:75], v[84:85] op_sel_hi:[1,0]
	v_pk_mul_f32 v[72:73], v[72:73], v[84:85] op_sel_hi:[1,0]
	v_add_f32_e32 v68, 1.0, v68
	v_add_f32_e32 v69, 1.0, v69
	v_add_f32_e32 v70, 1.0, v70
	global_store_dwordx4 v[80:81], v[76:79], off
	v_exp_f32_e32 v72, v72
	v_exp_f32_e32 v71, v71
	v_rcp_f32_e32 v76, v68
	v_exp_f32_e32 v68, v73
	v_rcp_f32_e32 v73, v69
	v_exp_f32_e32 v69, v74
	v_rcp_f32_e32 v74, v70
	v_exp_f32_e32 v70, v75
	v_add_f32_e32 v72, 1.0, v72
	v_add_f32_e32 v68, 1.0, v68
	v_add_f32_e32 v69, 1.0, v69
	v_add_f32_e32 v70, 1.0, v70
	v_add_f32_e32 v71, 1.0, v71
	v_rcp_f32_e32 v72, v72
	v_rcp_f32_e32 v68, v68
	v_rcp_f32_e32 v69, v69
	v_rcp_f32_e32 v70, v70
	v_rcp_f32_e32 v71, v71
	v_cvt_pk_bf16_f32 v68, v72, v68
	v_cvt_pk_bf16_f32 v69, v69, v70
	v_cvt_pk_bf16_f32 v70, v76, v73
	v_cvt_pk_bf16_f32 v71, v74, v71
	global_store_dwordx4 v[80:81], v[68:71], off offset:64
	s_nop 1
	v_fmamk_f32 v68, v149, 0x3a800000, v236
	v_rsq_f32_e32 v68, v68
	s_nop 0
	v_mul_f32_e32 v68, 0xbfb8aa3b, v68
	v_pk_mul_f32 v[62:63], v[62:63], v[68:69] op_sel_hi:[1,0]
	v_pk_mul_f32 v[60:61], v[60:61], v[68:69] op_sel_hi:[1,0]
	v_exp_f32_e32 v62, v62
	v_exp_f32_e32 v60, v60
	v_exp_f32_e32 v61, v61
	v_pk_mul_f32 v[66:67], v[66:67], v[68:69] op_sel_hi:[1,0]
	v_pk_mul_f32 v[64:65], v[64:65], v[68:69] op_sel_hi:[1,0]
	v_add_f32_e32 v60, 1.0, v60
	v_add_f32_e32 v61, 1.0, v61
; __device__ __forceinline__ float rstd_of(float ss, float invn) { return __builtin_amdgcn_rsqf(ss * invn + EPS); }
; __device__ __forceinline__ u32x4 pack8(f32x4 a, f32x4 b) { u32x4 w; w.x = cvtpk(a[0], a[1]); w.y = cvtpk(a[2], a[3]); w.z = cvtpk(b[0], b[1]); w.w = cvtpk(b[2], b[3]); return w; }
;     __device__ __forceinline__ void operator()(const Acc& acc, const Unit& u, int wr, int wc, int fr, int fq) const {
;         float tpre[2][4];
; #pragma unroll
;         for (int ai = 0; ai < 2; ++ai)
; #pragma unroll
;             for (int m = 0; m < 4; ++m) tpre[ai][m] = rs ? rs[u.pm * BM + ai * HALF + wr * 64 + m * 16 + fr] : 0.f;
;         asm volatile("" ::: "memory");
; #pragma unroll
;         for (int ai = 0; ai < 2; ++ai)
; #pragma unroll
;             for (int m = 0; m < 4; ++m) {
;                 const int r = u.pm * BM + ai * HALF + wr * 64 + m * 16 + fr; const float t = rs ? rstd_of(tpre[ai][m], invn) : 1.f;
; #pragma unroll
;                 for (int bj = 0; bj < 2; ++bj) {
;                     const int c0 = u.pn * BM + wc * 64 + bj * 32 + 8 * fq;
;                     f32x4 v0 = acc[ai][bj][m][0] * t, v1 = acc[ai][bj][m][1] * t;
;                     if (sig) { const float tl = -t * 1.4426950408889634f; const f32x4 z0 = acc[ai][bj][m][0] * tl, z1 = acc[ai][bj][m][1] * tl;
; #pragma unroll
;                         for (int j = 0; j < 4; ++j) { v0[j] = __builtin_amdgcn_rcpf(1.f + __builtin_amdgcn_exp2f(z0[j])); v1[j] = __builtin_amdgcn_rcpf(1.f + __builtin_amdgcn_exp2f(z1[j])); } }
;                     *(u32x4*)(O + (size_t)r * ldc + c0) = pack8(v0, v1);
;                 }
;             }
;     }
	v_add_f32_e32 v62, 1.0, v62
	v_exp_f32_e32 v64, v64
	v_rcp_f32_e32 v69, v60
	v_exp_f32_e32 v60, v65
	v_rcp_f32_e32 v65, v61
	v_exp_f32_e32 v61, v66
	v_rcp_f32_e32 v66, v62
	v_exp_f32_e32 v62, v67
	v_exp_f32_e32 v63, v63
	v_add_f32_e32 v64, 1.0, v64
	v_add_f32_e32 v60, 1.0, v60
	v_add_f32_e32 v61, 1.0, v61
	v_add_f32_e32 v62, 1.0, v62
	v_rcp_f32_e32 v64, v64
	v_rcp_f32_e32 v60, v60
	v_rcp_f32_e32 v61, v61
	v_rcp_f32_e32 v62, v62
	v_add_f32_e32 v63, 1.0, v63
	v_pk_mul_f32 v[54:55], v[54:55], v[68:69] op_sel_hi:[1,0]
	v_pk_mul_f32 v[52:53], v[52:53], v[68:69] op_sel_hi:[1,0]
	v_rcp_f32_e32 v63, v63
	v_exp_f32_e32 v52, v52
	v_exp_f32_e32 v53, v53
	v_exp_f32_e32 v54, v54
	v_cvt_pk_bf16_f32 v60, v64, v60
	v_cvt_pk_bf16_f32 v61, v61, v62
	v_cvt_pk_bf16_f32 v62, v69, v65
	v_mad_i64_i32 v[64:65], s[22:23], v148, s24, v[124:125]
	v_cvt_pk_bf16_f32 v63, v66, v63
	v_lshl_add_u64 v[64:65], v[64:65], 0, v[126:127]
	v_pk_mul_f32 v[58:59], v[58:59], v[68:69] op_sel_hi:[1,0]
	v_pk_mul_f32 v[56:57], v[56:57], v[68:69] op_sel_hi:[1,0]
	v_add_f32_e32 v52, 1.0, v52
	v_add_f32_e32 v53, 1.0, v53
	v_add_f32_e32 v54, 1.0, v54
	global_store_dwordx4 v[64:65], v[60:63], off
	v_exp_f32_e32 v56, v56
	v_exp_f32_e32 v55, v55
	v_rcp_f32_e32 v60, v52
	v_exp_f32_e32 v52, v57
	v_rcp_f32_e32 v57, v53
	v_exp_f32_e32 v53, v58
	v_rcp_f32_e32 v58, v54
	v_exp_f32_e32 v54, v59
	v_add_f32_e32 v56, 1.0, v56
	v_add_f32_e32 v52, 1.0, v52
	v_add_f32_e32 v53, 1.0, v53
	v_add_f32_e32 v54, 1.0, v54
	v_add_f32_e32 v55, 1.0, v55
	v_rcp_f32_e32 v56, v56
	v_rcp_f32_e32 v52, v52
	v_rcp_f32_e32 v53, v53
	v_rcp_f32_e32 v54, v54
	v_rcp_f32_e32 v55, v55
	v_cvt_pk_bf16_f32 v52, v56, v52
	v_cvt_pk_bf16_f32 v53, v53, v54
	v_cvt_pk_bf16_f32 v54, v60, v57
	v_cvt_pk_bf16_f32 v55, v58, v55
	global_store_dwordx4 v[64:65], v[52:55], off offset:64
	s_nop 1
	v_fmamk_f32 v52, v147, 0x3a800000, v236
	v_rsq_f32_e32 v52, v52
	s_nop 0
	v_mul_f32_e32 v52, 0xbfb8aa3b, v52
	v_pk_mul_f32 v[46:47], v[46:47], v[52:53] op_sel_hi:[1,0]
	v_pk_mul_f32 v[44:45], v[44:45], v[52:53] op_sel_hi:[1,0]
	v_exp_f32_e32 v46, v46
	v_exp_f32_e32 v44, v44
	v_exp_f32_e32 v45, v45
	v_pk_mul_f32 v[50:51], v[50:51], v[52:53] op_sel_hi:[1,0]
	v_pk_mul_f32 v[48:49], v[48:49], v[52:53] op_sel_hi:[1,0]
	v_add_f32_e32 v44, 1.0, v44
	v_add_f32_e32 v45, 1.0, v45
	v_add_f32_e32 v46, 1.0, v46
	v_exp_f32_e32 v48, v48
	v_rcp_f32_e32 v53, v44
	v_exp_f32_e32 v44, v49
	v_rcp_f32_e32 v49, v45
	v_exp_f32_e32 v45, v50
	v_rcp_f32_e32 v50, v46
	v_exp_f32_e32 v46, v51
	v_exp_f32_e32 v47, v47
	v_add_f32_e32 v48, 1.0, v48
	v_add_f32_e32 v44, 1.0, v44
	v_add_f32_e32 v45, 1.0, v45
	v_add_f32_e32 v46, 1.0, v46
	v_rcp_f32_e32 v48, v48
	v_rcp_f32_e32 v44, v44
	v_rcp_f32_e32 v45, v45
	v_rcp_f32_e32 v46, v46
	v_add_f32_e32 v47, 1.0, v47
	v_pk_mul_f32 v[38:39], v[38:39], v[52:53] op_sel_hi:[1,0]
	v_pk_mul_f32 v[36:37], v[36:37], v[52:53] op_sel_hi:[1,0]
	v_rcp_f32_e32 v47, v47
	v_exp_f32_e32 v36, v36
	v_exp_f32_e32 v37, v37
	v_exp_f32_e32 v38, v38
	v_cvt_pk_bf16_f32 v44, v48, v44
	v_cvt_pk_bf16_f32 v45, v45, v46
	v_cvt_pk_bf16_f32 v46, v53, v49
	v_mad_i64_i32 v[48:49], s[22:23], v146, s24, v[124:125]
	v_cvt_pk_bf16_f32 v47, v50, v47
	v_lshl_add_u64 v[48:49], v[48:49], 0, v[126:127]
	v_pk_mul_f32 v[42:43], v[42:43], v[52:53] op_sel_hi:[1,0]
	v_pk_mul_f32 v[40:41], v[40:41], v[52:53] op_sel_hi:[1,0]
	v_add_f32_e32 v36, 1.0, v36
	v_add_f32_e32 v37, 1.0, v37
	v_add_f32_e32 v38, 1.0, v38
	global_store_dwordx4 v[48:49], v[44:47], off
	v_exp_f32_e32 v40, v40
	v_exp_f32_e32 v39, v39
	v_rcp_f32_e32 v44, v36
	v_exp_f32_e32 v36, v41
	v_rcp_f32_e32 v41, v37
	v_exp_f32_e32 v37, v42
	v_rcp_f32_e32 v42, v38
	v_exp_f32_e32 v38, v43
	v_add_f32_e32 v40, 1.0, v40
	v_add_f32_e32 v36, 1.0, v36
	v_add_f32_e32 v37, 1.0, v37
	v_add_f32_e32 v38, 1.0, v38
	v_add_f32_e32 v39, 1.0, v39
	v_rcp_f32_e32 v40, v40
	v_rcp_f32_e32 v36, v36
	v_rcp_f32_e32 v37, v37
	v_rcp_f32_e32 v38, v38
	v_rcp_f32_e32 v39, v39
	v_cvt_pk_bf16_f32 v36, v40, v36
	v_cvt_pk_bf16_f32 v37, v37, v38
	v_cvt_pk_bf16_f32 v38, v44, v41
	v_cvt_pk_bf16_f32 v39, v42, v39
	global_store_dwordx4 v[48:49], v[36:39], off offset:64
	s_nop 1
	v_fmamk_f32 v36, v145, 0x3a800000, v236
	v_rsq_f32_e32 v36, v36
	s_nop 0
	v_mul_f32_e32 v36, 0xbfb8aa3b, v36
	v_pk_mul_f32 v[30:31], v[30:31], v[36:37] op_sel_hi:[1,0]
	v_pk_mul_f32 v[28:29], v[28:29], v[36:37] op_sel_hi:[1,0]
	v_exp_f32_e32 v30, v30
	v_exp_f32_e32 v28, v28
; __device__ __forceinline__ float rstd_of(float ss, float invn) { return __builtin_amdgcn_rsqf(ss * invn + EPS); }
; __device__ __forceinline__ u32x4 pack8(f32x4 a, f32x4 b) { u32x4 w; w.x = cvtpk(a[0], a[1]); w.y = cvtpk(a[2], a[3]); w.z = cvtpk(b[0], b[1]); w.w = cvtpk(b[2], b[3]); return w; }
;     __device__ __forceinline__ void operator()(const Acc& acc, const Unit& u, int wr, int wc, int fr, int fq) const {
;         float tpre[2][4];
; #pragma unroll
;         for (int ai = 0; ai < 2; ++ai)
; #pragma unroll
;             for (int m = 0; m < 4; ++m) tpre[ai][m] = rs ? rs[u.pm * BM + ai * HALF + wr * 64 + m * 16 + fr] : 0.f;
;         asm volatile("" ::: "memory");
; #pragma unroll
;         for (int ai = 0; ai < 2; ++ai)
; #pragma unroll
;             for (int m = 0; m < 4; ++m) {
;                 const int r = u.pm * BM + ai * HALF + wr * 64 + m * 16 + fr; const float t = rs ? rstd_of(tpre[ai][m], invn) : 1.f;
; #pragma unroll
;                 for (int bj = 0; bj < 2; ++bj) {
;                     const int c0 = u.pn * BM + wc * 64 + bj * 32 + 8 * fq;
;                     f32x4 v0 = acc[ai][bj][m][0] * t, v1 = acc[ai][bj][m][1] * t;
;                     if (sig) { const float tl = -t * 1.4426950408889634f; const f32x4 z0 = acc[ai][bj][m][0] * tl, z1 = acc[ai][bj][m][1] * tl;
; #pragma unroll
;                         for (int j = 0; j < 4; ++j) { v0[j] = __builtin_amdgcn_rcpf(1.f + __builtin_amdgcn_exp2f(z0[j])); v1[j] = __builtin_amdgcn_rcpf(1.f + __builtin_amdgcn_exp2f(z1[j])); } }
;                     *(u32x4*)(O + (size_t)r * ldc + c0) = pack8(v0, v1);
;                 }
;             }
;     }
	v_exp_f32_e32 v29, v29
	v_pk_mul_f32 v[34:35], v[34:35], v[36:37] op_sel_hi:[1,0]
	v_pk_mul_f32 v[32:33], v[32:33], v[36:37] op_sel_hi:[1,0]
	v_add_f32_e32 v28, 1.0, v28
	v_add_f32_e32 v29, 1.0, v29
	v_add_f32_e32 v30, 1.0, v30
	v_exp_f32_e32 v32, v32
	v_rcp_f32_e32 v37, v28
	v_exp_f32_e32 v28, v33
	v_rcp_f32_e32 v33, v29
	v_exp_f32_e32 v29, v34
	v_rcp_f32_e32 v34, v30
	v_exp_f32_e32 v30, v35
	v_exp_f32_e32 v31, v31
	v_add_f32_e32 v32, 1.0, v32
	v_add_f32_e32 v28, 1.0, v28
	v_add_f32_e32 v29, 1.0, v29
	v_add_f32_e32 v30, 1.0, v30
	v_rcp_f32_e32 v32, v32
	v_rcp_f32_e32 v28, v28
	v_rcp_f32_e32 v29, v29
	v_rcp_f32_e32 v30, v30
	v_add_f32_e32 v31, 1.0, v31
	v_pk_mul_f32 v[22:23], v[22:23], v[36:37] op_sel_hi:[1,0]
	v_pk_mul_f32 v[20:21], v[20:21], v[36:37] op_sel_hi:[1,0]
	v_rcp_f32_e32 v31, v31
	v_exp_f32_e32 v20, v20
	v_exp_f32_e32 v21, v21
	v_exp_f32_e32 v22, v22
	v_cvt_pk_bf16_f32 v28, v32, v28
	v_cvt_pk_bf16_f32 v29, v29, v30
	v_cvt_pk_bf16_f32 v30, v37, v33
	v_mad_i64_i32 v[32:33], s[22:23], v144, s24, v[124:125]
	v_cvt_pk_bf16_f32 v31, v34, v31
	v_lshl_add_u64 v[32:33], v[32:33], 0, v[126:127]
	v_pk_mul_f32 v[26:27], v[26:27], v[36:37] op_sel_hi:[1,0]
	v_pk_mul_f32 v[24:25], v[24:25], v[36:37] op_sel_hi:[1,0]
	v_add_f32_e32 v20, 1.0, v20
	v_add_f32_e32 v21, 1.0, v21
	v_add_f32_e32 v22, 1.0, v22
	global_store_dwordx4 v[32:33], v[28:31], off
	v_exp_f32_e32 v24, v24
	v_exp_f32_e32 v23, v23
	v_rcp_f32_e32 v28, v20
	v_exp_f32_e32 v20, v25
	v_rcp_f32_e32 v25, v21
	v_exp_f32_e32 v21, v26
	v_rcp_f32_e32 v26, v22
	v_exp_f32_e32 v22, v27
	v_add_f32_e32 v24, 1.0, v24
	v_add_f32_e32 v20, 1.0, v20
	v_add_f32_e32 v21, 1.0, v21
	v_add_f32_e32 v22, 1.0, v22
	v_add_f32_e32 v23, 1.0, v23
	v_rcp_f32_e32 v24, v24
	v_rcp_f32_e32 v20, v20
	v_rcp_f32_e32 v21, v21
	v_rcp_f32_e32 v22, v22
	v_rcp_f32_e32 v23, v23
	v_cvt_pk_bf16_f32 v20, v24, v20
	v_cvt_pk_bf16_f32 v21, v21, v22
	v_cvt_pk_bf16_f32 v22, v28, v25
	v_cvt_pk_bf16_f32 v23, v26, v23
	global_store_dwordx4 v[32:33], v[20:23], off offset:64
	s_nop 1
	v_fmamk_f32 v20, v143, 0x3a800000, v236
	v_rsq_f32_e32 v20, v20
	s_nop 0
	v_mul_f32_e32 v20, 0xbfb8aa3b, v20
	v_pk_mul_f32 v[14:15], v[14:15], v[20:21] op_sel_hi:[1,0]
	v_pk_mul_f32 v[12:13], v[12:13], v[20:21] op_sel_hi:[1,0]
	v_exp_f32_e32 v14, v14
	v_exp_f32_e32 v12, v12
	v_exp_f32_e32 v13, v13
	v_pk_mul_f32 v[18:19], v[18:19], v[20:21] op_sel_hi:[1,0]
	v_pk_mul_f32 v[16:17], v[16:17], v[20:21] op_sel_hi:[1,0]
	v_add_f32_e32 v12, 1.0, v12
	v_add_f32_e32 v13, 1.0, v13
	v_add_f32_e32 v14, 1.0, v14
	v_exp_f32_e32 v16, v16
	v_rcp_f32_e32 v21, v12
	v_exp_f32_e32 v12, v17
	v_rcp_f32_e32 v17, v13
	v_exp_f32_e32 v13, v18
	v_rcp_f32_e32 v18, v14
	v_exp_f32_e32 v14, v19
	v_exp_f32_e32 v15, v15
	v_add_f32_e32 v16, 1.0, v16
	v_add_f32_e32 v12, 1.0, v12
	v_add_f32_e32 v13, 1.0, v13
	v_add_f32_e32 v14, 1.0, v14
	v_rcp_f32_e32 v16, v16
	v_rcp_f32_e32 v12, v12
	v_rcp_f32_e32 v13, v13
	v_rcp_f32_e32 v14, v14
	v_add_f32_e32 v15, 1.0, v15
	v_pk_mul_f32 v[6:7], v[6:7], v[20:21] op_sel_hi:[1,0]
	v_pk_mul_f32 v[4:5], v[4:5], v[20:21] op_sel_hi:[1,0]
	v_rcp_f32_e32 v15, v15
	v_exp_f32_e32 v4, v4
	v_exp_f32_e32 v5, v5
	v_exp_f32_e32 v6, v6
	v_cvt_pk_bf16_f32 v12, v16, v12
	v_cvt_pk_bf16_f32 v13, v13, v14
	v_cvt_pk_bf16_f32 v14, v21, v17
	v_mad_i64_i32 v[16:17], s[22:23], v142, s24, v[124:125]
	v_cvt_pk_bf16_f32 v15, v18, v15
	v_lshl_add_u64 v[16:17], v[16:17], 0, v[126:127]
	v_pk_mul_f32 v[10:11], v[10:11], v[20:21] op_sel_hi:[1,0]
	v_pk_mul_f32 v[8:9], v[8:9], v[20:21] op_sel_hi:[1,0]
	v_add_f32_e32 v4, 1.0, v4
	v_add_f32_e32 v5, 1.0, v5
	v_add_f32_e32 v6, 1.0, v6
	global_store_dwordx4 v[16:17], v[12:15], off
	v_exp_f32_e32 v8, v8
	v_exp_f32_e32 v7, v7
	v_rcp_f32_e32 v12, v4
	v_exp_f32_e32 v4, v9
	v_rcp_f32_e32 v9, v5
	v_exp_f32_e32 v5, v10
	v_rcp_f32_e32 v10, v6
	v_exp_f32_e32 v6, v11
	v_add_f32_e32 v8, 1.0, v8
	v_add_f32_e32 v4, 1.0, v4
	v_add_f32_e32 v5, 1.0, v5
	v_add_f32_e32 v6, 1.0, v6
	v_add_f32_e32 v7, 1.0, v7
	v_rcp_f32_e32 v8, v8
	v_rcp_f32_e32 v4, v4
	v_rcp_f32_e32 v5, v5
	v_rcp_f32_e32 v6, v6
	v_rcp_f32_e32 v7, v7
	v_cvt_pk_bf16_f32 v4, v8, v4
	s_mov_b64 s[22:23], -1
	v_cvt_pk_bf16_f32 v5, v5, v6
	v_cvt_pk_bf16_f32 v6, v12, v9
	v_cvt_pk_bf16_f32 v7, v10, v7
	global_store_dwordx4 v[16:17], v[4:7], off offset:64
	s_cbranch_vccnz .LBB0_876
	s_andn2_b64 vcc, exec, s[4:5]
	s_cbranch_vccnz .LBB0_875
	s_barrier
	s_branch .LBB0_875

;     __device__ __forceinline__ void operator()(const Acc& acc, const Unit& u, int wr, int wc, int fr, int fq) const {
;         constexpr int MB = PLE ? 2 : 4;
; #pragma unroll
;         for (int ai = 0; ai < 2; ++ai)
; #pragma unroll
;         for (int mb = 0; mb < 4; mb += MB) {
;             f32x4 pa[MB][2], pb[MB][2]; u32x4 pt[MB][2]; float tt[MB];
; #pragma unroll
;             for (int mm = 0; mm < MB; ++mm) {
;                 const int m = mb + mm; const int r = u.pm * BM + ai * HALF + wr * 64 + m * 16 + fr;
;                 tt[mm] = PLE ? rs_in[r] : 0.f;
; #pragma unroll
;                 for (int bj = 0; bj < 2; ++bj) {
;                     const int c0 = u.pn * BM + wc * 64 + bj * 32 + 8 * fq; const float* hs = hsrc + (size_t)r * DM + c0;
;                     pa[mm][bj] = *(const f32x4*)hs; pb[mm][bj] = *(const f32x4*)(hs + 4);
;                     if (PLE) pt[mm][bj] = *(const u32x4*)(tmp + (size_t)r * DM + c0);
;                 }
;             }
; #pragma unroll
;             for (int mm = 0; mm < MB; ++mm) {
;                 const int m = mb + mm; const int r = u.pm * BM + ai * HALF + wr * 64 + m * 16 + fr; float ss = 0.f;
;                 const float t = PLE ? rstd_of(tt[mm], 1.f / 1024.f) : 1.f; const float tl = -t * 1.4426950408889634f; (void)tl;
; #pragma unroll
;                 for (int bj = 0; bj < 2; ++bj) {
;                     const int c0 = u.pn * BM + wc * 64 + bj * 32 + 8 * fq; float* hp = h + (size_t)r * DM + c0;
;                     f32x4 a = pa[mm][bj], b = pb[mm][bj];
;                     if (PLE) { f32x4 ta, tb; unpack8(pt[mm][bj], ta, tb);
; #pragma unroll
;                         for (int j = 0; j < 4; ++j) { a[j] += ta[j] * __builtin_amdgcn_rcpf(1.f + __builtin_amdgcn_exp2f(acc[ai][bj][m][0][j] * tl)); b[j] += tb[j] * __builtin_amdgcn_rcpf(1.f + __builtin_amdgcn_exp2f(acc[ai][bj][m][1][j] * tl)); } }
;                     else { a += acc[ai][bj][m][0] * alpha; b += acc[ai][bj][m][1] * alpha; }
;                     if (!dry || a[0] == 1234.56789f) { *(f32x4*)hp = a; *(f32x4*)(hp + 4) = b;
;                     *(u32x4*)(hb + (size_t)r * DM + c0) = pack8(a, b); }
;                     ss += (a[0] * a[0] + a[1] * a[1]) + (a[2] * a[2] + a[3] * a[3]) + (b[0] * b[0] + b[1] * b[1]) + (b[2] * b[2] + b[3] * b[3]);
;                 }
;                 ss += __shfl_xor(ss, 16); ss += __shfl_xor(ss, 32);
.LBB0_1008:
	v_xor_b32_e32 v132, 16, v238
	v_add_u32_e32 v133, 64, v239
	v_cmp_lt_i32_e32 vcc, v132, v133
	v_lshl_add_u32 v214, s66, 8, v3
	v_lshl_or_b32 v212, s65, 8, v233
	v_cndmask_b32_e32 v132, v238, v132, vcc
	v_lshlrev_b32_e32 v244, 2, v132
	v_xor_b32_e32 v132, 32, v238
	v_cmp_lt_i32_e32 vcc, v132, v133
	v_ashrrev_i32_e32 v215, 31, v214
	v_ashrrev_i32_e32 v213, 31, v212
	v_cndmask_b32_e32 v132, v238, v132, vcc
	v_lshlrev_b32_e32 v243, 2, v132
	v_lshlrev_b64 v[132:133], 12, v[214:215]
	v_lshl_add_u64 v[132:133], s[4:5], 0, v[132:133]
	v_lshlrev_b64 v[216:217], 2, v[212:213]
	v_lshl_add_u64 v[230:231], v[132:133], 0, v[216:217]
	global_load_dwordx4 v[246:249], v[230:231], off offset:16
	global_load_dwordx4 v[196:199], v[230:231], off
	global_load_dwordx4 v[180:183], v[230:231], off offset:144
	global_load_dwordx4 v[184:187], v[230:231], off offset:128
	v_or_b32_e32 v224, 16, v214
	v_ashrrev_i32_e32 v225, 31, v224
	v_lshlrev_b64 v[132:133], 12, v[224:225]
	v_or_b32_e32 v220, 32, v214
	v_lshl_add_u64 v[132:133], s[4:5], 0, v[132:133]
	v_ashrrev_i32_e32 v221, 31, v220
	v_lshl_add_u64 v[226:227], v[132:133], 0, v[216:217]
	v_lshlrev_b64 v[132:133], 12, v[220:221]
	v_lshl_add_u64 v[228:229], s[4:5], 0, v[132:133]
	v_or_b32_e32 v218, 48, v214
	v_lshl_add_u64 v[132:133], v[228:229], 0, v[216:217]
	v_ashrrev_i32_e32 v219, 31, v218
	global_load_dwordx4 v[172:175], v[226:227], off offset:16
	global_load_dwordx4 v[176:179], v[226:227], off
	global_load_dwordx4 v[164:167], v[226:227], off offset:144
	global_load_dwordx4 v[168:171], v[226:227], off offset:128
	global_load_dwordx4 v[156:159], v[132:133], off offset:16
	global_load_dwordx4 v[160:163], v[132:133], off
	global_load_dwordx4 v[140:143], v[132:133], off offset:144
	global_load_dwordx4 v[144:147], v[132:133], off offset:128
	v_lshlrev_b64 v[132:133], 12, v[218:219]
	v_lshl_add_u64 v[222:223], s[4:5], 0, v[132:133]
	v_lshl_add_u64 v[136:137], v[222:223], 0, v[216:217]
	global_load_dwordx4 v[148:151], v[136:137], off offset:16
	global_load_dwordx4 v[152:155], v[136:137], off
	global_load_dwordx4 v[132:135], v[136:137], off offset:144
	s_nop 0
	global_load_dwordx4 v[136:139], v[136:137], off offset:128
	s_waitcnt vmcnt(0)
	v_pk_add_f32 v[126:127], v[126:127], v[248:249]
	v_pk_add_f32 v[130:131], v[130:131], v[198:199]
	v_pk_add_f32 v[128:129], v[128:129], v[196:197]
	v_pk_add_f32 v[124:125], v[124:125], v[246:247]
	global_store_dwordx4 v[230:231], v[128:131], off
	global_store_dwordx4 v[230:231], v[124:127], off offset:16
	v_cvt_pk_bf16_f32 v196, v128, v129
	v_mul_f32_e32 v129, v129, v129
	v_fmac_f32_e32 v129, v128, v128
	v_mul_f32_e32 v128, v131, v131
	v_cvt_pk_bf16_f32 v198, v124, v125
	v_fmac_f32_e32 v128, v130, v130
	v_mul_f32_e32 v125, v125, v125
	v_lshlrev_b64 v[246:247], 11, v[214:215]
	v_add_f32_e32 v128, v129, v128
	v_fmac_f32_e32 v125, v124, v124
	v_lshl_add_u64 v[246:247], s[12:13], 0, v[246:247]
	v_add_f32_e32 v124, v125, v128
	v_mul_f32_e32 v125, v127, v127
	v_cvt_pk_bf16_f32 v197, v130, v131
	v_cvt_pk_bf16_f32 v199, v126, v127
	v_lshl_add_u64 v[246:247], v[212:213], 1, v[246:247]
	v_fmac_f32_e32 v125, v126, v126
	v_pk_add_f32 v[122:123], v[122:123], v[186:187]
	v_pk_add_f32 v[120:121], v[120:121], v[184:185]
	global_store_dwordx4 v[246:247], v[196:199], off
	v_add_f32_e32 v128, v125, v124
	v_pk_add_f32 v[118:119], v[118:119], v[182:183]
	v_pk_add_f32 v[116:117], v[116:117], v[180:181]
	global_store_dwordx4 v[230:231], v[120:123], off offset:128
	global_store_dwordx4 v[230:231], v[116:119], off offset:144
	v_cvt_pk_bf16_f32 v124, v120, v121
	v_mul_f32_e32 v121, v121, v121
	v_fmac_f32_e32 v121, v120, v120
	v_mul_f32_e32 v120, v123, v123
	v_cvt_pk_bf16_f32 v126, v116, v117
	v_fmac_f32_e32 v120, v122, v122
	v_mul_f32_e32 v117, v117, v117
	v_add_f32_e32 v120, v121, v120
	v_fmac_f32_e32 v117, v116, v116
	v_add_f32_e32 v116, v117, v120
	v_mul_f32_e32 v117, v119, v119
	v_fmac_f32_e32 v117, v118, v118
	v_add_f32_e32 v116, v117, v116
	v_add_f32_e32 v116, v128, v116
	ds_bpermute_b32 v117, v244, v116
	v_cvt_pk_bf16_f32 v125, v122, v123
	v_cvt_pk_bf16_f32 v127, v118, v119
	global_store_dwordx4 v[246:247], v[124:127], off offset:64
	s_waitcnt lgkmcnt(0)
	v_add_f32_e32 v116, v116, v117
	ds_bpermute_b32 v117, v243, v116
	s_and_saveexec_b64 s[22:23], s[44:45]
	v_readlane_b32 s68, v252, 32
	v_readlane_b32 s69, v252, 33
	s_cbranch_execz .LBB0_1010
	s_waitcnt lgkmcnt(0)
	v_add_f32_e32 v118, v116, v117
	v_lshl_add_u64 v[116:117], v[214:215], 2, s[6:7]
	global_atomic_add_f32 v[116:117], v118, off
;     __device__ __forceinline__ void operator()(const Acc& acc, const Unit& u, int wr, int wc, int fr, int fq) const {
;         constexpr int MB = PLE ? 2 : 4;
; #pragma unroll
;         for (int ai = 0; ai < 2; ++ai)
; #pragma unroll
;         for (int mb = 0; mb < 4; mb += MB) {
;             f32x4 pa[MB][2], pb[MB][2]; u32x4 pt[MB][2]; float tt[MB];
; #pragma unroll
;             for (int mm = 0; mm < MB; ++mm) {
;                 const int m = mb + mm; const int r = u.pm * BM + ai * HALF + wr * 64 + m * 16 + fr;
;                 tt[mm] = PLE ? rs_in[r] : 0.f;
; #pragma unroll
;                 for (int bj = 0; bj < 2; ++bj) {
;                     const int c0 = u.pn * BM + wc * 64 + bj * 32 + 8 * fq; const float* hs = hsrc + (size_t)r * DM + c0;
;                     pa[mm][bj] = *(const f32x4*)hs; pb[mm][bj] = *(const f32x4*)(hs + 4);
;                     if (PLE) pt[mm][bj] = *(const u32x4*)(tmp + (size_t)r * DM + c0);
;                 }
;             }
; #pragma unroll
;             for (int mm = 0; mm < MB; ++mm) {
;                 const int m = mb + mm; const int r = u.pm * BM + ai * HALF + wr * 64 + m * 16 + fr; float ss = 0.f;
;                 const float t = PLE ? rstd_of(tt[mm], 1.f / 1024.f) : 1.f; const float tl = -t * 1.4426950408889634f; (void)tl;
; #pragma unroll
;                 for (int bj = 0; bj < 2; ++bj) {
;                     const int c0 = u.pn * BM + wc * 64 + bj * 32 + 8 * fq; float* hp = h + (size_t)r * DM + c0;
;                     f32x4 a = pa[mm][bj], b = pb[mm][bj];
;                     if (PLE) { f32x4 ta, tb; unpack8(pt[mm][bj], ta, tb);
; #pragma unroll
;                         for (int j = 0; j < 4; ++j) { a[j] += ta[j] * __builtin_amdgcn_rcpf(1.f + __builtin_amdgcn_exp2f(acc[ai][bj][m][0][j] * tl)); b[j] += tb[j] * __builtin_amdgcn_rcpf(1.f + __builtin_amdgcn_exp2f(acc[ai][bj][m][1][j] * tl)); } }
;                     else { a += acc[ai][bj][m][0] * alpha; b += acc[ai][bj][m][1] * alpha; }
;                     if (!dry || a[0] == 1234.56789f) { *(f32x4*)hp = a; *(f32x4*)(hp + 4) = b;
;                     *(u32x4*)(hb + (size_t)r * DM + c0) = pack8(a, b); }
;                     ss += (a[0] * a[0] + a[1] * a[1]) + (a[2] * a[2] + a[3] * a[3]) + (b[0] * b[0] + b[1] * b[1]) + (b[2] * b[2] + b[3] * b[3]);
;                 }
;                 ss += __shfl_xor(ss, 16); ss += __shfl_xor(ss, 32);
.LBB0_1010:
	s_or_b64 exec, exec, s[22:23]
	v_pk_add_f32 v[114:115], v[114:115], v[178:179]
	v_pk_add_f32 v[112:113], v[112:113], v[176:177]
	v_pk_add_f32 v[110:111], v[110:111], v[174:175]
	v_pk_add_f32 v[108:109], v[108:109], v[172:173]
	global_store_dwordx4 v[226:227], v[112:115], off
	global_store_dwordx4 v[226:227], v[108:111], off offset:16
	v_cvt_pk_bf16_f32 v116, v112, v113
	v_mul_f32_e32 v113, v113, v113
	v_fmac_f32_e32 v113, v112, v112
	v_mul_f32_e32 v112, v115, v115
	v_cvt_pk_bf16_f32 v118, v108, v109
	v_fmac_f32_e32 v112, v114, v114
	v_mul_f32_e32 v109, v109, v109
	v_add_f32_e32 v112, v113, v112
	v_fmac_f32_e32 v109, v108, v108
	v_add_f32_e32 v108, v109, v112
	v_mul_f32_e32 v109, v111, v111
	v_fmac_f32_e32 v109, v110, v110
	v_pk_add_f32 v[106:107], v[106:107], v[170:171]
	v_pk_add_f32 v[104:105], v[104:105], v[168:169]
	v_add_f32_e32 v112, v109, v108
	v_pk_add_f32 v[108:109], v[100:101], v[164:165]
	v_mul_f32_e32 v100, v105, v105
	v_mul_f32_e32 v101, v107, v107
	v_fmac_f32_e32 v100, v104, v104
	v_fmac_f32_e32 v101, v106, v106
	v_add_f32_e32 v100, v100, v101
	v_mul_f32_e32 v101, v109, v109
	v_cvt_pk_bf16_f32 v119, v110, v111
	v_pk_add_f32 v[110:111], v[102:103], v[166:167]
	v_fmac_f32_e32 v101, v108, v108
	v_add_f32_e32 v100, v101, v100
	v_mul_f32_e32 v101, v111, v111
	v_fmac_f32_e32 v101, v110, v110
	v_add_f32_e32 v100, v101, v100
	v_add_f32_e32 v100, v112, v100
	ds_bpermute_b32 v101, v244, v100
	v_lshlrev_b64 v[120:121], 11, v[224:225]
	v_lshl_add_u64 v[120:121], s[12:13], 0, v[120:121]
	s_waitcnt lgkmcnt(1)
	v_cvt_pk_bf16_f32 v117, v114, v115
	v_lshl_add_u64 v[120:121], v[212:213], 1, v[120:121]
	s_waitcnt lgkmcnt(0)
	v_add_f32_e32 v100, v100, v101
	ds_bpermute_b32 v101, v243, v100
	global_store_dwordx4 v[120:121], v[116:119], off
	global_store_dwordx4 v[226:227], v[104:107], off offset:128
	global_store_dwordx4 v[226:227], v[108:111], off offset:144
	v_cvt_pk_bf16_f32 v102, v104, v105
	v_cvt_pk_bf16_f32 v103, v106, v107
	v_cvt_pk_bf16_f32 v104, v108, v109
	v_cvt_pk_bf16_f32 v105, v110, v111
	global_store_dwordx4 v[120:121], v[102:105], off offset:64
	s_and_saveexec_b64 s[22:23], s[44:45]
	s_cbranch_execz .LBB0_1012
	s_waitcnt lgkmcnt(0)
	v_add_f32_e32 v102, v100, v101
	v_lshl_add_u64 v[100:101], v[224:225], 2, s[6:7]
	global_atomic_add_f32 v[100:101], v102, off
.LBB0_1012:
	s_or_b64 exec, exec, s[22:23]
	v_pk_add_f32 v[98:99], v[98:99], v[162:163]
	v_pk_add_f32 v[96:97], v[96:97], v[160:161]
	v_lshl_add_u64 v[104:105], v[212:213], 2, v[228:229]
	v_pk_add_f32 v[94:95], v[94:95], v[158:159]
	v_pk_add_f32 v[92:93], v[92:93], v[156:157]
	global_store_dwordx4 v[104:105], v[96:99], off
	global_store_dwordx4 v[104:105], v[92:95], off offset:16
	v_cvt_pk_bf16_f32 v100, v96, v97
	v_mul_f32_e32 v97, v97, v97
	v_fmac_f32_e32 v97, v96, v96
	v_mul_f32_e32 v96, v99, v99
	v_cvt_pk_bf16_f32 v102, v92, v93
	v_fmac_f32_e32 v96, v98, v98
	v_mul_f32_e32 v93, v93, v93
	v_add_f32_e32 v96, v97, v96
	v_fmac_f32_e32 v93, v92, v92
	v_add_f32_e32 v92, v93, v96
	v_mul_f32_e32 v93, v95, v95
	v_fmac_f32_e32 v93, v94, v94
	v_pk_add_f32 v[90:91], v[90:91], v[146:147]
	v_pk_add_f32 v[88:89], v[88:89], v[144:145]
	v_add_f32_e32 v96, v93, v92
	v_pk_add_f32 v[92:93], v[84:85], v[140:141]
	v_mul_f32_e32 v84, v89, v89
	v_mul_f32_e32 v85, v91, v91
	v_fmac_f32_e32 v84, v88, v88
	v_fmac_f32_e32 v85, v90, v90
	v_add_f32_e32 v84, v84, v85
	v_mul_f32_e32 v85, v93, v93
	v_cvt_pk_bf16_f32 v103, v94, v95
	v_pk_add_f32 v[94:95], v[86:87], v[142:143]
	v_fmac_f32_e32 v85, v92, v92
	v_add_f32_e32 v84, v85, v84
	v_mul_f32_e32 v85, v95, v95
	v_fmac_f32_e32 v85, v94, v94
	v_add_f32_e32 v84, v85, v84
	v_add_f32_e32 v84, v96, v84
	ds_bpermute_b32 v85, v244, v84
	v_lshlrev_b64 v[106:107], 11, v[220:221]
	v_lshl_add_u64 v[106:107], s[12:13], 0, v[106:107]
	s_waitcnt lgkmcnt(1)
	v_cvt_pk_bf16_f32 v101, v98, v99
	v_lshl_add_u64 v[106:107], v[212:213], 1, v[106:107]
	s_waitcnt lgkmcnt(0)
	v_add_f32_e32 v84, v84, v85
	ds_bpermute_b32 v85, v243, v84
	global_store_dwordx4 v[106:107], v[100:103], off
	global_store_dwordx4 v[104:105], v[88:91], off offset:128
	global_store_dwordx4 v[104:105], v[92:95], off offset:144
	v_cvt_pk_bf16_f32 v86, v88, v89
	v_cvt_pk_bf16_f32 v87, v90, v91
	v_cvt_pk_bf16_f32 v88, v92, v93
	v_cvt_pk_bf16_f32 v89, v94, v95
	global_store_dwordx4 v[106:107], v[86:89], off offset:64
	s_and_saveexec_b64 s[22:23], s[44:45]
	s_cbranch_execz .LBB0_1014
	s_waitcnt lgkmcnt(0)
	v_add_f32_e32 v86, v84, v85
	v_lshl_add_u64 v[84:85], v[220:221], 2, s[6:7]
	global_atomic_add_f32 v[84:85], v86, off
.LBB0_1014:
	s_or_b64 exec, exec, s[22:23]
	v_pk_add_f32 v[82:83], v[82:83], v[154:155]
	v_pk_add_f32 v[80:81], v[80:81], v[152:153]
	v_lshl_add_u64 v[88:89], v[212:213], 2, v[222:223]
	v_pk_add_f32 v[78:79], v[78:79], v[150:151]
	v_pk_add_f32 v[76:77], v[76:77], v[148:149]
	global_store_dwordx4 v[88:89], v[80:83], off
	global_store_dwordx4 v[88:89], v[76:79], off offset:16
	v_cvt_pk_bf16_f32 v84, v80, v81
	v_mul_f32_e32 v81, v81, v81
	v_fmac_f32_e32 v81, v80, v80
	v_mul_f32_e32 v80, v83, v83
	v_cvt_pk_bf16_f32 v86, v76, v77
	v_fmac_f32_e32 v80, v82, v82
	v_mul_f32_e32 v77, v77, v77
	v_add_f32_e32 v80, v81, v80
	v_fmac_f32_e32 v77, v76, v76
	v_add_f32_e32 v76, v77, v80
	v_mul_f32_e32 v77, v79, v79
	v_fmac_f32_e32 v77, v78, v78
	v_pk_add_f32 v[74:75], v[74:75], v[138:139]
	v_pk_add_f32 v[72:73], v[72:73], v[136:137]
	v_add_f32_e32 v80, v77, v76
	v_pk_add_f32 v[76:77], v[68:69], v[132:133]
	v_mul_f32_e32 v68, v73, v73
	v_mul_f32_e32 v69, v75, v75
	v_fmac_f32_e32 v68, v72, v72
	v_fmac_f32_e32 v69, v74, v74
	v_add_f32_e32 v68, v68, v69
	v_mul_f32_e32 v69, v77, v77
	v_cvt_pk_bf16_f32 v87, v78, v79
	v_pk_add_f32 v[78:79], v[70:71], v[134:135]
	v_fmac_f32_e32 v69, v76, v76
	v_add_f32_e32 v68, v69, v68
	v_mul_f32_e32 v69, v79, v79
	v_fmac_f32_e32 v69, v78, v78
	v_add_f32_e32 v68, v69, v68
	v_add_f32_e32 v68, v80, v68
	ds_bpermute_b32 v69, v244, v68
	v_lshlrev_b64 v[90:91], 11, v[218:219]
	v_lshl_add_u64 v[90:91], s[12:13], 0, v[90:91]
	s_waitcnt lgkmcnt(1)
	v_cvt_pk_bf16_f32 v85, v82, v83
	v_lshl_add_u64 v[90:91], v[212:213], 1, v[90:91]
	s_waitcnt lgkmcnt(0)
	v_add_f32_e32 v68, v68, v69
	ds_bpermute_b32 v69, v243, v68
	global_store_dwordx4 v[90:91], v[84:87], off
	global_store_dwordx4 v[88:89], v[72:75], off offset:128
	global_store_dwordx4 v[88:89], v[76:79], off offset:144
	v_cvt_pk_bf16_f32 v70, v72, v73
	v_cvt_pk_bf16_f32 v71, v74, v75
	v_cvt_pk_bf16_f32 v72, v76, v77
	v_cvt_pk_bf16_f32 v73, v78, v79
	global_store_dwordx4 v[90:91], v[70:73], off offset:64
	s_and_saveexec_b64 s[22:23], s[44:45]
	s_cbranch_execz .LBB0_1016
	s_waitcnt lgkmcnt(0)
	v_add_f32_e32 v70, v68, v69
	v_lshl_add_u64 v[68:69], v[218:219], 2, s[6:7]
	global_atomic_add_f32 v[68:69], v70, off
;     __device__ __forceinline__ void operator()(const Acc& acc, const Unit& u, int wr, int wc, int fr, int fq) const {
;         constexpr int MB = PLE ? 2 : 4;
; #pragma unroll
;         for (int ai = 0; ai < 2; ++ai)
; #pragma unroll
;         for (int mb = 0; mb < 4; mb += MB) {
;             f32x4 pa[MB][2], pb[MB][2]; u32x4 pt[MB][2]; float tt[MB];
; #pragma unroll
;             for (int mm = 0; mm < MB; ++mm) {
;                 const int m = mb + mm; const int r = u.pm * BM + ai * HALF + wr * 64 + m * 16 + fr;
;                 tt[mm] = PLE ? rs_in[r] : 0.f;
; #pragma unroll
;                 for (int bj = 0; bj < 2; ++bj) {
;                     const int c0 = u.pn * BM + wc * 64 + bj * 32 + 8 * fq; const float* hs = hsrc + (size_t)r * DM + c0;
;                     pa[mm][bj] = *(const f32x4*)hs; pb[mm][bj] = *(const f32x4*)(hs + 4);
;                     if (PLE) pt[mm][bj] = *(const u32x4*)(tmp + (size_t)r * DM + c0);
;                 }
;             }
; #pragma unroll
;             for (int mm = 0; mm < MB; ++mm) {
;                 const int m = mb + mm; const int r = u.pm * BM + ai * HALF + wr * 64 + m * 16 + fr; float ss = 0.f;
;                 const float t = PLE ? rstd_of(tt[mm], 1.f / 1024.f) : 1.f; const float tl = -t * 1.4426950408889634f; (void)tl;
; #pragma unroll
;                 for (int bj = 0; bj < 2; ++bj) {
;                     const int c0 = u.pn * BM + wc * 64 + bj * 32 + 8 * fq; float* hp = h + (size_t)r * DM + c0;
;                     f32x4 a = pa[mm][bj], b = pb[mm][bj];
;                     if (PLE) { f32x4 ta, tb; unpack8(pt[mm][bj], ta, tb);
; #pragma unroll
;                         for (int j = 0; j < 4; ++j) { a[j] += ta[j] * __builtin_amdgcn_rcpf(1.f + __builtin_amdgcn_exp2f(acc[ai][bj][m][0][j] * tl)); b[j] += tb[j] * __builtin_amdgcn_rcpf(1.f + __builtin_amdgcn_exp2f(acc[ai][bj][m][1][j] * tl)); } }
;                     else { a += acc[ai][bj][m][0] * alpha; b += acc[ai][bj][m][1] * alpha; }
;                     if (!dry || a[0] == 1234.56789f) { *(f32x4*)hp = a; *(f32x4*)(hp + 4) = b;
;                     *(u32x4*)(hb + (size_t)r * DM + c0) = pack8(a, b); }
;                     ss += (a[0] * a[0] + a[1] * a[1]) + (a[2] * a[2] + a[3] * a[3]) + (b[0] * b[0] + b[1] * b[1]) + (b[2] * b[2] + b[3] * b[3]);
;                 }
;                 ss += __shfl_xor(ss, 16); ss += __shfl_xor(ss, 32);
.LBB0_1016:
	s_or_b64 exec, exec, s[22:23]
	v_add_u32_e32 v136, 0x80, v214
	v_ashrrev_i32_e32 v137, 31, v136
	s_waitcnt lgkmcnt(0)
	v_lshlrev_b64 v[68:69], 12, v[136:137]
	v_lshl_add_u64 v[68:69], s[4:5], 0, v[68:69]
	v_lshl_add_u64 v[138:139], v[68:69], 0, v[216:217]
	global_load_dwordx4 v[140:143], v[138:139], off offset:16
	global_load_dwordx4 v[144:147], v[138:139], off
	global_load_dwordx4 v[116:119], v[138:139], off offset:144
	global_load_dwordx4 v[120:123], v[138:139], off offset:128
	v_add_u32_e32 v130, 0x90, v214
	v_ashrrev_i32_e32 v131, 31, v130
	v_lshlrev_b64 v[68:69], 12, v[130:131]
	v_add_u32_e32 v126, 0xa0, v214
	v_lshl_add_u64 v[68:69], s[4:5], 0, v[68:69]
	v_ashrrev_i32_e32 v127, 31, v126
	v_lshl_add_u64 v[132:133], v[68:69], 0, v[216:217]
	v_lshlrev_b64 v[68:69], 12, v[126:127]
	v_lshl_add_u64 v[134:135], s[4:5], 0, v[68:69]
	v_add_u32_e32 v124, 0xb0, v214
	v_lshl_add_u64 v[68:69], v[134:135], 0, v[216:217]
	v_ashrrev_i32_e32 v125, 31, v124
	global_load_dwordx4 v[108:111], v[132:133], off offset:16
	global_load_dwordx4 v[112:115], v[132:133], off
	global_load_dwordx4 v[100:103], v[132:133], off offset:144
	global_load_dwordx4 v[104:107], v[132:133], off offset:128
	global_load_dwordx4 v[92:95], v[68:69], off offset:16
	global_load_dwordx4 v[96:99], v[68:69], off
	global_load_dwordx4 v[76:79], v[68:69], off offset:144
	global_load_dwordx4 v[80:83], v[68:69], off offset:128
	v_lshlrev_b64 v[68:69], 12, v[124:125]
	v_lshl_add_u64 v[128:129], s[4:5], 0, v[68:69]
	v_lshl_add_u64 v[72:73], v[128:129], 0, v[216:217]
	global_load_dwordx4 v[84:87], v[72:73], off offset:16
	global_load_dwordx4 v[88:91], v[72:73], off
	global_load_dwordx4 v[68:71], v[72:73], off offset:144
	s_nop 0
	global_load_dwordx4 v[72:75], v[72:73], off offset:128
	s_waitcnt vmcnt(15)
	v_pk_add_f32 v[62:63], v[62:63], v[142:143]
	s_waitcnt vmcnt(14)
	v_pk_add_f32 v[66:67], v[66:67], v[146:147]
	v_pk_add_f32 v[64:65], v[64:65], v[144:145]
	v_pk_add_f32 v[60:61], v[60:61], v[140:141]
	global_store_dwordx4 v[138:139], v[64:67], off
	global_store_dwordx4 v[138:139], v[60:63], off offset:16
	v_cvt_pk_bf16_f32 v140, v64, v65
	v_mul_f32_e32 v65, v65, v65
	v_fmac_f32_e32 v65, v64, v64
	v_mul_f32_e32 v64, v67, v67
	v_cvt_pk_bf16_f32 v142, v60, v61
	v_fmac_f32_e32 v64, v66, v66
	v_mul_f32_e32 v61, v61, v61
	v_lshlrev_b64 v[144:145], 11, v[136:137]
	v_add_f32_e32 v64, v65, v64
	v_fmac_f32_e32 v61, v60, v60
	v_lshl_add_u64 v[144:145], s[12:13], 0, v[144:145]
	v_add_f32_e32 v60, v61, v64
	v_mul_f32_e32 v61, v63, v63
	v_cvt_pk_bf16_f32 v141, v66, v67
	v_cvt_pk_bf16_f32 v143, v62, v63
	v_lshl_add_u64 v[144:145], v[212:213], 1, v[144:145]
	v_fmac_f32_e32 v61, v62, v62
	s_waitcnt vmcnt(14)
	v_pk_add_f32 v[58:59], v[58:59], v[122:123]
	v_pk_add_f32 v[56:57], v[56:57], v[120:121]
	global_store_dwordx4 v[144:145], v[140:143], off
	v_add_f32_e32 v64, v61, v60
	v_pk_add_f32 v[54:55], v[54:55], v[118:119]
	v_pk_add_f32 v[52:53], v[52:53], v[116:117]
	global_store_dwordx4 v[138:139], v[56:59], off offset:128
	global_store_dwordx4 v[138:139], v[52:55], off offset:144
	v_cvt_pk_bf16_f32 v60, v56, v57
	v_mul_f32_e32 v57, v57, v57
	v_fmac_f32_e32 v57, v56, v56
	v_mul_f32_e32 v56, v59, v59
	v_cvt_pk_bf16_f32 v62, v52, v53
	v_fmac_f32_e32 v56, v58, v58
	v_mul_f32_e32 v53, v53, v53
	v_add_f32_e32 v56, v57, v56
	v_fmac_f32_e32 v53, v52, v52
	v_add_f32_e32 v52, v53, v56
	v_mul_f32_e32 v53, v55, v55
	v_fmac_f32_e32 v53, v54, v54
	v_add_f32_e32 v52, v53, v52
	v_add_f32_e32 v52, v64, v52
	ds_bpermute_b32 v53, v244, v52
	v_cvt_pk_bf16_f32 v61, v58, v59
	v_cvt_pk_bf16_f32 v63, v54, v55
	global_store_dwordx4 v[144:145], v[60:63], off offset:64
	s_waitcnt lgkmcnt(0)
	v_add_f32_e32 v52, v52, v53
	ds_bpermute_b32 v53, v243, v52
	s_and_saveexec_b64 s[22:23], s[44:45]
	s_cbranch_execz .LBB0_1018
	s_waitcnt lgkmcnt(0)
	v_add_f32_e32 v54, v52, v53
	v_lshl_add_u64 v[52:53], v[136:137], 2, s[6:7]
	global_atomic_add_f32 v[52:53], v54, off
.LBB0_1018:
	s_or_b64 exec, exec, s[22:23]
	s_waitcnt vmcnt(16)
	v_pk_add_f32 v[50:51], v[50:51], v[114:115]
	v_pk_add_f32 v[48:49], v[48:49], v[112:113]
	v_pk_add_f32 v[46:47], v[46:47], v[110:111]
	v_pk_add_f32 v[44:45], v[44:45], v[108:109]
	global_store_dwordx4 v[132:133], v[48:51], off
	global_store_dwordx4 v[132:133], v[44:47], off offset:16
	v_cvt_pk_bf16_f32 v52, v48, v49
	v_mul_f32_e32 v49, v49, v49
	v_fmac_f32_e32 v49, v48, v48
	v_mul_f32_e32 v48, v51, v51
	v_cvt_pk_bf16_f32 v54, v44, v45
	v_fmac_f32_e32 v48, v50, v50
	v_mul_f32_e32 v45, v45, v45
	v_add_f32_e32 v48, v49, v48
	v_fmac_f32_e32 v45, v44, v44
	v_add_f32_e32 v44, v45, v48
	v_mul_f32_e32 v45, v47, v47
	v_fmac_f32_e32 v45, v46, v46
	s_waitcnt vmcnt(16)
	v_pk_add_f32 v[42:43], v[42:43], v[106:107]
	v_pk_add_f32 v[40:41], v[40:41], v[104:105]
	v_add_f32_e32 v48, v45, v44
	v_pk_add_f32 v[44:45], v[36:37], v[100:101]
	v_mul_f32_e32 v36, v41, v41
	v_mul_f32_e32 v37, v43, v43
	v_fmac_f32_e32 v36, v40, v40
	v_fmac_f32_e32 v37, v42, v42
	v_add_f32_e32 v36, v36, v37
	v_mul_f32_e32 v37, v45, v45
	v_cvt_pk_bf16_f32 v55, v46, v47
	v_pk_add_f32 v[46:47], v[38:39], v[102:103]
	v_fmac_f32_e32 v37, v44, v44
	v_add_f32_e32 v36, v37, v36
	v_mul_f32_e32 v37, v47, v47
	v_fmac_f32_e32 v37, v46, v46
	v_add_f32_e32 v36, v37, v36
	v_add_f32_e32 v36, v48, v36
	ds_bpermute_b32 v37, v244, v36
	v_lshlrev_b64 v[56:57], 11, v[130:131]
	v_lshl_add_u64 v[56:57], s[12:13], 0, v[56:57]
	s_waitcnt lgkmcnt(1)
	v_cvt_pk_bf16_f32 v53, v50, v51
	v_lshl_add_u64 v[56:57], v[212:213], 1, v[56:57]
	s_waitcnt lgkmcnt(0)
	v_add_f32_e32 v36, v36, v37
	ds_bpermute_b32 v37, v243, v36
	global_store_dwordx4 v[56:57], v[52:55], off
	global_store_dwordx4 v[132:133], v[40:43], off offset:128
	global_store_dwordx4 v[132:133], v[44:47], off offset:144
	v_cvt_pk_bf16_f32 v38, v40, v41
	v_cvt_pk_bf16_f32 v39, v42, v43
	v_cvt_pk_bf16_f32 v40, v44, v45
	v_cvt_pk_bf16_f32 v41, v46, v47
	global_store_dwordx4 v[56:57], v[38:41], off offset:64
	s_and_saveexec_b64 s[22:23], s[44:45]
	s_cbranch_execz .LBB0_1020
	s_waitcnt lgkmcnt(0)
	v_add_f32_e32 v38, v36, v37
	v_lshl_add_u64 v[36:37], v[130:131], 2, s[6:7]
	global_atomic_add_f32 v[36:37], v38, off
;     __device__ __forceinline__ void operator()(const Acc& acc, const Unit& u, int wr, int wc, int fr, int fq) const {
;         constexpr int MB = PLE ? 2 : 4;
; #pragma unroll
;         for (int ai = 0; ai < 2; ++ai)
; #pragma unroll
;         for (int mb = 0; mb < 4; mb += MB) {
;             f32x4 pa[MB][2], pb[MB][2]; u32x4 pt[MB][2]; float tt[MB];
; #pragma unroll
;             for (int mm = 0; mm < MB; ++mm) {
;                 const int m = mb + mm; const int r = u.pm * BM + ai * HALF + wr * 64 + m * 16 + fr;
;                 tt[mm] = PLE ? rs_in[r] : 0.f;
; #pragma unroll
;                 for (int bj = 0; bj < 2; ++bj) {
;                     const int c0 = u.pn * BM + wc * 64 + bj * 32 + 8 * fq; const float* hs = hsrc + (size_t)r * DM + c0;
;                     pa[mm][bj] = *(const f32x4*)hs; pb[mm][bj] = *(const f32x4*)(hs + 4);
;                     if (PLE) pt[mm][bj] = *(const u32x4*)(tmp + (size_t)r * DM + c0);
;                 }
;             }
; #pragma unroll
;             for (int mm = 0; mm < MB; ++mm) {
;                 const int m = mb + mm; const int r = u.pm * BM + ai * HALF + wr * 64 + m * 16 + fr; float ss = 0.f;
;                 const float t = PLE ? rstd_of(tt[mm], 1.f / 1024.f) : 1.f; const float tl = -t * 1.4426950408889634f; (void)tl;
; #pragma unroll
;                 for (int bj = 0; bj < 2; ++bj) {
;                     const int c0 = u.pn * BM + wc * 64 + bj * 32 + 8 * fq; float* hp = h + (size_t)r * DM + c0;
;                     f32x4 a = pa[mm][bj], b = pb[mm][bj];
;                     if (PLE) { f32x4 ta, tb; unpack8(pt[mm][bj], ta, tb);
; #pragma unroll
;                         for (int j = 0; j < 4; ++j) { a[j] += ta[j] * __builtin_amdgcn_rcpf(1.f + __builtin_amdgcn_exp2f(acc[ai][bj][m][0][j] * tl)); b[j] += tb[j] * __builtin_amdgcn_rcpf(1.f + __builtin_amdgcn_exp2f(acc[ai][bj][m][1][j] * tl)); } }
;                     else { a += acc[ai][bj][m][0] * alpha; b += acc[ai][bj][m][1] * alpha; }
;                     if (!dry || a[0] == 1234.56789f) { *(f32x4*)hp = a; *(f32x4*)(hp + 4) = b;
;                     *(u32x4*)(hb + (size_t)r * DM + c0) = pack8(a, b); }
;                     ss += (a[0] * a[0] + a[1] * a[1]) + (a[2] * a[2] + a[3] * a[3]) + (b[0] * b[0] + b[1] * b[1]) + (b[2] * b[2] + b[3] * b[3]);
;                 }
;                 ss += __shfl_xor(ss, 16); ss += __shfl_xor(ss, 32);
.LBB0_1020:
	s_or_b64 exec, exec, s[22:23]
	s_waitcnt vmcnt(18)
	v_pk_add_f32 v[34:35], v[34:35], v[98:99]
	v_pk_add_f32 v[32:33], v[32:33], v[96:97]
	v_lshl_add_u64 v[40:41], v[212:213], 2, v[134:135]
	v_pk_add_f32 v[30:31], v[30:31], v[94:95]
	v_pk_add_f32 v[28:29], v[28:29], v[92:93]
	global_store_dwordx4 v[40:41], v[32:35], off
	global_store_dwordx4 v[40:41], v[28:31], off offset:16
	v_cvt_pk_bf16_f32 v36, v32, v33
	v_mul_f32_e32 v33, v33, v33
	v_fmac_f32_e32 v33, v32, v32
	v_mul_f32_e32 v32, v35, v35
	v_cvt_pk_bf16_f32 v38, v28, v29
	v_fmac_f32_e32 v32, v34, v34
	v_mul_f32_e32 v29, v29, v29
	v_add_f32_e32 v32, v33, v32
	v_fmac_f32_e32 v29, v28, v28
	v_add_f32_e32 v28, v29, v32
	v_mul_f32_e32 v29, v31, v31
	v_fmac_f32_e32 v29, v30, v30
	s_waitcnt vmcnt(18)
	v_pk_add_f32 v[26:27], v[26:27], v[82:83]
	v_pk_add_f32 v[24:25], v[24:25], v[80:81]
	v_add_f32_e32 v32, v29, v28
	v_pk_add_f32 v[28:29], v[20:21], v[76:77]
	v_mul_f32_e32 v20, v25, v25
	v_mul_f32_e32 v21, v27, v27
	v_fmac_f32_e32 v20, v24, v24
	v_fmac_f32_e32 v21, v26, v26
	v_add_f32_e32 v20, v20, v21
	v_mul_f32_e32 v21, v29, v29
	v_cvt_pk_bf16_f32 v39, v30, v31
	v_pk_add_f32 v[30:31], v[22:23], v[78:79]
	v_fmac_f32_e32 v21, v28, v28
	v_add_f32_e32 v20, v21, v20
	v_mul_f32_e32 v21, v31, v31
	v_fmac_f32_e32 v21, v30, v30
	v_add_f32_e32 v20, v21, v20
	v_add_f32_e32 v20, v32, v20
	ds_bpermute_b32 v21, v244, v20
	v_lshlrev_b64 v[42:43], 11, v[126:127]
	v_lshl_add_u64 v[42:43], s[12:13], 0, v[42:43]
	s_waitcnt lgkmcnt(1)
	v_cvt_pk_bf16_f32 v37, v34, v35
	v_lshl_add_u64 v[42:43], v[212:213], 1, v[42:43]
	s_waitcnt lgkmcnt(0)
	v_add_f32_e32 v20, v20, v21
	ds_bpermute_b32 v21, v243, v20
	global_store_dwordx4 v[42:43], v[36:39], off
	global_store_dwordx4 v[40:41], v[24:27], off offset:128
	global_store_dwordx4 v[40:41], v[28:31], off offset:144
	v_cvt_pk_bf16_f32 v22, v24, v25
	v_cvt_pk_bf16_f32 v23, v26, v27
	v_cvt_pk_bf16_f32 v24, v28, v29
	v_cvt_pk_bf16_f32 v25, v30, v31
	global_store_dwordx4 v[42:43], v[22:25], off offset:64
	s_and_saveexec_b64 s[22:23], s[44:45]
	s_cbranch_execz .LBB0_1022
	s_waitcnt lgkmcnt(0)
	v_add_f32_e32 v22, v20, v21
	v_lshl_add_u64 v[20:21], v[126:127], 2, s[6:7]
	global_atomic_add_f32 v[20:21], v22, off
.LBB0_1022:
	s_or_b64 exec, exec, s[22:23]
	s_waitcnt vmcnt(20)
	v_pk_add_f32 v[18:19], v[18:19], v[90:91]
	v_pk_add_f32 v[16:17], v[16:17], v[88:89]
	v_lshl_add_u64 v[24:25], v[212:213], 2, v[128:129]
	v_pk_add_f32 v[14:15], v[14:15], v[86:87]
	v_pk_add_f32 v[12:13], v[12:13], v[84:85]
	global_store_dwordx4 v[24:25], v[16:19], off
	global_store_dwordx4 v[24:25], v[12:15], off offset:16
	v_cvt_pk_bf16_f32 v20, v16, v17
	v_mul_f32_e32 v17, v17, v17
	v_fmac_f32_e32 v17, v16, v16
	v_mul_f32_e32 v16, v19, v19
	v_cvt_pk_bf16_f32 v22, v12, v13
	v_fmac_f32_e32 v16, v18, v18
	v_mul_f32_e32 v13, v13, v13
	v_add_f32_e32 v16, v17, v16
	v_fmac_f32_e32 v13, v12, v12
	v_add_f32_e32 v12, v13, v16
	v_mul_f32_e32 v13, v15, v15
	v_fmac_f32_e32 v13, v14, v14
	s_waitcnt vmcnt(20)
	v_pk_add_f32 v[10:11], v[10:11], v[74:75]
	v_pk_add_f32 v[8:9], v[8:9], v[72:73]
	v_add_f32_e32 v16, v13, v12
	v_pk_add_f32 v[12:13], v[4:5], v[68:69]
	v_mul_f32_e32 v4, v9, v9
	v_mul_f32_e32 v5, v11, v11
	v_fmac_f32_e32 v4, v8, v8
	v_fmac_f32_e32 v5, v10, v10
	v_add_f32_e32 v4, v4, v5
	v_mul_f32_e32 v5, v13, v13
	v_cvt_pk_bf16_f32 v23, v14, v15
	v_pk_add_f32 v[14:15], v[6:7], v[70:71]
	v_fmac_f32_e32 v5, v12, v12
	v_add_f32_e32 v4, v5, v4
	v_mul_f32_e32 v5, v15, v15
	v_fmac_f32_e32 v5, v14, v14
	v_add_f32_e32 v4, v5, v4
	v_add_f32_e32 v4, v16, v4
	ds_bpermute_b32 v5, v244, v4
	v_lshlrev_b64 v[26:27], 11, v[124:125]
	v_lshl_add_u64 v[26:27], s[12:13], 0, v[26:27]
	s_waitcnt lgkmcnt(1)
	v_cvt_pk_bf16_f32 v21, v18, v19
	v_lshl_add_u64 v[26:27], v[212:213], 1, v[26:27]
	s_waitcnt lgkmcnt(0)
	v_add_f32_e32 v4, v4, v5
	ds_bpermute_b32 v5, v243, v4
	global_store_dwordx4 v[26:27], v[20:23], off
	global_store_dwordx4 v[24:25], v[8:11], off offset:128
	global_store_dwordx4 v[24:25], v[12:15], off offset:144
	v_cvt_pk_bf16_f32 v6, v8, v9
	v_cvt_pk_bf16_f32 v7, v10, v11
	v_cvt_pk_bf16_f32 v8, v12, v13
	v_cvt_pk_bf16_f32 v9, v14, v15
	global_store_dwordx4 v[26:27], v[6:9], off offset:64
	s_and_saveexec_b64 s[22:23], s[44:45]
	s_cbranch_execz .LBB0_1024
	s_waitcnt lgkmcnt(0)
	v_add_f32_e32 v6, v4, v5
	v_lshl_add_u64 v[4:5], v[124:125], 2, s[6:7]
	global_atomic_add_f32 v[4:5], v6, off

; __device__ __forceinline__ float rstd_of(float ss, float invn) { return __builtin_amdgcn_rsqf(ss * invn + EPS); }
; __device__ __forceinline__ u32x4 pack8(f32x4 a, f32x4 b) { u32x4 w; w.x = cvtpk(a[0], a[1]); w.y = cvtpk(a[2], a[3]); w.z = cvtpk(b[0], b[1]); w.w = cvtpk(b[2], b[3]); return w; }
;     __device__ __forceinline__ void operator()(const Acc& acc, const Unit& u, int wr, int wc, int fr, int fq) const {
;         const int col0 = u.pn * 128 + wc * 32 + 8 * fq;
;         float tpre[2][4];
; #pragma unroll
;         for (int ai = 0; ai < 2; ++ai)
; #pragma unroll
;             for (int m = 0; m < 4; ++m) tpre[ai][m] = rs[u.pm * BM + ai * HALF + wr * 64 + m * 16 + fr];
;         asm volatile("" ::: "memory");
; #pragma unroll
;         for (int ai = 0; ai < 2; ++ai)
; #pragma unroll
;             for (int m = 0; m < 4; ++m) {
;                 const int r = u.pm * BM + ai * HALF + wr * 64 + m * 16 + fr; const float t = rstd_of(tpre[ai][m], 1.f / 1024.f);
;                 const float tl = -t * 1.4426950408889634f, t2 = t * t;
;                 f32x4 o0, o1;
; #pragma unroll
;                 for (int n = 0; n < 2; ++n)
; #pragma unroll
;                     for (int jj = 0; jj < 2; ++jj) {
;                         const f32x2_t g = {acc[ai][0][m][n][2 * jj], acc[ai][0][m][n][2 * jj + 1]}, uu = {acc[ai][1][m][n][2 * jj], acc[ai][1][m][n][2 * jj + 1]};
;                         const f32x2_t z = g * tl; f32x2_t e; e.x = __builtin_amdgcn_exp2f(z.x); e.y = __builtin_amdgcn_exp2f(z.y);
;                         const f32x2_t d = e + 1.0f; f32x2_t rr; rr.x = __builtin_amdgcn_rcpf(d.x); rr.y = __builtin_amdgcn_rcpf(d.y);
;                         const f32x2_t o = (g * uu) * (rr * t2);
;                         if (n == 0) { o0[2 * jj] = o.x; o0[2 * jj + 1] = o.y; } else { o1[2 * jj] = o.x; o1[2 * jj + 1] = o.y; }
;                     }
;                 *(u32x4*)(H + (size_t)r * FF + col0) = pack8(o0, o1);
;             }
;     }
.LBB0_1091:
	v_lshl_add_u32 v156, s62, 8, v3
	v_ashrrev_i32_e32 v157, 31, v156
	v_lshl_add_u64 v[142:143], v[156:157], 2, s[10:11]
	global_load_dword v157, v[142:143], off
	v_or_b32_e32 v154, 16, v156
	v_ashrrev_i32_e32 v155, 31, v154
	v_lshl_add_u64 v[142:143], v[154:155], 2, s[10:11]
	global_load_dword v155, v[142:143], off
	v_or_b32_e32 v152, 32, v156
	v_ashrrev_i32_e32 v153, 31, v152
	v_lshl_add_u64 v[142:143], v[152:153], 2, s[10:11]
	global_load_dword v153, v[142:143], off
	v_pk_mul_f32 v[116:117], v[120:121], v[116:117]
	v_pk_mul_f32 v[124:125], v[128:129], v[124:125]
	v_or_b32_e32 v150, 48, v156
	v_ashrrev_i32_e32 v151, 31, v150
	v_lshl_add_u64 v[142:143], v[150:151], 2, s[10:11]
	global_load_dword v151, v[142:143], off
	v_add_u32_e32 v148, 0x80, v156
	v_ashrrev_i32_e32 v149, 31, v148
	v_add_u32_e32 v146, 0x90, v156
	v_lshl_add_u64 v[142:143], v[148:149], 2, s[10:11]
	v_ashrrev_i32_e32 v147, 31, v146
	v_add_u32_e32 v144, 0xa0, v156
	global_load_dword v149, v[142:143], off
	v_lshl_add_u64 v[142:143], v[146:147], 2, s[10:11]
	v_ashrrev_i32_e32 v145, 31, v144
	global_load_dword v147, v[142:143], off
	v_lshl_add_u64 v[142:143], v[144:145], 2, s[10:11]
	global_load_dword v145, v[142:143], off
	v_add_u32_e32 v142, 0xb0, v156
	v_ashrrev_i32_e32 v143, 31, v142
	v_lshl_add_u64 v[162:163], v[142:143], 2, s[10:11]
	global_load_dword v143, v[162:163], off
	v_lshl_or_b32 v162, s61, 7, v159
	v_pk_mul_f32 v[118:119], v[122:123], v[118:119]
	v_ashrrev_i32_e32 v163, 31, v162
	v_pk_mul_f32 v[126:127], v[130:131], v[126:127]
	v_pk_mul_f32 v[104:105], v[100:101], v[104:105]
	v_pk_mul_f32 v[114:115], v[110:111], v[114:115]
	v_pk_mul_f32 v[112:113], v[108:109], v[112:113]
	v_pk_mul_f32 v[106:107], v[102:103], v[106:107]
	v_pk_mul_f32 v[88:89], v[84:85], v[88:89]
	v_pk_mul_f32 v[98:99], v[94:95], v[98:99]
	v_pk_mul_f32 v[96:97], v[92:93], v[96:97]
	v_pk_mul_f32 v[90:91], v[86:87], v[90:91]
	v_pk_mul_f32 v[72:73], v[68:69], v[72:73]
	v_pk_mul_f32 v[82:83], v[78:79], v[82:83]
	v_pk_mul_f32 v[80:81], v[76:77], v[80:81]
	v_pk_mul_f32 v[74:75], v[70:71], v[74:75]
	v_pk_mul_f32 v[56:57], v[52:53], v[56:57]
	v_pk_mul_f32 v[66:67], v[62:63], v[66:67]
	v_pk_mul_f32 v[64:65], v[60:61], v[64:65]
	v_pk_mul_f32 v[58:59], v[54:55], v[58:59]
	v_pk_mul_f32 v[40:41], v[36:37], v[40:41]
	v_pk_mul_f32 v[50:51], v[46:47], v[50:51]
	v_pk_mul_f32 v[48:49], v[44:45], v[48:49]
	v_pk_mul_f32 v[42:43], v[38:39], v[42:43]
	v_pk_mul_f32 v[24:25], v[20:21], v[24:25]
	v_pk_mul_f32 v[34:35], v[30:31], v[34:35]
	v_pk_mul_f32 v[32:33], v[28:29], v[32:33]
	v_pk_mul_f32 v[26:27], v[22:23], v[26:27]
	v_pk_mul_f32 v[18:19], v[14:15], v[18:19]
	v_pk_mul_f32 v[16:17], v[12:13], v[16:17]
	v_pk_mul_f32 v[10:11], v[6:7], v[10:11]
	v_pk_mul_f32 v[8:9], v[4:5], v[8:9]
	v_readlane_b32 s64, v252, 28
	v_readlane_b32 s66, v252, 30
	v_readlane_b32 s68, v252, 32
	s_andn2_b64 vcc, exec, s[40:41]
	v_readlane_b32 s65, v252, 29
	v_readlane_b32 s67, v252, 31
	v_readlane_b32 s69, v252, 33
	s_waitcnt vmcnt(0)
	v_fmamk_f32 v157, v157, 0x3a800000, v236
	v_rsq_f32_e32 v157, v157
	s_nop 0
	v_mul_f32_e32 v164, 0xbfb8aa3b, v157
	v_pk_mul_f32 v[120:121], v[120:121], v[164:165] op_sel_hi:[1,0]
	v_pk_mul_f32 v[128:129], v[128:129], v[164:165] op_sel_hi:[1,0]
	v_exp_f32_e32 v120, v120
	v_exp_f32_e32 v121, v121
	v_exp_f32_e32 v128, v128
	v_exp_f32_e32 v129, v129
	v_mul_f32_e32 v166, v157, v157
	v_pk_add_f32 v[120:121], v[120:121], 1.0 op_sel_hi:[1,0]
	v_pk_add_f32 v[128:129], v[128:129], 1.0 op_sel_hi:[1,0]
	v_rcp_f32_e32 v120, v120
	v_rcp_f32_e32 v121, v121
	v_rcp_f32_e32 v128, v128
	v_rcp_f32_e32 v129, v129
	v_pk_mul_f32 v[120:121], v[166:167], v[120:121] op_sel_hi:[0,1]
	v_pk_mul_f32 v[116:117], v[116:117], v[120:121]
	v_pk_mul_f32 v[128:129], v[166:167], v[128:129] op_sel_hi:[0,1]
	v_pk_mul_f32 v[120:121], v[122:123], v[164:165] op_sel_hi:[1,0]
	v_pk_mul_f32 v[124:125], v[124:125], v[128:129]
	v_pk_mul_f32 v[128:129], v[130:131], v[164:165] op_sel_hi:[1,0]
	v_exp_f32_e32 v120, v120
	v_exp_f32_e32 v121, v121
	v_exp_f32_e32 v128, v128
	v_exp_f32_e32 v129, v129
	v_cvt_pk_bf16_f32 v122, v116, v117
	v_pk_add_f32 v[120:121], v[120:121], 1.0 op_sel_hi:[1,0]
	v_mov_b64_e32 v[116:117], s[8:9]
	v_pk_add_f32 v[128:129], v[128:129], 1.0 op_sel_hi:[1,0]
	v_rcp_f32_e32 v120, v120
	v_rcp_f32_e32 v121, v121
	v_rcp_f32_e32 v128, v128
	v_rcp_f32_e32 v129, v129
	v_pk_mul_f32 v[120:121], v[166:167], v[120:121] op_sel_hi:[0,1]
	v_pk_mul_f32 v[118:119], v[118:119], v[120:121]
	v_pk_mul_f32 v[128:129], v[166:167], v[128:129] op_sel_hi:[0,1]
	v_pk_mul_f32 v[126:127], v[126:127], v[128:129]
	v_cvt_pk_bf16_f32 v120, v124, v125
	v_cvt_pk_bf16_f32 v123, v118, v119
	v_mad_i64_i32 v[124:125], s[22:23], v156, s0, v[116:117]
	v_lshlrev_b64 v[118:119], 1, v[162:163]
	v_cvt_pk_bf16_f32 v121, v126, v127
	v_lshl_add_u64 v[124:125], v[124:125], 0, v[118:119]
	global_store_dwordx4 v[124:125], v[120:123], off
	s_nop 1
	v_fmamk_f32 v120, v155, 0x3a800000, v236
	v_rsq_f32_e32 v120, v120
	s_nop 0
	v_mul_f32_e32 v122, 0xbfb8aa3b, v120
	v_pk_mul_f32 v[100:101], v[100:101], v[122:123] op_sel_hi:[1,0]
	v_mul_f32_e32 v120, v120, v120
	v_exp_f32_e32 v100, v100
	v_exp_f32_e32 v101, v101
	v_pk_mul_f32 v[108:109], v[108:109], v[122:123] op_sel_hi:[1,0]
	v_pk_mul_f32 v[110:111], v[110:111], v[122:123] op_sel_hi:[1,0]
	v_exp_f32_e32 v108, v108
	v_pk_add_f32 v[100:101], v[100:101], 1.0 op_sel_hi:[1,0]
	v_exp_f32_e32 v109, v109
	v_rcp_f32_e32 v100, v100
	v_rcp_f32_e32 v101, v101
	v_exp_f32_e32 v110, v110
	v_exp_f32_e32 v111, v111
	v_pk_add_f32 v[108:109], v[108:109], 1.0 op_sel_hi:[1,0]
	v_pk_mul_f32 v[100:101], v[120:121], v[100:101] op_sel_hi:[0,1]
; __device__ __forceinline__ float rstd_of(float ss, float invn) { return __builtin_amdgcn_rsqf(ss * invn + EPS); }
; __device__ __forceinline__ u32x4 pack8(f32x4 a, f32x4 b) { u32x4 w; w.x = cvtpk(a[0], a[1]); w.y = cvtpk(a[2], a[3]); w.z = cvtpk(b[0], b[1]); w.w = cvtpk(b[2], b[3]); return w; }
;     __device__ __forceinline__ void operator()(const Acc& acc, const Unit& u, int wr, int wc, int fr, int fq) const {
;         const int col0 = u.pn * 128 + wc * 32 + 8 * fq;
;         float tpre[2][4];
; #pragma unroll
;         for (int ai = 0; ai < 2; ++ai)
; #pragma unroll
;             for (int m = 0; m < 4; ++m) tpre[ai][m] = rs[u.pm * BM + ai * HALF + wr * 64 + m * 16 + fr];
;         asm volatile("" ::: "memory");
; #pragma unroll
;         for (int ai = 0; ai < 2; ++ai)
; #pragma unroll
;             for (int m = 0; m < 4; ++m) {
;                 const int r = u.pm * BM + ai * HALF + wr * 64 + m * 16 + fr; const float t = rstd_of(tpre[ai][m], 1.f / 1024.f);
;                 const float tl = -t * 1.4426950408889634f, t2 = t * t;
;                 f32x4 o0, o1;
; #pragma unroll
;                 for (int n = 0; n < 2; ++n)
; #pragma unroll
;                     for (int jj = 0; jj < 2; ++jj) {
;                         const f32x2_t g = {acc[ai][0][m][n][2 * jj], acc[ai][0][m][n][2 * jj + 1]}, uu = {acc[ai][1][m][n][2 * jj], acc[ai][1][m][n][2 * jj + 1]};
;                         const f32x2_t z = g * tl; f32x2_t e; e.x = __builtin_amdgcn_exp2f(z.x); e.y = __builtin_amdgcn_exp2f(z.y);
;                         const f32x2_t d = e + 1.0f; f32x2_t rr; rr.x = __builtin_amdgcn_rcpf(d.x); rr.y = __builtin_amdgcn_rcpf(d.y);
;                         const f32x2_t o = (g * uu) * (rr * t2);
;                         if (n == 0) { o0[2 * jj] = o.x; o0[2 * jj + 1] = o.y; } else { o1[2 * jj] = o.x; o1[2 * jj + 1] = o.y; }
;                     }
;                 *(u32x4*)(H + (size_t)r * FF + col0) = pack8(o0, o1);
;             }
;     }
	v_pk_mul_f32 v[104:105], v[104:105], v[100:101]
	v_pk_mul_f32 v[100:101], v[102:103], v[122:123] op_sel_hi:[1,0]
	v_pk_add_f32 v[110:111], v[110:111], 1.0 op_sel_hi:[1,0]
	v_exp_f32_e32 v100, v100
	v_exp_f32_e32 v101, v101
	v_rcp_f32_e32 v108, v108
	v_rcp_f32_e32 v109, v109
	v_rcp_f32_e32 v110, v110
	v_pk_add_f32 v[100:101], v[100:101], 1.0 op_sel_hi:[1,0]
	v_rcp_f32_e32 v111, v111
	v_rcp_f32_e32 v100, v100
	v_rcp_f32_e32 v101, v101
	v_pk_mul_f32 v[108:109], v[120:121], v[108:109] op_sel_hi:[0,1]
	v_pk_mul_f32 v[110:111], v[120:121], v[110:111] op_sel_hi:[0,1]
	v_pk_mul_f32 v[108:109], v[112:113], v[108:109]
	v_pk_mul_f32 v[100:101], v[120:121], v[100:101] op_sel_hi:[0,1]
	v_pk_mul_f32 v[110:111], v[114:115], v[110:111]
	v_pk_mul_f32 v[106:107], v[106:107], v[100:101]
	v_cvt_pk_bf16_f32 v102, v104, v105
	v_mad_i64_i32 v[104:105], s[22:23], v154, s0, v[116:117]
	v_cvt_pk_bf16_f32 v100, v108, v109
	v_cvt_pk_bf16_f32 v101, v110, v111
	v_cvt_pk_bf16_f32 v103, v106, v107
	v_lshl_add_u64 v[104:105], v[104:105], 0, v[118:119]
	global_store_dwordx4 v[104:105], v[100:103], off
	s_nop 1
	v_fmamk_f32 v100, v153, 0x3a800000, v236
	v_rsq_f32_e32 v101, v100
	s_nop 0
	v_mul_f32_e32 v100, 0xbfb8aa3b, v101
	v_pk_mul_f32 v[84:85], v[84:85], v[100:101] op_sel_hi:[1,0]
	v_mul_f32_e32 v102, v101, v101
	v_exp_f32_e32 v84, v84
	v_exp_f32_e32 v85, v85
	v_pk_mul_f32 v[92:93], v[92:93], v[100:101] op_sel_hi:[1,0]
	v_pk_mul_f32 v[94:95], v[94:95], v[100:101] op_sel_hi:[1,0]
	v_exp_f32_e32 v92, v92
	v_pk_add_f32 v[84:85], v[84:85], 1.0 op_sel_hi:[1,0]
	v_exp_f32_e32 v93, v93
	v_rcp_f32_e32 v84, v84
	v_rcp_f32_e32 v85, v85
	v_exp_f32_e32 v94, v94
	v_exp_f32_e32 v95, v95
	v_pk_add_f32 v[92:93], v[92:93], 1.0 op_sel_hi:[1,0]
	v_pk_mul_f32 v[84:85], v[102:103], v[84:85] op_sel_hi:[0,1]
	v_pk_mul_f32 v[88:89], v[88:89], v[84:85]
	v_pk_mul_f32 v[84:85], v[86:87], v[100:101] op_sel_hi:[1,0]
	v_pk_add_f32 v[94:95], v[94:95], 1.0 op_sel_hi:[1,0]
	v_exp_f32_e32 v84, v84
	v_exp_f32_e32 v85, v85
	v_rcp_f32_e32 v92, v92
	v_rcp_f32_e32 v93, v93
	v_rcp_f32_e32 v94, v94
	v_pk_add_f32 v[84:85], v[84:85], 1.0 op_sel_hi:[1,0]
	v_rcp_f32_e32 v95, v95
	v_rcp_f32_e32 v84, v84
	v_rcp_f32_e32 v85, v85
	v_pk_mul_f32 v[92:93], v[102:103], v[92:93] op_sel_hi:[0,1]
	v_pk_mul_f32 v[94:95], v[102:103], v[94:95] op_sel_hi:[0,1]
	v_pk_mul_f32 v[92:93], v[96:97], v[92:93]
	v_pk_mul_f32 v[84:85], v[102:103], v[84:85] op_sel_hi:[0,1]
	v_pk_mul_f32 v[94:95], v[98:99], v[94:95]
	v_pk_mul_f32 v[90:91], v[90:91], v[84:85]
	v_cvt_pk_bf16_f32 v86, v88, v89
	v_mad_i64_i32 v[88:89], s[22:23], v152, s0, v[116:117]
	v_cvt_pk_bf16_f32 v84, v92, v93
	v_cvt_pk_bf16_f32 v85, v94, v95
	v_cvt_pk_bf16_f32 v87, v90, v91
	v_lshl_add_u64 v[88:89], v[88:89], 0, v[118:119]
	global_store_dwordx4 v[88:89], v[84:87], off
	s_nop 1
	v_fmamk_f32 v84, v151, 0x3a800000, v236
	v_rsq_f32_e32 v85, v84
	s_nop 0
	v_mul_f32_e32 v84, 0xbfb8aa3b, v85
	v_pk_mul_f32 v[68:69], v[68:69], v[84:85] op_sel_hi:[1,0]
	v_mul_f32_e32 v86, v85, v85
	v_exp_f32_e32 v68, v68
	v_exp_f32_e32 v69, v69
	v_pk_mul_f32 v[76:77], v[76:77], v[84:85] op_sel_hi:[1,0]
	v_pk_mul_f32 v[78:79], v[78:79], v[84:85] op_sel_hi:[1,0]
	v_exp_f32_e32 v76, v76
	v_pk_add_f32 v[68:69], v[68:69], 1.0 op_sel_hi:[1,0]
	v_exp_f32_e32 v77, v77
	v_rcp_f32_e32 v68, v68
	v_rcp_f32_e32 v69, v69
	v_exp_f32_e32 v78, v78
	v_exp_f32_e32 v79, v79
	v_pk_add_f32 v[76:77], v[76:77], 1.0 op_sel_hi:[1,0]
	v_pk_mul_f32 v[68:69], v[86:87], v[68:69] op_sel_hi:[0,1]
	v_pk_mul_f32 v[72:73], v[72:73], v[68:69]
	v_pk_mul_f32 v[68:69], v[70:71], v[84:85] op_sel_hi:[1,0]
	v_pk_add_f32 v[78:79], v[78:79], 1.0 op_sel_hi:[1,0]
	v_exp_f32_e32 v68, v68
	v_exp_f32_e32 v69, v69
	v_rcp_f32_e32 v76, v76
	v_rcp_f32_e32 v77, v77
	v_rcp_f32_e32 v78, v78
	v_pk_add_f32 v[68:69], v[68:69], 1.0 op_sel_hi:[1,0]
	v_rcp_f32_e32 v79, v79
	v_rcp_f32_e32 v68, v68
	v_rcp_f32_e32 v69, v69
	v_pk_mul_f32 v[76:77], v[86:87], v[76:77] op_sel_hi:[0,1]
	v_pk_mul_f32 v[78:79], v[86:87], v[78:79] op_sel_hi:[0,1]
	v_pk_mul_f32 v[76:77], v[80:81], v[76:77]
	v_pk_mul_f32 v[68:69], v[86:87], v[68:69] op_sel_hi:[0,1]
	v_pk_mul_f32 v[78:79], v[82:83], v[78:79]
	v_pk_mul_f32 v[74:75], v[74:75], v[68:69]
	v_cvt_pk_bf16_f32 v70, v72, v73
	v_mad_i64_i32 v[72:73], s[22:23], v150, s0, v[116:117]
	v_cvt_pk_bf16_f32 v68, v76, v77
	v_cvt_pk_bf16_f32 v69, v78, v79
	v_cvt_pk_bf16_f32 v71, v74, v75
	v_lshl_add_u64 v[72:73], v[72:73], 0, v[118:119]
	global_store_dwordx4 v[72:73], v[68:71], off
	s_nop 1
	v_fmamk_f32 v68, v149, 0x3a800000, v236
	v_rsq_f32_e32 v69, v68
	s_nop 0
	v_mul_f32_e32 v68, 0xbfb8aa3b, v69
	v_pk_mul_f32 v[52:53], v[52:53], v[68:69] op_sel_hi:[1,0]
	v_mul_f32_e32 v70, v69, v69
	v_exp_f32_e32 v52, v52
	v_exp_f32_e32 v53, v53
	v_pk_mul_f32 v[60:61], v[60:61], v[68:69] op_sel_hi:[1,0]
	v_pk_mul_f32 v[62:63], v[62:63], v[68:69] op_sel_hi:[1,0]
	v_exp_f32_e32 v60, v60
	v_pk_add_f32 v[52:53], v[52:53], 1.0 op_sel_hi:[1,0]
	v_exp_f32_e32 v61, v61
	v_rcp_f32_e32 v52, v52
	v_rcp_f32_e32 v53, v53
	v_exp_f32_e32 v62, v62
	v_exp_f32_e32 v63, v63
	v_pk_add_f32 v[60:61], v[60:61], 1.0 op_sel_hi:[1,0]
	v_pk_mul_f32 v[52:53], v[70:71], v[52:53] op_sel_hi:[0,1]
	v_pk_mul_f32 v[56:57], v[56:57], v[52:53]
	v_pk_mul_f32 v[52:53], v[54:55], v[68:69] op_sel_hi:[1,0]
	v_pk_add_f32 v[62:63], v[62:63], 1.0 op_sel_hi:[1,0]
	v_exp_f32_e32 v52, v52
	v_exp_f32_e32 v53, v53
	v_rcp_f32_e32 v60, v60
	v_rcp_f32_e32 v61, v61
	v_rcp_f32_e32 v62, v62
	v_pk_add_f32 v[52:53], v[52:53], 1.0 op_sel_hi:[1,0]
	v_rcp_f32_e32 v63, v63
	v_rcp_f32_e32 v52, v52
	v_rcp_f32_e32 v53, v53
	v_pk_mul_f32 v[60:61], v[70:71], v[60:61] op_sel_hi:[0,1]
; __device__ __forceinline__ float rstd_of(float ss, float invn) { return __builtin_amdgcn_rsqf(ss * invn + EPS); }
; __device__ __forceinline__ u32x4 pack8(f32x4 a, f32x4 b) { u32x4 w; w.x = cvtpk(a[0], a[1]); w.y = cvtpk(a[2], a[3]); w.z = cvtpk(b[0], b[1]); w.w = cvtpk(b[2], b[3]); return w; }
;     __device__ __forceinline__ void operator()(const Acc& acc, const Unit& u, int wr, int wc, int fr, int fq) const {
;         const int col0 = u.pn * 128 + wc * 32 + 8 * fq;
;         float tpre[2][4];
; #pragma unroll
;         for (int ai = 0; ai < 2; ++ai)
; #pragma unroll
;             for (int m = 0; m < 4; ++m) tpre[ai][m] = rs[u.pm * BM + ai * HALF + wr * 64 + m * 16 + fr];
;         asm volatile("" ::: "memory");
; #pragma unroll
;         for (int ai = 0; ai < 2; ++ai)
; #pragma unroll
;             for (int m = 0; m < 4; ++m) {
;                 const int r = u.pm * BM + ai * HALF + wr * 64 + m * 16 + fr; const float t = rstd_of(tpre[ai][m], 1.f / 1024.f);
;                 const float tl = -t * 1.4426950408889634f, t2 = t * t;
;                 f32x4 o0, o1;
; #pragma unroll
;                 for (int n = 0; n < 2; ++n)
; #pragma unroll
;                     for (int jj = 0; jj < 2; ++jj) {
;                         const f32x2_t g = {acc[ai][0][m][n][2 * jj], acc[ai][0][m][n][2 * jj + 1]}, uu = {acc[ai][1][m][n][2 * jj], acc[ai][1][m][n][2 * jj + 1]};
;                         const f32x2_t z = g * tl; f32x2_t e; e.x = __builtin_amdgcn_exp2f(z.x); e.y = __builtin_amdgcn_exp2f(z.y);
;                         const f32x2_t d = e + 1.0f; f32x2_t rr; rr.x = __builtin_amdgcn_rcpf(d.x); rr.y = __builtin_amdgcn_rcpf(d.y);
;                         const f32x2_t o = (g * uu) * (rr * t2);
;                         if (n == 0) { o0[2 * jj] = o.x; o0[2 * jj + 1] = o.y; } else { o1[2 * jj] = o.x; o1[2 * jj + 1] = o.y; }
;                     }
;                 *(u32x4*)(H + (size_t)r * FF + col0) = pack8(o0, o1);
;             }
;     }
	v_pk_mul_f32 v[62:63], v[70:71], v[62:63] op_sel_hi:[0,1]
	v_pk_mul_f32 v[60:61], v[64:65], v[60:61]
	v_pk_mul_f32 v[52:53], v[70:71], v[52:53] op_sel_hi:[0,1]
	v_pk_mul_f32 v[62:63], v[66:67], v[62:63]
	v_pk_mul_f32 v[58:59], v[58:59], v[52:53]
	v_cvt_pk_bf16_f32 v54, v56, v57
	v_mad_i64_i32 v[56:57], s[22:23], v148, s0, v[116:117]
	v_cvt_pk_bf16_f32 v52, v60, v61
	v_cvt_pk_bf16_f32 v53, v62, v63
	v_cvt_pk_bf16_f32 v55, v58, v59
	v_lshl_add_u64 v[56:57], v[56:57], 0, v[118:119]
	global_store_dwordx4 v[56:57], v[52:55], off
	s_nop 1
	v_fmamk_f32 v52, v147, 0x3a800000, v236
	v_rsq_f32_e32 v53, v52
	s_nop 0
	v_mul_f32_e32 v52, 0xbfb8aa3b, v53
	v_pk_mul_f32 v[36:37], v[36:37], v[52:53] op_sel_hi:[1,0]
	v_mul_f32_e32 v54, v53, v53
	v_exp_f32_e32 v36, v36
	v_exp_f32_e32 v37, v37
	v_pk_mul_f32 v[44:45], v[44:45], v[52:53] op_sel_hi:[1,0]
	v_pk_mul_f32 v[46:47], v[46:47], v[52:53] op_sel_hi:[1,0]
	v_exp_f32_e32 v44, v44
	v_pk_add_f32 v[36:37], v[36:37], 1.0 op_sel_hi:[1,0]
	v_exp_f32_e32 v45, v45
	v_rcp_f32_e32 v36, v36
	v_rcp_f32_e32 v37, v37
	v_exp_f32_e32 v46, v46
	v_exp_f32_e32 v47, v47
	v_pk_add_f32 v[44:45], v[44:45], 1.0 op_sel_hi:[1,0]
	v_pk_mul_f32 v[36:37], v[54:55], v[36:37] op_sel_hi:[0,1]
	v_pk_mul_f32 v[40:41], v[40:41], v[36:37]
	v_pk_mul_f32 v[36:37], v[38:39], v[52:53] op_sel_hi:[1,0]
	v_pk_add_f32 v[46:47], v[46:47], 1.0 op_sel_hi:[1,0]
	v_exp_f32_e32 v36, v36
	v_exp_f32_e32 v37, v37
	v_rcp_f32_e32 v44, v44
	v_rcp_f32_e32 v45, v45
	v_rcp_f32_e32 v46, v46
	v_pk_add_f32 v[36:37], v[36:37], 1.0 op_sel_hi:[1,0]
	v_rcp_f32_e32 v47, v47
	v_rcp_f32_e32 v36, v36
	v_rcp_f32_e32 v37, v37
	v_pk_mul_f32 v[44:45], v[54:55], v[44:45] op_sel_hi:[0,1]
	v_pk_mul_f32 v[46:47], v[54:55], v[46:47] op_sel_hi:[0,1]
	v_pk_mul_f32 v[44:45], v[48:49], v[44:45]
	v_pk_mul_f32 v[36:37], v[54:55], v[36:37] op_sel_hi:[0,1]
	v_pk_mul_f32 v[46:47], v[50:51], v[46:47]
	v_pk_mul_f32 v[42:43], v[42:43], v[36:37]
	v_cvt_pk_bf16_f32 v38, v40, v41
	v_mad_i64_i32 v[40:41], s[22:23], v146, s0, v[116:117]
	v_cvt_pk_bf16_f32 v36, v44, v45
	v_cvt_pk_bf16_f32 v37, v46, v47
	v_cvt_pk_bf16_f32 v39, v42, v43
	v_lshl_add_u64 v[40:41], v[40:41], 0, v[118:119]
	global_store_dwordx4 v[40:41], v[36:39], off
	s_nop 1
	v_fmamk_f32 v36, v145, 0x3a800000, v236
	v_rsq_f32_e32 v37, v36
	s_nop 0
	v_mul_f32_e32 v36, 0xbfb8aa3b, v37
	v_pk_mul_f32 v[20:21], v[20:21], v[36:37] op_sel_hi:[1,0]
	v_mul_f32_e32 v38, v37, v37
	v_exp_f32_e32 v20, v20
	v_exp_f32_e32 v21, v21
	v_pk_mul_f32 v[28:29], v[28:29], v[36:37] op_sel_hi:[1,0]
	v_pk_mul_f32 v[30:31], v[30:31], v[36:37] op_sel_hi:[1,0]
	v_exp_f32_e32 v28, v28
	v_pk_add_f32 v[20:21], v[20:21], 1.0 op_sel_hi:[1,0]
	v_exp_f32_e32 v29, v29
	v_rcp_f32_e32 v20, v20
	v_rcp_f32_e32 v21, v21
	v_exp_f32_e32 v30, v30
	v_exp_f32_e32 v31, v31
	v_pk_add_f32 v[28:29], v[28:29], 1.0 op_sel_hi:[1,0]
	v_pk_mul_f32 v[20:21], v[38:39], v[20:21] op_sel_hi:[0,1]
	v_pk_mul_f32 v[24:25], v[24:25], v[20:21]
	v_pk_mul_f32 v[20:21], v[22:23], v[36:37] op_sel_hi:[1,0]
	v_pk_add_f32 v[30:31], v[30:31], 1.0 op_sel_hi:[1,0]
	v_exp_f32_e32 v20, v20
	v_exp_f32_e32 v21, v21
	v_rcp_f32_e32 v28, v28
	v_rcp_f32_e32 v29, v29
	v_rcp_f32_e32 v30, v30
	v_pk_add_f32 v[20:21], v[20:21], 1.0 op_sel_hi:[1,0]
	v_rcp_f32_e32 v31, v31
	v_rcp_f32_e32 v20, v20
	v_rcp_f32_e32 v21, v21
	v_pk_mul_f32 v[28:29], v[38:39], v[28:29] op_sel_hi:[0,1]
	v_pk_mul_f32 v[30:31], v[38:39], v[30:31] op_sel_hi:[0,1]
	v_pk_mul_f32 v[28:29], v[32:33], v[28:29]
	v_pk_mul_f32 v[20:21], v[38:39], v[20:21] op_sel_hi:[0,1]
	v_pk_mul_f32 v[30:31], v[34:35], v[30:31]
	v_pk_mul_f32 v[26:27], v[26:27], v[20:21]
	v_cvt_pk_bf16_f32 v22, v24, v25
	v_mad_i64_i32 v[24:25], s[22:23], v144, s0, v[116:117]
	v_cvt_pk_bf16_f32 v20, v28, v29
	v_cvt_pk_bf16_f32 v21, v30, v31
	v_cvt_pk_bf16_f32 v23, v26, v27
	v_lshl_add_u64 v[24:25], v[24:25], 0, v[118:119]
	global_store_dwordx4 v[24:25], v[20:23], off
	s_nop 1
	v_fmamk_f32 v20, v143, 0x3a800000, v236
	v_rsq_f32_e32 v21, v20
	s_nop 0
	v_mul_f32_e32 v22, 0xbfb8aa3b, v21
	v_pk_mul_f32 v[14:15], v[14:15], v[22:23] op_sel_hi:[1,0]
	v_pk_mul_f32 v[12:13], v[12:13], v[22:23] op_sel_hi:[1,0]
	v_pk_mul_f32 v[6:7], v[6:7], v[22:23] op_sel_hi:[1,0]
	v_pk_mul_f32 v[4:5], v[4:5], v[22:23] op_sel_hi:[1,0]
	v_exp_f32_e32 v14, v14
	v_exp_f32_e32 v15, v15
	v_exp_f32_e32 v12, v12
	v_exp_f32_e32 v13, v13
	v_exp_f32_e32 v6, v6
	v_exp_f32_e32 v7, v7
	v_exp_f32_e32 v4, v4
	v_exp_f32_e32 v5, v5
	v_pk_add_f32 v[14:15], v[14:15], 1.0 op_sel_hi:[1,0]
	v_pk_add_f32 v[12:13], v[12:13], 1.0 op_sel_hi:[1,0]
	v_pk_add_f32 v[6:7], v[6:7], 1.0 op_sel_hi:[1,0]
	v_pk_add_f32 v[4:5], v[4:5], 1.0 op_sel_hi:[1,0]
	v_rcp_f32_e32 v14, v14
	v_rcp_f32_e32 v15, v15
	v_rcp_f32_e32 v12, v12
	v_rcp_f32_e32 v13, v13
	v_rcp_f32_e32 v6, v6
	v_rcp_f32_e32 v7, v7
	v_rcp_f32_e32 v4, v4
	v_rcp_f32_e32 v5, v5
	v_mul_f32_e32 v20, v21, v21
	v_pk_mul_f32 v[14:15], v[20:21], v[14:15] op_sel_hi:[0,1]
	v_pk_mul_f32 v[12:13], v[20:21], v[12:13] op_sel_hi:[0,1]
	v_pk_mul_f32 v[6:7], v[20:21], v[6:7] op_sel_hi:[0,1]
	v_pk_mul_f32 v[4:5], v[20:21], v[4:5] op_sel_hi:[0,1]
	v_pk_mul_f32 v[14:15], v[18:19], v[14:15]
	v_pk_mul_f32 v[12:13], v[16:17], v[12:13]
	v_pk_mul_f32 v[6:7], v[10:11], v[6:7]
	v_pk_mul_f32 v[4:5], v[8:9], v[4:5]
	v_mad_i64_i32 v[8:9], s[22:23], v142, s0, v[116:117]
	v_cvt_pk_bf16_f32 v4, v4, v5
	v_cvt_pk_bf16_f32 v5, v6, v7
	v_cvt_pk_bf16_f32 v6, v12, v13
	v_cvt_pk_bf16_f32 v7, v14, v15
	v_lshl_add_u64 v[8:9], v[8:9], 0, v[118:119]
	s_mov_b64 s[22:23], -1
	global_store_dwordx4 v[8:9], v[4:7], off
	s_cbranch_vccnz .LBB0_1084
	s_andn2_b64 vcc, exec, s[6:7]
	s_cbranch_vccnz .LBB0_1083
	s_barrier
	s_branch .LBB0_1083

;     __device__ __forceinline__ void operator()(const Acc& acc, const Unit& u, int wr, int wc, int fr, int fq) const {
;         constexpr int MB = PLE ? 2 : 4;
; #pragma unroll
;         for (int ai = 0; ai < 2; ++ai)
; #pragma unroll
;         for (int mb = 0; mb < 4; mb += MB) {
;             f32x4 pa[MB][2], pb[MB][2]; u32x4 pt[MB][2]; float tt[MB];
; #pragma unroll
;             for (int mm = 0; mm < MB; ++mm) {
;                 const int m = mb + mm; const int r = u.pm * BM + ai * HALF + wr * 64 + m * 16 + fr;
;                 tt[mm] = PLE ? rs_in[r] : 0.f;
; #pragma unroll
;                 for (int bj = 0; bj < 2; ++bj) {
;                     const int c0 = u.pn * BM + wc * 64 + bj * 32 + 8 * fq; const float* hs = hsrc + (size_t)r * DM + c0;
;                     pa[mm][bj] = *(const f32x4*)hs; pb[mm][bj] = *(const f32x4*)(hs + 4);
;                     if (PLE) pt[mm][bj] = *(const u32x4*)(tmp + (size_t)r * DM + c0);
;                 }
;             }
; #pragma unroll
;             for (int mm = 0; mm < MB; ++mm) {
;                 const int m = mb + mm; const int r = u.pm * BM + ai * HALF + wr * 64 + m * 16 + fr; float ss = 0.f;
;                 const float t = PLE ? rstd_of(tt[mm], 1.f / 1024.f) : 1.f; const float tl = -t * 1.4426950408889634f; (void)tl;
; #pragma unroll
;                 for (int bj = 0; bj < 2; ++bj) {
;                     const int c0 = u.pn * BM + wc * 64 + bj * 32 + 8 * fq; float* hp = h + (size_t)r * DM + c0;
;                     f32x4 a = pa[mm][bj], b = pb[mm][bj];
;                     if (PLE) { f32x4 ta, tb; unpack8(pt[mm][bj], ta, tb);
; #pragma unroll
;                         for (int j = 0; j < 4; ++j) { a[j] += ta[j] * __builtin_amdgcn_rcpf(1.f + __builtin_amdgcn_exp2f(acc[ai][bj][m][0][j] * tl)); b[j] += tb[j] * __builtin_amdgcn_rcpf(1.f + __builtin_amdgcn_exp2f(acc[ai][bj][m][1][j] * tl)); } }
;                     else { a += acc[ai][bj][m][0] * alpha; b += acc[ai][bj][m][1] * alpha; }
;                     if (!dry || a[0] == 1234.56789f) { *(f32x4*)hp = a; *(f32x4*)(hp + 4) = b;
;                     *(u32x4*)(hb + (size_t)r * DM + c0) = pack8(a, b); }
;                     ss += (a[0] * a[0] + a[1] * a[1]) + (a[2] * a[2] + a[3] * a[3]) + (b[0] * b[0] + b[1] * b[1]) + (b[2] * b[2] + b[3] * b[3]);
;                 }
;                 ss += __shfl_xor(ss, 16); ss += __shfl_xor(ss, 32);
.LBB0_1166:
	v_xor_b32_e32 v132, 16, v238
	v_add_u32_e32 v133, 64, v239
	v_cmp_lt_i32_e32 vcc, v132, v133
	v_lshl_add_u32 v214, s66, 8, v3
	v_lshl_or_b32 v212, s65, 8, v233
	v_cndmask_b32_e32 v132, v238, v132, vcc
	v_lshlrev_b32_e32 v244, 2, v132
	v_xor_b32_e32 v132, 32, v238
	v_cmp_lt_i32_e32 vcc, v132, v133
	v_ashrrev_i32_e32 v215, 31, v214
	v_ashrrev_i32_e32 v213, 31, v212
	v_cndmask_b32_e32 v132, v238, v132, vcc
	v_lshlrev_b32_e32 v243, 2, v132
	v_lshlrev_b64 v[132:133], 12, v[214:215]
	v_lshl_add_u64 v[132:133], s[8:9], 0, v[132:133]
	v_lshlrev_b64 v[216:217], 2, v[212:213]
	v_lshl_add_u64 v[230:231], v[132:133], 0, v[216:217]
	global_load_dwordx4 v[196:199], v[230:231], off offset:16
	global_load_dwordx4 v[246:249], v[230:231], off
	global_load_dwordx4 v[180:183], v[230:231], off offset:144
	global_load_dwordx4 v[184:187], v[230:231], off offset:128
	v_or_b32_e32 v224, 16, v214
	v_ashrrev_i32_e32 v225, 31, v224
	v_lshlrev_b64 v[132:133], 12, v[224:225]
	v_or_b32_e32 v220, 32, v214
	v_lshl_add_u64 v[132:133], s[8:9], 0, v[132:133]
	v_ashrrev_i32_e32 v221, 31, v220
	v_lshl_add_u64 v[226:227], v[132:133], 0, v[216:217]
	v_lshlrev_b64 v[132:133], 12, v[220:221]
	v_lshl_add_u64 v[228:229], s[8:9], 0, v[132:133]
	v_or_b32_e32 v218, 48, v214
	v_lshl_add_u64 v[132:133], v[228:229], 0, v[216:217]
	v_ashrrev_i32_e32 v219, 31, v218
	global_load_dwordx4 v[172:175], v[226:227], off offset:16
	global_load_dwordx4 v[176:179], v[226:227], off
	global_load_dwordx4 v[164:167], v[226:227], off offset:144
	global_load_dwordx4 v[168:171], v[226:227], off offset:128
	global_load_dwordx4 v[156:159], v[132:133], off offset:16
	global_load_dwordx4 v[160:163], v[132:133], off
	global_load_dwordx4 v[140:143], v[132:133], off offset:144
	global_load_dwordx4 v[144:147], v[132:133], off offset:128
	v_lshlrev_b64 v[132:133], 12, v[218:219]
	v_lshl_add_u64 v[222:223], s[8:9], 0, v[132:133]
	v_lshl_add_u64 v[136:137], v[222:223], 0, v[216:217]
	global_load_dwordx4 v[148:151], v[136:137], off offset:16
	global_load_dwordx4 v[152:155], v[136:137], off
	global_load_dwordx4 v[132:135], v[136:137], off offset:144
	s_nop 0
	global_load_dwordx4 v[136:139], v[136:137], off offset:128
	s_waitcnt vmcnt(0)
	v_pk_fma_f32 v[126:127], v[126:127], 0.5, v[198:199] op_sel_hi:[1,0,1]
	v_pk_fma_f32 v[130:131], v[130:131], 0.5, v[248:249] op_sel_hi:[1,0,1]
	v_pk_fma_f32 v[128:129], v[128:129], 0.5, v[246:247] op_sel_hi:[1,0,1]
	v_pk_fma_f32 v[124:125], v[124:125], 0.5, v[196:197] op_sel_hi:[1,0,1]
	global_store_dwordx4 v[230:231], v[128:131], off
	global_store_dwordx4 v[230:231], v[124:127], off offset:16
	v_cvt_pk_bf16_f32 v196, v128, v129
	v_mul_f32_e32 v129, v129, v129
	v_fmac_f32_e32 v129, v128, v128
	v_mul_f32_e32 v128, v131, v131
	v_cvt_pk_bf16_f32 v198, v124, v125
	v_fmac_f32_e32 v128, v130, v130
	v_mul_f32_e32 v125, v125, v125
	v_lshlrev_b64 v[246:247], 11, v[214:215]
	v_add_f32_e32 v128, v129, v128
	v_fmac_f32_e32 v125, v124, v124
	v_lshl_add_u64 v[246:247], s[14:15], 0, v[246:247]
	v_add_f32_e32 v124, v125, v128
	v_mul_f32_e32 v125, v127, v127
	v_cvt_pk_bf16_f32 v197, v130, v131
	v_cvt_pk_bf16_f32 v199, v126, v127
	v_lshl_add_u64 v[246:247], v[212:213], 1, v[246:247]
	v_fmac_f32_e32 v125, v126, v126
	v_pk_fma_f32 v[122:123], v[122:123], 0.5, v[186:187] op_sel_hi:[1,0,1]
	v_pk_fma_f32 v[120:121], v[120:121], 0.5, v[184:185] op_sel_hi:[1,0,1]
	global_store_dwordx4 v[246:247], v[196:199], off
	v_add_f32_e32 v128, v125, v124
	v_pk_fma_f32 v[118:119], v[118:119], 0.5, v[182:183] op_sel_hi:[1,0,1]
	v_pk_fma_f32 v[116:117], v[116:117], 0.5, v[180:181] op_sel_hi:[1,0,1]
	global_store_dwordx4 v[230:231], v[120:123], off offset:128
	global_store_dwordx4 v[230:231], v[116:119], off offset:144
	v_cvt_pk_bf16_f32 v124, v120, v121
	v_mul_f32_e32 v121, v121, v121
	v_fmac_f32_e32 v121, v120, v120
	v_mul_f32_e32 v120, v123, v123
	v_cvt_pk_bf16_f32 v126, v116, v117
	v_fmac_f32_e32 v120, v122, v122
	v_mul_f32_e32 v117, v117, v117
	v_add_f32_e32 v120, v121, v120
	v_fmac_f32_e32 v117, v116, v116
	v_add_f32_e32 v116, v117, v120
	v_mul_f32_e32 v117, v119, v119
	v_fmac_f32_e32 v117, v118, v118
	v_add_f32_e32 v116, v117, v116
	v_add_f32_e32 v116, v128, v116
	ds_bpermute_b32 v117, v244, v116
	v_cvt_pk_bf16_f32 v125, v122, v123
	v_cvt_pk_bf16_f32 v127, v118, v119
	global_store_dwordx4 v[246:247], v[124:127], off offset:64
	s_waitcnt lgkmcnt(0)
	v_add_f32_e32 v116, v116, v117
	ds_bpermute_b32 v117, v243, v116
	s_and_saveexec_b64 s[22:23], s[40:41]
	v_readlane_b32 s68, v252, 32
	v_readlane_b32 s69, v252, 33
	s_cbranch_execz .LBB0_1168
	s_waitcnt lgkmcnt(0)
	v_add_f32_e32 v118, v116, v117
	v_lshl_add_u64 v[116:117], v[214:215], 2, s[10:11]
	global_atomic_add_f32 v[116:117], v118, off
;     __device__ __forceinline__ void operator()(const Acc& acc, const Unit& u, int wr, int wc, int fr, int fq) const {
;         constexpr int MB = PLE ? 2 : 4;
; #pragma unroll
;         for (int ai = 0; ai < 2; ++ai)
; #pragma unroll
;         for (int mb = 0; mb < 4; mb += MB) {
;             f32x4 pa[MB][2], pb[MB][2]; u32x4 pt[MB][2]; float tt[MB];
; #pragma unroll
;             for (int mm = 0; mm < MB; ++mm) {
;                 const int m = mb + mm; const int r = u.pm * BM + ai * HALF + wr * 64 + m * 16 + fr;
;                 tt[mm] = PLE ? rs_in[r] : 0.f;
; #pragma unroll
;                 for (int bj = 0; bj < 2; ++bj) {
;                     const int c0 = u.pn * BM + wc * 64 + bj * 32 + 8 * fq; const float* hs = hsrc + (size_t)r * DM + c0;
;                     pa[mm][bj] = *(const f32x4*)hs; pb[mm][bj] = *(const f32x4*)(hs + 4);
;                     if (PLE) pt[mm][bj] = *(const u32x4*)(tmp + (size_t)r * DM + c0);
;                 }
;             }
; #pragma unroll
;             for (int mm = 0; mm < MB; ++mm) {
;                 const int m = mb + mm; const int r = u.pm * BM + ai * HALF + wr * 64 + m * 16 + fr; float ss = 0.f;
;                 const float t = PLE ? rstd_of(tt[mm], 1.f / 1024.f) : 1.f; const float tl = -t * 1.4426950408889634f; (void)tl;
; #pragma unroll
;                 for (int bj = 0; bj < 2; ++bj) {
;                     const int c0 = u.pn * BM + wc * 64 + bj * 32 + 8 * fq; float* hp = h + (size_t)r * DM + c0;
;                     f32x4 a = pa[mm][bj], b = pb[mm][bj];
;                     if (PLE) { f32x4 ta, tb; unpack8(pt[mm][bj], ta, tb);
; #pragma unroll
;                         for (int j = 0; j < 4; ++j) { a[j] += ta[j] * __builtin_amdgcn_rcpf(1.f + __builtin_amdgcn_exp2f(acc[ai][bj][m][0][j] * tl)); b[j] += tb[j] * __builtin_amdgcn_rcpf(1.f + __builtin_amdgcn_exp2f(acc[ai][bj][m][1][j] * tl)); } }
;                     else { a += acc[ai][bj][m][0] * alpha; b += acc[ai][bj][m][1] * alpha; }
;                     if (!dry || a[0] == 1234.56789f) { *(f32x4*)hp = a; *(f32x4*)(hp + 4) = b;
;                     *(u32x4*)(hb + (size_t)r * DM + c0) = pack8(a, b); }
;                     ss += (a[0] * a[0] + a[1] * a[1]) + (a[2] * a[2] + a[3] * a[3]) + (b[0] * b[0] + b[1] * b[1]) + (b[2] * b[2] + b[3] * b[3]);
;                 }
;                 ss += __shfl_xor(ss, 16); ss += __shfl_xor(ss, 32);
.LBB0_1168:
	s_or_b64 exec, exec, s[22:23]
	v_pk_fma_f32 v[114:115], v[114:115], 0.5, v[178:179] op_sel_hi:[1,0,1]
	v_pk_fma_f32 v[112:113], v[112:113], 0.5, v[176:177] op_sel_hi:[1,0,1]
	v_pk_fma_f32 v[110:111], v[110:111], 0.5, v[174:175] op_sel_hi:[1,0,1]
	v_pk_fma_f32 v[108:109], v[108:109], 0.5, v[172:173] op_sel_hi:[1,0,1]
	global_store_dwordx4 v[226:227], v[112:115], off
	global_store_dwordx4 v[226:227], v[108:111], off offset:16
	v_cvt_pk_bf16_f32 v116, v112, v113
	v_mul_f32_e32 v113, v113, v113
	v_fmac_f32_e32 v113, v112, v112
	v_mul_f32_e32 v112, v115, v115
	v_cvt_pk_bf16_f32 v118, v108, v109
	v_fmac_f32_e32 v112, v114, v114
	v_mul_f32_e32 v109, v109, v109
	v_add_f32_e32 v112, v113, v112
	v_fmac_f32_e32 v109, v108, v108
	v_add_f32_e32 v108, v109, v112
	v_mul_f32_e32 v109, v111, v111
	v_fmac_f32_e32 v109, v110, v110
	v_pk_fma_f32 v[106:107], v[106:107], 0.5, v[170:171] op_sel_hi:[1,0,1]
	v_pk_fma_f32 v[104:105], v[104:105], 0.5, v[168:169] op_sel_hi:[1,0,1]
	v_add_f32_e32 v112, v109, v108
	v_pk_fma_f32 v[108:109], v[100:101], 0.5, v[164:165] op_sel_hi:[1,0,1]
	v_mul_f32_e32 v100, v105, v105
	v_mul_f32_e32 v101, v107, v107
	v_fmac_f32_e32 v100, v104, v104
	v_fmac_f32_e32 v101, v106, v106
	v_add_f32_e32 v100, v100, v101
	v_mul_f32_e32 v101, v109, v109
	v_cvt_pk_bf16_f32 v119, v110, v111
	v_pk_fma_f32 v[110:111], v[102:103], 0.5, v[166:167] op_sel_hi:[1,0,1]
	v_fmac_f32_e32 v101, v108, v108
	v_add_f32_e32 v100, v101, v100
	v_mul_f32_e32 v101, v111, v111
	v_fmac_f32_e32 v101, v110, v110
	v_add_f32_e32 v100, v101, v100
	v_add_f32_e32 v100, v112, v100
	ds_bpermute_b32 v101, v244, v100
	v_lshlrev_b64 v[120:121], 11, v[224:225]
	v_lshl_add_u64 v[120:121], s[14:15], 0, v[120:121]
	s_waitcnt lgkmcnt(1)
	v_cvt_pk_bf16_f32 v117, v114, v115
	v_lshl_add_u64 v[120:121], v[212:213], 1, v[120:121]
	s_waitcnt lgkmcnt(0)
	v_add_f32_e32 v100, v100, v101
	ds_bpermute_b32 v101, v243, v100
	global_store_dwordx4 v[120:121], v[116:119], off
	global_store_dwordx4 v[226:227], v[104:107], off offset:128
	global_store_dwordx4 v[226:227], v[108:111], off offset:144
	v_cvt_pk_bf16_f32 v102, v104, v105
	v_cvt_pk_bf16_f32 v103, v106, v107
	v_cvt_pk_bf16_f32 v104, v108, v109
	v_cvt_pk_bf16_f32 v105, v110, v111
	global_store_dwordx4 v[120:121], v[102:105], off offset:64
	s_and_saveexec_b64 s[22:23], s[40:41]
	s_cbranch_execz .LBB0_1170
	s_waitcnt lgkmcnt(0)
	v_add_f32_e32 v102, v100, v101
	v_lshl_add_u64 v[100:101], v[224:225], 2, s[10:11]
	global_atomic_add_f32 v[100:101], v102, off
.LBB0_1170:
	s_or_b64 exec, exec, s[22:23]
	v_pk_fma_f32 v[98:99], v[98:99], 0.5, v[162:163] op_sel_hi:[1,0,1]
	v_pk_fma_f32 v[96:97], v[96:97], 0.5, v[160:161] op_sel_hi:[1,0,1]
	v_lshl_add_u64 v[104:105], v[212:213], 2, v[228:229]
	v_pk_fma_f32 v[94:95], v[94:95], 0.5, v[158:159] op_sel_hi:[1,0,1]
	v_pk_fma_f32 v[92:93], v[92:93], 0.5, v[156:157] op_sel_hi:[1,0,1]
	global_store_dwordx4 v[104:105], v[96:99], off
	global_store_dwordx4 v[104:105], v[92:95], off offset:16
	v_cvt_pk_bf16_f32 v100, v96, v97
	v_mul_f32_e32 v97, v97, v97
	v_fmac_f32_e32 v97, v96, v96
	v_mul_f32_e32 v96, v99, v99
	v_cvt_pk_bf16_f32 v102, v92, v93
	v_fmac_f32_e32 v96, v98, v98
	v_mul_f32_e32 v93, v93, v93
	v_add_f32_e32 v96, v97, v96
	v_fmac_f32_e32 v93, v92, v92
	v_add_f32_e32 v92, v93, v96
	v_mul_f32_e32 v93, v95, v95
	v_fmac_f32_e32 v93, v94, v94
	v_pk_fma_f32 v[90:91], v[90:91], 0.5, v[146:147] op_sel_hi:[1,0,1]
	v_pk_fma_f32 v[88:89], v[88:89], 0.5, v[144:145] op_sel_hi:[1,0,1]
	v_add_f32_e32 v96, v93, v92
	v_pk_fma_f32 v[92:93], v[84:85], 0.5, v[140:141] op_sel_hi:[1,0,1]
	v_mul_f32_e32 v84, v89, v89
	v_mul_f32_e32 v85, v91, v91
	v_fmac_f32_e32 v84, v88, v88
	v_fmac_f32_e32 v85, v90, v90
	v_add_f32_e32 v84, v84, v85
	v_mul_f32_e32 v85, v93, v93
	v_cvt_pk_bf16_f32 v103, v94, v95
	v_pk_fma_f32 v[94:95], v[86:87], 0.5, v[142:143] op_sel_hi:[1,0,1]
	v_fmac_f32_e32 v85, v92, v92
	v_add_f32_e32 v84, v85, v84
	v_mul_f32_e32 v85, v95, v95
	v_fmac_f32_e32 v85, v94, v94
	v_add_f32_e32 v84, v85, v84
	v_add_f32_e32 v84, v96, v84
	ds_bpermute_b32 v85, v244, v84
	v_lshlrev_b64 v[106:107], 11, v[220:221]
	v_lshl_add_u64 v[106:107], s[14:15], 0, v[106:107]
	s_waitcnt lgkmcnt(1)
	v_cvt_pk_bf16_f32 v101, v98, v99
	v_lshl_add_u64 v[106:107], v[212:213], 1, v[106:107]
	s_waitcnt lgkmcnt(0)
	v_add_f32_e32 v84, v84, v85
	ds_bpermute_b32 v85, v243, v84
	global_store_dwordx4 v[106:107], v[100:103], off
	global_store_dwordx4 v[104:105], v[88:91], off offset:128
	global_store_dwordx4 v[104:105], v[92:95], off offset:144
	v_cvt_pk_bf16_f32 v86, v88, v89
	v_cvt_pk_bf16_f32 v87, v90, v91
	v_cvt_pk_bf16_f32 v88, v92, v93
	v_cvt_pk_bf16_f32 v89, v94, v95
	global_store_dwordx4 v[106:107], v[86:89], off offset:64
	s_and_saveexec_b64 s[22:23], s[40:41]
	s_cbranch_execz .LBB0_1172
	s_waitcnt lgkmcnt(0)
	v_add_f32_e32 v86, v84, v85
	v_lshl_add_u64 v[84:85], v[220:221], 2, s[10:11]
	global_atomic_add_f32 v[84:85], v86, off
;     __device__ __forceinline__ void operator()(const Acc& acc, const Unit& u, int wr, int wc, int fr, int fq) const {
;         constexpr int MB = PLE ? 2 : 4;
; #pragma unroll
;         for (int ai = 0; ai < 2; ++ai)
; #pragma unroll
;         for (int mb = 0; mb < 4; mb += MB) {
;             f32x4 pa[MB][2], pb[MB][2]; u32x4 pt[MB][2]; float tt[MB];
; #pragma unroll
;             for (int mm = 0; mm < MB; ++mm) {
;                 const int m = mb + mm; const int r = u.pm * BM + ai * HALF + wr * 64 + m * 16 + fr;
;                 tt[mm] = PLE ? rs_in[r] : 0.f;
; #pragma unroll
;                 for (int bj = 0; bj < 2; ++bj) {
;                     const int c0 = u.pn * BM + wc * 64 + bj * 32 + 8 * fq; const float* hs = hsrc + (size_t)r * DM + c0;
;                     pa[mm][bj] = *(const f32x4*)hs; pb[mm][bj] = *(const f32x4*)(hs + 4);
;                     if (PLE) pt[mm][bj] = *(const u32x4*)(tmp + (size_t)r * DM + c0);
;                 }
;             }
; #pragma unroll
;             for (int mm = 0; mm < MB; ++mm) {
;                 const int m = mb + mm; const int r = u.pm * BM + ai * HALF + wr * 64 + m * 16 + fr; float ss = 0.f;
;                 const float t = PLE ? rstd_of(tt[mm], 1.f / 1024.f) : 1.f; const float tl = -t * 1.4426950408889634f; (void)tl;
; #pragma unroll
;                 for (int bj = 0; bj < 2; ++bj) {
;                     const int c0 = u.pn * BM + wc * 64 + bj * 32 + 8 * fq; float* hp = h + (size_t)r * DM + c0;
;                     f32x4 a = pa[mm][bj], b = pb[mm][bj];
;                     if (PLE) { f32x4 ta, tb; unpack8(pt[mm][bj], ta, tb);
; #pragma unroll
;                         for (int j = 0; j < 4; ++j) { a[j] += ta[j] * __builtin_amdgcn_rcpf(1.f + __builtin_amdgcn_exp2f(acc[ai][bj][m][0][j] * tl)); b[j] += tb[j] * __builtin_amdgcn_rcpf(1.f + __builtin_amdgcn_exp2f(acc[ai][bj][m][1][j] * tl)); } }
;                     else { a += acc[ai][bj][m][0] * alpha; b += acc[ai][bj][m][1] * alpha; }
;                     if (!dry || a[0] == 1234.56789f) { *(f32x4*)hp = a; *(f32x4*)(hp + 4) = b;
;                     *(u32x4*)(hb + (size_t)r * DM + c0) = pack8(a, b); }
;                     ss += (a[0] * a[0] + a[1] * a[1]) + (a[2] * a[2] + a[3] * a[3]) + (b[0] * b[0] + b[1] * b[1]) + (b[2] * b[2] + b[3] * b[3]);
;                 }
;                 ss += __shfl_xor(ss, 16); ss += __shfl_xor(ss, 32);
.LBB0_1172:
	s_or_b64 exec, exec, s[22:23]
	v_pk_fma_f32 v[82:83], v[82:83], 0.5, v[154:155] op_sel_hi:[1,0,1]
	v_pk_fma_f32 v[80:81], v[80:81], 0.5, v[152:153] op_sel_hi:[1,0,1]
	v_lshl_add_u64 v[88:89], v[212:213], 2, v[222:223]
	v_pk_fma_f32 v[78:79], v[78:79], 0.5, v[150:151] op_sel_hi:[1,0,1]
	v_pk_fma_f32 v[76:77], v[76:77], 0.5, v[148:149] op_sel_hi:[1,0,1]
	global_store_dwordx4 v[88:89], v[80:83], off
	global_store_dwordx4 v[88:89], v[76:79], off offset:16
	v_cvt_pk_bf16_f32 v84, v80, v81
	v_mul_f32_e32 v81, v81, v81
	v_fmac_f32_e32 v81, v80, v80
	v_mul_f32_e32 v80, v83, v83
	v_cvt_pk_bf16_f32 v86, v76, v77
	v_fmac_f32_e32 v80, v82, v82
	v_mul_f32_e32 v77, v77, v77
	v_add_f32_e32 v80, v81, v80
	v_fmac_f32_e32 v77, v76, v76
	v_add_f32_e32 v76, v77, v80
	v_mul_f32_e32 v77, v79, v79
	v_fmac_f32_e32 v77, v78, v78
	v_pk_fma_f32 v[74:75], v[74:75], 0.5, v[138:139] op_sel_hi:[1,0,1]
	v_pk_fma_f32 v[72:73], v[72:73], 0.5, v[136:137] op_sel_hi:[1,0,1]
	v_add_f32_e32 v80, v77, v76
	v_pk_fma_f32 v[76:77], v[68:69], 0.5, v[132:133] op_sel_hi:[1,0,1]
	v_mul_f32_e32 v68, v73, v73
	v_mul_f32_e32 v69, v75, v75
	v_fmac_f32_e32 v68, v72, v72
	v_fmac_f32_e32 v69, v74, v74
	v_add_f32_e32 v68, v68, v69
	v_mul_f32_e32 v69, v77, v77
	v_cvt_pk_bf16_f32 v87, v78, v79
	v_pk_fma_f32 v[78:79], v[70:71], 0.5, v[134:135] op_sel_hi:[1,0,1]
	v_fmac_f32_e32 v69, v76, v76
	v_add_f32_e32 v68, v69, v68
	v_mul_f32_e32 v69, v79, v79
	v_fmac_f32_e32 v69, v78, v78
	v_add_f32_e32 v68, v69, v68
	v_add_f32_e32 v68, v80, v68
	ds_bpermute_b32 v69, v244, v68
	v_lshlrev_b64 v[90:91], 11, v[218:219]
	v_lshl_add_u64 v[90:91], s[14:15], 0, v[90:91]
	s_waitcnt lgkmcnt(1)
	v_cvt_pk_bf16_f32 v85, v82, v83
	v_lshl_add_u64 v[90:91], v[212:213], 1, v[90:91]
	s_waitcnt lgkmcnt(0)
	v_add_f32_e32 v68, v68, v69
	ds_bpermute_b32 v69, v243, v68
	global_store_dwordx4 v[90:91], v[84:87], off
	global_store_dwordx4 v[88:89], v[72:75], off offset:128
	global_store_dwordx4 v[88:89], v[76:79], off offset:144
	v_cvt_pk_bf16_f32 v70, v72, v73
	v_cvt_pk_bf16_f32 v71, v74, v75
	v_cvt_pk_bf16_f32 v72, v76, v77
	v_cvt_pk_bf16_f32 v73, v78, v79
	global_store_dwordx4 v[90:91], v[70:73], off offset:64
	s_and_saveexec_b64 s[22:23], s[40:41]
	s_cbranch_execz .LBB0_1174
	s_waitcnt lgkmcnt(0)
	v_add_f32_e32 v70, v68, v69
	v_lshl_add_u64 v[68:69], v[218:219], 2, s[10:11]
	global_atomic_add_f32 v[68:69], v70, off
.LBB0_1174:
	s_or_b64 exec, exec, s[22:23]
	v_add_u32_e32 v136, 0x80, v214
	v_ashrrev_i32_e32 v137, 31, v136
	s_waitcnt lgkmcnt(0)
	v_lshlrev_b64 v[68:69], 12, v[136:137]
	v_lshl_add_u64 v[68:69], s[8:9], 0, v[68:69]
	v_lshl_add_u64 v[138:139], v[68:69], 0, v[216:217]
	global_load_dwordx4 v[140:143], v[138:139], off offset:16
	global_load_dwordx4 v[144:147], v[138:139], off
	global_load_dwordx4 v[116:119], v[138:139], off offset:144
	global_load_dwordx4 v[120:123], v[138:139], off offset:128
	v_add_u32_e32 v130, 0x90, v214
	v_ashrrev_i32_e32 v131, 31, v130
	v_lshlrev_b64 v[68:69], 12, v[130:131]
	v_add_u32_e32 v126, 0xa0, v214
	v_lshl_add_u64 v[68:69], s[8:9], 0, v[68:69]
	v_ashrrev_i32_e32 v127, 31, v126
	v_lshl_add_u64 v[132:133], v[68:69], 0, v[216:217]
	v_lshlrev_b64 v[68:69], 12, v[126:127]
	v_lshl_add_u64 v[134:135], s[8:9], 0, v[68:69]
	v_add_u32_e32 v124, 0xb0, v214
	v_lshl_add_u64 v[68:69], v[134:135], 0, v[216:217]
	v_ashrrev_i32_e32 v125, 31, v124
	global_load_dwordx4 v[108:111], v[132:133], off offset:16
	global_load_dwordx4 v[112:115], v[132:133], off
	global_load_dwordx4 v[100:103], v[132:133], off offset:144
	global_load_dwordx4 v[104:107], v[132:133], off offset:128
	global_load_dwordx4 v[92:95], v[68:69], off offset:16
	global_load_dwordx4 v[96:99], v[68:69], off
	global_load_dwordx4 v[76:79], v[68:69], off offset:144
	global_load_dwordx4 v[80:83], v[68:69], off offset:128
	v_lshlrev_b64 v[68:69], 12, v[124:125]
	v_lshl_add_u64 v[128:129], s[8:9], 0, v[68:69]
	v_lshl_add_u64 v[72:73], v[128:129], 0, v[216:217]
	global_load_dwordx4 v[84:87], v[72:73], off offset:16
	global_load_dwordx4 v[88:91], v[72:73], off
	global_load_dwordx4 v[68:71], v[72:73], off offset:144
	s_nop 0
	global_load_dwordx4 v[72:75], v[72:73], off offset:128
	s_waitcnt vmcnt(15)
	v_pk_fma_f32 v[62:63], v[62:63], 0.5, v[142:143] op_sel_hi:[1,0,1]
	s_waitcnt vmcnt(14)
	v_pk_fma_f32 v[66:67], v[66:67], 0.5, v[146:147] op_sel_hi:[1,0,1]
	v_pk_fma_f32 v[64:65], v[64:65], 0.5, v[144:145] op_sel_hi:[1,0,1]
	v_pk_fma_f32 v[60:61], v[60:61], 0.5, v[140:141] op_sel_hi:[1,0,1]
	global_store_dwordx4 v[138:139], v[64:67], off
	global_store_dwordx4 v[138:139], v[60:63], off offset:16
	v_cvt_pk_bf16_f32 v140, v64, v65
	v_mul_f32_e32 v65, v65, v65
	v_fmac_f32_e32 v65, v64, v64
	v_mul_f32_e32 v64, v67, v67
	v_cvt_pk_bf16_f32 v142, v60, v61
	v_fmac_f32_e32 v64, v66, v66
	v_mul_f32_e32 v61, v61, v61
	v_lshlrev_b64 v[144:145], 11, v[136:137]
	v_add_f32_e32 v64, v65, v64
	v_fmac_f32_e32 v61, v60, v60
	v_lshl_add_u64 v[144:145], s[14:15], 0, v[144:145]
	v_add_f32_e32 v60, v61, v64
	v_mul_f32_e32 v61, v63, v63
	v_cvt_pk_bf16_f32 v141, v66, v67
	v_cvt_pk_bf16_f32 v143, v62, v63
	v_lshl_add_u64 v[144:145], v[212:213], 1, v[144:145]
	v_fmac_f32_e32 v61, v62, v62
	s_waitcnt vmcnt(14)
	v_pk_fma_f32 v[58:59], v[58:59], 0.5, v[122:123] op_sel_hi:[1,0,1]
	v_pk_fma_f32 v[56:57], v[56:57], 0.5, v[120:121] op_sel_hi:[1,0,1]
	global_store_dwordx4 v[144:145], v[140:143], off
	v_add_f32_e32 v64, v61, v60
	v_pk_fma_f32 v[54:55], v[54:55], 0.5, v[118:119] op_sel_hi:[1,0,1]
	v_pk_fma_f32 v[52:53], v[52:53], 0.5, v[116:117] op_sel_hi:[1,0,1]
	global_store_dwordx4 v[138:139], v[56:59], off offset:128
	global_store_dwordx4 v[138:139], v[52:55], off offset:144
	v_cvt_pk_bf16_f32 v60, v56, v57
	v_mul_f32_e32 v57, v57, v57
	v_fmac_f32_e32 v57, v56, v56
	v_mul_f32_e32 v56, v59, v59
	v_cvt_pk_bf16_f32 v62, v52, v53
	v_fmac_f32_e32 v56, v58, v58
	v_mul_f32_e32 v53, v53, v53
	v_add_f32_e32 v56, v57, v56
	v_fmac_f32_e32 v53, v52, v52
	v_add_f32_e32 v52, v53, v56
	v_mul_f32_e32 v53, v55, v55
	v_fmac_f32_e32 v53, v54, v54
	v_add_f32_e32 v52, v53, v52
	v_add_f32_e32 v52, v64, v52
	ds_bpermute_b32 v53, v244, v52
	v_cvt_pk_bf16_f32 v61, v58, v59
	v_cvt_pk_bf16_f32 v63, v54, v55
	global_store_dwordx4 v[144:145], v[60:63], off offset:64
	s_waitcnt lgkmcnt(0)
	v_add_f32_e32 v52, v52, v53
	ds_bpermute_b32 v53, v243, v52
	s_and_saveexec_b64 s[22:23], s[40:41]
	s_cbranch_execz .LBB0_1176
	s_waitcnt lgkmcnt(0)
	v_add_f32_e32 v54, v52, v53
	v_lshl_add_u64 v[52:53], v[136:137], 2, s[10:11]
	global_atomic_add_f32 v[52:53], v54, off
;     __device__ __forceinline__ void operator()(const Acc& acc, const Unit& u, int wr, int wc, int fr, int fq) const {
;         constexpr int MB = PLE ? 2 : 4;
; #pragma unroll
;         for (int ai = 0; ai < 2; ++ai)
; #pragma unroll
;         for (int mb = 0; mb < 4; mb += MB) {
;             f32x4 pa[MB][2], pb[MB][2]; u32x4 pt[MB][2]; float tt[MB];
; #pragma unroll
;             for (int mm = 0; mm < MB; ++mm) {
;                 const int m = mb + mm; const int r = u.pm * BM + ai * HALF + wr * 64 + m * 16 + fr;
;                 tt[mm] = PLE ? rs_in[r] : 0.f;
; #pragma unroll
;                 for (int bj = 0; bj < 2; ++bj) {
;                     const int c0 = u.pn * BM + wc * 64 + bj * 32 + 8 * fq; const float* hs = hsrc + (size_t)r * DM + c0;
;                     pa[mm][bj] = *(const f32x4*)hs; pb[mm][bj] = *(const f32x4*)(hs + 4);
;                     if (PLE) pt[mm][bj] = *(const u32x4*)(tmp + (size_t)r * DM + c0);
;                 }
;             }
; #pragma unroll
;             for (int mm = 0; mm < MB; ++mm) {
;                 const int m = mb + mm; const int r = u.pm * BM + ai * HALF + wr * 64 + m * 16 + fr; float ss = 0.f;
;                 const float t = PLE ? rstd_of(tt[mm], 1.f / 1024.f) : 1.f; const float tl = -t * 1.4426950408889634f; (void)tl;
; #pragma unroll
;                 for (int bj = 0; bj < 2; ++bj) {
;                     const int c0 = u.pn * BM + wc * 64 + bj * 32 + 8 * fq; float* hp = h + (size_t)r * DM + c0;
;                     f32x4 a = pa[mm][bj], b = pb[mm][bj];
;                     if (PLE) { f32x4 ta, tb; unpack8(pt[mm][bj], ta, tb);
; #pragma unroll
;                         for (int j = 0; j < 4; ++j) { a[j] += ta[j] * __builtin_amdgcn_rcpf(1.f + __builtin_amdgcn_exp2f(acc[ai][bj][m][0][j] * tl)); b[j] += tb[j] * __builtin_amdgcn_rcpf(1.f + __builtin_amdgcn_exp2f(acc[ai][bj][m][1][j] * tl)); } }
;                     else { a += acc[ai][bj][m][0] * alpha; b += acc[ai][bj][m][1] * alpha; }
;                     if (!dry || a[0] == 1234.56789f) { *(f32x4*)hp = a; *(f32x4*)(hp + 4) = b;
;                     *(u32x4*)(hb + (size_t)r * DM + c0) = pack8(a, b); }
;                     ss += (a[0] * a[0] + a[1] * a[1]) + (a[2] * a[2] + a[3] * a[3]) + (b[0] * b[0] + b[1] * b[1]) + (b[2] * b[2] + b[3] * b[3]);
;                 }
;                 ss += __shfl_xor(ss, 16); ss += __shfl_xor(ss, 32);
.LBB0_1176:
	s_or_b64 exec, exec, s[22:23]
	s_waitcnt vmcnt(16)
	v_pk_fma_f32 v[50:51], v[50:51], 0.5, v[114:115] op_sel_hi:[1,0,1]
	v_pk_fma_f32 v[48:49], v[48:49], 0.5, v[112:113] op_sel_hi:[1,0,1]
	v_pk_fma_f32 v[46:47], v[46:47], 0.5, v[110:111] op_sel_hi:[1,0,1]
	v_pk_fma_f32 v[44:45], v[44:45], 0.5, v[108:109] op_sel_hi:[1,0,1]
	global_store_dwordx4 v[132:133], v[48:51], off
	global_store_dwordx4 v[132:133], v[44:47], off offset:16
	v_cvt_pk_bf16_f32 v52, v48, v49
	v_mul_f32_e32 v49, v49, v49
	v_fmac_f32_e32 v49, v48, v48
	v_mul_f32_e32 v48, v51, v51
	v_cvt_pk_bf16_f32 v54, v44, v45
	v_fmac_f32_e32 v48, v50, v50
	v_mul_f32_e32 v45, v45, v45
	v_add_f32_e32 v48, v49, v48
	v_fmac_f32_e32 v45, v44, v44
	v_add_f32_e32 v44, v45, v48
	v_mul_f32_e32 v45, v47, v47
	v_fmac_f32_e32 v45, v46, v46
	s_waitcnt vmcnt(16)
	v_pk_fma_f32 v[42:43], v[42:43], 0.5, v[106:107] op_sel_hi:[1,0,1]
	v_pk_fma_f32 v[40:41], v[40:41], 0.5, v[104:105] op_sel_hi:[1,0,1]
	v_add_f32_e32 v48, v45, v44
	v_pk_fma_f32 v[44:45], v[36:37], 0.5, v[100:101] op_sel_hi:[1,0,1]
	v_mul_f32_e32 v36, v41, v41
	v_mul_f32_e32 v37, v43, v43
	v_fmac_f32_e32 v36, v40, v40
	v_fmac_f32_e32 v37, v42, v42
	v_add_f32_e32 v36, v36, v37
	v_mul_f32_e32 v37, v45, v45
	v_cvt_pk_bf16_f32 v55, v46, v47
	v_pk_fma_f32 v[46:47], v[38:39], 0.5, v[102:103] op_sel_hi:[1,0,1]
	v_fmac_f32_e32 v37, v44, v44
	v_add_f32_e32 v36, v37, v36
	v_mul_f32_e32 v37, v47, v47
	v_fmac_f32_e32 v37, v46, v46
	v_add_f32_e32 v36, v37, v36
	v_add_f32_e32 v36, v48, v36
	ds_bpermute_b32 v37, v244, v36
	v_lshlrev_b64 v[56:57], 11, v[130:131]
	v_lshl_add_u64 v[56:57], s[14:15], 0, v[56:57]
	s_waitcnt lgkmcnt(1)
	v_cvt_pk_bf16_f32 v53, v50, v51
	v_lshl_add_u64 v[56:57], v[212:213], 1, v[56:57]
	s_waitcnt lgkmcnt(0)
	v_add_f32_e32 v36, v36, v37
	ds_bpermute_b32 v37, v243, v36
	global_store_dwordx4 v[56:57], v[52:55], off
	global_store_dwordx4 v[132:133], v[40:43], off offset:128
	global_store_dwordx4 v[132:133], v[44:47], off offset:144
	v_cvt_pk_bf16_f32 v38, v40, v41
	v_cvt_pk_bf16_f32 v39, v42, v43
	v_cvt_pk_bf16_f32 v40, v44, v45
	v_cvt_pk_bf16_f32 v41, v46, v47
	global_store_dwordx4 v[56:57], v[38:41], off offset:64
	s_and_saveexec_b64 s[22:23], s[40:41]
	s_cbranch_execz .LBB0_1178
	s_waitcnt lgkmcnt(0)
	v_add_f32_e32 v38, v36, v37
	v_lshl_add_u64 v[36:37], v[130:131], 2, s[10:11]
	global_atomic_add_f32 v[36:37], v38, off
;     __device__ __forceinline__ void operator()(const Acc& acc, const Unit& u, int wr, int wc, int fr, int fq) const {
;         constexpr int MB = PLE ? 2 : 4;
; #pragma unroll
;         for (int ai = 0; ai < 2; ++ai)
; #pragma unroll
;         for (int mb = 0; mb < 4; mb += MB) {
;             f32x4 pa[MB][2], pb[MB][2]; u32x4 pt[MB][2]; float tt[MB];
; #pragma unroll
;             for (int mm = 0; mm < MB; ++mm) {
;                 const int m = mb + mm; const int r = u.pm * BM + ai * HALF + wr * 64 + m * 16 + fr;
;                 tt[mm] = PLE ? rs_in[r] : 0.f;
; #pragma unroll
;                 for (int bj = 0; bj < 2; ++bj) {
;                     const int c0 = u.pn * BM + wc * 64 + bj * 32 + 8 * fq; const float* hs = hsrc + (size_t)r * DM + c0;
;                     pa[mm][bj] = *(const f32x4*)hs; pb[mm][bj] = *(const f32x4*)(hs + 4);
;                     if (PLE) pt[mm][bj] = *(const u32x4*)(tmp + (size_t)r * DM + c0);
;                 }
;             }
; #pragma unroll
;             for (int mm = 0; mm < MB; ++mm) {
;                 const int m = mb + mm; const int r = u.pm * BM + ai * HALF + wr * 64 + m * 16 + fr; float ss = 0.f;
;                 const float t = PLE ? rstd_of(tt[mm], 1.f / 1024.f) : 1.f; const float tl = -t * 1.4426950408889634f; (void)tl;
; #pragma unroll
;                 for (int bj = 0; bj < 2; ++bj) {
;                     const int c0 = u.pn * BM + wc * 64 + bj * 32 + 8 * fq; float* hp = h + (size_t)r * DM + c0;
;                     f32x4 a = pa[mm][bj], b = pb[mm][bj];
;                     if (PLE) { f32x4 ta, tb; unpack8(pt[mm][bj], ta, tb);
; #pragma unroll
;                         for (int j = 0; j < 4; ++j) { a[j] += ta[j] * __builtin_amdgcn_rcpf(1.f + __builtin_amdgcn_exp2f(acc[ai][bj][m][0][j] * tl)); b[j] += tb[j] * __builtin_amdgcn_rcpf(1.f + __builtin_amdgcn_exp2f(acc[ai][bj][m][1][j] * tl)); } }
;                     else { a += acc[ai][bj][m][0] * alpha; b += acc[ai][bj][m][1] * alpha; }
;                     if (!dry || a[0] == 1234.56789f) { *(f32x4*)hp = a; *(f32x4*)(hp + 4) = b;
;                     *(u32x4*)(hb + (size_t)r * DM + c0) = pack8(a, b); }
;                     ss += (a[0] * a[0] + a[1] * a[1]) + (a[2] * a[2] + a[3] * a[3]) + (b[0] * b[0] + b[1] * b[1]) + (b[2] * b[2] + b[3] * b[3]);
;                 }
;                 ss += __shfl_xor(ss, 16); ss += __shfl_xor(ss, 32);
.LBB0_1178:
	s_or_b64 exec, exec, s[22:23]
	s_waitcnt vmcnt(18)
	v_pk_fma_f32 v[34:35], v[34:35], 0.5, v[98:99] op_sel_hi:[1,0,1]
	v_pk_fma_f32 v[32:33], v[32:33], 0.5, v[96:97] op_sel_hi:[1,0,1]
	v_lshl_add_u64 v[40:41], v[212:213], 2, v[134:135]
	v_pk_fma_f32 v[30:31], v[30:31], 0.5, v[94:95] op_sel_hi:[1,0,1]
	v_pk_fma_f32 v[28:29], v[28:29], 0.5, v[92:93] op_sel_hi:[1,0,1]
	global_store_dwordx4 v[40:41], v[32:35], off
	global_store_dwordx4 v[40:41], v[28:31], off offset:16
	v_cvt_pk_bf16_f32 v36, v32, v33
	v_mul_f32_e32 v33, v33, v33
	v_fmac_f32_e32 v33, v32, v32
	v_mul_f32_e32 v32, v35, v35
	v_cvt_pk_bf16_f32 v38, v28, v29
	v_fmac_f32_e32 v32, v34, v34
	v_mul_f32_e32 v29, v29, v29
	v_add_f32_e32 v32, v33, v32
	v_fmac_f32_e32 v29, v28, v28
	v_add_f32_e32 v28, v29, v32
	v_mul_f32_e32 v29, v31, v31
	v_fmac_f32_e32 v29, v30, v30
	s_waitcnt vmcnt(18)
	v_pk_fma_f32 v[26:27], v[26:27], 0.5, v[82:83] op_sel_hi:[1,0,1]
	v_pk_fma_f32 v[24:25], v[24:25], 0.5, v[80:81] op_sel_hi:[1,0,1]
	v_add_f32_e32 v32, v29, v28
	v_pk_fma_f32 v[28:29], v[20:21], 0.5, v[76:77] op_sel_hi:[1,0,1]
	v_mul_f32_e32 v20, v25, v25
	v_mul_f32_e32 v21, v27, v27
	v_fmac_f32_e32 v20, v24, v24
	v_fmac_f32_e32 v21, v26, v26
	v_add_f32_e32 v20, v20, v21
	v_mul_f32_e32 v21, v29, v29
	v_cvt_pk_bf16_f32 v39, v30, v31
	v_pk_fma_f32 v[30:31], v[22:23], 0.5, v[78:79] op_sel_hi:[1,0,1]
	v_fmac_f32_e32 v21, v28, v28
	v_add_f32_e32 v20, v21, v20
	v_mul_f32_e32 v21, v31, v31
	v_fmac_f32_e32 v21, v30, v30
	v_add_f32_e32 v20, v21, v20
	v_add_f32_e32 v20, v32, v20
	ds_bpermute_b32 v21, v244, v20
	v_lshlrev_b64 v[42:43], 11, v[126:127]
	v_lshl_add_u64 v[42:43], s[14:15], 0, v[42:43]
	s_waitcnt lgkmcnt(1)
	v_cvt_pk_bf16_f32 v37, v34, v35
	v_lshl_add_u64 v[42:43], v[212:213], 1, v[42:43]
	s_waitcnt lgkmcnt(0)
	v_add_f32_e32 v20, v20, v21
	ds_bpermute_b32 v21, v243, v20
	global_store_dwordx4 v[42:43], v[36:39], off
	global_store_dwordx4 v[40:41], v[24:27], off offset:128
	global_store_dwordx4 v[40:41], v[28:31], off offset:144
	v_cvt_pk_bf16_f32 v22, v24, v25
	v_cvt_pk_bf16_f32 v23, v26, v27
	v_cvt_pk_bf16_f32 v24, v28, v29
	v_cvt_pk_bf16_f32 v25, v30, v31
	global_store_dwordx4 v[42:43], v[22:25], off offset:64
	s_and_saveexec_b64 s[22:23], s[40:41]
	s_cbranch_execz .LBB0_1180
	s_waitcnt lgkmcnt(0)
	v_add_f32_e32 v22, v20, v21
	v_lshl_add_u64 v[20:21], v[126:127], 2, s[10:11]
	global_atomic_add_f32 v[20:21], v22, off
.LBB0_1180:
	s_or_b64 exec, exec, s[22:23]
	s_waitcnt vmcnt(20)
	v_pk_fma_f32 v[18:19], v[18:19], 0.5, v[90:91] op_sel_hi:[1,0,1]
	v_pk_fma_f32 v[16:17], v[16:17], 0.5, v[88:89] op_sel_hi:[1,0,1]
	v_lshl_add_u64 v[24:25], v[212:213], 2, v[128:129]
	v_pk_fma_f32 v[14:15], v[14:15], 0.5, v[86:87] op_sel_hi:[1,0,1]
	v_pk_fma_f32 v[12:13], v[12:13], 0.5, v[84:85] op_sel_hi:[1,0,1]
	global_store_dwordx4 v[24:25], v[16:19], off
	global_store_dwordx4 v[24:25], v[12:15], off offset:16
	v_cvt_pk_bf16_f32 v20, v16, v17
	v_mul_f32_e32 v17, v17, v17
	v_fmac_f32_e32 v17, v16, v16
	v_mul_f32_e32 v16, v19, v19
	v_cvt_pk_bf16_f32 v22, v12, v13
	v_fmac_f32_e32 v16, v18, v18
	v_mul_f32_e32 v13, v13, v13
	v_add_f32_e32 v16, v17, v16
	v_fmac_f32_e32 v13, v12, v12
	v_add_f32_e32 v12, v13, v16
	v_mul_f32_e32 v13, v15, v15
	v_fmac_f32_e32 v13, v14, v14
	s_waitcnt vmcnt(20)
	v_pk_fma_f32 v[10:11], v[10:11], 0.5, v[74:75] op_sel_hi:[1,0,1]
	v_pk_fma_f32 v[8:9], v[8:9], 0.5, v[72:73] op_sel_hi:[1,0,1]
	v_add_f32_e32 v16, v13, v12
	v_pk_fma_f32 v[12:13], v[4:5], 0.5, v[68:69] op_sel_hi:[1,0,1]
	v_mul_f32_e32 v4, v9, v9
	v_mul_f32_e32 v5, v11, v11
	v_fmac_f32_e32 v4, v8, v8
	v_fmac_f32_e32 v5, v10, v10
	v_add_f32_e32 v4, v4, v5
	v_mul_f32_e32 v5, v13, v13
	v_cvt_pk_bf16_f32 v23, v14, v15
	v_pk_fma_f32 v[14:15], v[6:7], 0.5, v[70:71] op_sel_hi:[1,0,1]
	v_fmac_f32_e32 v5, v12, v12
	v_add_f32_e32 v4, v5, v4
	v_mul_f32_e32 v5, v15, v15
	v_fmac_f32_e32 v5, v14, v14
	v_add_f32_e32 v4, v5, v4
	v_add_f32_e32 v4, v16, v4
	ds_bpermute_b32 v5, v244, v4
	v_lshlrev_b64 v[26:27], 11, v[124:125]
	v_lshl_add_u64 v[26:27], s[14:15], 0, v[26:27]
	s_waitcnt lgkmcnt(1)
	v_cvt_pk_bf16_f32 v21, v18, v19
	v_lshl_add_u64 v[26:27], v[212:213], 1, v[26:27]
	s_waitcnt lgkmcnt(0)
	v_add_f32_e32 v4, v4, v5
	ds_bpermute_b32 v5, v243, v4
	global_store_dwordx4 v[26:27], v[20:23], off
	global_store_dwordx4 v[24:25], v[8:11], off offset:128
	global_store_dwordx4 v[24:25], v[12:15], off offset:144
	v_cvt_pk_bf16_f32 v6, v8, v9
	v_cvt_pk_bf16_f32 v7, v10, v11
	v_cvt_pk_bf16_f32 v8, v12, v13
	v_cvt_pk_bf16_f32 v9, v14, v15
	global_store_dwordx4 v[26:27], v[6:9], off offset:64
	s_and_saveexec_b64 s[22:23], s[40:41]
	s_cbranch_execz .LBB0_1182
	s_waitcnt lgkmcnt(0)
	v_add_f32_e32 v6, v4, v5
	v_lshl_add_u64 v[4:5], v[124:125], 2, s[10:11]
	global_atomic_add_f32 v[4:5], v6, off

; __device__ __forceinline__ float rstd_of(float ss, float invn) { return __builtin_amdgcn_rsqf(ss * invn + EPS); }
;     __device__ __forceinline__ void operator()(const Acc& acc, const Unit& u, int wr, int wc, int fr, int fq) const {
;     ...
; #pragma unroll
;             for (int mm = 0; mm < MB; ++mm) {
;                 const int m = mb + mm; const int r = u.pm * BM + ai * HALF + wr * 64 + m * 16 + fr;
;                 tt[mm] = PLE ? rs_in[r] : 0.f;
; #pragma unroll
;                 for (int bj = 0; bj < 2; ++bj) {
;                     const int c0 = u.pn * BM + wc * 64 + bj * 32 + 8 * fq; const float* hs = hsrc + (size_t)r * DM + c0;
;                     pa[mm][bj] = *(const f32x4*)hs; pb[mm][bj] = *(const f32x4*)(hs + 4);
;                     if (PLE) pt[mm][bj] = *(const u32x4*)(tmp + (size_t)r * DM + c0);
;                 }
;             }
; #pragma unroll
;             for (int mm = 0; mm < MB; ++mm) {
;                 const int m = mb + mm; const int r = u.pm * BM + ai * HALF + wr * 64 + m * 16 + fr; float ss = 0.f;
;                 const float t = PLE ? rstd_of(tt[mm], 1.f / 1024.f) : 1.f; const float tl = -t * 1.4426950408889634f; (void)tl;
; #pragma unroll
;                 for (int bj = 0; bj < 2; ++bj) {
;                     const int c0 = u.pn * BM + wc * 64 + bj * 32 + 8 * fq; float* hp = h + (size_t)r * DM + c0;
;                     f32x4 a = pa[mm][bj], b = pb[mm][bj];
;                     if (PLE) { f32x4 ta, tb; unpack8(pt[mm][bj], ta, tb);
; #pragma unroll
;                         for (int j = 0; j < 4; ++j) { a[j] += ta[j] * __builtin_amdgcn_rcpf(1.f + __builtin_amdgcn_exp2f(acc[ai][bj][m][0][j] * tl)); b[j] += tb[j] * __builtin_amdgcn_rcpf(1.f + __builtin_amdgcn_exp2f(acc[ai][bj][m][1][j] * tl)); } }
;                     else { a += acc[ai][bj][m][0] * alpha; b += acc[ai][bj][m][1] * alpha; }
;                     if (!dry || a[0] == 1234.56789f) { *(f32x4*)hp = a; *(f32x4*)(hp + 4) = b;
;                     *(u32x4*)(hb + (size_t)r * DM + c0) = pack8(a, b); }
;                     ss += (a[0] * a[0] + a[1] * a[1]) + (a[2] * a[2] + a[3] * a[3]) + (b[0] * b[0] + b[1] * b[1]) + (b[2] * b[2] + b[3] * b[3]);
;                 }
;                 ss += __shfl_xor(ss, 16); ss += __shfl_xor(ss, 32);
;                 if (fq == 0 && (!dry || ss == 1234.56789f)) unsafeAtomicAdd(rs_out + r, ss);
;             }
.LBB0_1273:
	v_lshl_add_u32 v172, s54, 8, v3
	v_ashrrev_i32_e32 v173, 31, v172
	v_lshl_add_u64 v[132:133], v[172:173], 2, s[6:7]
	global_load_dword v222, v[132:133], off
	v_lshl_or_b32 v166, s52, 8, v181
	v_ashrrev_i32_e32 v167, 31, v166
	v_lshlrev_b64 v[132:133], 11, v[172:173]
	v_lshl_add_u64 v[134:135], s[14:15], 0, v[132:133]
	v_lshlrev_b64 v[168:169], 1, v[166:167]
	v_lshl_add_u64 v[134:135], v[134:135], 0, v[168:169]
	v_lshlrev_b64 v[136:137], 12, v[172:173]
	global_load_dwordx4 v[186:189], v[134:135], off
	v_lshlrev_b64 v[170:171], 2, v[166:167]
	v_lshl_add_u64 v[136:137], s[4:5], 0, v[136:137]
	v_lshl_add_u64 v[178:179], v[136:137], 0, v[170:171]
	global_load_dwordx4 v[190:193], v[178:179], off
	global_load_dwordx4 v[194:197], v[178:179], off offset:16
	global_load_dwordx4 v[210:213], v[178:179], off offset:144
	global_load_dwordx4 v[214:217], v[178:179], off offset:128
	global_load_dwordx4 v[218:221], v[134:135], off offset:64
	v_xor_b32_e32 v136, 16, v238
	v_add_u32_e32 v137, 64, v239
	v_xor_b32_e32 v138, 32, v238
	v_cmp_lt_i32_e32 vcc, v136, v137
	v_or_b32_e32 v174, 16, v172
	v_ashrrev_i32_e32 v175, 31, v174
	v_cndmask_b32_e32 v136, v238, v136, vcc
	v_cmp_lt_i32_e32 vcc, v138, v137
	v_lshlrev_b64 v[140:141], 11, v[174:175]
	v_lshl_add_u64 v[140:141], s[14:15], 0, v[140:141]
	v_cndmask_b32_e32 v137, v238, v138, vcc
	v_lshlrev_b64 v[138:139], 12, v[174:175]
	v_lshl_add_u64 v[138:139], s[4:5], 0, v[138:139]
	v_lshlrev_b32_e32 v184, 2, v136
	v_lshlrev_b32_e32 v183, 2, v137
	v_lshl_add_u64 v[136:137], v[174:175], 2, s[6:7]
	v_lshl_add_u64 v[132:133], s[12:13], 0, v[132:133]
	v_lshl_add_u64 v[176:177], v[138:139], 0, v[170:171]
	v_lshl_add_u64 v[138:139], v[140:141], 0, v[168:169]
	v_lshl_add_u64 v[198:199], v[132:133], 0, v[168:169]
	global_load_dwordx4 v[144:147], v[176:177], off offset:16
	global_load_dwordx4 v[148:151], v[176:177], off
	global_load_dword v185, v[136:137], off
	global_load_dwordx4 v[152:155], v[138:139], off
	global_load_dwordx4 v[132:135], v[176:177], off offset:144
	global_load_dwordx4 v[140:143], v[176:177], off offset:128
	s_nop 0
	global_load_dwordx4 v[136:139], v[138:139], off offset:64
	s_waitcnt vmcnt(0)
	v_fmamk_f32 v222, v222, 0x3a800000, v236
	v_rsq_f32_e32 v226, v222
	v_lshlrev_b32_e32 v222, 16, v186
	v_mul_f32_e32 v228, 0xbfb8aa3b, v226
	v_mul_f32_e32 v128, v128, v228
	v_mul_f32_e32 v129, v129, v228
	v_mul_f32_e32 v124, v124, v228
	v_mul_f32_e32 v125, v125, v228
	v_exp_f32_e32 v128, v128
	v_exp_f32_e32 v129, v129
	v_exp_f32_e32 v124, v124
	v_exp_f32_e32 v125, v125
	v_mul_f32_e32 v116, v116, v228
	v_add_f32_e32 v128, 1.0, v128
	v_add_f32_e32 v129, 1.0, v129
	v_exp_f32_e32 v116, v116
	v_mul_f32_e32 v121, v121, v228
	v_add_f32_e32 v226, 1.0, v124
	v_add_f32_e32 v227, 1.0, v125
	v_rcp_f32_e32 v124, v128
	v_rcp_f32_e32 v125, v129
	v_mul_f32_e32 v120, v120, v228
	v_exp_f32_e32 v121, v121
	v_exp_f32_e32 v120, v120
	v_and_b32_e32 v223, 0xffff0000, v186
	v_add_f32_e32 v116, 1.0, v116
	v_pk_fma_f32 v[124:125], v[124:125], v[222:223], v[190:191]
	v_rcp_f32_e32 v190, v116
	v_add_f32_e32 v116, 1.0, v121
	v_add_f32_e32 v120, 1.0, v120
	v_rcp_f32_e32 v121, v116
	v_mul_f32_e32 v116, v117, v228
	v_rcp_f32_e32 v120, v120
	v_exp_f32_e32 v191, v116
	v_mul_f32_e32 v130, v130, v228
	v_mul_f32_e32 v131, v131, v228
	v_mul_f32_e32 v126, v126, v228
	v_mul_f32_e32 v127, v127, v228
	v_exp_f32_e32 v130, v130
	v_exp_f32_e32 v131, v131
	v_exp_f32_e32 v126, v126
	v_exp_f32_e32 v127, v127
	v_lshlrev_b32_e32 v116, 16, v218
	v_and_b32_e32 v117, 0xffff0000, v218
	v_pk_fma_f32 v[116:117], v[120:121], v[116:117], v[214:215]
	v_add_f32_e32 v120, 1.0, v191
	v_rcp_f32_e32 v191, v120
	v_add_f32_e32 v130, 1.0, v130
	v_add_f32_e32 v131, 1.0, v131
	v_add_f32_e32 v229, 1.0, v126
	v_add_f32_e32 v230, 1.0, v127
	v_rcp_f32_e32 v126, v226
	v_rcp_f32_e32 v127, v227
	v_rcp_f32_e32 v130, v130
	v_rcp_f32_e32 v131, v131
	v_mul_f32_e32 v120, v122, v228
	v_exp_f32_e32 v122, v120
	v_lshlrev_b32_e32 v120, 16, v220
	v_and_b32_e32 v121, 0xffff0000, v220
	v_mul_f32_e32 v118, v118, v228
	v_pk_fma_f32 v[120:121], v[190:191], v[120:121], v[210:211]
	v_exp_f32_e32 v190, v118
	v_mul_f32_e32 v118, v123, v228
	v_lshlrev_b32_e32 v224, 16, v188
	v_and_b32_e32 v225, 0xffff0000, v188
	v_lshlrev_b32_e32 v186, 16, v187
	v_and_b32_e32 v187, 0xffff0000, v187
	v_exp_f32_e32 v123, v118
	v_mul_f32_e32 v119, v119, v228
	v_pk_fma_f32 v[128:129], v[126:127], v[224:225], v[194:195]
	v_pk_fma_f32 v[126:127], v[130:131], v[186:187], v[192:193]
	v_exp_f32_e32 v192, v119
	v_add_f32_e32 v122, 1.0, v122
	v_add_f32_e32 v123, 1.0, v123
	v_rcp_f32_e32 v118, v122
	v_add_f32_e32 v122, 1.0, v190
	v_rcp_f32_e32 v119, v123
	v_add_f32_e32 v123, 1.0, v192
	v_rcp_f32_e32 v226, v229
	v_rcp_f32_e32 v227, v230
	v_rcp_f32_e32 v122, v122
	v_rcp_f32_e32 v123, v123
	v_lshlrev_b32_e32 v190, 16, v219
	v_and_b32_e32 v191, 0xffff0000, v219
	v_lshlrev_b32_e32 v188, 16, v189
	v_and_b32_e32 v189, 0xffff0000, v189
	v_pk_fma_f32 v[118:119], v[118:119], v[190:191], v[216:217]
	v_lshlrev_b32_e32 v190, 16, v221
	v_and_b32_e32 v191, 0xffff0000, v221
	v_pk_fma_f32 v[130:131], v[226:227], v[188:189], v[196:197]
	global_store_dwordx4 v[178:179], v[124:127], off
	global_store_dwordx4 v[178:179], v[128:131], off offset:16
	v_cvt_pk_bf16_f32 v186, v124, v125
	v_cvt_pk_bf16_f32 v187, v126, v127
	v_pk_mul_f32 v[124:125], v[124:125], v[124:125]
	v_pk_mul_f32 v[126:127], v[126:127], v[126:127]
	v_pk_fma_f32 v[122:123], v[122:123], v[190:191], v[212:213]
	v_pk_mul_f32 v[190:191], v[116:117], v[116:117]
	v_pk_mul_f32 v[192:193], v[118:119], v[118:119]
	v_cvt_pk_bf16_f32 v188, v128, v129
	v_pk_mul_f32 v[128:129], v[128:129], v[128:129]
	v_pk_mul_f32 v[194:195], v[120:121], v[120:121]
	v_add_f32_e32 v192, v192, v193
	v_add_f32_e32 v190, v190, v191
	v_add_f32_e32 v126, v126, v127
	v_add_f32_e32 v124, v124, v125
	v_cvt_pk_bf16_f32 v189, v130, v131
	v_pk_mul_f32 v[130:131], v[130:131], v[130:131]
	v_pk_mul_f32 v[196:197], v[122:123], v[122:123]
	v_add_f32_e32 v190, v190, v192
	v_add_f32_e32 v191, v194, v195
	v_add_f32_e32 v124, v124, v126
	v_add_f32_e32 v125, v128, v129
	v_add_f32_e32 v196, v196, v197
	v_add_f32_e32 v190, v191, v190
	v_add_f32_e32 v130, v130, v131
	v_add_f32_e32 v124, v125, v124
	v_add_f32_e32 v190, v196, v190
	v_add_f32_e32 v124, v130, v124
	v_add_f32_e32 v125, v124, v190
	ds_bpermute_b32 v126, v184, v125
	global_store_dwordx4 v[198:199], v[186:189], off
	global_store_dwordx4 v[178:179], v[116:119], off offset:128
	global_store_dwordx4 v[178:179], v[120:123], off offset:144
	v_cvt_pk_bf16_f32 v124, v116, v117
	v_cvt_pk_bf16_f32 v127, v122, v123
	s_waitcnt lgkmcnt(0)
	v_add_f32_e32 v116, v125, v126
	ds_bpermute_b32 v117, v183, v116
	v_cvt_pk_bf16_f32 v125, v118, v119
	v_cvt_pk_bf16_f32 v126, v120, v121
	global_store_dwordx4 v[198:199], v[124:127], off offset:64
	s_and_saveexec_b64 s[22:23], s[40:41]
	s_cbranch_execz .LBB0_1275
	s_waitcnt lgkmcnt(0)
	v_add_f32_e32 v118, v116, v117
	v_lshl_add_u64 v[116:117], v[172:173], 2, s[34:35]
	global_atomic_add_f32 v[116:117], v118, off
; __device__ __forceinline__ float rstd_of(float ss, float invn) { return __builtin_amdgcn_rsqf(ss * invn + EPS); }
; __device__ __forceinline__ u32x4 pack8(f32x4 a, f32x4 b) { u32x4 w; w.x = cvtpk(a[0], a[1]); w.y = cvtpk(a[2], a[3]); w.z = cvtpk(b[0], b[1]); w.w = cvtpk(b[2], b[3]); return w; }
; __device__ __forceinline__ void unpack8(u32x4 w, f32x4& a, f32x4& b) { a = (f32x4){bflo(w.x), bfhi(w.x), bflo(w.y), bfhi(w.y)}; b = (f32x4){bflo(w.z), bfhi(w.z), bflo(w.w), bfhi(w.w)}; }
;     __device__ __forceinline__ void operator()(const Acc& acc, const Unit& u, int wr, int wc, int fr, int fq) const {
;     ...
;             for (int mm = 0; mm < MB; ++mm) {
;                 const int m = mb + mm; const int r = u.pm * BM + ai * HALF + wr * 64 + m * 16 + fr; float ss = 0.f;
;                 const float t = PLE ? rstd_of(tt[mm], 1.f / 1024.f) : 1.f; const float tl = -t * 1.4426950408889634f; (void)tl;
; #pragma unroll
;                 for (int bj = 0; bj < 2; ++bj) {
;                     const int c0 = u.pn * BM + wc * 64 + bj * 32 + 8 * fq; float* hp = h + (size_t)r * DM + c0;
;                     f32x4 a = pa[mm][bj], b = pb[mm][bj];
;                     if (PLE) { f32x4 ta, tb; unpack8(pt[mm][bj], ta, tb);
; #pragma unroll
;                         for (int j = 0; j < 4; ++j) { a[j] += ta[j] * __builtin_amdgcn_rcpf(1.f + __builtin_amdgcn_exp2f(acc[ai][bj][m][0][j] * tl)); b[j] += tb[j] * __builtin_amdgcn_rcpf(1.f + __builtin_amdgcn_exp2f(acc[ai][bj][m][1][j] * tl)); } }
;                     else { a += acc[ai][bj][m][0] * alpha; b += acc[ai][bj][m][1] * alpha; }
;                     if (!dry || a[0] == 1234.56789f) { *(f32x4*)hp = a; *(f32x4*)(hp + 4) = b;
;                     *(u32x4*)(hb + (size_t)r * DM + c0) = pack8(a, b); }
;                     ss += (a[0] * a[0] + a[1] * a[1]) + (a[2] * a[2] + a[3] * a[3]) + (b[0] * b[0] + b[1] * b[1]) + (b[2] * b[2] + b[3] * b[3]);
;                 }
;                 ss += __shfl_xor(ss, 16); ss += __shfl_xor(ss, 32);
;                 if (fq == 0 && (!dry || ss == 1234.56789f)) unsafeAtomicAdd(rs_out + r, ss);
;             }
.LBB0_1275:
	s_or_b64 exec, exec, s[22:23]
	v_fmamk_f32 v116, v185, 0x3a800000, v236
	v_rsq_f32_e32 v116, v116
	v_lshlrev_b64 v[120:121], 10, v[174:175]
	v_lshl_add_u64 v[120:121], v[120:121], 1, s[12:13]
	v_lshl_add_u64 v[120:121], v[166:167], 1, v[120:121]
	v_mul_f32_e32 v124, 0xbfb8aa3b, v116
	v_mul_f32_e32 v108, v108, v124
	v_mul_f32_e32 v100, v100, v124
	v_exp_f32_e32 v108, v108
	v_mul_f32_e32 v113, v113, v124
	v_exp_f32_e32 v100, v100
	v_mul_f32_e32 v105, v105, v124
	v_mul_f32_e32 v112, v112, v124
	v_exp_f32_e32 v113, v113
	v_mul_f32_e32 v104, v104, v124
	v_exp_f32_e32 v105, v105
	v_exp_f32_e32 v112, v112
	v_exp_f32_e32 v104, v104
	v_add_f32_e32 v108, 1.0, v108
	v_add_f32_e32 v100, 1.0, v100
	v_rcp_f32_e32 v116, v108
	v_add_f32_e32 v108, 1.0, v113
	v_rcp_f32_e32 v122, v100
	v_add_f32_e32 v100, 1.0, v105
	v_add_f32_e32 v112, 1.0, v112
	v_rcp_f32_e32 v113, v108
	v_mul_f32_e32 v108, v109, v124
	v_add_f32_e32 v104, 1.0, v104
	v_rcp_f32_e32 v105, v100
	v_mul_f32_e32 v100, v101, v124
	v_rcp_f32_e32 v112, v112
	s_waitcnt lgkmcnt(0)
	v_exp_f32_e32 v117, v108
	v_rcp_f32_e32 v104, v104
	v_exp_f32_e32 v123, v100
	v_lshlrev_b32_e32 v108, 16, v152
	v_and_b32_e32 v109, 0xffff0000, v152
	v_lshlrev_b32_e32 v100, 16, v136
	v_and_b32_e32 v101, 0xffff0000, v136
	v_pk_fma_f32 v[108:109], v[112:113], v[108:109], v[148:149]
	v_add_f32_e32 v112, 1.0, v117
	v_pk_fma_f32 v[100:101], v[104:105], v[100:101], v[140:141]
	v_add_f32_e32 v104, 1.0, v123
	v_rcp_f32_e32 v117, v112
	v_rcp_f32_e32 v123, v104
	v_mul_f32_e32 v112, v114, v124
	v_mul_f32_e32 v104, v106, v124
	v_exp_f32_e32 v114, v112
	v_lshlrev_b32_e32 v112, 16, v154
	v_and_b32_e32 v113, 0xffff0000, v154
	v_mul_f32_e32 v110, v110, v124
	v_exp_f32_e32 v106, v104
	v_lshlrev_b32_e32 v104, 16, v138
	v_and_b32_e32 v105, 0xffff0000, v138
	v_mul_f32_e32 v102, v102, v124
	v_pk_fma_f32 v[112:113], v[116:117], v[112:113], v[144:145]
	v_exp_f32_e32 v116, v110
	v_mul_f32_e32 v110, v115, v124
	v_pk_fma_f32 v[104:105], v[122:123], v[104:105], v[132:133]
	v_exp_f32_e32 v122, v102
	v_mul_f32_e32 v102, v107, v124
	v_exp_f32_e32 v115, v110
	v_mul_f32_e32 v111, v111, v124
	v_exp_f32_e32 v107, v102
	v_mul_f32_e32 v103, v103, v124
	v_exp_f32_e32 v118, v111
	v_exp_f32_e32 v124, v103
	v_add_f32_e32 v114, 1.0, v114
	v_add_f32_e32 v115, 1.0, v115
	v_add_f32_e32 v106, 1.0, v106
	v_add_f32_e32 v107, 1.0, v107
	v_rcp_f32_e32 v110, v114
	v_add_f32_e32 v114, 1.0, v116
	v_rcp_f32_e32 v111, v115
	v_add_f32_e32 v115, 1.0, v118
	v_rcp_f32_e32 v102, v106
	v_add_f32_e32 v106, 1.0, v122
	v_rcp_f32_e32 v103, v107
	v_add_f32_e32 v107, 1.0, v124
	v_rcp_f32_e32 v114, v114
	v_rcp_f32_e32 v115, v115
	v_rcp_f32_e32 v106, v106
	v_rcp_f32_e32 v107, v107
	v_lshlrev_b32_e32 v116, 16, v153
	v_and_b32_e32 v117, 0xffff0000, v153
	v_lshlrev_b32_e32 v122, 16, v137
	v_and_b32_e32 v123, 0xffff0000, v137
	v_pk_fma_f32 v[110:111], v[110:111], v[116:117], v[150:151]
	v_lshlrev_b32_e32 v116, 16, v155
	v_and_b32_e32 v117, 0xffff0000, v155
	v_pk_fma_f32 v[102:103], v[102:103], v[122:123], v[142:143]
	v_lshlrev_b32_e32 v122, 16, v139
	v_and_b32_e32 v123, 0xffff0000, v139
	v_pk_fma_f32 v[114:115], v[114:115], v[116:117], v[146:147]
	global_store_dwordx4 v[176:177], v[108:111], off
	global_store_dwordx4 v[176:177], v[112:115], off offset:16
	v_cvt_pk_bf16_f32 v116, v108, v109
	v_cvt_pk_bf16_f32 v117, v110, v111
	v_pk_mul_f32 v[108:109], v[108:109], v[108:109]
	v_pk_mul_f32 v[110:111], v[110:111], v[110:111]
	v_pk_fma_f32 v[106:107], v[106:107], v[122:123], v[134:135]
	v_pk_mul_f32 v[122:123], v[100:101], v[100:101]
	v_pk_mul_f32 v[124:125], v[102:103], v[102:103]
	v_cvt_pk_bf16_f32 v118, v112, v113
	v_pk_mul_f32 v[112:113], v[112:113], v[112:113]
	v_pk_mul_f32 v[126:127], v[104:105], v[104:105]
	v_add_f32_e32 v124, v124, v125
	v_add_f32_e32 v122, v122, v123
	v_add_f32_e32 v110, v110, v111
	v_add_f32_e32 v108, v108, v109
	v_cvt_pk_bf16_f32 v119, v114, v115
	v_pk_mul_f32 v[114:115], v[114:115], v[114:115]
	v_pk_mul_f32 v[128:129], v[106:107], v[106:107]
	v_add_f32_e32 v122, v122, v124
	v_add_f32_e32 v123, v126, v127
	v_add_f32_e32 v108, v108, v110
	v_add_f32_e32 v109, v112, v113
	v_add_f32_e32 v128, v128, v129
	v_add_f32_e32 v122, v123, v122
	v_add_f32_e32 v114, v114, v115
	v_add_f32_e32 v108, v109, v108
	v_add_f32_e32 v122, v128, v122
	v_add_f32_e32 v108, v114, v108
	v_add_f32_e32 v109, v108, v122
	ds_bpermute_b32 v110, v184, v109
	global_store_dwordx4 v[120:121], v[116:119], off
	global_store_dwordx4 v[176:177], v[100:103], off offset:128
	global_store_dwordx4 v[176:177], v[104:107], off offset:144
	v_cvt_pk_bf16_f32 v108, v100, v101
	v_cvt_pk_bf16_f32 v111, v106, v107
	s_waitcnt lgkmcnt(0)
	v_add_f32_e32 v100, v109, v110
	ds_bpermute_b32 v101, v183, v100
	v_cvt_pk_bf16_f32 v109, v102, v103
	v_cvt_pk_bf16_f32 v110, v104, v105
	global_store_dwordx4 v[120:121], v[108:111], off offset:64
	s_and_saveexec_b64 s[22:23], s[40:41]
	s_cbranch_execz .LBB0_1277
	s_waitcnt lgkmcnt(0)
	v_add_f32_e32 v102, v100, v101
	v_lshl_add_u64 v[100:101], v[174:175], 2, s[34:35]
	global_atomic_add_f32 v[100:101], v102, off
; __device__ __forceinline__ float rstd_of(float ss, float invn) { return __builtin_amdgcn_rsqf(ss * invn + EPS); }
;     __device__ __forceinline__ void operator()(const Acc& acc, const Unit& u, int wr, int wc, int fr, int fq) const {
;     ...
; #pragma unroll
;             for (int mm = 0; mm < MB; ++mm) {
;                 const int m = mb + mm; const int r = u.pm * BM + ai * HALF + wr * 64 + m * 16 + fr;
;                 tt[mm] = PLE ? rs_in[r] : 0.f;
; #pragma unroll
;                 for (int bj = 0; bj < 2; ++bj) {
;                     const int c0 = u.pn * BM + wc * 64 + bj * 32 + 8 * fq; const float* hs = hsrc + (size_t)r * DM + c0;
;                     pa[mm][bj] = *(const f32x4*)hs; pb[mm][bj] = *(const f32x4*)(hs + 4);
;                     if (PLE) pt[mm][bj] = *(const u32x4*)(tmp + (size_t)r * DM + c0);
;                 }
;             }
; #pragma unroll
;             for (int mm = 0; mm < MB; ++mm) {
;                 const int m = mb + mm; const int r = u.pm * BM + ai * HALF + wr * 64 + m * 16 + fr; float ss = 0.f;
;                 const float t = PLE ? rstd_of(tt[mm], 1.f / 1024.f) : 1.f; const float tl = -t * 1.4426950408889634f; (void)tl;
; #pragma unroll
;                 for (int bj = 0; bj < 2; ++bj) {
;                     const int c0 = u.pn * BM + wc * 64 + bj * 32 + 8 * fq; float* hp = h + (size_t)r * DM + c0;
;                     f32x4 a = pa[mm][bj], b = pb[mm][bj];
;                     if (PLE) { f32x4 ta, tb; unpack8(pt[mm][bj], ta, tb);
; #pragma unroll
;                         for (int j = 0; j < 4; ++j) { a[j] += ta[j] * __builtin_amdgcn_rcpf(1.f + __builtin_amdgcn_exp2f(acc[ai][bj][m][0][j] * tl)); b[j] += tb[j] * __builtin_amdgcn_rcpf(1.f + __builtin_amdgcn_exp2f(acc[ai][bj][m][1][j] * tl)); } }
;                     else { a += acc[ai][bj][m][0] * alpha; b += acc[ai][bj][m][1] * alpha; }
;                     if (!dry || a[0] == 1234.56789f) { *(f32x4*)hp = a; *(f32x4*)(hp + 4) = b;
;                     *(u32x4*)(hb + (size_t)r * DM + c0) = pack8(a, b); }
;                     ss += (a[0] * a[0] + a[1] * a[1]) + (a[2] * a[2] + a[3] * a[3]) + (b[0] * b[0] + b[1] * b[1]) + (b[2] * b[2] + b[3] * b[3]);
;                 }
;                 ss += __shfl_xor(ss, 16); ss += __shfl_xor(ss, 32);
;                 if (fq == 0 && (!dry || ss == 1234.56789f)) unsafeAtomicAdd(rs_out + r, ss);
;             }
.LBB0_1277:
	s_or_b64 exec, exec, s[22:23]
	v_or_b32_e32 v128, 32, v172
	v_ashrrev_i32_e32 v129, 31, v128
	s_waitcnt lgkmcnt(0)
	v_lshl_add_u64 v[100:101], v[128:129], 2, s[6:7]
	global_load_dword v133, v[100:101], off
	v_lshlrev_b64 v[100:101], 11, v[128:129]
	v_lshl_add_u64 v[102:103], s[14:15], 0, v[100:101]
	v_lshl_add_u64 v[102:103], v[102:103], 0, v[168:169]
	v_lshlrev_b64 v[104:105], 12, v[128:129]
	global_load_dwordx4 v[134:137], v[102:103], off
	v_lshl_add_u64 v[104:105], s[4:5], 0, v[104:105]
	v_lshl_add_u64 v[130:131], v[104:105], 0, v[170:171]
	global_load_dwordx4 v[138:141], v[130:131], off
	global_load_dwordx4 v[142:145], v[130:131], off offset:16
	v_or_b32_e32 v124, 48, v172
	v_ashrrev_i32_e32 v125, 31, v124
	v_lshlrev_b64 v[106:107], 12, v[124:125]
	v_lshlrev_b64 v[108:109], 11, v[124:125]
	v_lshl_add_u64 v[106:107], s[4:5], 0, v[106:107]
	v_lshl_add_u64 v[108:109], s[14:15], 0, v[108:109]
	v_lshl_add_u64 v[104:105], v[124:125], 2, s[6:7]
	v_lshl_add_u64 v[100:101], s[12:13], 0, v[100:101]
	v_lshl_add_u64 v[126:127], v[106:107], 0, v[170:171]
	v_lshl_add_u64 v[106:107], v[108:109], 0, v[168:169]
	v_lshl_add_u64 v[154:155], v[100:101], 0, v[168:169]
	global_load_dwordx4 v[146:149], v[102:103], off offset:64
	global_load_dwordx4 v[150:153], v[130:131], off offset:144
	global_load_dwordx4 v[174:177], v[130:131], off offset:128
	global_load_dwordx4 v[112:115], v[126:127], off offset:16
	global_load_dwordx4 v[116:119], v[126:127], off
	global_load_dword v132, v[104:105], off
	global_load_dwordx4 v[120:123], v[106:107], off
	global_load_dwordx4 v[100:103], v[126:127], off offset:144
	global_load_dwordx4 v[108:111], v[126:127], off offset:128
	s_nop 0
	global_load_dwordx4 v[104:107], v[106:107], off offset:64
	s_waitcnt vmcnt(13)
	v_fmamk_f32 v133, v133, 0x3a800000, v236
	v_rsq_f32_e32 v133, v133
	s_waitcnt vmcnt(12)
	v_lshlrev_b32_e32 v178, 16, v134
	v_mul_f32_e32 v133, 0xbfb8aa3b, v133
	v_mul_f32_e32 v96, v96, v133
	v_mul_f32_e32 v97, v97, v133
	v_mul_f32_e32 v88, v88, v133
	v_exp_f32_e32 v96, v96
	v_exp_f32_e32 v97, v97
	v_exp_f32_e32 v88, v88
	v_mul_f32_e32 v92, v92, v133
	v_mul_f32_e32 v93, v93, v133
	v_mul_f32_e32 v84, v84, v133
	v_mul_f32_e32 v89, v89, v133
	v_mul_f32_e32 v94, v94, v133
	v_mul_f32_e32 v95, v95, v133
	v_exp_f32_e32 v92, v92
	v_exp_f32_e32 v93, v93
	v_exp_f32_e32 v84, v84
	v_exp_f32_e32 v173, v89
	v_add_f32_e32 v89, 1.0, v96
	v_add_f32_e32 v96, 1.0, v97
	v_exp_f32_e32 v94, v94
	v_exp_f32_e32 v95, v95
	v_add_f32_e32 v190, 1.0, v88
	v_rcp_f32_e32 v88, v89
	v_rcp_f32_e32 v89, v96
	v_and_b32_e32 v179, 0xffff0000, v134
	v_add_f32_e32 v92, 1.0, v92
	v_add_f32_e32 v93, 1.0, v93
	v_add_f32_e32 v84, 1.0, v84
	v_add_f32_e32 v185, 1.0, v94
	v_add_f32_e32 v189, 1.0, v95
	v_rcp_f32_e32 v94, v92
	v_rcp_f32_e32 v95, v93
	s_waitcnt vmcnt(11)
	v_pk_fma_f32 v[92:93], v[88:89], v[178:179], v[138:139]
	v_rcp_f32_e32 v88, v84
	v_add_f32_e32 v84, 1.0, v173
	v_rcp_f32_e32 v191, v84
	v_mul_f32_e32 v84, v85, v133
	v_exp_f32_e32 v89, v84
	s_waitcnt vmcnt(9)
	v_lshlrev_b32_e32 v138, 16, v148
	v_and_b32_e32 v139, 0xffff0000, v148
	v_mul_f32_e32 v86, v86, v133
	v_add_f32_e32 v89, 1.0, v89
	v_rcp_f32_e32 v89, v89
	v_mul_f32_e32 v98, v98, v133
	v_mul_f32_e32 v99, v99, v133
	v_mul_f32_e32 v90, v90, v133
	s_waitcnt vmcnt(8)
	v_pk_fma_f32 v[88:89], v[88:89], v[138:139], v[150:151]
	v_exp_f32_e32 v138, v86
	v_mul_f32_e32 v86, v91, v133
	v_exp_f32_e32 v98, v98
	v_exp_f32_e32 v99, v99
	v_exp_f32_e32 v90, v90
	v_exp_f32_e32 v91, v86
	v_mul_f32_e32 v87, v87, v133
	v_exp_f32_e32 v133, v87
	v_add_f32_e32 v97, 1.0, v98
	v_add_f32_e32 v99, 1.0, v99
	v_add_f32_e32 v90, 1.0, v90
	v_add_f32_e32 v91, 1.0, v91
	v_rcp_f32_e32 v98, v97
	v_rcp_f32_e32 v99, v99
	v_rcp_f32_e32 v190, v190
	v_rcp_f32_e32 v86, v90
	v_add_f32_e32 v90, 1.0, v138
	v_rcp_f32_e32 v87, v91
	v_add_f32_e32 v91, 1.0, v133
	v_rcp_f32_e32 v188, v185
	v_rcp_f32_e32 v189, v189
	v_rcp_f32_e32 v90, v90
	v_rcp_f32_e32 v91, v91
	v_lshlrev_b32_e32 v186, 16, v136
	v_and_b32_e32 v187, 0xffff0000, v136
	v_lshlrev_b32_e32 v134, 16, v135
	v_and_b32_e32 v135, 0xffff0000, v135
	v_lshlrev_b32_e32 v84, 16, v146
	v_and_b32_e32 v85, 0xffff0000, v146
	v_lshlrev_b32_e32 v138, 16, v147
	v_and_b32_e32 v139, 0xffff0000, v147
	v_lshlrev_b32_e32 v136, 16, v137
	v_and_b32_e32 v137, 0xffff0000, v137
	v_pk_fma_f32 v[96:97], v[94:95], v[186:187], v[142:143]
	v_pk_fma_f32 v[94:95], v[98:99], v[134:135], v[140:141]
	s_waitcnt vmcnt(7)
	v_pk_fma_f32 v[84:85], v[190:191], v[84:85], v[174:175]
	v_pk_fma_f32 v[86:87], v[86:87], v[138:139], v[176:177]
	v_lshlrev_b32_e32 v138, 16, v149
	v_and_b32_e32 v139, 0xffff0000, v149
	v_pk_fma_f32 v[98:99], v[188:189], v[136:137], v[144:145]
	global_store_dwordx4 v[130:131], v[92:95], off
	global_store_dwordx4 v[130:131], v[96:99], off offset:16
	v_cvt_pk_bf16_f32 v134, v92, v93
	v_cvt_pk_bf16_f32 v135, v94, v95
	v_pk_mul_f32 v[92:93], v[92:93], v[92:93]
	v_pk_mul_f32 v[94:95], v[94:95], v[94:95]
	v_pk_fma_f32 v[90:91], v[90:91], v[138:139], v[152:153]
	v_pk_mul_f32 v[138:139], v[84:85], v[84:85]
	v_pk_mul_f32 v[140:141], v[86:87], v[86:87]
	v_cvt_pk_bf16_f32 v136, v96, v97
	v_pk_mul_f32 v[96:97], v[96:97], v[96:97]
	v_pk_mul_f32 v[142:143], v[88:89], v[88:89]
	v_add_f32_e32 v133, v140, v141
	v_add_f32_e32 v138, v138, v139
	v_add_f32_e32 v94, v94, v95
	v_add_f32_e32 v92, v92, v93
	v_cvt_pk_bf16_f32 v137, v98, v99
	v_pk_mul_f32 v[98:99], v[98:99], v[98:99]
	v_pk_mul_f32 v[144:145], v[90:91], v[90:91]
	v_add_f32_e32 v133, v138, v133
	v_add_f32_e32 v138, v142, v143
	v_add_f32_e32 v92, v92, v94
	v_add_f32_e32 v93, v96, v97
	v_add_f32_e32 v133, v138, v133
	v_add_f32_e32 v138, v144, v145
	v_add_f32_e32 v92, v93, v92
	v_add_f32_e32 v93, v98, v99
	v_add_f32_e32 v133, v138, v133
	v_add_f32_e32 v92, v93, v92
	v_add_f32_e32 v93, v92, v133
	ds_bpermute_b32 v94, v184, v93
	global_store_dwordx4 v[154:155], v[134:137], off
	global_store_dwordx4 v[130:131], v[84:87], off offset:128
	global_store_dwordx4 v[130:131], v[88:91], off offset:144
	v_cvt_pk_bf16_f32 v92, v84, v85
	v_cvt_pk_bf16_f32 v95, v90, v91
	s_waitcnt lgkmcnt(0)
	v_add_f32_e32 v84, v93, v94
	ds_bpermute_b32 v85, v183, v84
	v_cvt_pk_bf16_f32 v93, v86, v87
	v_cvt_pk_bf16_f32 v94, v88, v89
	global_store_dwordx4 v[154:155], v[92:95], off offset:64
	s_and_saveexec_b64 s[22:23], s[40:41]
	v_readlane_b32 s76, v252, 25
	v_readlane_b32 s77, v252, 26
	s_cbranch_execz .LBB0_1279
	s_waitcnt lgkmcnt(0)
	v_add_f32_e32 v86, v84, v85
	v_lshl_add_u64 v[84:85], v[128:129], 2, s[34:35]
	global_atomic_add_f32 v[84:85], v86, off
; __device__ __forceinline__ float rstd_of(float ss, float invn) { return __builtin_amdgcn_rsqf(ss * invn + EPS); }
; __device__ __forceinline__ u32x4 pack8(f32x4 a, f32x4 b) { u32x4 w; w.x = cvtpk(a[0], a[1]); w.y = cvtpk(a[2], a[3]); w.z = cvtpk(b[0], b[1]); w.w = cvtpk(b[2], b[3]); return w; }
; __device__ __forceinline__ void unpack8(u32x4 w, f32x4& a, f32x4& b) { a = (f32x4){bflo(w.x), bfhi(w.x), bflo(w.y), bfhi(w.y)}; b = (f32x4){bflo(w.z), bfhi(w.z), bflo(w.w), bfhi(w.w)}; }
;     __device__ __forceinline__ void operator()(const Acc& acc, const Unit& u, int wr, int wc, int fr, int fq) const {
;     ...
;             for (int mm = 0; mm < MB; ++mm) {
;                 const int m = mb + mm; const int r = u.pm * BM + ai * HALF + wr * 64 + m * 16 + fr; float ss = 0.f;
;                 const float t = PLE ? rstd_of(tt[mm], 1.f / 1024.f) : 1.f; const float tl = -t * 1.4426950408889634f; (void)tl;
; #pragma unroll
;                 for (int bj = 0; bj < 2; ++bj) {
;                     const int c0 = u.pn * BM + wc * 64 + bj * 32 + 8 * fq; float* hp = h + (size_t)r * DM + c0;
;                     f32x4 a = pa[mm][bj], b = pb[mm][bj];
;                     if (PLE) { f32x4 ta, tb; unpack8(pt[mm][bj], ta, tb);
; #pragma unroll
;                         for (int j = 0; j < 4; ++j) { a[j] += ta[j] * __builtin_amdgcn_rcpf(1.f + __builtin_amdgcn_exp2f(acc[ai][bj][m][0][j] * tl)); b[j] += tb[j] * __builtin_amdgcn_rcpf(1.f + __builtin_amdgcn_exp2f(acc[ai][bj][m][1][j] * tl)); } }
;                     else { a += acc[ai][bj][m][0] * alpha; b += acc[ai][bj][m][1] * alpha; }
;                     if (!dry || a[0] == 1234.56789f) { *(f32x4*)hp = a; *(f32x4*)(hp + 4) = b;
;                     *(u32x4*)(hb + (size_t)r * DM + c0) = pack8(a, b); }
;                     ss += (a[0] * a[0] + a[1] * a[1]) + (a[2] * a[2] + a[3] * a[3]) + (b[0] * b[0] + b[1] * b[1]) + (b[2] * b[2] + b[3] * b[3]);
;                 }
;                 ss += __shfl_xor(ss, 16); ss += __shfl_xor(ss, 32);
;                 if (fq == 0 && (!dry || ss == 1234.56789f)) unsafeAtomicAdd(rs_out + r, ss);
;             }
.LBB0_1279:
	s_or_b64 exec, exec, s[22:23]
	s_waitcnt vmcnt(10)
	v_fmamk_f32 v84, v132, 0x3a800000, v236
	v_rsq_f32_e32 v84, v84
	v_lshlrev_b64 v[88:89], 10, v[124:125]
	v_lshl_add_u64 v[88:89], v[88:89], 1, s[12:13]
	v_lshl_add_u64 v[88:89], v[166:167], 1, v[88:89]
	v_mul_f32_e32 v92, 0xbfb8aa3b, v84
	v_mul_f32_e32 v76, v76, v92
	v_mul_f32_e32 v68, v68, v92
	v_exp_f32_e32 v76, v76
	v_mul_f32_e32 v81, v81, v92
	v_exp_f32_e32 v68, v68
	v_mul_f32_e32 v73, v73, v92
	v_mul_f32_e32 v80, v80, v92
	v_exp_f32_e32 v81, v81
	v_mul_f32_e32 v72, v72, v92
	v_exp_f32_e32 v73, v73
	v_exp_f32_e32 v80, v80
	v_exp_f32_e32 v72, v72
	v_add_f32_e32 v76, 1.0, v76
	v_add_f32_e32 v68, 1.0, v68
	v_rcp_f32_e32 v84, v76
	v_add_f32_e32 v76, 1.0, v81
	v_rcp_f32_e32 v90, v68
	v_add_f32_e32 v68, 1.0, v73
	v_add_f32_e32 v80, 1.0, v80
	v_rcp_f32_e32 v81, v76
	v_mul_f32_e32 v76, v77, v92
	v_add_f32_e32 v72, 1.0, v72
	v_rcp_f32_e32 v73, v68
	v_mul_f32_e32 v68, v69, v92
	v_rcp_f32_e32 v80, v80
	s_waitcnt lgkmcnt(0)
	v_exp_f32_e32 v85, v76
	v_rcp_f32_e32 v72, v72
	v_exp_f32_e32 v91, v68
	s_waitcnt vmcnt(9)
	v_lshlrev_b32_e32 v76, 16, v120
	v_and_b32_e32 v77, 0xffff0000, v120
	s_waitcnt vmcnt(6)
	v_lshlrev_b32_e32 v68, 16, v104
	v_and_b32_e32 v69, 0xffff0000, v104
	v_pk_fma_f32 v[76:77], v[80:81], v[76:77], v[116:117]
	v_add_f32_e32 v80, 1.0, v85
	v_pk_fma_f32 v[68:69], v[72:73], v[68:69], v[108:109]
	v_add_f32_e32 v72, 1.0, v91
	v_rcp_f32_e32 v85, v80
	v_rcp_f32_e32 v91, v72
	v_mul_f32_e32 v80, v82, v92
	v_mul_f32_e32 v72, v74, v92
	v_exp_f32_e32 v82, v80
	v_lshlrev_b32_e32 v80, 16, v122
	v_and_b32_e32 v81, 0xffff0000, v122
	v_mul_f32_e32 v78, v78, v92
	v_exp_f32_e32 v74, v72
	v_lshlrev_b32_e32 v72, 16, v106
	v_and_b32_e32 v73, 0xffff0000, v106
	v_mul_f32_e32 v70, v70, v92
	v_pk_fma_f32 v[80:81], v[84:85], v[80:81], v[112:113]
	v_exp_f32_e32 v84, v78
	v_mul_f32_e32 v78, v83, v92
	v_pk_fma_f32 v[72:73], v[90:91], v[72:73], v[100:101]
	v_exp_f32_e32 v90, v70
	v_mul_f32_e32 v70, v75, v92
	v_exp_f32_e32 v83, v78
	v_mul_f32_e32 v79, v79, v92
	v_exp_f32_e32 v75, v70
	v_mul_f32_e32 v71, v71, v92
	v_exp_f32_e32 v86, v79
	v_exp_f32_e32 v92, v71
	v_add_f32_e32 v82, 1.0, v82
	v_add_f32_e32 v83, 1.0, v83
	v_add_f32_e32 v74, 1.0, v74
	v_add_f32_e32 v75, 1.0, v75
	v_rcp_f32_e32 v78, v82
	v_add_f32_e32 v82, 1.0, v84
	v_rcp_f32_e32 v79, v83
	v_add_f32_e32 v83, 1.0, v86
	v_rcp_f32_e32 v70, v74
	v_add_f32_e32 v74, 1.0, v90
	v_rcp_f32_e32 v71, v75
	v_add_f32_e32 v75, 1.0, v92
	v_rcp_f32_e32 v82, v82
	v_rcp_f32_e32 v83, v83
	v_rcp_f32_e32 v74, v74
	v_rcp_f32_e32 v75, v75
	v_lshlrev_b32_e32 v84, 16, v121
	v_and_b32_e32 v85, 0xffff0000, v121
	v_lshlrev_b32_e32 v90, 16, v105
	v_and_b32_e32 v91, 0xffff0000, v105
	v_pk_fma_f32 v[78:79], v[78:79], v[84:85], v[118:119]
	v_lshlrev_b32_e32 v84, 16, v123
	v_and_b32_e32 v85, 0xffff0000, v123
	v_pk_fma_f32 v[70:71], v[70:71], v[90:91], v[110:111]
	v_lshlrev_b32_e32 v90, 16, v107
	v_and_b32_e32 v91, 0xffff0000, v107
	v_pk_fma_f32 v[82:83], v[82:83], v[84:85], v[114:115]
	global_store_dwordx4 v[126:127], v[76:79], off
	global_store_dwordx4 v[126:127], v[80:83], off offset:16
	v_cvt_pk_bf16_f32 v84, v76, v77
	v_cvt_pk_bf16_f32 v85, v78, v79
	v_pk_mul_f32 v[76:77], v[76:77], v[76:77]
	v_pk_mul_f32 v[78:79], v[78:79], v[78:79]
	v_pk_fma_f32 v[74:75], v[74:75], v[90:91], v[102:103]
	v_pk_mul_f32 v[90:91], v[68:69], v[68:69]
	v_pk_mul_f32 v[92:93], v[70:71], v[70:71]
	v_cvt_pk_bf16_f32 v86, v80, v81
	v_pk_mul_f32 v[80:81], v[80:81], v[80:81]
	v_pk_mul_f32 v[94:95], v[72:73], v[72:73]
	v_add_f32_e32 v92, v92, v93
	v_add_f32_e32 v90, v90, v91
	v_add_f32_e32 v78, v78, v79
	v_add_f32_e32 v76, v76, v77
	v_cvt_pk_bf16_f32 v87, v82, v83
	v_pk_mul_f32 v[82:83], v[82:83], v[82:83]
	v_pk_mul_f32 v[96:97], v[74:75], v[74:75]
	v_add_f32_e32 v90, v90, v92
	v_add_f32_e32 v91, v94, v95
	v_add_f32_e32 v76, v76, v78
	v_add_f32_e32 v77, v80, v81
	v_add_f32_e32 v96, v96, v97
	v_add_f32_e32 v90, v91, v90
	v_add_f32_e32 v82, v82, v83
	v_add_f32_e32 v76, v77, v76
	v_add_f32_e32 v90, v96, v90
	v_add_f32_e32 v76, v82, v76
	v_add_f32_e32 v77, v76, v90
	ds_bpermute_b32 v78, v184, v77
	global_store_dwordx4 v[88:89], v[84:87], off
	global_store_dwordx4 v[126:127], v[68:71], off offset:128
	global_store_dwordx4 v[126:127], v[72:75], off offset:144
	v_cvt_pk_bf16_f32 v76, v68, v69
	v_cvt_pk_bf16_f32 v79, v74, v75
	s_waitcnt lgkmcnt(0)
	v_add_f32_e32 v68, v77, v78
	ds_bpermute_b32 v69, v183, v68
	v_cvt_pk_bf16_f32 v77, v70, v71
	v_cvt_pk_bf16_f32 v78, v72, v73
	global_store_dwordx4 v[88:89], v[76:79], off offset:64
	s_and_saveexec_b64 s[22:23], s[40:41]
	s_cbranch_execz .LBB0_1281
	s_waitcnt lgkmcnt(0)
	v_add_f32_e32 v70, v68, v69
	v_lshl_add_u64 v[68:69], v[124:125], 2, s[34:35]
	global_atomic_add_f32 v[68:69], v70, off
; __device__ __forceinline__ float rstd_of(float ss, float invn) { return __builtin_amdgcn_rsqf(ss * invn + EPS); }
;     __device__ __forceinline__ void operator()(const Acc& acc, const Unit& u, int wr, int wc, int fr, int fq) const {
;     ...
; #pragma unroll
;             for (int mm = 0; mm < MB; ++mm) {
;                 const int m = mb + mm; const int r = u.pm * BM + ai * HALF + wr * 64 + m * 16 + fr;
;                 tt[mm] = PLE ? rs_in[r] : 0.f;
; #pragma unroll
;                 for (int bj = 0; bj < 2; ++bj) {
;                     const int c0 = u.pn * BM + wc * 64 + bj * 32 + 8 * fq; const float* hs = hsrc + (size_t)r * DM + c0;
;                     pa[mm][bj] = *(const f32x4*)hs; pb[mm][bj] = *(const f32x4*)(hs + 4);
;                     if (PLE) pt[mm][bj] = *(const u32x4*)(tmp + (size_t)r * DM + c0);
;                 }
;             }
; #pragma unroll
;             for (int mm = 0; mm < MB; ++mm) {
;                 const int m = mb + mm; const int r = u.pm * BM + ai * HALF + wr * 64 + m * 16 + fr; float ss = 0.f;
;                 const float t = PLE ? rstd_of(tt[mm], 1.f / 1024.f) : 1.f; const float tl = -t * 1.4426950408889634f; (void)tl;
; #pragma unroll
;                 for (int bj = 0; bj < 2; ++bj) {
;                     const int c0 = u.pn * BM + wc * 64 + bj * 32 + 8 * fq; float* hp = h + (size_t)r * DM + c0;
;                     f32x4 a = pa[mm][bj], b = pb[mm][bj];
;                     if (PLE) { f32x4 ta, tb; unpack8(pt[mm][bj], ta, tb);
; #pragma unroll
;                         for (int j = 0; j < 4; ++j) { a[j] += ta[j] * __builtin_amdgcn_rcpf(1.f + __builtin_amdgcn_exp2f(acc[ai][bj][m][0][j] * tl)); b[j] += tb[j] * __builtin_amdgcn_rcpf(1.f + __builtin_amdgcn_exp2f(acc[ai][bj][m][1][j] * tl)); } }
;                     else { a += acc[ai][bj][m][0] * alpha; b += acc[ai][bj][m][1] * alpha; }
;                     if (!dry || a[0] == 1234.56789f) { *(f32x4*)hp = a; *(f32x4*)(hp + 4) = b;
;                     *(u32x4*)(hb + (size_t)r * DM + c0) = pack8(a, b); }
;                     ss += (a[0] * a[0] + a[1] * a[1]) + (a[2] * a[2] + a[3] * a[3]) + (b[0] * b[0] + b[1] * b[1]) + (b[2] * b[2] + b[3] * b[3]);
;                 }
;                 ss += __shfl_xor(ss, 16); ss += __shfl_xor(ss, 32);
;                 if (fq == 0 && (!dry || ss == 1234.56789f)) unsafeAtomicAdd(rs_out + r, ss);
;             }
.LBB0_1281:
	s_or_b64 exec, exec, s[22:23]
	v_add_u32_e32 v96, 0x80, v172
	v_ashrrev_i32_e32 v97, 31, v96
	s_waitcnt lgkmcnt(0)
	v_lshl_add_u64 v[68:69], v[96:97], 2, s[6:7]
	global_load_dword v101, v[68:69], off
	v_lshlrev_b64 v[68:69], 11, v[96:97]
	v_lshl_add_u64 v[70:71], s[14:15], 0, v[68:69]
	v_lshl_add_u64 v[70:71], v[70:71], 0, v[168:169]
	v_lshlrev_b64 v[72:73], 12, v[96:97]
	global_load_dwordx4 v[102:105], v[70:71], off
	v_lshl_add_u64 v[72:73], s[4:5], 0, v[72:73]
	v_lshl_add_u64 v[98:99], v[72:73], 0, v[170:171]
	global_load_dwordx4 v[106:109], v[98:99], off
	global_load_dwordx4 v[110:113], v[98:99], off offset:16
	v_add_u32_e32 v92, 0x90, v172
	v_ashrrev_i32_e32 v93, 31, v92
	v_lshlrev_b64 v[74:75], 12, v[92:93]
	v_lshlrev_b64 v[76:77], 11, v[92:93]
	v_lshl_add_u64 v[74:75], s[4:5], 0, v[74:75]
	v_lshl_add_u64 v[76:77], s[14:15], 0, v[76:77]
	v_lshl_add_u64 v[72:73], v[92:93], 2, s[6:7]
	v_lshl_add_u64 v[68:69], s[12:13], 0, v[68:69]
	v_lshl_add_u64 v[94:95], v[74:75], 0, v[170:171]
	v_lshl_add_u64 v[74:75], v[76:77], 0, v[168:169]
	v_lshl_add_u64 v[126:127], v[68:69], 0, v[168:169]
	global_load_dwordx4 v[114:117], v[70:71], off offset:64
	global_load_dwordx4 v[118:121], v[98:99], off offset:144
	global_load_dwordx4 v[122:125], v[98:99], off offset:128
	global_load_dwordx4 v[80:83], v[94:95], off offset:16
	global_load_dwordx4 v[84:87], v[94:95], off
	global_load_dword v100, v[72:73], off
	global_load_dwordx4 v[88:91], v[74:75], off
	global_load_dwordx4 v[68:71], v[94:95], off offset:144
	global_load_dwordx4 v[76:79], v[94:95], off offset:128
	s_nop 0
	global_load_dwordx4 v[72:75], v[74:75], off offset:64
	s_waitcnt vmcnt(13)
	v_fmamk_f32 v101, v101, 0x3a800000, v236
	v_rsq_f32_e32 v101, v101
	s_waitcnt vmcnt(12)
	v_lshlrev_b32_e32 v128, 16, v102
	v_mul_f32_e32 v101, 0xbfb8aa3b, v101
	v_mul_f32_e32 v64, v64, v101
	v_mul_f32_e32 v65, v65, v101
	v_mul_f32_e32 v56, v56, v101
	v_exp_f32_e32 v64, v64
	v_exp_f32_e32 v65, v65
	v_exp_f32_e32 v56, v56
	v_mul_f32_e32 v60, v60, v101
	v_mul_f32_e32 v61, v61, v101
	v_mul_f32_e32 v52, v52, v101
	v_mul_f32_e32 v57, v57, v101
	v_mul_f32_e32 v62, v62, v101
	v_mul_f32_e32 v63, v63, v101
	v_exp_f32_e32 v60, v60
	v_exp_f32_e32 v61, v61
	v_exp_f32_e32 v52, v52
	v_exp_f32_e32 v135, v57
	v_add_f32_e32 v57, 1.0, v64
	v_add_f32_e32 v64, 1.0, v65
	v_exp_f32_e32 v62, v62
	v_exp_f32_e32 v63, v63
	v_add_f32_e32 v134, 1.0, v56
	v_rcp_f32_e32 v56, v57
	v_rcp_f32_e32 v57, v64
	v_and_b32_e32 v129, 0xffff0000, v102
	v_add_f32_e32 v60, 1.0, v60
	v_add_f32_e32 v61, 1.0, v61
	v_add_f32_e32 v52, 1.0, v52
	v_add_f32_e32 v132, 1.0, v62
	v_add_f32_e32 v133, 1.0, v63
	v_rcp_f32_e32 v62, v60
	v_rcp_f32_e32 v63, v61
	s_waitcnt vmcnt(11)
	v_pk_fma_f32 v[60:61], v[56:57], v[128:129], v[106:107]
	v_rcp_f32_e32 v56, v52
	v_add_f32_e32 v52, 1.0, v135
	v_rcp_f32_e32 v135, v52
	v_mul_f32_e32 v52, v53, v101
	v_exp_f32_e32 v57, v52
	s_waitcnt vmcnt(9)
	v_lshlrev_b32_e32 v106, 16, v116
	v_and_b32_e32 v107, 0xffff0000, v116
	v_mul_f32_e32 v54, v54, v101
	v_add_f32_e32 v57, 1.0, v57
	v_rcp_f32_e32 v57, v57
	v_mul_f32_e32 v66, v66, v101
	v_mul_f32_e32 v67, v67, v101
	v_mul_f32_e32 v58, v58, v101
	s_waitcnt vmcnt(8)
	v_pk_fma_f32 v[56:57], v[56:57], v[106:107], v[118:119]
	v_exp_f32_e32 v106, v54
	v_mul_f32_e32 v54, v59, v101
	v_exp_f32_e32 v66, v66
	v_exp_f32_e32 v67, v67
	v_exp_f32_e32 v58, v58
	v_exp_f32_e32 v59, v54
	v_mul_f32_e32 v55, v55, v101
	v_exp_f32_e32 v101, v55
	v_add_f32_e32 v65, 1.0, v66
	v_add_f32_e32 v67, 1.0, v67
	v_add_f32_e32 v58, 1.0, v58
	v_add_f32_e32 v59, 1.0, v59
	v_rcp_f32_e32 v66, v65
	v_rcp_f32_e32 v67, v67
	v_rcp_f32_e32 v134, v134
	v_rcp_f32_e32 v54, v58
	v_add_f32_e32 v58, 1.0, v106
	v_rcp_f32_e32 v55, v59
	v_add_f32_e32 v59, 1.0, v101
	v_rcp_f32_e32 v132, v132
	v_rcp_f32_e32 v133, v133
	v_rcp_f32_e32 v58, v58
	v_rcp_f32_e32 v59, v59
	v_lshlrev_b32_e32 v130, 16, v104
	v_and_b32_e32 v131, 0xffff0000, v104
	v_lshlrev_b32_e32 v102, 16, v103
	v_and_b32_e32 v103, 0xffff0000, v103
	v_lshlrev_b32_e32 v52, 16, v114
	v_and_b32_e32 v53, 0xffff0000, v114
	v_lshlrev_b32_e32 v106, 16, v115
	v_and_b32_e32 v107, 0xffff0000, v115
	v_lshlrev_b32_e32 v104, 16, v105
	v_and_b32_e32 v105, 0xffff0000, v105
	v_pk_fma_f32 v[64:65], v[62:63], v[130:131], v[110:111]
	v_pk_fma_f32 v[62:63], v[66:67], v[102:103], v[108:109]
	s_waitcnt vmcnt(7)
	v_pk_fma_f32 v[52:53], v[134:135], v[52:53], v[122:123]
	v_pk_fma_f32 v[54:55], v[54:55], v[106:107], v[124:125]
	v_lshlrev_b32_e32 v106, 16, v117
	v_and_b32_e32 v107, 0xffff0000, v117
	v_pk_fma_f32 v[66:67], v[132:133], v[104:105], v[112:113]
	global_store_dwordx4 v[98:99], v[60:63], off
	global_store_dwordx4 v[98:99], v[64:67], off offset:16
	v_cvt_pk_bf16_f32 v102, v60, v61
	v_cvt_pk_bf16_f32 v103, v62, v63
	v_pk_mul_f32 v[60:61], v[60:61], v[60:61]
	v_pk_mul_f32 v[62:63], v[62:63], v[62:63]
	v_pk_fma_f32 v[58:59], v[58:59], v[106:107], v[120:121]
	v_pk_mul_f32 v[106:107], v[52:53], v[52:53]
	v_pk_mul_f32 v[108:109], v[54:55], v[54:55]
	v_cvt_pk_bf16_f32 v104, v64, v65
	v_pk_mul_f32 v[64:65], v[64:65], v[64:65]
	v_pk_mul_f32 v[110:111], v[56:57], v[56:57]
	v_add_f32_e32 v101, v108, v109
	v_add_f32_e32 v106, v106, v107
	v_add_f32_e32 v62, v62, v63
	v_add_f32_e32 v60, v60, v61
	v_cvt_pk_bf16_f32 v105, v66, v67
	v_pk_mul_f32 v[66:67], v[66:67], v[66:67]
	v_pk_mul_f32 v[112:113], v[58:59], v[58:59]
	v_add_f32_e32 v101, v106, v101
	v_add_f32_e32 v106, v110, v111
	v_add_f32_e32 v60, v60, v62
	v_add_f32_e32 v61, v64, v65
	v_add_f32_e32 v101, v106, v101
	v_add_f32_e32 v106, v112, v113
	v_add_f32_e32 v60, v61, v60
	v_add_f32_e32 v61, v66, v67
	v_add_f32_e32 v101, v106, v101
	v_add_f32_e32 v60, v61, v60
	v_add_f32_e32 v61, v60, v101
	ds_bpermute_b32 v62, v184, v61
	global_store_dwordx4 v[126:127], v[102:105], off
	global_store_dwordx4 v[98:99], v[52:55], off offset:128
	global_store_dwordx4 v[98:99], v[56:59], off offset:144
	v_cvt_pk_bf16_f32 v60, v52, v53
	v_cvt_pk_bf16_f32 v63, v58, v59
	s_waitcnt lgkmcnt(0)
	v_add_f32_e32 v52, v61, v62
	ds_bpermute_b32 v53, v183, v52
	v_cvt_pk_bf16_f32 v61, v54, v55
	v_cvt_pk_bf16_f32 v62, v56, v57
	global_store_dwordx4 v[126:127], v[60:63], off offset:64
	s_and_saveexec_b64 s[22:23], s[40:41]
	s_cbranch_execz .LBB0_1283
	s_waitcnt lgkmcnt(0)
	v_add_f32_e32 v54, v52, v53
	v_lshl_add_u64 v[52:53], v[96:97], 2, s[34:35]
	global_atomic_add_f32 v[52:53], v54, off
; __device__ __forceinline__ float rstd_of(float ss, float invn) { return __builtin_amdgcn_rsqf(ss * invn + EPS); }
; __device__ __forceinline__ u32x4 pack8(f32x4 a, f32x4 b) { u32x4 w; w.x = cvtpk(a[0], a[1]); w.y = cvtpk(a[2], a[3]); w.z = cvtpk(b[0], b[1]); w.w = cvtpk(b[2], b[3]); return w; }
; __device__ __forceinline__ void unpack8(u32x4 w, f32x4& a, f32x4& b) { a = (f32x4){bflo(w.x), bfhi(w.x), bflo(w.y), bfhi(w.y)}; b = (f32x4){bflo(w.z), bfhi(w.z), bflo(w.w), bfhi(w.w)}; }
;     __device__ __forceinline__ void operator()(const Acc& acc, const Unit& u, int wr, int wc, int fr, int fq) const {
;     ...
;             for (int mm = 0; mm < MB; ++mm) {
;                 const int m = mb + mm; const int r = u.pm * BM + ai * HALF + wr * 64 + m * 16 + fr; float ss = 0.f;
;                 const float t = PLE ? rstd_of(tt[mm], 1.f / 1024.f) : 1.f; const float tl = -t * 1.4426950408889634f; (void)tl;
; #pragma unroll
;                 for (int bj = 0; bj < 2; ++bj) {
;                     const int c0 = u.pn * BM + wc * 64 + bj * 32 + 8 * fq; float* hp = h + (size_t)r * DM + c0;
;                     f32x4 a = pa[mm][bj], b = pb[mm][bj];
;                     if (PLE) { f32x4 ta, tb; unpack8(pt[mm][bj], ta, tb);
; #pragma unroll
;                         for (int j = 0; j < 4; ++j) { a[j] += ta[j] * __builtin_amdgcn_rcpf(1.f + __builtin_amdgcn_exp2f(acc[ai][bj][m][0][j] * tl)); b[j] += tb[j] * __builtin_amdgcn_rcpf(1.f + __builtin_amdgcn_exp2f(acc[ai][bj][m][1][j] * tl)); } }
;                     else { a += acc[ai][bj][m][0] * alpha; b += acc[ai][bj][m][1] * alpha; }
;                     if (!dry || a[0] == 1234.56789f) { *(f32x4*)hp = a; *(f32x4*)(hp + 4) = b;
;                     *(u32x4*)(hb + (size_t)r * DM + c0) = pack8(a, b); }
;                     ss += (a[0] * a[0] + a[1] * a[1]) + (a[2] * a[2] + a[3] * a[3]) + (b[0] * b[0] + b[1] * b[1]) + (b[2] * b[2] + b[3] * b[3]);
;                 }
;                 ss += __shfl_xor(ss, 16); ss += __shfl_xor(ss, 32);
;                 if (fq == 0 && (!dry || ss == 1234.56789f)) unsafeAtomicAdd(rs_out + r, ss);
;             }
.LBB0_1283:
	s_or_b64 exec, exec, s[22:23]
	s_waitcnt vmcnt(10)
	v_fmamk_f32 v52, v100, 0x3a800000, v236
	v_rsq_f32_e32 v52, v52
	v_lshlrev_b64 v[56:57], 10, v[92:93]
	v_lshl_add_u64 v[56:57], v[56:57], 1, s[12:13]
	v_lshl_add_u64 v[56:57], v[166:167], 1, v[56:57]
	v_mul_f32_e32 v60, 0xbfb8aa3b, v52
	v_mul_f32_e32 v44, v44, v60
	v_mul_f32_e32 v36, v36, v60
	v_exp_f32_e32 v44, v44
	v_mul_f32_e32 v49, v49, v60
	v_exp_f32_e32 v36, v36
	v_mul_f32_e32 v41, v41, v60
	v_mul_f32_e32 v48, v48, v60
	v_exp_f32_e32 v49, v49
	v_mul_f32_e32 v40, v40, v60
	v_exp_f32_e32 v41, v41
	v_exp_f32_e32 v48, v48
	v_exp_f32_e32 v40, v40
	v_add_f32_e32 v44, 1.0, v44
	v_add_f32_e32 v36, 1.0, v36
	v_rcp_f32_e32 v52, v44
	v_add_f32_e32 v44, 1.0, v49
	v_rcp_f32_e32 v58, v36
	v_add_f32_e32 v36, 1.0, v41
	v_add_f32_e32 v48, 1.0, v48
	v_rcp_f32_e32 v49, v44
	v_mul_f32_e32 v44, v45, v60
	v_add_f32_e32 v40, 1.0, v40
	v_rcp_f32_e32 v41, v36
	v_mul_f32_e32 v36, v37, v60
	v_rcp_f32_e32 v48, v48
	s_waitcnt lgkmcnt(0)
	v_exp_f32_e32 v53, v44
	v_rcp_f32_e32 v40, v40
	v_exp_f32_e32 v59, v36
	s_waitcnt vmcnt(9)
	v_lshlrev_b32_e32 v44, 16, v88
	v_and_b32_e32 v45, 0xffff0000, v88
	s_waitcnt vmcnt(6)
	v_lshlrev_b32_e32 v36, 16, v72
	v_and_b32_e32 v37, 0xffff0000, v72
	v_pk_fma_f32 v[44:45], v[48:49], v[44:45], v[84:85]
	v_add_f32_e32 v48, 1.0, v53
	v_pk_fma_f32 v[36:37], v[40:41], v[36:37], v[76:77]
	v_add_f32_e32 v40, 1.0, v59
	v_rcp_f32_e32 v53, v48
	v_rcp_f32_e32 v59, v40
	v_mul_f32_e32 v48, v50, v60
	v_mul_f32_e32 v40, v42, v60
	v_exp_f32_e32 v50, v48
	v_lshlrev_b32_e32 v48, 16, v90
	v_and_b32_e32 v49, 0xffff0000, v90
	v_mul_f32_e32 v46, v46, v60
	v_exp_f32_e32 v42, v40
	v_lshlrev_b32_e32 v40, 16, v74
	v_and_b32_e32 v41, 0xffff0000, v74
	v_mul_f32_e32 v38, v38, v60
	v_pk_fma_f32 v[48:49], v[52:53], v[48:49], v[80:81]
	v_exp_f32_e32 v52, v46
	v_mul_f32_e32 v46, v51, v60
	v_pk_fma_f32 v[40:41], v[58:59], v[40:41], v[68:69]
	v_exp_f32_e32 v58, v38
	v_mul_f32_e32 v38, v43, v60
	v_exp_f32_e32 v51, v46
	v_mul_f32_e32 v47, v47, v60
	v_exp_f32_e32 v43, v38
	v_mul_f32_e32 v39, v39, v60
	v_exp_f32_e32 v54, v47
	v_exp_f32_e32 v60, v39
	v_add_f32_e32 v50, 1.0, v50
	v_add_f32_e32 v51, 1.0, v51
	v_add_f32_e32 v42, 1.0, v42
	v_add_f32_e32 v43, 1.0, v43
	v_rcp_f32_e32 v46, v50
	v_add_f32_e32 v50, 1.0, v52
	v_rcp_f32_e32 v47, v51
	v_add_f32_e32 v51, 1.0, v54
	v_rcp_f32_e32 v38, v42
	v_add_f32_e32 v42, 1.0, v58
	v_rcp_f32_e32 v39, v43
	v_add_f32_e32 v43, 1.0, v60
	v_rcp_f32_e32 v50, v50
	v_rcp_f32_e32 v51, v51
	v_rcp_f32_e32 v42, v42
	v_rcp_f32_e32 v43, v43
	v_lshlrev_b32_e32 v52, 16, v89
	v_and_b32_e32 v53, 0xffff0000, v89
	v_lshlrev_b32_e32 v58, 16, v73
	v_and_b32_e32 v59, 0xffff0000, v73
	v_pk_fma_f32 v[46:47], v[46:47], v[52:53], v[86:87]
	v_lshlrev_b32_e32 v52, 16, v91
	v_and_b32_e32 v53, 0xffff0000, v91
	v_pk_fma_f32 v[38:39], v[38:39], v[58:59], v[78:79]
	v_lshlrev_b32_e32 v58, 16, v75
	v_and_b32_e32 v59, 0xffff0000, v75
	v_pk_fma_f32 v[50:51], v[50:51], v[52:53], v[82:83]
	global_store_dwordx4 v[94:95], v[44:47], off
	global_store_dwordx4 v[94:95], v[48:51], off offset:16
	v_cvt_pk_bf16_f32 v52, v44, v45
	v_cvt_pk_bf16_f32 v53, v46, v47
	v_pk_mul_f32 v[44:45], v[44:45], v[44:45]
	v_pk_mul_f32 v[46:47], v[46:47], v[46:47]
	v_pk_fma_f32 v[42:43], v[42:43], v[58:59], v[70:71]
	v_pk_mul_f32 v[58:59], v[36:37], v[36:37]
	v_pk_mul_f32 v[60:61], v[38:39], v[38:39]
	v_cvt_pk_bf16_f32 v54, v48, v49
	v_pk_mul_f32 v[48:49], v[48:49], v[48:49]
	v_pk_mul_f32 v[62:63], v[40:41], v[40:41]
	v_add_f32_e32 v60, v60, v61
	v_add_f32_e32 v58, v58, v59
	v_add_f32_e32 v46, v46, v47
	v_add_f32_e32 v44, v44, v45
	v_cvt_pk_bf16_f32 v55, v50, v51
	v_pk_mul_f32 v[50:51], v[50:51], v[50:51]
	v_pk_mul_f32 v[64:65], v[42:43], v[42:43]
	v_add_f32_e32 v58, v58, v60
	v_add_f32_e32 v59, v62, v63
	v_add_f32_e32 v44, v44, v46
	v_add_f32_e32 v45, v48, v49
	v_add_f32_e32 v64, v64, v65
	v_add_f32_e32 v58, v59, v58
	v_add_f32_e32 v50, v50, v51
	v_add_f32_e32 v44, v45, v44
	v_add_f32_e32 v58, v64, v58
	v_add_f32_e32 v44, v50, v44
	v_add_f32_e32 v45, v44, v58
	ds_bpermute_b32 v46, v184, v45
	global_store_dwordx4 v[56:57], v[52:55], off
	global_store_dwordx4 v[94:95], v[36:39], off offset:128
	global_store_dwordx4 v[94:95], v[40:43], off offset:144
	v_cvt_pk_bf16_f32 v44, v36, v37
	v_cvt_pk_bf16_f32 v47, v42, v43
	s_waitcnt lgkmcnt(0)
	v_add_f32_e32 v36, v45, v46
	ds_bpermute_b32 v37, v183, v36
	v_cvt_pk_bf16_f32 v45, v38, v39
	v_cvt_pk_bf16_f32 v46, v40, v41
	global_store_dwordx4 v[56:57], v[44:47], off offset:64
	s_and_saveexec_b64 s[22:23], s[40:41]
	s_cbranch_execz .LBB0_1285
	s_waitcnt lgkmcnt(0)
	v_add_f32_e32 v38, v36, v37
	v_lshl_add_u64 v[36:37], v[92:93], 2, s[34:35]
	global_atomic_add_f32 v[36:37], v38, off
; __device__ __forceinline__ float rstd_of(float ss, float invn) { return __builtin_amdgcn_rsqf(ss * invn + EPS); }
;     __device__ __forceinline__ void operator()(const Acc& acc, const Unit& u, int wr, int wc, int fr, int fq) const {
;     ...
; #pragma unroll
;             for (int mm = 0; mm < MB; ++mm) {
;                 const int m = mb + mm; const int r = u.pm * BM + ai * HALF + wr * 64 + m * 16 + fr;
;                 tt[mm] = PLE ? rs_in[r] : 0.f;
; #pragma unroll
;                 for (int bj = 0; bj < 2; ++bj) {
;                     const int c0 = u.pn * BM + wc * 64 + bj * 32 + 8 * fq; const float* hs = hsrc + (size_t)r * DM + c0;
;                     pa[mm][bj] = *(const f32x4*)hs; pb[mm][bj] = *(const f32x4*)(hs + 4);
;                     if (PLE) pt[mm][bj] = *(const u32x4*)(tmp + (size_t)r * DM + c0);
;                 }
;             }
; #pragma unroll
;             for (int mm = 0; mm < MB; ++mm) {
;                 const int m = mb + mm; const int r = u.pm * BM + ai * HALF + wr * 64 + m * 16 + fr; float ss = 0.f;
;                 const float t = PLE ? rstd_of(tt[mm], 1.f / 1024.f) : 1.f; const float tl = -t * 1.4426950408889634f; (void)tl;
; #pragma unroll
;                 for (int bj = 0; bj < 2; ++bj) {
;                     const int c0 = u.pn * BM + wc * 64 + bj * 32 + 8 * fq; float* hp = h + (size_t)r * DM + c0;
;                     f32x4 a = pa[mm][bj], b = pb[mm][bj];
;                     if (PLE) { f32x4 ta, tb; unpack8(pt[mm][bj], ta, tb);
; #pragma unroll
;                         for (int j = 0; j < 4; ++j) { a[j] += ta[j] * __builtin_amdgcn_rcpf(1.f + __builtin_amdgcn_exp2f(acc[ai][bj][m][0][j] * tl)); b[j] += tb[j] * __builtin_amdgcn_rcpf(1.f + __builtin_amdgcn_exp2f(acc[ai][bj][m][1][j] * tl)); } }
;                     else { a += acc[ai][bj][m][0] * alpha; b += acc[ai][bj][m][1] * alpha; }
;                     if (!dry || a[0] == 1234.56789f) { *(f32x4*)hp = a; *(f32x4*)(hp + 4) = b;
;                     *(u32x4*)(hb + (size_t)r * DM + c0) = pack8(a, b); }
;                     ss += (a[0] * a[0] + a[1] * a[1]) + (a[2] * a[2] + a[3] * a[3]) + (b[0] * b[0] + b[1] * b[1]) + (b[2] * b[2] + b[3] * b[3]);
;                 }
;                 ss += __shfl_xor(ss, 16); ss += __shfl_xor(ss, 32);
;                 if (fq == 0 && (!dry || ss == 1234.56789f)) unsafeAtomicAdd(rs_out + r, ss);
;             }
.LBB0_1285:
	s_or_b64 exec, exec, s[22:23]
	v_add_u32_e32 v64, 0xa0, v172
	v_ashrrev_i32_e32 v65, 31, v64
	s_waitcnt lgkmcnt(0)
	v_lshl_add_u64 v[36:37], v[64:65], 2, s[6:7]
	global_load_dword v69, v[36:37], off
	v_lshlrev_b64 v[36:37], 11, v[64:65]
	v_lshl_add_u64 v[38:39], s[14:15], 0, v[36:37]
	v_lshl_add_u64 v[38:39], v[38:39], 0, v[168:169]
	v_lshlrev_b64 v[40:41], 12, v[64:65]
	global_load_dwordx4 v[70:73], v[38:39], off
	v_lshl_add_u64 v[40:41], s[4:5], 0, v[40:41]
	v_lshl_add_u64 v[66:67], v[40:41], 0, v[170:171]
	global_load_dwordx4 v[74:77], v[66:67], off
	global_load_dwordx4 v[78:81], v[66:67], off offset:16
	v_add_u32_e32 v60, 0xb0, v172
	v_ashrrev_i32_e32 v61, 31, v60
	v_lshlrev_b64 v[42:43], 12, v[60:61]
	v_lshlrev_b64 v[44:45], 11, v[60:61]
	v_lshl_add_u64 v[42:43], s[4:5], 0, v[42:43]
	v_lshl_add_u64 v[44:45], s[14:15], 0, v[44:45]
	v_lshl_add_u64 v[40:41], v[60:61], 2, s[6:7]
	v_lshl_add_u64 v[36:37], s[12:13], 0, v[36:37]
	v_lshl_add_u64 v[62:63], v[42:43], 0, v[170:171]
	v_lshl_add_u64 v[42:43], v[44:45], 0, v[168:169]
	v_lshl_add_u64 v[94:95], v[36:37], 0, v[168:169]
	global_load_dwordx4 v[82:85], v[38:39], off offset:64
	global_load_dwordx4 v[86:89], v[66:67], off offset:144
	global_load_dwordx4 v[90:93], v[66:67], off offset:128
	global_load_dwordx4 v[48:51], v[62:63], off offset:16
	global_load_dwordx4 v[52:55], v[62:63], off
	global_load_dword v68, v[40:41], off
	global_load_dwordx4 v[56:59], v[42:43], off
	global_load_dwordx4 v[36:39], v[62:63], off offset:144
	global_load_dwordx4 v[44:47], v[62:63], off offset:128
	s_nop 0
	global_load_dwordx4 v[40:43], v[42:43], off offset:64
	s_waitcnt vmcnt(13)
	v_fmamk_f32 v69, v69, 0x3a800000, v236
	v_rsq_f32_e32 v69, v69
	s_waitcnt vmcnt(12)
	v_lshlrev_b32_e32 v96, 16, v70
	v_mul_f32_e32 v69, 0xbfb8aa3b, v69
	v_mul_f32_e32 v32, v32, v69
	v_mul_f32_e32 v33, v33, v69
	v_mul_f32_e32 v24, v24, v69
	v_exp_f32_e32 v32, v32
	v_exp_f32_e32 v33, v33
	v_exp_f32_e32 v24, v24
	v_mul_f32_e32 v28, v28, v69
	v_mul_f32_e32 v29, v29, v69
	v_mul_f32_e32 v20, v20, v69
	v_mul_f32_e32 v25, v25, v69
	v_mul_f32_e32 v30, v30, v69
	v_mul_f32_e32 v31, v31, v69
	v_exp_f32_e32 v28, v28
	v_exp_f32_e32 v29, v29
	v_exp_f32_e32 v20, v20
	v_exp_f32_e32 v103, v25
	v_add_f32_e32 v25, 1.0, v32
	v_add_f32_e32 v32, 1.0, v33
	v_exp_f32_e32 v30, v30
	v_exp_f32_e32 v31, v31
	v_add_f32_e32 v102, 1.0, v24
	v_rcp_f32_e32 v24, v25
	v_rcp_f32_e32 v25, v32
	v_and_b32_e32 v97, 0xffff0000, v70
	v_add_f32_e32 v28, 1.0, v28
	v_add_f32_e32 v29, 1.0, v29
	v_add_f32_e32 v20, 1.0, v20
	v_add_f32_e32 v100, 1.0, v30
	v_add_f32_e32 v101, 1.0, v31
	v_rcp_f32_e32 v30, v28
	v_rcp_f32_e32 v31, v29
	s_waitcnt vmcnt(11)
	v_pk_fma_f32 v[28:29], v[24:25], v[96:97], v[74:75]
	v_rcp_f32_e32 v24, v20
	v_add_f32_e32 v20, 1.0, v103
	v_rcp_f32_e32 v103, v20
	v_mul_f32_e32 v20, v21, v69
	v_exp_f32_e32 v25, v20
	s_waitcnt vmcnt(9)
	v_lshlrev_b32_e32 v74, 16, v84
	v_and_b32_e32 v75, 0xffff0000, v84
	v_mul_f32_e32 v22, v22, v69
	v_add_f32_e32 v25, 1.0, v25
	v_rcp_f32_e32 v25, v25
	v_mul_f32_e32 v34, v34, v69
	v_mul_f32_e32 v35, v35, v69
	v_mul_f32_e32 v26, v26, v69
	s_waitcnt vmcnt(8)
	v_pk_fma_f32 v[24:25], v[24:25], v[74:75], v[86:87]
	v_exp_f32_e32 v74, v22
	v_mul_f32_e32 v22, v27, v69
	v_exp_f32_e32 v34, v34
	v_exp_f32_e32 v35, v35
	v_exp_f32_e32 v26, v26
	v_exp_f32_e32 v27, v22
	v_mul_f32_e32 v23, v23, v69
	v_exp_f32_e32 v69, v23
	v_add_f32_e32 v33, 1.0, v34
	v_add_f32_e32 v35, 1.0, v35
	v_add_f32_e32 v26, 1.0, v26
	v_add_f32_e32 v27, 1.0, v27
	v_rcp_f32_e32 v34, v33
	v_rcp_f32_e32 v35, v35
	v_rcp_f32_e32 v102, v102
	v_rcp_f32_e32 v22, v26
	v_add_f32_e32 v26, 1.0, v74
	v_rcp_f32_e32 v23, v27
	v_add_f32_e32 v27, 1.0, v69
	v_rcp_f32_e32 v100, v100
	v_rcp_f32_e32 v101, v101
	v_rcp_f32_e32 v26, v26
	v_rcp_f32_e32 v27, v27
	v_lshlrev_b32_e32 v98, 16, v72
	v_and_b32_e32 v99, 0xffff0000, v72
	v_lshlrev_b32_e32 v70, 16, v71
	v_and_b32_e32 v71, 0xffff0000, v71
	v_lshlrev_b32_e32 v20, 16, v82
	v_and_b32_e32 v21, 0xffff0000, v82
	v_lshlrev_b32_e32 v74, 16, v83
	v_and_b32_e32 v75, 0xffff0000, v83
	v_lshlrev_b32_e32 v72, 16, v73
	v_and_b32_e32 v73, 0xffff0000, v73
	v_pk_fma_f32 v[32:33], v[30:31], v[98:99], v[78:79]
	v_pk_fma_f32 v[30:31], v[34:35], v[70:71], v[76:77]
	s_waitcnt vmcnt(7)
	v_pk_fma_f32 v[20:21], v[102:103], v[20:21], v[90:91]
	v_pk_fma_f32 v[22:23], v[22:23], v[74:75], v[92:93]
	v_lshlrev_b32_e32 v74, 16, v85
	v_and_b32_e32 v75, 0xffff0000, v85
	v_pk_fma_f32 v[34:35], v[100:101], v[72:73], v[80:81]
	global_store_dwordx4 v[66:67], v[28:31], off
	global_store_dwordx4 v[66:67], v[32:35], off offset:16
	v_cvt_pk_bf16_f32 v70, v28, v29
	v_cvt_pk_bf16_f32 v71, v30, v31
	v_pk_mul_f32 v[28:29], v[28:29], v[28:29]
	v_pk_mul_f32 v[30:31], v[30:31], v[30:31]
	v_pk_fma_f32 v[26:27], v[26:27], v[74:75], v[88:89]
	v_pk_mul_f32 v[74:75], v[20:21], v[20:21]
	v_pk_mul_f32 v[76:77], v[22:23], v[22:23]
	v_cvt_pk_bf16_f32 v72, v32, v33
	v_pk_mul_f32 v[32:33], v[32:33], v[32:33]
	v_pk_mul_f32 v[78:79], v[24:25], v[24:25]
	v_add_f32_e32 v69, v76, v77
	v_add_f32_e32 v74, v74, v75
	v_add_f32_e32 v30, v30, v31
	v_add_f32_e32 v28, v28, v29
	v_cvt_pk_bf16_f32 v73, v34, v35
	v_pk_mul_f32 v[34:35], v[34:35], v[34:35]
	v_pk_mul_f32 v[80:81], v[26:27], v[26:27]
	v_add_f32_e32 v69, v74, v69
	v_add_f32_e32 v74, v78, v79
	v_add_f32_e32 v28, v28, v30
	v_add_f32_e32 v29, v32, v33
	v_add_f32_e32 v69, v74, v69
	v_add_f32_e32 v74, v80, v81
	v_add_f32_e32 v28, v29, v28
	v_add_f32_e32 v29, v34, v35
	v_add_f32_e32 v69, v74, v69
	v_add_f32_e32 v28, v29, v28
	v_add_f32_e32 v29, v28, v69
	ds_bpermute_b32 v30, v184, v29
	global_store_dwordx4 v[94:95], v[70:73], off
	global_store_dwordx4 v[66:67], v[20:23], off offset:128
	global_store_dwordx4 v[66:67], v[24:27], off offset:144
	v_cvt_pk_bf16_f32 v28, v20, v21
	v_cvt_pk_bf16_f32 v31, v26, v27
	s_waitcnt lgkmcnt(0)
	v_add_f32_e32 v20, v29, v30
	ds_bpermute_b32 v21, v183, v20
	v_cvt_pk_bf16_f32 v29, v22, v23
	v_cvt_pk_bf16_f32 v30, v24, v25
	global_store_dwordx4 v[94:95], v[28:31], off offset:64
	s_and_saveexec_b64 s[22:23], s[40:41]
	s_cbranch_execz .LBB0_1287
	s_waitcnt lgkmcnt(0)
	v_add_f32_e32 v22, v20, v21
	v_lshl_add_u64 v[20:21], v[64:65], 2, s[34:35]
	global_atomic_add_f32 v[20:21], v22, off
; __device__ __forceinline__ float rstd_of(float ss, float invn) { return __builtin_amdgcn_rsqf(ss * invn + EPS); }
; __device__ __forceinline__ u32x4 pack8(f32x4 a, f32x4 b) { u32x4 w; w.x = cvtpk(a[0], a[1]); w.y = cvtpk(a[2], a[3]); w.z = cvtpk(b[0], b[1]); w.w = cvtpk(b[2], b[3]); return w; }
; __device__ __forceinline__ void unpack8(u32x4 w, f32x4& a, f32x4& b) { a = (f32x4){bflo(w.x), bfhi(w.x), bflo(w.y), bfhi(w.y)}; b = (f32x4){bflo(w.z), bfhi(w.z), bflo(w.w), bfhi(w.w)}; }
;     __device__ __forceinline__ void operator()(const Acc& acc, const Unit& u, int wr, int wc, int fr, int fq) const {
;     ...
;             for (int mm = 0; mm < MB; ++mm) {
;                 const int m = mb + mm; const int r = u.pm * BM + ai * HALF + wr * 64 + m * 16 + fr; float ss = 0.f;
;                 const float t = PLE ? rstd_of(tt[mm], 1.f / 1024.f) : 1.f; const float tl = -t * 1.4426950408889634f; (void)tl;
; #pragma unroll
;                 for (int bj = 0; bj < 2; ++bj) {
;                     const int c0 = u.pn * BM + wc * 64 + bj * 32 + 8 * fq; float* hp = h + (size_t)r * DM + c0;
;                     f32x4 a = pa[mm][bj], b = pb[mm][bj];
;                     if (PLE) { f32x4 ta, tb; unpack8(pt[mm][bj], ta, tb);
; #pragma unroll
;                         for (int j = 0; j < 4; ++j) { a[j] += ta[j] * __builtin_amdgcn_rcpf(1.f + __builtin_amdgcn_exp2f(acc[ai][bj][m][0][j] * tl)); b[j] += tb[j] * __builtin_amdgcn_rcpf(1.f + __builtin_amdgcn_exp2f(acc[ai][bj][m][1][j] * tl)); } }
;                     else { a += acc[ai][bj][m][0] * alpha; b += acc[ai][bj][m][1] * alpha; }
;                     if (!dry || a[0] == 1234.56789f) { *(f32x4*)hp = a; *(f32x4*)(hp + 4) = b;
;                     *(u32x4*)(hb + (size_t)r * DM + c0) = pack8(a, b); }
;                     ss += (a[0] * a[0] + a[1] * a[1]) + (a[2] * a[2] + a[3] * a[3]) + (b[0] * b[0] + b[1] * b[1]) + (b[2] * b[2] + b[3] * b[3]);
;                 }
;                 ss += __shfl_xor(ss, 16); ss += __shfl_xor(ss, 32);
;                 if (fq == 0 && (!dry || ss == 1234.56789f)) unsafeAtomicAdd(rs_out + r, ss);
;             }
.LBB0_1287:
	s_or_b64 exec, exec, s[22:23]
	s_waitcnt vmcnt(10)
	v_fmamk_f32 v20, v68, 0x3a800000, v236
	v_rsq_f32_e32 v20, v20
	v_lshlrev_b64 v[24:25], 10, v[60:61]
	v_lshl_add_u64 v[24:25], v[24:25], 1, s[12:13]
	v_lshl_add_u64 v[24:25], v[166:167], 1, v[24:25]
	v_mul_f32_e32 v28, 0xbfb8aa3b, v20
	v_mul_f32_e32 v12, v12, v28
	v_mul_f32_e32 v4, v4, v28
	v_exp_f32_e32 v12, v12
	v_mul_f32_e32 v17, v17, v28
	v_exp_f32_e32 v4, v4
	v_mul_f32_e32 v9, v9, v28
	v_mul_f32_e32 v16, v16, v28
	v_exp_f32_e32 v17, v17
	v_mul_f32_e32 v8, v8, v28
	v_exp_f32_e32 v9, v9
	v_exp_f32_e32 v16, v16
	v_exp_f32_e32 v8, v8
	v_add_f32_e32 v12, 1.0, v12
	v_add_f32_e32 v4, 1.0, v4
	v_rcp_f32_e32 v20, v12
	v_add_f32_e32 v12, 1.0, v17
	v_rcp_f32_e32 v26, v4
	v_add_f32_e32 v4, 1.0, v9
	v_add_f32_e32 v16, 1.0, v16
	v_rcp_f32_e32 v17, v12
	v_mul_f32_e32 v12, v13, v28
	v_add_f32_e32 v8, 1.0, v8
	v_rcp_f32_e32 v9, v4
	v_mul_f32_e32 v4, v5, v28
	v_rcp_f32_e32 v16, v16
	s_waitcnt lgkmcnt(0)
	v_exp_f32_e32 v21, v12
	v_rcp_f32_e32 v8, v8
	v_exp_f32_e32 v27, v4
	s_waitcnt vmcnt(9)
	v_lshlrev_b32_e32 v12, 16, v56
	v_and_b32_e32 v13, 0xffff0000, v56
	s_waitcnt vmcnt(6)
	v_lshlrev_b32_e32 v4, 16, v40
	v_and_b32_e32 v5, 0xffff0000, v40
	v_pk_fma_f32 v[12:13], v[16:17], v[12:13], v[52:53]
	v_add_f32_e32 v16, 1.0, v21
	v_pk_fma_f32 v[4:5], v[8:9], v[4:5], v[44:45]
	v_add_f32_e32 v8, 1.0, v27
	v_rcp_f32_e32 v21, v16
	v_rcp_f32_e32 v27, v8
	v_mul_f32_e32 v16, v18, v28
	v_mul_f32_e32 v8, v10, v28
	v_exp_f32_e32 v18, v16
	v_lshlrev_b32_e32 v16, 16, v58
	v_and_b32_e32 v17, 0xffff0000, v58
	v_mul_f32_e32 v14, v14, v28
	v_exp_f32_e32 v10, v8
	v_lshlrev_b32_e32 v8, 16, v42
	v_and_b32_e32 v9, 0xffff0000, v42
	v_mul_f32_e32 v6, v6, v28
	v_pk_fma_f32 v[16:17], v[20:21], v[16:17], v[48:49]
	v_exp_f32_e32 v20, v14
	v_mul_f32_e32 v14, v19, v28
	v_pk_fma_f32 v[8:9], v[26:27], v[8:9], v[36:37]
	v_exp_f32_e32 v26, v6
	v_mul_f32_e32 v6, v11, v28
	v_exp_f32_e32 v19, v14
	v_mul_f32_e32 v15, v15, v28
	v_exp_f32_e32 v11, v6
	v_mul_f32_e32 v7, v7, v28
	v_exp_f32_e32 v22, v15
	v_exp_f32_e32 v28, v7
	v_add_f32_e32 v18, 1.0, v18
	v_add_f32_e32 v19, 1.0, v19
	v_add_f32_e32 v10, 1.0, v10
	v_add_f32_e32 v11, 1.0, v11
	v_rcp_f32_e32 v14, v18
	v_add_f32_e32 v18, 1.0, v20
	v_rcp_f32_e32 v15, v19
	v_add_f32_e32 v19, 1.0, v22
	v_rcp_f32_e32 v6, v10
	v_add_f32_e32 v10, 1.0, v26
	v_rcp_f32_e32 v7, v11
	v_add_f32_e32 v11, 1.0, v28
	v_rcp_f32_e32 v18, v18
	v_rcp_f32_e32 v19, v19
	v_rcp_f32_e32 v10, v10
	v_rcp_f32_e32 v11, v11
	v_lshlrev_b32_e32 v20, 16, v57
	v_and_b32_e32 v21, 0xffff0000, v57
	v_lshlrev_b32_e32 v26, 16, v41
	v_and_b32_e32 v27, 0xffff0000, v41
	v_pk_fma_f32 v[14:15], v[14:15], v[20:21], v[54:55]
	v_lshlrev_b32_e32 v20, 16, v59
	v_and_b32_e32 v21, 0xffff0000, v59
	v_pk_fma_f32 v[6:7], v[6:7], v[26:27], v[46:47]
	v_lshlrev_b32_e32 v26, 16, v43
	v_and_b32_e32 v27, 0xffff0000, v43
	v_pk_fma_f32 v[18:19], v[18:19], v[20:21], v[50:51]
	global_store_dwordx4 v[62:63], v[12:15], off
	global_store_dwordx4 v[62:63], v[16:19], off offset:16
	v_cvt_pk_bf16_f32 v20, v12, v13
	v_cvt_pk_bf16_f32 v21, v14, v15
	v_pk_mul_f32 v[12:13], v[12:13], v[12:13]
	v_pk_mul_f32 v[14:15], v[14:15], v[14:15]
	v_pk_fma_f32 v[10:11], v[10:11], v[26:27], v[38:39]
	v_pk_mul_f32 v[26:27], v[4:5], v[4:5]
	v_pk_mul_f32 v[28:29], v[6:7], v[6:7]
	v_cvt_pk_bf16_f32 v22, v16, v17
	v_pk_mul_f32 v[16:17], v[16:17], v[16:17]
	v_pk_mul_f32 v[30:31], v[8:9], v[8:9]
	v_add_f32_e32 v28, v28, v29
	v_add_f32_e32 v26, v26, v27
	v_add_f32_e32 v14, v14, v15
	v_add_f32_e32 v12, v12, v13
	v_cvt_pk_bf16_f32 v23, v18, v19
	v_pk_mul_f32 v[18:19], v[18:19], v[18:19]
	v_pk_mul_f32 v[32:33], v[10:11], v[10:11]
	v_add_f32_e32 v26, v26, v28
	v_add_f32_e32 v27, v30, v31
	v_add_f32_e32 v12, v12, v14
	v_add_f32_e32 v13, v16, v17
	v_add_f32_e32 v32, v32, v33
	v_add_f32_e32 v26, v27, v26
	v_add_f32_e32 v18, v18, v19
	v_add_f32_e32 v12, v13, v12
	v_add_f32_e32 v26, v32, v26
	v_add_f32_e32 v12, v18, v12
	v_add_f32_e32 v13, v12, v26
	ds_bpermute_b32 v14, v184, v13
	global_store_dwordx4 v[24:25], v[20:23], off
	global_store_dwordx4 v[62:63], v[4:7], off offset:128
	global_store_dwordx4 v[62:63], v[8:11], off offset:144
	v_cvt_pk_bf16_f32 v12, v4, v5
	v_cvt_pk_bf16_f32 v15, v10, v11
	s_waitcnt lgkmcnt(0)
	v_add_f32_e32 v4, v13, v14
	ds_bpermute_b32 v5, v183, v4
	v_cvt_pk_bf16_f32 v13, v6, v7
	v_cvt_pk_bf16_f32 v14, v8, v9
	global_store_dwordx4 v[24:25], v[12:15], off offset:64
	s_and_saveexec_b64 s[22:23], s[40:41]
	s_cbranch_execz .LBB0_1289
	s_waitcnt lgkmcnt(0)
	v_add_f32_e32 v6, v4, v5
	v_lshl_add_u64 v[4:5], v[60:61], 2, s[34:35]
	global_atomic_add_f32 v[4:5], v6, off

; #define LAS __attribute__((address_space(3)))
; __device__ __forceinline__ int otid() { int t = threadIdx.x; asm volatile("" : "+v"(t)); return t; }
; __device__ __forceinline__ void convert_weights(LAS unsigned char* lds, int layer, int j0, int j1) {
;     const int tid = otid(); const int lane = tid & 63, wid = tid >> 6;
;     LAS float* scr = (LAS float*)(lds + wid * 8704);
;     const int gw = blockIdx.x * NWAVES + wid, NGW = gridDim.x * NWAVES;
;     for (int j = j0; j < j1; ++j) {
.LBB0_1293:
	v_readlane_b32 s4, v252, 45
	v_readlane_b32 s5, v252, 46
	v_readlane_b32 s22, v252, 23
	s_and_b64 vcc, exec, s[4:5]
	v_readlane_b32 s23, v252, 24
	s_cbranch_vccnz .LBB0_1388
	v_mov_b32_e32 v4, v234
	s_waitcnt vmcnt(0) lgkmcnt(0)
	s_barrier
	s_movk_i32 s4, 0x2200
	v_ashrrev_i32_e32 v5, 6, v4
	v_mul_lo_u32 v0, v5, s4
	v_add_u32_e32 v6, 0, v0
	v_lshlrev_b32_e32 v0, 2, v4
	v_and_b32_e32 v10, 7, v4
	v_bfe_u32 v19, v4, 3, 3
	v_and_b32_e32 v3, 31, v4
	v_and_b32_e32 v7, 3, v4
	v_and_b32_e32 v8, 16, v0
	v_lshrrev_b32_e32 v9, 1, v4
	s_movk_i32 s4, 0x280
	v_lshlrev_b32_e32 v0, 3, v10
	v_mul_u32_u24_e32 v10, 0x420, v10
	v_lshlrev_b32_e32 v12, 2, v19
	v_or3_b32 v13, v7, v8, s4
	v_lshl_add_u32 v11, v3, 2, v6
	v_add3_u32 v21, v6, v10, v12
	v_and_or_b32 v6, v9, 12, v8
	v_readlane_b32 s4, v252, 0
	v_or3_b32 v12, v7, v6, 64
	v_and_b32_e32 v6, 0xffffffc0, v4
	v_lshl_add_u32 v24, v5, 5, s4
	v_readlane_b32 s4, v252, 1
	v_bfe_u32 v17, v4, 5, 1
	v_add_u32_e32 v1, s93, v5
	v_add_u32_e32 v25, s4, v6
	v_readlane_b32 s4, v252, 2
	v_mul_u32_u24_e32 v14, 0x84, v17
	s_mov_b32 s28, 0
	v_lshl_add_u32 v26, v5, 4, s4
	v_lshlrev_b16_e32 v5, 5, v5
	v_bitop3_b16 v27, v5, v4, 31 bitop3:0xf8
	v_add_u32_e32 v28, v11, v14
	s_mov_b32 s60, 0
	s_branch .LBB0_1296

; __device__ __forceinline__ void convert_weights(LAS unsigned char* lds, int layer, int j0, int j1) {
;     ...
;     for (int j = j0; j < j1; ++j) {
;         const Job J = get_job(layer, j);
;         const int nitems = (J.K / 64) * (J.Nd / 32);
;         for (int it = gw; it < nitems; it += NGW) convert_item(J, scr, it, lane);
.LBB0_1349:
	s_waitcnt lgkmcnt(0)
	s_lshr_b32 s12, s45, 6
	s_mul_i32 s48, s44, s12
	v_subrev_u32_e32 v100, s60, v1
	v_add_u32_e32 v101, s26, v100
	v_cmp_gt_i32_e32 vcc, 0, v100
	s_nop 1
	v_cndmask_b32_e32 v100, v100, v101, vcc
	s_add_i32 s60, s60, s48
	s_cmp_ge_u32 s60, s26
	s_cselect_b32 s61, s26, 0
	s_sub_i32 s60, s60, s61
	s_cmp_ge_u32 s60, s26
	s_cselect_b32 s61, s26, 0
	s_sub_i32 s60, s60, s61
	v_cmp_gt_i32_e32 vcc, s48, v100
	s_and_saveexec_b64 s[12:13], vcc
	s_cbranch_execz .LBB0_1295
	v_cvt_f32_u32_e32 v5, s44
	v_lshlrev_b32_e32 v4, 2, v0
	s_lshl_b64 s[14:15], s[10:11], 3
	s_cmp_lg_u64 s[38:39], 0
	v_rcp_iflag_f32_e32 v6, v5
	v_mov_b32_e32 v5, v2
	v_lshl_add_u64 v[14:15], s[38:39], 0, v[4:5]
	s_cselect_b64 s[40:41], -1, 0
	v_mul_f32_e32 v4, 0x4f7ffffe, v6
	v_cvt_u32_f32_e32 v4, v4
	s_sub_i32 s49, 0, s44
	s_lshl_b32 s22, s44, 6
	s_lshl_b32 s50, s44, 5
	v_mul_lo_u32 v5, s49, v4
	v_mul_hi_u32 v5, v4, v5
	s_sub_i32 s53, 0, s22
	s_lshl_b32 s22, s44, 4
	s_mov_b64 s[34:35], 0
	v_add_u32_e32 v29, v4, v5
	s_sub_i32 s51, 0, s50
	s_lshl_b32 s52, s26, 5
	s_lshl_b32 s54, s26, 6
	s_sub_i32 s55, 0, s22
	s_lshl_b32 s56, s26, 4
	v_sub_u32_e32 v101, v100, v1
	v_lshlrev_b32_e32 v102, 5, v101
	v_add_u16_e32 v30, v27, v102
	v_lshl_add_u32 v16, v101, 4, v26
	v_lshl_add_u32 v18, v101, 6, v25
	v_lshl_add_u32 v31, v101, 5, v24
	v_mov_b32_e32 v20, v100
	s_branch .LBB0_1354

; __device__ __forceinline__ float rstd_of(float ss, float invn) { return __builtin_amdgcn_rsqf(ss * invn + EPS); }
; __global__ void __launch_bounds__(NTHREADS, 2) fwd_megakernel(Params Pkern) {
;     ...
;         for (int m = gw; m < T; m += NGW) {
;             const float t = rstd_of(rsf[m], 1.f / 1024.f); f32x4* orow = (f32x4*)(OUT + (size_t)m * DM) + lane;
; #pragma unroll
;             for (int j = 0; j < 4; ++j) orow[64 * j] = orow[64 * j] * t * w[j];
;         }
.LBB0_1439:
	global_load_dword v38, v[18:19], off
	global_load_dwordx4 v[22:25], v[20:21], off offset:-2048
	global_load_dwordx4 v[26:29], v[20:21], off offset:-1024
	global_load_dwordx4 v[30:33], v[20:21], off
	global_load_dwordx4 v[34:37], v[20:21], off offset:1024
	v_add_u32_e32 v16, s26, v16
	v_cmp_lt_i32_e32 vcc, s6, v16
	v_lshl_add_u64 v[18:19], v[18:19], 0, s[0:1]
	s_or_b64 s[4:5], vcc, s[4:5]
	s_waitcnt vmcnt(0)
	v_fmamk_f32 v38, v38, 0x3a800000, v17
	v_rsq_f32_e32 v38, v38
	s_nop 0
	v_pk_mul_f32 v[22:23], v[38:39], v[22:23] op_sel_hi:[0,1]
	v_pk_mul_f32 v[24:25], v[38:39], v[24:25] op_sel_hi:[0,1]
	v_pk_mul_f32 v[26:27], v[38:39], v[26:27] op_sel_hi:[0,1]
	v_pk_mul_f32 v[28:29], v[38:39], v[28:29] op_sel_hi:[0,1]
	v_pk_mul_f32 v[30:31], v[38:39], v[30:31] op_sel_hi:[0,1]
	v_pk_mul_f32 v[32:33], v[38:39], v[32:33] op_sel_hi:[0,1]
	v_pk_mul_f32 v[34:35], v[38:39], v[34:35] op_sel_hi:[0,1]
	v_pk_mul_f32 v[36:37], v[38:39], v[36:37] op_sel_hi:[0,1]
	v_pk_mul_f32 v[24:25], v[2:3], v[24:25]
	v_pk_mul_f32 v[22:23], v[0:1], v[22:23]
	v_pk_mul_f32 v[28:29], v[6:7], v[28:29]
	v_pk_mul_f32 v[26:27], v[4:5], v[26:27]
	v_pk_mul_f32 v[32:33], v[10:11], v[32:33]
	v_pk_mul_f32 v[30:31], v[8:9], v[30:31]
	v_pk_mul_f32 v[36:37], v[14:15], v[36:37]
	v_pk_mul_f32 v[34:35], v[12:13], v[34:35]
	global_store_dwordx4 v[20:21], v[22:25], off offset:-2048
	global_store_dwordx4 v[20:21], v[26:29], off offset:-1024
	global_store_dwordx4 v[20:21], v[30:33], off
	global_store_dwordx4 v[20:21], v[34:37], off offset:1024
	v_lshl_add_u64 v[20:21], v[20:21], 0, s[2:3]
	s_andn2_b64 exec, exec, s[4:5]
	s_cbranch_execnz .LBB0_1439
